# t45 with the priority no-ops and redundant wait parked right before each load segment's vmcnt wait instead of at the segment start (same bytes)
# baseline (speedup 1.0000x reference)
; #define PG8_STAGE(bufoff, gbase, voff) do { _Pragma("unroll") for (int _i = 0; _i < 2; ++_i) \
;         __builtin_amdgcn_global_load_lds((const unsigned*)((const char*)(gbase) + (voff)[_i]), (PG8_LAS unsigned*)(lds + (bufoff) + ldsw + _i * 8192), 16, 0, 0); } while (0)
; #define PG8_LDA(dst, b, h) do { _Pragma("unroll") for (int m = 0; m < 4; ++m) _Pragma("unroll") for (int k = 0; k < 2; ++k) dst[m][k] = *(const PG8_LAS bf16x8*)(lds + PG8_SA(b, h) + aoff + m * 2048 + k * 1024); } while (0)
; #define PG8_LDB(dst, b, h) do { _Pragma("unroll") for (int n = 0; n < 2; ++n) _Pragma("unroll") for (int k = 0; k < 2; ++k) dst[n][k] = *(const PG8_LAS bf16x8*)(lds + PG8_SB(b, h) + boff + n * 2048 + k * 1024); } while (0)
; template <class Epi, class Sched, bool ALIGN_EPI = false, bool SP2 = false>
; __device__ __forceinline__ void gemm_phase(PG8_LAS unsigned char* lds, const Gemm g, const Sched& S, const Epi& E) {
;     ...
;         for (int t = 0; t < nt; t += 2) {
;             const bool last = (t == nt - 2);
;             const char* a1 = cA + (size_t)(t + 1) * kstep;
;             const char* a2 = last ? nA : cA + (size_t)(t + 2) * kstep; const char* b2 = last ? nB : cB + (size_t)(t + 2) * kstep;
;             const char* a3 = a2 + kstep; const char* b3 = b2 + kstep;
;             if (last && has_next) S.a_ready(nxt);
;             if constexpr (SP2) {
;             PG8_LDB(B0, 0, 0); PG8_LDB(B1, 0, 1); PG8_SCHED; PG8_LDA(At, 0, 0); PG8_STAGE(PG8_SA(1, 1), a1 + hstep, voffA);
;             PG8_WAIT_V(8); PG8_WAIT_L(0); PG8_BAR; PG8_MMA(0, 0, At, B0); PG8_MMA(0, 1, At, B1); PG8_BAR; PG8_SCHED;
;             PG8_LDA(At, 0, 1); PG8_STAGE(PG8_SB(0, 0), b2, voffB); PG8_STAGE(PG8_SB(0, 1), b2 + hstep, voffB); PG8_STAGE(PG8_SA(0, 0), a2, voffA);
;             PG8_WAIT_V(8); PG8_WAIT_L(0); PG8_BAR; PG8_MMA(1, 0, At, B0); PG8_MMA(1, 1, At, B1); PG8_BAR; PG8_SCHED;
;             PG8_LDB(B0, 1, 0); PG8_LDB(B1, 1, 1); PG8_SCHED; PG8_LDA(At, 1, 0); PG8_STAGE(PG8_SA(0, 1), a2 + hstep, voffA);
;             PG8_WAIT_V(8); PG8_WAIT_L(0); PG8_BAR; PG8_MMA(0, 0, At, B0); PG8_MMA(0, 1, At, B1); PG8_BAR; PG8_SCHED;
;             PG8_LDA(At, 1, 1); PG8_STAGE(PG8_SB(1, 0), b3, voffB); PG8_STAGE(PG8_SB(1, 1), b3 + hstep, voffB); PG8_STAGE(PG8_SA(1, 0), a3, voffA);
;             PG8_WAIT_V(8); PG8_WAIT_L(0); PG8_BAR; PG8_MMA(1, 0, At, B0); PG8_MMA(1, 1, At, B1); PG8_BAR; PG8_SCHED;
.LBB0_239:
	s_add_u32 s48, s12, 0xfff80080
	s_addc_u32 s49, s13, -1
	s_cmp_eq_u32 s47, 28
	s_cselect_b32 s51, s1, s49
	s_cselect_b32 s50, s2, s48
	s_cselect_b32 s49, s3, s37
	s_cselect_b32 s48, s15, s35
	s_add_i32 s65, 0, 0x10000
	v_add_u32_e32 v0, s65, v185
	s_add_i32 s68, 0, 0x14000
	ds_read_b128 v[132:135], v0
	ds_read_b128 v[136:139], v0 offset:1024
	ds_read_b128 v[140:143], v0 offset:2048
	ds_read_b128 v[144:147], v0 offset:3072
	v_add_u32_e32 v0, s68, v185
	ds_read_b128 v[148:151], v0
	ds_read_b128 v[152:155], v0 offset:1024
	ds_read_b128 v[172:175], v0 offset:2048
	ds_read_b128 v[176:179], v0 offset:3072
	v_lshl_add_u64 v[228:229], s[12:13], 0, v[168:169]
	s_add_i32 m0, s53, 0xc000
	ds_read_b128 v[180:183], v190
	ds_read_b128 v[192:195], v190 offset:1024
	ds_read_b128 v[196:199], v190 offset:2048
	ds_read_b128 v[200:203], v190 offset:3072
	ds_read_b128 v[204:207], v190 offset:4096
	ds_read_b128 v[208:211], v190 offset:5120
	ds_read_b128 v[220:223], v190 offset:6144
	ds_read_b128 v[224:227], v190 offset:7168
	global_load_lds_dwordx4 v[228:229], off
	v_lshl_add_u64 v[228:229], s[12:13], 0, v[170:171]
	s_add_i32 m0, s53, 0xe000
	s_nop 0
	global_load_lds_dwordx4 v[228:229], off
	s_setprio 1
	s_waitcnt vmcnt(8)
	s_waitcnt lgkmcnt(0)
	s_barrier
	v_mfma_f32_16x16x32_bf16 v[128:131], v[132:135], v[180:183], v[128:131]
	v_mfma_f32_16x16x32_bf16 v[124:127], v[140:143], v[180:183], v[124:127]
	v_mfma_f32_16x16x32_bf16 v[112:115], v[132:135], v[196:199], v[112:115]
	v_mfma_f32_16x16x32_bf16 v[108:111], v[140:143], v[196:199], v[108:111]
	v_mfma_f32_16x16x32_bf16 v[96:99], v[132:135], v[204:207], v[96:99]
	v_mfma_f32_16x16x32_bf16 v[92:95], v[140:143], v[204:207], v[92:95]
	v_mfma_f32_16x16x32_bf16 v[80:83], v[132:135], v[220:223], v[80:83]
	v_mfma_f32_16x16x32_bf16 v[76:79], v[140:143], v[220:223], v[76:79]
	v_mfma_f32_16x16x32_bf16 v[128:131], v[136:139], v[192:195], v[128:131]
	v_mfma_f32_16x16x32_bf16 v[124:127], v[144:147], v[192:195], v[124:127]
	v_mfma_f32_16x16x32_bf16 v[112:115], v[136:139], v[200:203], v[112:115]
	v_mfma_f32_16x16x32_bf16 v[108:111], v[144:147], v[200:203], v[108:111]
	v_mfma_f32_16x16x32_bf16 v[96:99], v[136:139], v[208:211], v[96:99]
	v_mfma_f32_16x16x32_bf16 v[92:95], v[144:147], v[208:211], v[92:95]
	v_mfma_f32_16x16x32_bf16 v[80:83], v[136:139], v[224:227], v[80:83]
	v_mfma_f32_16x16x32_bf16 v[76:79], v[144:147], v[224:227], v[76:79]
	v_mfma_f32_16x16x32_bf16 v[120:123], v[148:151], v[180:183], v[120:123]
	v_mfma_f32_16x16x32_bf16 v[116:119], v[172:175], v[180:183], v[116:119]
	v_mfma_f32_16x16x32_bf16 v[104:107], v[148:151], v[196:199], v[104:107]
	v_mfma_f32_16x16x32_bf16 v[100:103], v[172:175], v[196:199], v[100:103]
	v_mfma_f32_16x16x32_bf16 v[88:91], v[148:151], v[204:207], v[88:91]
	v_mfma_f32_16x16x32_bf16 v[84:87], v[172:175], v[204:207], v[84:87]
	v_mfma_f32_16x16x32_bf16 v[72:75], v[148:151], v[220:223], v[72:75]
	v_mfma_f32_16x16x32_bf16 v[68:71], v[172:175], v[220:223], v[68:71]
	v_mfma_f32_16x16x32_bf16 v[120:123], v[152:155], v[192:195], v[120:123]
	v_mfma_f32_16x16x32_bf16 v[116:119], v[176:179], v[192:195], v[116:119]
	v_mfma_f32_16x16x32_bf16 v[104:107], v[152:155], v[200:203], v[104:107]
	v_mfma_f32_16x16x32_bf16 v[100:103], v[176:179], v[200:203], v[100:103]
	v_mfma_f32_16x16x32_bf16 v[88:91], v[152:155], v[208:211], v[88:91]
	v_mfma_f32_16x16x32_bf16 v[84:87], v[176:179], v[208:211], v[84:87]
	v_mfma_f32_16x16x32_bf16 v[72:75], v[152:155], v[224:227], v[72:75]
	v_mfma_f32_16x16x32_bf16 v[68:71], v[176:179], v[224:227], v[68:71]
	s_barrier
	s_add_i32 s65, s65, s52
	v_lshl_add_u64 v[228:229], s[48:49], 0, v[158:159]
	s_mov_b32 m0, s65
	ds_read_b128 v[180:183], v190 offset:16384
	ds_read_b128 v[192:195], v190 offset:17408
	ds_read_b128 v[196:199], v190 offset:18432
	ds_read_b128 v[200:203], v190 offset:19456
	ds_read_b128 v[204:207], v190 offset:20480
	ds_read_b128 v[208:211], v190 offset:21504
	ds_read_b128 v[220:223], v190 offset:22528
	ds_read_b128 v[224:227], v190 offset:23552
	global_load_lds_dwordx4 v[228:229], off
	s_add_i32 m0, s65, 0x2000
	s_add_u32 s66, s48, 0x80000
	v_lshl_add_u64 v[230:231], s[48:49], 0, v[162:163]
	s_addc_u32 s67, s49, 0
	s_add_i32 s65, s68, s52
	global_load_lds_dwordx4 v[230:231], off
	v_lshl_add_u64 v[232:233], s[66:67], 0, v[158:159]
	s_mov_b32 m0, s65
	v_lshl_add_u64 v[234:235], s[50:51], 0, v[160:161]
	global_load_lds_dwordx4 v[232:233], off
	v_lshl_add_u64 v[232:233], s[66:67], 0, v[162:163]
	s_add_i32 m0, s65, 0x2000
	s_nop 0
	global_load_lds_dwordx4 v[232:233], off
	v_lshl_add_u64 v[232:233], s[50:51], 0, v[156:157]
	s_mov_b32 m0, s53
	s_nop 0
	global_load_lds_dwordx4 v[232:233], off
	s_mov_b32 m0, s54
	s_nop 0
	global_load_lds_dwordx4 v[234:235], off
	s_setprio 0
	s_setprio 1
	s_setprio 0
	s_waitcnt lgkmcnt(0)
	s_setprio 1
	s_waitcnt vmcnt(8)
	s_waitcnt lgkmcnt(0)
	s_barrier
; #define PG8_STAGE(bufoff, gbase, voff) do { _Pragma("unroll") for (int _i = 0; _i < 2; ++_i) \
;         __builtin_amdgcn_global_load_lds((const unsigned*)((const char*)(gbase) + (voff)[_i]), (PG8_LAS unsigned*)(lds + (bufoff) + ldsw + _i * 8192), 16, 0, 0); } while (0)
; #define PG8_LDA(dst, b, h) do { _Pragma("unroll") for (int m = 0; m < 4; ++m) _Pragma("unroll") for (int k = 0; k < 2; ++k) dst[m][k] = *(const PG8_LAS bf16x8*)(lds + PG8_SA(b, h) + aoff + m * 2048 + k * 1024); } while (0)
; #define PG8_LDB(dst, b, h) do { _Pragma("unroll") for (int n = 0; n < 2; ++n) _Pragma("unroll") for (int k = 0; k < 2; ++k) dst[n][k] = *(const PG8_LAS bf16x8*)(lds + PG8_SB(b, h) + boff + n * 2048 + k * 1024); } while (0)
; #define PG8_MMA(ai, bj, At, Bt) do { __builtin_amdgcn_s_setprio(1); _Pragma("unroll") for (int m = 0; m < 4; ++m) _Pragma("unroll") for (int n = 0; n < 2; ++n) _Pragma("unroll") for (int k = 0; k < 2; ++k) \
;         acc[ai][bj][m][n] = __builtin_amdgcn_mfma_f32_16x16x32_bf16(Bt[n][k], At[m][k], acc[ai][bj][m][n], 0, 0, 0); __builtin_amdgcn_s_setprio(0); } while (0)
; #define PG8_WAIT_V(n) asm volatile("s_waitcnt vmcnt(" #n ")" ::: "memory")
; #define PG8_WAIT_L(n) asm volatile("s_waitcnt lgkmcnt(" #n ")" ::: "memory")
; #define PG8_BAR __builtin_amdgcn_s_barrier()
; #define PG8_SCHED __builtin_amdgcn_sched_barrier(0)
; template <class Epi, class Sched, bool ALIGN_EPI = false, bool SP2 = false>
; __device__ __forceinline__ void gemm_phase(PG8_LAS unsigned char* lds, const Gemm g, const Sched& S, const Epi& E) {
;     ...
;             PG8_WAIT_V(8); PG8_WAIT_L(0); PG8_BAR; PG8_MMA(1, 0, At, B0); PG8_MMA(1, 1, At, B1); PG8_BAR; PG8_SCHED;
;             PG8_LDB(B0, 1, 0); PG8_LDB(B1, 1, 1); PG8_SCHED; PG8_LDA(At, 1, 0); PG8_STAGE(PG8_SA(0, 1), a2 + hstep, voffA);
;             PG8_WAIT_V(8); PG8_WAIT_L(0); PG8_BAR; PG8_MMA(0, 0, At, B0); PG8_MMA(0, 1, At, B1); PG8_BAR; PG8_SCHED;
;             PG8_LDA(At, 1, 1); PG8_STAGE(PG8_SB(1, 0), b3, voffB); PG8_STAGE(PG8_SB(1, 1), b3 + hstep, voffB); PG8_STAGE(PG8_SA(1, 0), a3, voffA);
	v_mfma_f32_16x16x32_bf16 v[62:65], v[132:135], v[180:183], v[62:65]
	v_mfma_f32_16x16x32_bf16 v[58:61], v[140:143], v[180:183], v[58:61]
	v_mfma_f32_16x16x32_bf16 v[46:49], v[132:135], v[196:199], v[46:49]
	v_mfma_f32_16x16x32_bf16 v[42:45], v[140:143], v[196:199], v[42:45]
	v_mfma_f32_16x16x32_bf16 v[30:33], v[132:135], v[204:207], v[30:33]
	v_mfma_f32_16x16x32_bf16 v[26:29], v[140:143], v[204:207], v[26:29]
	v_mfma_f32_16x16x32_bf16 v[14:17], v[132:135], v[220:223], v[14:17]
	v_mfma_f32_16x16x32_bf16 v[10:13], v[140:143], v[220:223], v[10:13]
	v_mfma_f32_16x16x32_bf16 v[62:65], v[136:139], v[192:195], v[62:65]
	v_mfma_f32_16x16x32_bf16 v[58:61], v[144:147], v[192:195], v[58:61]
	v_mfma_f32_16x16x32_bf16 v[46:49], v[136:139], v[200:203], v[46:49]
	v_mfma_f32_16x16x32_bf16 v[42:45], v[144:147], v[200:203], v[42:45]
	v_mfma_f32_16x16x32_bf16 v[30:33], v[136:139], v[208:211], v[30:33]
	v_mfma_f32_16x16x32_bf16 v[26:29], v[144:147], v[208:211], v[26:29]
	v_mfma_f32_16x16x32_bf16 v[14:17], v[136:139], v[224:227], v[14:17]
	v_mfma_f32_16x16x32_bf16 v[10:13], v[144:147], v[224:227], v[10:13]
	v_mfma_f32_16x16x32_bf16 v[54:57], v[148:151], v[180:183], v[54:57]
	v_mfma_f32_16x16x32_bf16 v[50:53], v[172:175], v[180:183], v[50:53]
	v_mfma_f32_16x16x32_bf16 v[38:41], v[148:151], v[196:199], v[38:41]
	v_mfma_f32_16x16x32_bf16 v[34:37], v[172:175], v[196:199], v[34:37]
	v_mfma_f32_16x16x32_bf16 v[22:25], v[148:151], v[204:207], v[22:25]
	v_mfma_f32_16x16x32_bf16 v[18:21], v[172:175], v[204:207], v[18:21]
	v_mfma_f32_16x16x32_bf16 v[6:9], v[148:151], v[220:223], v[6:9]
	v_mfma_f32_16x16x32_bf16 v[2:5], v[172:175], v[220:223], v[2:5]
	v_mfma_f32_16x16x32_bf16 v[54:57], v[152:155], v[192:195], v[54:57]
	v_mfma_f32_16x16x32_bf16 v[50:53], v[176:179], v[192:195], v[50:53]
	v_mfma_f32_16x16x32_bf16 v[38:41], v[152:155], v[200:203], v[38:41]
	v_mfma_f32_16x16x32_bf16 v[34:37], v[176:179], v[200:203], v[34:37]
	v_mfma_f32_16x16x32_bf16 v[22:25], v[152:155], v[208:211], v[22:25]
	v_mfma_f32_16x16x32_bf16 v[18:21], v[176:179], v[208:211], v[18:21]
	v_mfma_f32_16x16x32_bf16 v[6:9], v[152:155], v[224:227], v[6:9]
	v_mfma_f32_16x16x32_bf16 v[2:5], v[176:179], v[224:227], v[2:5]
	s_barrier
	s_add_i32 s65, 0, 0x18000
	v_add_u32_e32 v0, s65, v185
	s_add_i32 s66, 0, 0x1c000
	ds_read_b128 v[132:135], v0
	ds_read_b128 v[136:139], v0 offset:1024
	ds_read_b128 v[140:143], v0 offset:2048
	ds_read_b128 v[144:147], v0 offset:3072
	v_add_u32_e32 v0, s66, v185
	ds_read_b128 v[148:151], v0
	ds_read_b128 v[152:155], v0 offset:1024
	ds_read_b128 v[172:175], v0 offset:2048
	ds_read_b128 v[176:179], v0 offset:3072
	s_add_u32 s50, s50, 0x80000
	s_addc_u32 s51, s51, 0
	s_mov_b32 m0, s55
	v_lshl_add_u64 v[246:247], s[50:51], 0, v[156:157]
	ds_read_b128 v[180:183], v190 offset:32768
	ds_read_b128 v[192:195], v190 offset:33792
	ds_read_b128 v[196:199], v190 offset:34816
	ds_read_b128 v[200:203], v190 offset:35840
	ds_read_b128 v[204:207], v190 offset:36864
	ds_read_b128 v[208:211], v190 offset:37888
	ds_read_b128 v[220:223], v190 offset:38912
	ds_read_b128 v[224:227], v190 offset:39936
	global_load_lds_dwordx4 v[246:247], off
	v_lshl_add_u64 v[246:247], s[50:51], 0, v[160:161]
	s_mov_b32 m0, s56
	s_nop 0
	global_load_lds_dwordx4 v[246:247], off
	s_setprio 0
	s_setprio 1
	s_setprio 0
	s_waitcnt lgkmcnt(0)
	s_setprio 1
	s_waitcnt vmcnt(8)
	s_waitcnt lgkmcnt(0)
	s_barrier
	v_mfma_f32_16x16x32_bf16 v[128:131], v[132:135], v[180:183], v[128:131]
	v_mfma_f32_16x16x32_bf16 v[124:127], v[140:143], v[180:183], v[124:127]
	v_mfma_f32_16x16x32_bf16 v[112:115], v[132:135], v[196:199], v[112:115]
	v_mfma_f32_16x16x32_bf16 v[108:111], v[140:143], v[196:199], v[108:111]
	v_mfma_f32_16x16x32_bf16 v[96:99], v[132:135], v[204:207], v[96:99]
	v_mfma_f32_16x16x32_bf16 v[92:95], v[140:143], v[204:207], v[92:95]
	v_mfma_f32_16x16x32_bf16 v[80:83], v[132:135], v[220:223], v[80:83]
	v_mfma_f32_16x16x32_bf16 v[76:79], v[140:143], v[220:223], v[76:79]
	v_mfma_f32_16x16x32_bf16 v[128:131], v[136:139], v[192:195], v[128:131]
	v_mfma_f32_16x16x32_bf16 v[124:127], v[144:147], v[192:195], v[124:127]
	v_mfma_f32_16x16x32_bf16 v[112:115], v[136:139], v[200:203], v[112:115]
	v_mfma_f32_16x16x32_bf16 v[108:111], v[144:147], v[200:203], v[108:111]
	v_mfma_f32_16x16x32_bf16 v[96:99], v[136:139], v[208:211], v[96:99]
	v_mfma_f32_16x16x32_bf16 v[92:95], v[144:147], v[208:211], v[92:95]
	v_mfma_f32_16x16x32_bf16 v[80:83], v[136:139], v[224:227], v[80:83]
	v_mfma_f32_16x16x32_bf16 v[76:79], v[144:147], v[224:227], v[76:79]
	v_mfma_f32_16x16x32_bf16 v[120:123], v[148:151], v[180:183], v[120:123]
	v_mfma_f32_16x16x32_bf16 v[116:119], v[172:175], v[180:183], v[116:119]
	v_mfma_f32_16x16x32_bf16 v[104:107], v[148:151], v[196:199], v[104:107]
	v_mfma_f32_16x16x32_bf16 v[100:103], v[172:175], v[196:199], v[100:103]
	v_mfma_f32_16x16x32_bf16 v[88:91], v[148:151], v[204:207], v[88:91]
	v_mfma_f32_16x16x32_bf16 v[84:87], v[172:175], v[204:207], v[84:87]
	v_mfma_f32_16x16x32_bf16 v[72:75], v[148:151], v[220:223], v[72:75]
	v_mfma_f32_16x16x32_bf16 v[68:71], v[172:175], v[220:223], v[68:71]
	v_mfma_f32_16x16x32_bf16 v[120:123], v[152:155], v[192:195], v[120:123]
	v_mfma_f32_16x16x32_bf16 v[116:119], v[176:179], v[192:195], v[116:119]
	v_mfma_f32_16x16x32_bf16 v[104:107], v[152:155], v[200:203], v[104:107]
	v_mfma_f32_16x16x32_bf16 v[100:103], v[176:179], v[200:203], v[100:103]
	v_mfma_f32_16x16x32_bf16 v[88:91], v[152:155], v[208:211], v[88:91]
	v_mfma_f32_16x16x32_bf16 v[84:87], v[176:179], v[208:211], v[84:87]
	v_mfma_f32_16x16x32_bf16 v[72:75], v[152:155], v[224:227], v[72:75]
	v_mfma_f32_16x16x32_bf16 v[68:71], v[176:179], v[224:227], v[68:71]
	s_barrier
; #define PG8_STAGE(bufoff, gbase, voff) do { _Pragma("unroll") for (int _i = 0; _i < 2; ++_i) \
;         __builtin_amdgcn_global_load_lds((const unsigned*)((const char*)(gbase) + (voff)[_i]), (PG8_LAS unsigned*)(lds + (bufoff) + ldsw + _i * 8192), 16, 0, 0); } while (0)
; #define PG8_LDA(dst, b, h) do { _Pragma("unroll") for (int m = 0; m < 4; ++m) _Pragma("unroll") for (int k = 0; k < 2; ++k) dst[m][k] = *(const PG8_LAS bf16x8*)(lds + PG8_SA(b, h) + aoff + m * 2048 + k * 1024); } while (0)
; #define PG8_LDB(dst, b, h) do { _Pragma("unroll") for (int n = 0; n < 2; ++n) _Pragma("unroll") for (int k = 0; k < 2; ++k) dst[n][k] = *(const PG8_LAS bf16x8*)(lds + PG8_SB(b, h) + boff + n * 2048 + k * 1024); } while (0)
; #define PG8_MMA(ai, bj, At, Bt) do { __builtin_amdgcn_s_setprio(1); _Pragma("unroll") for (int m = 0; m < 4; ++m) _Pragma("unroll") for (int n = 0; n < 2; ++n) _Pragma("unroll") for (int k = 0; k < 2; ++k) \
;         acc[ai][bj][m][n] = __builtin_amdgcn_mfma_f32_16x16x32_bf16(Bt[n][k], At[m][k], acc[ai][bj][m][n], 0, 0, 0); __builtin_amdgcn_s_setprio(0); } while (0)
; #define PG8_WAIT_V(n) asm volatile("s_waitcnt vmcnt(" #n ")" ::: "memory")
; template <class Epi, class Sched, bool ALIGN_EPI = false, bool SP2 = false>
; __device__ __forceinline__ void gemm_phase(PG8_LAS unsigned char* lds, const Gemm g, const Sched& S, const Epi& E) {
;     ...
;             PG8_LDB(B0, 0, 0); PG8_LDB(B1, 0, 1); PG8_SCHED; PG8_LDA(At, 0, 0); PG8_STAGE(PG8_SA(1, 1), a1 + hstep, voffA);
;             PG8_WAIT_V(8); PG8_WAIT_L(0); PG8_BAR; PG8_MMA(0, 0, At, B0); PG8_MMA(0, 1, At, B1); PG8_BAR; PG8_SCHED;
;             PG8_LDA(At, 0, 1); PG8_STAGE(PG8_SB(0, 0), b2, voffB); PG8_STAGE(PG8_SB(0, 1), b2 + hstep, voffB); PG8_STAGE(PG8_SA(0, 0), a2, voffA);
;             PG8_WAIT_V(8); PG8_WAIT_L(0); PG8_BAR; PG8_MMA(1, 0, At, B0); PG8_MMA(1, 1, At, B1); PG8_BAR; PG8_SCHED;
;             PG8_LDB(B0, 1, 0); PG8_LDB(B1, 1, 1); PG8_SCHED; PG8_LDA(At, 1, 0); PG8_STAGE(PG8_SA(0, 1), a2 + hstep, voffA);
;             PG8_WAIT_V(8); PG8_WAIT_L(0); PG8_BAR; PG8_MMA(0, 0, At, B0); PG8_MMA(0, 1, At, B1); PG8_BAR; PG8_SCHED;
;             PG8_LDA(At, 1, 1); PG8_STAGE(PG8_SB(1, 0), b3, voffB); PG8_STAGE(PG8_SB(1, 1), b3 + hstep, voffB); PG8_STAGE(PG8_SA(1, 0), a3, voffA);
;             PG8_WAIT_V(8); PG8_WAIT_L(0); PG8_BAR; PG8_MMA(1, 0, At, B0); PG8_MMA(1, 1, At, B1); PG8_BAR; PG8_SCHED;
	s_add_i32 s50, s65, s52
	v_lshl_add_u64 v[228:229], v[228:229], 0, s[88:89]
	s_mov_b32 m0, s50
	ds_read_b128 v[180:183], v190 offset:49152
	ds_read_b128 v[192:195], v190 offset:50176
	ds_read_b128 v[196:199], v190 offset:51200
	ds_read_b128 v[200:203], v190 offset:52224
	ds_read_b128 v[204:207], v190 offset:53248
	ds_read_b128 v[208:211], v190 offset:54272
	ds_read_b128 v[220:223], v190 offset:55296
	ds_read_b128 v[224:227], v190 offset:56320
	global_load_lds_dwordx4 v[228:229], off
	s_add_i32 m0, s50, 0x2000
	s_add_u32 s48, s48, 0x80080
	v_lshl_add_u64 v[228:229], v[230:231], 0, s[88:89]
	s_addc_u32 s49, s49, 0
	s_add_i32 s50, s66, s52
	global_load_lds_dwordx4 v[228:229], off
	v_lshl_add_u64 v[228:229], s[48:49], 0, v[158:159]
	s_mov_b32 m0, s50
	s_nop 0
	global_load_lds_dwordx4 v[228:229], off
	v_lshl_add_u64 v[228:229], s[48:49], 0, v[162:163]
	s_add_i32 m0, s50, 0x2000
	s_nop 0
	global_load_lds_dwordx4 v[228:229], off
	v_lshl_add_u64 v[228:229], v[232:233], 0, s[88:89]
	s_mov_b32 m0, s58
	s_nop 0
	global_load_lds_dwordx4 v[228:229], off
	v_lshl_add_u64 v[228:229], v[234:235], 0, s[88:89]
	s_mov_b32 m0, s59
	s_nop 0
	global_load_lds_dwordx4 v[228:229], off
	s_setprio 0
	s_setprio 1
	s_setprio 0
	s_waitcnt lgkmcnt(0)
	s_setprio 1
	s_waitcnt vmcnt(8)
	s_waitcnt lgkmcnt(0)
	s_barrier
	v_mfma_f32_16x16x32_bf16 v[62:65], v[132:135], v[180:183], v[62:65]
	v_mfma_f32_16x16x32_bf16 v[58:61], v[140:143], v[180:183], v[58:61]
	v_mfma_f32_16x16x32_bf16 v[46:49], v[132:135], v[196:199], v[46:49]
	v_mfma_f32_16x16x32_bf16 v[42:45], v[140:143], v[196:199], v[42:45]
	v_mfma_f32_16x16x32_bf16 v[30:33], v[132:135], v[204:207], v[30:33]
	v_mfma_f32_16x16x32_bf16 v[26:29], v[140:143], v[204:207], v[26:29]
	v_mfma_f32_16x16x32_bf16 v[14:17], v[132:135], v[220:223], v[14:17]
	v_mfma_f32_16x16x32_bf16 v[10:13], v[140:143], v[220:223], v[10:13]
	v_mfma_f32_16x16x32_bf16 v[62:65], v[136:139], v[192:195], v[62:65]
	v_mfma_f32_16x16x32_bf16 v[58:61], v[144:147], v[192:195], v[58:61]
	v_mfma_f32_16x16x32_bf16 v[46:49], v[136:139], v[200:203], v[46:49]
	v_mfma_f32_16x16x32_bf16 v[42:45], v[144:147], v[200:203], v[42:45]
	v_mfma_f32_16x16x32_bf16 v[30:33], v[136:139], v[208:211], v[30:33]
	v_mfma_f32_16x16x32_bf16 v[26:29], v[144:147], v[208:211], v[26:29]
	v_mfma_f32_16x16x32_bf16 v[14:17], v[136:139], v[224:227], v[14:17]
	v_mfma_f32_16x16x32_bf16 v[10:13], v[144:147], v[224:227], v[10:13]
	v_mfma_f32_16x16x32_bf16 v[54:57], v[148:151], v[180:183], v[54:57]
	v_mfma_f32_16x16x32_bf16 v[50:53], v[172:175], v[180:183], v[50:53]
	v_mfma_f32_16x16x32_bf16 v[38:41], v[148:151], v[196:199], v[38:41]
	v_mfma_f32_16x16x32_bf16 v[34:37], v[172:175], v[196:199], v[34:37]
	v_mfma_f32_16x16x32_bf16 v[22:25], v[148:151], v[204:207], v[22:25]
	v_mfma_f32_16x16x32_bf16 v[18:21], v[172:175], v[204:207], v[18:21]
	v_mfma_f32_16x16x32_bf16 v[6:9], v[148:151], v[220:223], v[6:9]
	v_mfma_f32_16x16x32_bf16 v[2:5], v[172:175], v[220:223], v[2:5]
	v_mfma_f32_16x16x32_bf16 v[54:57], v[152:155], v[192:195], v[54:57]
	v_mfma_f32_16x16x32_bf16 v[50:53], v[176:179], v[192:195], v[50:53]
	v_mfma_f32_16x16x32_bf16 v[38:41], v[152:155], v[200:203], v[38:41]
	v_mfma_f32_16x16x32_bf16 v[34:37], v[176:179], v[200:203], v[34:37]
	v_mfma_f32_16x16x32_bf16 v[22:25], v[152:155], v[208:211], v[22:25]
	v_mfma_f32_16x16x32_bf16 v[18:21], v[176:179], v[208:211], v[18:21]
	v_mfma_f32_16x16x32_bf16 v[6:9], v[152:155], v[224:227], v[6:9]
	v_mfma_f32_16x16x32_bf16 v[2:5], v[176:179], v[224:227], v[2:5]
	s_barrier
	s_setprio 0
	s_setprio 1
	s_setprio 0
	s_waitcnt lgkmcnt(0)
	s_add_i32 s47, s47, 2
	s_add_u32 s12, s12, 0x100
	s_addc_u32 s13, s13, 0
	s_add_u32 s35, s35, 0x100
	s_addc_u32 s37, s37, 0
	s_cmp_gt_u32 s47, 29
	s_cbranch_scc0 .LBB0_239
	s_and_b64 vcc, exec, s[30:31]
	s_cbranch_vccz .LBB0_242
	s_barrier

;     __host__ __device__ bool next(int i, Unit& u) const { if (i != 0 || r < 0 || r >= 148) return false; if (r < 116) { u.pm = r % 29; u.pn = 47 + r / 29; } else { u.pm = 32; u.pn = 19 + (r - 116); } u.ko = 0; return true; }
;     __host__ __device__ bool next(int i, Unit& u) const { const int L = i * G + (G - 1 - c); if (L >= nN * S) return false; u.pm = pm; u.pn = L % nN; u.ko = (L / nN) * ksub; return true; }
; #define PG8_BAR __builtin_amdgcn_s_barrier()
; template <class Epi, class Sched, bool ALIGN_EPI = false, bool SP2 = false>
; __device__ __forceinline__ void gemm_phase(PG8_LAS unsigned char* lds, const Gemm g, const Sched& S, const Epi& E) {
;     ...
;         const bool has_next = S.next(ui + 1, nxt);
;         const char* nA = has_next ? (const char*)g.A + (size_t)nxt.pm * tstep + (size_t)nxt.ko * 2 : cA; const char* nB = has_next ? (const char*)g.Bt + (size_t)nxt.pn * tstep + (size_t)nxt.ko * 2 : cB;
;         for (int t = 0; t < nt; t += 2) {
;             const bool last = (t == nt - 2);
;             const char* a1 = cA + (size_t)(t + 1) * kstep;
;             const char* a2 = last ? nA : cA + (size_t)(t + 2) * kstep; const char* b2 = last ? nB : cB + (size_t)(t + 2) * kstep;
;             const char* a3 = a2 + kstep; const char* b3 = b2 + kstep;
;             if (last && has_next) S.a_ready(nxt);
;             if constexpr (SP2) {
;             PG8_LDB(B0, 0, 0); PG8_LDB(B1, 0, 1); PG8_SCHED; PG8_LDA(At, 0, 0); PG8_STAGE(PG8_SA(1, 1), a1 + hstep, voffA);
;             PG8_WAIT_V(8); PG8_WAIT_L(0); PG8_BAR; PG8_MMA(0, 0, At, B0); PG8_MMA(0, 1, At, B1); PG8_BAR; PG8_SCHED;
;             PG8_LDA(At, 0, 1); PG8_STAGE(PG8_SB(0, 0), b2, voffB); PG8_STAGE(PG8_SB(0, 1), b2 + hstep, voffB); PG8_STAGE(PG8_SA(0, 0), a2, voffA);
;             PG8_WAIT_V(8); PG8_WAIT_L(0); PG8_BAR; PG8_MMA(1, 0, At, B0); PG8_MMA(1, 1, At, B1); PG8_BAR; PG8_SCHED;
;             PG8_LDB(B0, 1, 0); PG8_LDB(B1, 1, 1); PG8_SCHED; PG8_LDA(At, 1, 0); PG8_STAGE(PG8_SA(0, 1), a2 + hstep, voffA);
;             PG8_WAIT_V(8); PG8_WAIT_L(0); PG8_BAR; PG8_MMA(0, 0, At, B0); PG8_MMA(0, 1, At, B1); PG8_BAR; PG8_SCHED;
;             PG8_LDA(At, 1, 1); PG8_STAGE(PG8_SB(1, 0), b3, voffB); PG8_STAGE(PG8_SB(1, 1), b3 + hstep, voffB); PG8_STAGE(PG8_SA(1, 0), a3, voffA);
;             PG8_WAIT_V(8); PG8_WAIT_L(0); PG8_BAR; PG8_MMA(1, 0, At, B0); PG8_MMA(1, 1, At, B1); PG8_BAR; PG8_SCHED;
.LBB0_398:
	s_lshl_b32 s54, s43, 7
	s_add_u32 s55, s30, s54
	s_addc_u32 s56, s31, 0
	s_add_u32 s57, s55, 0x100
	s_addc_u32 s58, s56, 0
	s_and_b64 s[52:53], s[12:13], exec
	s_cselect_b32 s53, s58, s1
	s_cselect_b32 s52, s57, s2
	s_add_u32 s54, s34, s54
	s_addc_u32 s57, s35, 0
	s_add_u32 s54, s54, 0x100
	s_addc_u32 s57, s57, 0
	s_and_b64 s[12:13], s[12:13], exec
	s_cselect_b32 s13, s57, s3
	s_cselect_b32 s12, s54, s41
	s_add_i32 s57, 0, 0x10000
	v_add_u32_e32 v0, s57, v181
	s_add_i32 s58, 0, 0x14000
	ds_read_b128 v[132:135], v0
	ds_read_b128 v[136:139], v0 offset:1024
	ds_read_b128 v[140:143], v0 offset:2048
	ds_read_b128 v[144:147], v0 offset:3072
	v_add_u32_e32 v0, s58, v181
	ds_read_b128 v[148:151], v0
	ds_read_b128 v[152:155], v0 offset:1024
	ds_read_b128 v[168:171], v0 offset:2048
	ds_read_b128 v[172:175], v0 offset:3072
	s_add_u32 s54, s55, 0x80080
	s_addc_u32 s55, s56, 0
	v_lshl_add_u64 v[224:225], s[54:55], 0, v[156:157]
	s_add_i32 m0, s29, 0xc000
	ds_read_b128 v[176:179], v187
	ds_read_b128 v[188:191], v187 offset:1024
	ds_read_b128 v[192:195], v187 offset:2048
	ds_read_b128 v[196:199], v187 offset:3072
	ds_read_b128 v[200:203], v187 offset:4096
	ds_read_b128 v[204:207], v187 offset:5120
	ds_read_b128 v[208:211], v187 offset:6144
	ds_read_b128 v[220:223], v187 offset:7168
	global_load_lds_dwordx4 v[224:225], off
	v_lshl_add_u64 v[224:225], s[54:55], 0, v[160:161]
	s_add_i32 m0, s29, 0xe000
	s_nop 0
	global_load_lds_dwordx4 v[224:225], off
	s_setprio 1
	s_waitcnt vmcnt(8)
	s_waitcnt lgkmcnt(0)
	s_barrier
	v_mfma_f32_16x16x32_bf16 v[128:131], v[132:135], v[176:179], v[128:131]
	v_mfma_f32_16x16x32_bf16 v[124:127], v[140:143], v[176:179], v[124:127]
	v_mfma_f32_16x16x32_bf16 v[120:123], v[132:135], v[192:195], v[120:123]
	v_mfma_f32_16x16x32_bf16 v[116:119], v[140:143], v[192:195], v[116:119]
	v_mfma_f32_16x16x32_bf16 v[112:115], v[132:135], v[200:203], v[112:115]
	v_mfma_f32_16x16x32_bf16 v[108:111], v[140:143], v[200:203], v[108:111]
	v_mfma_f32_16x16x32_bf16 v[104:107], v[132:135], v[208:211], v[104:107]
	v_mfma_f32_16x16x32_bf16 v[100:103], v[140:143], v[208:211], v[100:103]
	v_mfma_f32_16x16x32_bf16 v[128:131], v[136:139], v[188:191], v[128:131]
	v_mfma_f32_16x16x32_bf16 v[124:127], v[144:147], v[188:191], v[124:127]
	v_mfma_f32_16x16x32_bf16 v[120:123], v[136:139], v[196:199], v[120:123]
	v_mfma_f32_16x16x32_bf16 v[116:119], v[144:147], v[196:199], v[116:119]
	v_mfma_f32_16x16x32_bf16 v[112:115], v[136:139], v[204:207], v[112:115]
	v_mfma_f32_16x16x32_bf16 v[108:111], v[144:147], v[204:207], v[108:111]
	v_mfma_f32_16x16x32_bf16 v[104:107], v[136:139], v[220:223], v[104:107]
	v_mfma_f32_16x16x32_bf16 v[100:103], v[144:147], v[220:223], v[100:103]
	v_mfma_f32_16x16x32_bf16 v[96:99], v[148:151], v[176:179], v[96:99]
	v_mfma_f32_16x16x32_bf16 v[92:95], v[168:171], v[176:179], v[92:95]
	v_mfma_f32_16x16x32_bf16 v[88:91], v[148:151], v[192:195], v[88:91]
	v_mfma_f32_16x16x32_bf16 v[84:87], v[168:171], v[192:195], v[84:87]
	v_mfma_f32_16x16x32_bf16 v[80:83], v[148:151], v[200:203], v[80:83]
	v_mfma_f32_16x16x32_bf16 v[76:79], v[168:171], v[200:203], v[76:79]
	v_mfma_f32_16x16x32_bf16 v[72:75], v[148:151], v[208:211], v[72:75]
	v_mfma_f32_16x16x32_bf16 v[68:71], v[168:171], v[208:211], v[68:71]
	v_mfma_f32_16x16x32_bf16 v[96:99], v[152:155], v[188:191], v[96:99]
	v_mfma_f32_16x16x32_bf16 v[92:95], v[172:175], v[188:191], v[92:95]
	v_mfma_f32_16x16x32_bf16 v[88:91], v[152:155], v[196:199], v[88:91]
	v_mfma_f32_16x16x32_bf16 v[84:87], v[172:175], v[196:199], v[84:87]
	v_mfma_f32_16x16x32_bf16 v[80:83], v[152:155], v[204:207], v[80:83]
	v_mfma_f32_16x16x32_bf16 v[76:79], v[172:175], v[204:207], v[76:79]
	v_mfma_f32_16x16x32_bf16 v[72:75], v[152:155], v[220:223], v[72:75]
	v_mfma_f32_16x16x32_bf16 v[68:71], v[172:175], v[220:223], v[68:71]
	s_barrier
	s_add_i32 s54, s57, s15
	v_lshl_add_u64 v[224:225], s[12:13], 0, v[158:159]
	s_mov_b32 m0, s54
	ds_read_b128 v[176:179], v187 offset:16384
	ds_read_b128 v[188:191], v187 offset:17408
	ds_read_b128 v[192:195], v187 offset:18432
	ds_read_b128 v[196:199], v187 offset:19456
	ds_read_b128 v[200:203], v187 offset:20480
	ds_read_b128 v[204:207], v187 offset:21504
	ds_read_b128 v[208:211], v187 offset:22528
	ds_read_b128 v[220:223], v187 offset:23552
	global_load_lds_dwordx4 v[224:225], off
	s_add_i32 m0, s54, 0x2000
	s_add_u32 s54, s12, 0x80000
	v_lshl_add_u64 v[226:227], s[12:13], 0, v[162:163]
	s_addc_u32 s55, s13, 0
	s_add_i32 s56, s58, s15
	global_load_lds_dwordx4 v[226:227], off
	v_lshl_add_u64 v[228:229], s[54:55], 0, v[158:159]
	s_mov_b32 m0, s56
	v_lshl_add_u64 v[230:231], s[52:53], 0, v[160:161]
	global_load_lds_dwordx4 v[228:229], off
	v_lshl_add_u64 v[228:229], s[54:55], 0, v[162:163]
	s_add_i32 m0, s56, 0x2000
	s_nop 0
	global_load_lds_dwordx4 v[228:229], off
	v_lshl_add_u64 v[228:229], s[52:53], 0, v[156:157]
	s_mov_b32 m0, s29
	s_nop 0
	global_load_lds_dwordx4 v[228:229], off
	s_mov_b32 m0, s65
	s_nop 0
	global_load_lds_dwordx4 v[230:231], off
	s_setprio 0
	s_setprio 1
	s_setprio 0
	s_waitcnt lgkmcnt(0)
	s_setprio 1
	s_waitcnt vmcnt(8)
	s_waitcnt lgkmcnt(0)
	s_barrier
; #define PG8_STAGE(bufoff, gbase, voff) do { _Pragma("unroll") for (int _i = 0; _i < 2; ++_i) \
;         __builtin_amdgcn_global_load_lds((const unsigned*)((const char*)(gbase) + (voff)[_i]), (PG8_LAS unsigned*)(lds + (bufoff) + ldsw + _i * 8192), 16, 0, 0); } while (0)
; #define PG8_LDA(dst, b, h) do { _Pragma("unroll") for (int m = 0; m < 4; ++m) _Pragma("unroll") for (int k = 0; k < 2; ++k) dst[m][k] = *(const PG8_LAS bf16x8*)(lds + PG8_SA(b, h) + aoff + m * 2048 + k * 1024); } while (0)
; #define PG8_LDB(dst, b, h) do { _Pragma("unroll") for (int n = 0; n < 2; ++n) _Pragma("unroll") for (int k = 0; k < 2; ++k) dst[n][k] = *(const PG8_LAS bf16x8*)(lds + PG8_SB(b, h) + boff + n * 2048 + k * 1024); } while (0)
; #define PG8_MMA(ai, bj, At, Bt) do { __builtin_amdgcn_s_setprio(1); _Pragma("unroll") for (int m = 0; m < 4; ++m) _Pragma("unroll") for (int n = 0; n < 2; ++n) _Pragma("unroll") for (int k = 0; k < 2; ++k) \
;         acc[ai][bj][m][n] = __builtin_amdgcn_mfma_f32_16x16x32_bf16(Bt[n][k], At[m][k], acc[ai][bj][m][n], 0, 0, 0); __builtin_amdgcn_s_setprio(0); } while (0)
; #define PG8_WAIT_V(n) asm volatile("s_waitcnt vmcnt(" #n ")" ::: "memory")
; #define PG8_WAIT_L(n) asm volatile("s_waitcnt lgkmcnt(" #n ")" ::: "memory")
; #define PG8_BAR __builtin_amdgcn_s_barrier()
; #define PG8_SCHED __builtin_amdgcn_sched_barrier(0)
; template <class Epi, class Sched, bool ALIGN_EPI = false, bool SP2 = false>
; __device__ __forceinline__ void gemm_phase(PG8_LAS unsigned char* lds, const Gemm g, const Sched& S, const Epi& E) {
;     ...
;             PG8_WAIT_V(8); PG8_WAIT_L(0); PG8_BAR; PG8_MMA(1, 0, At, B0); PG8_MMA(1, 1, At, B1); PG8_BAR; PG8_SCHED;
;             PG8_LDB(B0, 1, 0); PG8_LDB(B1, 1, 1); PG8_SCHED; PG8_LDA(At, 1, 0); PG8_STAGE(PG8_SA(0, 1), a2 + hstep, voffA);
;             PG8_WAIT_V(8); PG8_WAIT_L(0); PG8_BAR; PG8_MMA(0, 0, At, B0); PG8_MMA(0, 1, At, B1); PG8_BAR; PG8_SCHED;
;             PG8_LDA(At, 1, 1); PG8_STAGE(PG8_SB(1, 0), b3, voffB); PG8_STAGE(PG8_SB(1, 1), b3 + hstep, voffB); PG8_STAGE(PG8_SA(1, 0), a3, voffA);
	v_mfma_f32_16x16x32_bf16 v[62:65], v[132:135], v[176:179], v[62:65]
	v_mfma_f32_16x16x32_bf16 v[58:61], v[140:143], v[176:179], v[58:61]
	v_mfma_f32_16x16x32_bf16 v[54:57], v[132:135], v[192:195], v[54:57]
	v_mfma_f32_16x16x32_bf16 v[50:53], v[140:143], v[192:195], v[50:53]
	v_mfma_f32_16x16x32_bf16 v[46:49], v[132:135], v[200:203], v[46:49]
	v_mfma_f32_16x16x32_bf16 v[42:45], v[140:143], v[200:203], v[42:45]
	v_mfma_f32_16x16x32_bf16 v[38:41], v[132:135], v[208:211], v[38:41]
	v_mfma_f32_16x16x32_bf16 v[34:37], v[140:143], v[208:211], v[34:37]
	v_mfma_f32_16x16x32_bf16 v[62:65], v[136:139], v[188:191], v[62:65]
	v_mfma_f32_16x16x32_bf16 v[58:61], v[144:147], v[188:191], v[58:61]
	v_mfma_f32_16x16x32_bf16 v[54:57], v[136:139], v[196:199], v[54:57]
	v_mfma_f32_16x16x32_bf16 v[50:53], v[144:147], v[196:199], v[50:53]
	v_mfma_f32_16x16x32_bf16 v[46:49], v[136:139], v[204:207], v[46:49]
	v_mfma_f32_16x16x32_bf16 v[42:45], v[144:147], v[204:207], v[42:45]
	v_mfma_f32_16x16x32_bf16 v[38:41], v[136:139], v[220:223], v[38:41]
	v_mfma_f32_16x16x32_bf16 v[34:37], v[144:147], v[220:223], v[34:37]
	v_mfma_f32_16x16x32_bf16 v[30:33], v[148:151], v[176:179], v[30:33]
	v_mfma_f32_16x16x32_bf16 v[26:29], v[168:171], v[176:179], v[26:29]
	v_mfma_f32_16x16x32_bf16 v[22:25], v[148:151], v[192:195], v[22:25]
	v_mfma_f32_16x16x32_bf16 v[18:21], v[168:171], v[192:195], v[18:21]
	v_mfma_f32_16x16x32_bf16 v[14:17], v[148:151], v[200:203], v[14:17]
	v_mfma_f32_16x16x32_bf16 v[10:13], v[168:171], v[200:203], v[10:13]
	v_mfma_f32_16x16x32_bf16 v[6:9], v[148:151], v[208:211], v[6:9]
	v_mfma_f32_16x16x32_bf16 v[2:5], v[168:171], v[208:211], v[2:5]
	v_mfma_f32_16x16x32_bf16 v[30:33], v[152:155], v[188:191], v[30:33]
	v_mfma_f32_16x16x32_bf16 v[26:29], v[172:175], v[188:191], v[26:29]
	v_mfma_f32_16x16x32_bf16 v[22:25], v[152:155], v[196:199], v[22:25]
	v_mfma_f32_16x16x32_bf16 v[18:21], v[172:175], v[196:199], v[18:21]
	v_mfma_f32_16x16x32_bf16 v[14:17], v[152:155], v[204:207], v[14:17]
	v_mfma_f32_16x16x32_bf16 v[10:13], v[172:175], v[204:207], v[10:13]
	v_mfma_f32_16x16x32_bf16 v[6:9], v[152:155], v[220:223], v[6:9]
	v_mfma_f32_16x16x32_bf16 v[2:5], v[172:175], v[220:223], v[2:5]
	s_barrier
	s_add_i32 s54, 0, 0x18000
	v_add_u32_e32 v0, s54, v181
	s_add_i32 s55, 0, 0x1c000
	ds_read_b128 v[132:135], v0
	ds_read_b128 v[136:139], v0 offset:1024
	ds_read_b128 v[140:143], v0 offset:2048
	ds_read_b128 v[144:147], v0 offset:3072
	v_add_u32_e32 v0, s55, v181
	ds_read_b128 v[148:151], v0
	ds_read_b128 v[152:155], v0 offset:1024
	ds_read_b128 v[168:171], v0 offset:2048
	ds_read_b128 v[172:175], v0 offset:3072
	s_add_u32 s52, s52, 0x80000
	s_addc_u32 s53, s53, 0
	s_mov_b32 m0, s66
	v_lshl_add_u64 v[232:233], s[52:53], 0, v[156:157]
	ds_read_b128 v[176:179], v187 offset:32768
	ds_read_b128 v[188:191], v187 offset:33792
	ds_read_b128 v[192:195], v187 offset:34816
	ds_read_b128 v[196:199], v187 offset:35840
	ds_read_b128 v[200:203], v187 offset:36864
	ds_read_b128 v[204:207], v187 offset:37888
	ds_read_b128 v[208:211], v187 offset:38912
	ds_read_b128 v[220:223], v187 offset:39936
	global_load_lds_dwordx4 v[232:233], off
	v_lshl_add_u64 v[232:233], s[52:53], 0, v[160:161]
	s_mov_b32 m0, s67
	s_nop 0
	global_load_lds_dwordx4 v[232:233], off
	s_setprio 0
	s_setprio 1
	s_setprio 0
	s_waitcnt lgkmcnt(0)
	s_setprio 1
	s_waitcnt vmcnt(8)
	s_waitcnt lgkmcnt(0)
	s_barrier
	v_mfma_f32_16x16x32_bf16 v[128:131], v[132:135], v[176:179], v[128:131]
	v_mfma_f32_16x16x32_bf16 v[124:127], v[140:143], v[176:179], v[124:127]
	v_mfma_f32_16x16x32_bf16 v[120:123], v[132:135], v[192:195], v[120:123]
	v_mfma_f32_16x16x32_bf16 v[116:119], v[140:143], v[192:195], v[116:119]
	v_mfma_f32_16x16x32_bf16 v[112:115], v[132:135], v[200:203], v[112:115]
	v_mfma_f32_16x16x32_bf16 v[108:111], v[140:143], v[200:203], v[108:111]
	v_mfma_f32_16x16x32_bf16 v[104:107], v[132:135], v[208:211], v[104:107]
	v_mfma_f32_16x16x32_bf16 v[100:103], v[140:143], v[208:211], v[100:103]
	v_mfma_f32_16x16x32_bf16 v[128:131], v[136:139], v[188:191], v[128:131]
	v_mfma_f32_16x16x32_bf16 v[124:127], v[144:147], v[188:191], v[124:127]
	v_mfma_f32_16x16x32_bf16 v[120:123], v[136:139], v[196:199], v[120:123]
	v_mfma_f32_16x16x32_bf16 v[116:119], v[144:147], v[196:199], v[116:119]
	v_mfma_f32_16x16x32_bf16 v[112:115], v[136:139], v[204:207], v[112:115]
	v_mfma_f32_16x16x32_bf16 v[108:111], v[144:147], v[204:207], v[108:111]
	v_mfma_f32_16x16x32_bf16 v[104:107], v[136:139], v[220:223], v[104:107]
	v_mfma_f32_16x16x32_bf16 v[100:103], v[144:147], v[220:223], v[100:103]
	v_mfma_f32_16x16x32_bf16 v[96:99], v[148:151], v[176:179], v[96:99]
	v_mfma_f32_16x16x32_bf16 v[92:95], v[168:171], v[176:179], v[92:95]
	v_mfma_f32_16x16x32_bf16 v[88:91], v[148:151], v[192:195], v[88:91]
	v_mfma_f32_16x16x32_bf16 v[84:87], v[168:171], v[192:195], v[84:87]
	v_mfma_f32_16x16x32_bf16 v[80:83], v[148:151], v[200:203], v[80:83]
	v_mfma_f32_16x16x32_bf16 v[76:79], v[168:171], v[200:203], v[76:79]
	v_mfma_f32_16x16x32_bf16 v[72:75], v[148:151], v[208:211], v[72:75]
	v_mfma_f32_16x16x32_bf16 v[68:71], v[168:171], v[208:211], v[68:71]
	v_mfma_f32_16x16x32_bf16 v[96:99], v[152:155], v[188:191], v[96:99]
	v_mfma_f32_16x16x32_bf16 v[92:95], v[172:175], v[188:191], v[92:95]
	v_mfma_f32_16x16x32_bf16 v[88:91], v[152:155], v[196:199], v[88:91]
	v_mfma_f32_16x16x32_bf16 v[84:87], v[172:175], v[196:199], v[84:87]
	v_mfma_f32_16x16x32_bf16 v[80:83], v[152:155], v[204:207], v[80:83]
	v_mfma_f32_16x16x32_bf16 v[76:79], v[172:175], v[204:207], v[76:79]
	v_mfma_f32_16x16x32_bf16 v[72:75], v[152:155], v[220:223], v[72:75]
	v_mfma_f32_16x16x32_bf16 v[68:71], v[172:175], v[220:223], v[68:71]
	s_barrier
; #define PG8_STAGE(bufoff, gbase, voff) do { _Pragma("unroll") for (int _i = 0; _i < 2; ++_i) \
;         __builtin_amdgcn_global_load_lds((const unsigned*)((const char*)(gbase) + (voff)[_i]), (PG8_LAS unsigned*)(lds + (bufoff) + ldsw + _i * 8192), 16, 0, 0); } while (0)
; #define PG8_LDA(dst, b, h) do { _Pragma("unroll") for (int m = 0; m < 4; ++m) _Pragma("unroll") for (int k = 0; k < 2; ++k) dst[m][k] = *(const PG8_LAS bf16x8*)(lds + PG8_SA(b, h) + aoff + m * 2048 + k * 1024); } while (0)
; #define PG8_LDB(dst, b, h) do { _Pragma("unroll") for (int n = 0; n < 2; ++n) _Pragma("unroll") for (int k = 0; k < 2; ++k) dst[n][k] = *(const PG8_LAS bf16x8*)(lds + PG8_SB(b, h) + boff + n * 2048 + k * 1024); } while (0)
; #define PG8_MMA(ai, bj, At, Bt) do { __builtin_amdgcn_s_setprio(1); _Pragma("unroll") for (int m = 0; m < 4; ++m) _Pragma("unroll") for (int n = 0; n < 2; ++n) _Pragma("unroll") for (int k = 0; k < 2; ++k) \
;         acc[ai][bj][m][n] = __builtin_amdgcn_mfma_f32_16x16x32_bf16(Bt[n][k], At[m][k], acc[ai][bj][m][n], 0, 0, 0); __builtin_amdgcn_s_setprio(0); } while (0)
; #define PG8_WAIT_V(n) asm volatile("s_waitcnt vmcnt(" #n ")" ::: "memory")
; template <class Epi, class Sched, bool ALIGN_EPI = false, bool SP2 = false>
; __device__ __forceinline__ void gemm_phase(PG8_LAS unsigned char* lds, const Gemm g, const Sched& S, const Epi& E) {
;     ...
;             PG8_LDB(B0, 0, 0); PG8_LDB(B1, 0, 1); PG8_SCHED; PG8_LDA(At, 0, 0); PG8_STAGE(PG8_SA(1, 1), a1 + hstep, voffA);
;             PG8_WAIT_V(8); PG8_WAIT_L(0); PG8_BAR; PG8_MMA(0, 0, At, B0); PG8_MMA(0, 1, At, B1); PG8_BAR; PG8_SCHED;
;             PG8_LDA(At, 0, 1); PG8_STAGE(PG8_SB(0, 0), b2, voffB); PG8_STAGE(PG8_SB(0, 1), b2 + hstep, voffB); PG8_STAGE(PG8_SA(0, 0), a2, voffA);
;             PG8_WAIT_V(8); PG8_WAIT_L(0); PG8_BAR; PG8_MMA(1, 0, At, B0); PG8_MMA(1, 1, At, B1); PG8_BAR; PG8_SCHED;
;             PG8_LDB(B0, 1, 0); PG8_LDB(B1, 1, 1); PG8_SCHED; PG8_LDA(At, 1, 0); PG8_STAGE(PG8_SA(0, 1), a2 + hstep, voffA);
;             PG8_WAIT_V(8); PG8_WAIT_L(0); PG8_BAR; PG8_MMA(0, 0, At, B0); PG8_MMA(0, 1, At, B1); PG8_BAR; PG8_SCHED;
;             PG8_LDA(At, 1, 1); PG8_STAGE(PG8_SB(1, 0), b3, voffB); PG8_STAGE(PG8_SB(1, 1), b3 + hstep, voffB); PG8_STAGE(PG8_SA(1, 0), a3, voffA);
;             PG8_WAIT_V(8); PG8_WAIT_L(0); PG8_BAR; PG8_MMA(1, 0, At, B0); PG8_MMA(1, 1, At, B1); PG8_BAR; PG8_SCHED;
	s_add_i32 s52, s54, s15
	v_lshl_add_u64 v[224:225], v[224:225], 0, s[88:89]
	s_mov_b32 m0, s52
	ds_read_b128 v[176:179], v187 offset:49152
	ds_read_b128 v[188:191], v187 offset:50176
	ds_read_b128 v[192:195], v187 offset:51200
	ds_read_b128 v[196:199], v187 offset:52224
	ds_read_b128 v[200:203], v187 offset:53248
	ds_read_b128 v[204:207], v187 offset:54272
	ds_read_b128 v[208:211], v187 offset:55296
	ds_read_b128 v[220:223], v187 offset:56320
	global_load_lds_dwordx4 v[224:225], off
	s_add_i32 m0, s52, 0x2000
	s_add_u32 s12, s12, 0x80080
	v_lshl_add_u64 v[224:225], v[226:227], 0, s[88:89]
	s_addc_u32 s13, s13, 0
	s_add_i32 s52, s55, s15
	global_load_lds_dwordx4 v[224:225], off
	v_lshl_add_u64 v[224:225], s[12:13], 0, v[158:159]
	s_mov_b32 m0, s52
	s_nop 0
	global_load_lds_dwordx4 v[224:225], off
	v_lshl_add_u64 v[224:225], s[12:13], 0, v[162:163]
	s_add_i32 m0, s52, 0x2000
	s_nop 0
	global_load_lds_dwordx4 v[224:225], off
	v_lshl_add_u64 v[224:225], v[228:229], 0, s[88:89]
	s_mov_b32 m0, s69
	s_nop 0
	global_load_lds_dwordx4 v[224:225], off
	v_lshl_add_u64 v[224:225], v[230:231], 0, s[88:89]
	s_mov_b32 m0, s70
	s_nop 0
	global_load_lds_dwordx4 v[224:225], off
	s_setprio 0
	s_setprio 1
	s_setprio 0
	s_waitcnt lgkmcnt(0)
	s_setprio 1
	s_waitcnt vmcnt(8)
	s_waitcnt lgkmcnt(0)
	s_barrier
	v_mfma_f32_16x16x32_bf16 v[62:65], v[132:135], v[176:179], v[62:65]
	v_mfma_f32_16x16x32_bf16 v[58:61], v[140:143], v[176:179], v[58:61]
	v_mfma_f32_16x16x32_bf16 v[54:57], v[132:135], v[192:195], v[54:57]
	v_mfma_f32_16x16x32_bf16 v[50:53], v[140:143], v[192:195], v[50:53]
	v_mfma_f32_16x16x32_bf16 v[46:49], v[132:135], v[200:203], v[46:49]
	v_mfma_f32_16x16x32_bf16 v[42:45], v[140:143], v[200:203], v[42:45]
	v_mfma_f32_16x16x32_bf16 v[38:41], v[132:135], v[208:211], v[38:41]
	v_mfma_f32_16x16x32_bf16 v[34:37], v[140:143], v[208:211], v[34:37]
	v_mfma_f32_16x16x32_bf16 v[62:65], v[136:139], v[188:191], v[62:65]
	v_mfma_f32_16x16x32_bf16 v[58:61], v[144:147], v[188:191], v[58:61]
	v_mfma_f32_16x16x32_bf16 v[54:57], v[136:139], v[196:199], v[54:57]
	v_mfma_f32_16x16x32_bf16 v[50:53], v[144:147], v[196:199], v[50:53]
	v_mfma_f32_16x16x32_bf16 v[46:49], v[136:139], v[204:207], v[46:49]
	v_mfma_f32_16x16x32_bf16 v[42:45], v[144:147], v[204:207], v[42:45]
	v_mfma_f32_16x16x32_bf16 v[38:41], v[136:139], v[220:223], v[38:41]
	v_mfma_f32_16x16x32_bf16 v[34:37], v[144:147], v[220:223], v[34:37]
	v_mfma_f32_16x16x32_bf16 v[30:33], v[148:151], v[176:179], v[30:33]
	v_mfma_f32_16x16x32_bf16 v[26:29], v[168:171], v[176:179], v[26:29]
	v_mfma_f32_16x16x32_bf16 v[22:25], v[148:151], v[192:195], v[22:25]
	v_mfma_f32_16x16x32_bf16 v[18:21], v[168:171], v[192:195], v[18:21]
	v_mfma_f32_16x16x32_bf16 v[14:17], v[148:151], v[200:203], v[14:17]
	v_mfma_f32_16x16x32_bf16 v[10:13], v[168:171], v[200:203], v[10:13]
	v_mfma_f32_16x16x32_bf16 v[6:9], v[148:151], v[208:211], v[6:9]
	v_mfma_f32_16x16x32_bf16 v[2:5], v[168:171], v[208:211], v[2:5]
	v_mfma_f32_16x16x32_bf16 v[30:33], v[152:155], v[188:191], v[30:33]
	v_mfma_f32_16x16x32_bf16 v[26:29], v[172:175], v[188:191], v[26:29]
	v_mfma_f32_16x16x32_bf16 v[22:25], v[152:155], v[196:199], v[22:25]
	v_mfma_f32_16x16x32_bf16 v[18:21], v[172:175], v[196:199], v[18:21]
	v_mfma_f32_16x16x32_bf16 v[14:17], v[152:155], v[204:207], v[14:17]
	v_mfma_f32_16x16x32_bf16 v[10:13], v[172:175], v[204:207], v[10:13]
	v_mfma_f32_16x16x32_bf16 v[6:9], v[152:155], v[220:223], v[6:9]
	v_mfma_f32_16x16x32_bf16 v[2:5], v[172:175], v[220:223], v[2:5]
	s_barrier
	s_setprio 0
	s_setprio 1
	s_setprio 0
	s_waitcnt lgkmcnt(0)
	s_add_i32 s12, s43, 2
	s_cmp_gt_u32 s43, 29
	s_cbranch_scc1 .LBB0_400
	s_mov_b32 s43, s12
	s_branch .LBB0_384

; #define PG8_STAGE(bufoff, gbase, voff) do { _Pragma("unroll") for (int _i = 0; _i < 2; ++_i) \
;         __builtin_amdgcn_global_load_lds((const unsigned*)((const char*)(gbase) + (voff)[_i]), (PG8_LAS unsigned*)(lds + (bufoff) + ldsw + _i * 8192), 16, 0, 0); } while (0)
; #define PG8_LDA(dst, b, h) do { _Pragma("unroll") for (int m = 0; m < 4; ++m) _Pragma("unroll") for (int k = 0; k < 2; ++k) dst[m][k] = *(const PG8_LAS bf16x8*)(lds + PG8_SA(b, h) + aoff + m * 2048 + k * 1024); } while (0)
; #define PG8_LDB(dst, b, h) do { _Pragma("unroll") for (int n = 0; n < 2; ++n) _Pragma("unroll") for (int k = 0; k < 2; ++k) dst[n][k] = *(const PG8_LAS bf16x8*)(lds + PG8_SB(b, h) + boff + n * 2048 + k * 1024); } while (0)
; template <class Epi, class Sched, bool ALIGN_EPI = false, bool SP2 = false>
; __device__ __forceinline__ void gemm_phase(PG8_LAS unsigned char* lds, const Gemm g, const Sched& S, const Epi& E) {
;     ...
;         for (int t = 0; t < nt; t += 2) {
;             const bool last = (t == nt - 2);
;             const char* a1 = cA + (size_t)(t + 1) * kstep;
;             const char* a2 = last ? nA : cA + (size_t)(t + 2) * kstep; const char* b2 = last ? nB : cB + (size_t)(t + 2) * kstep;
;             const char* a3 = a2 + kstep; const char* b3 = b2 + kstep;
;             if (last && has_next) S.a_ready(nxt);
;             if constexpr (SP2) {
;             PG8_LDB(B0, 0, 0); PG8_LDB(B1, 0, 1); PG8_SCHED; PG8_LDA(At, 0, 0); PG8_STAGE(PG8_SA(1, 1), a1 + hstep, voffA);
;             PG8_WAIT_V(8); PG8_WAIT_L(0); PG8_BAR; PG8_MMA(0, 0, At, B0); PG8_MMA(0, 1, At, B1); PG8_BAR; PG8_SCHED;
;             PG8_LDA(At, 0, 1); PG8_STAGE(PG8_SB(0, 0), b2, voffB); PG8_STAGE(PG8_SB(0, 1), b2 + hstep, voffB); PG8_STAGE(PG8_SA(0, 0), a2, voffA);
;             PG8_WAIT_V(8); PG8_WAIT_L(0); PG8_BAR; PG8_MMA(1, 0, At, B0); PG8_MMA(1, 1, At, B1); PG8_BAR; PG8_SCHED;
;             PG8_LDB(B0, 1, 0); PG8_LDB(B1, 1, 1); PG8_SCHED; PG8_LDA(At, 1, 0); PG8_STAGE(PG8_SA(0, 1), a2 + hstep, voffA);
;             PG8_WAIT_V(8); PG8_WAIT_L(0); PG8_BAR; PG8_MMA(0, 0, At, B0); PG8_MMA(0, 1, At, B1); PG8_BAR; PG8_SCHED;
;             PG8_LDA(At, 1, 1); PG8_STAGE(PG8_SB(1, 0), b3, voffB); PG8_STAGE(PG8_SB(1, 1), b3 + hstep, voffB); PG8_STAGE(PG8_SA(1, 0), a3, voffA);
;             PG8_WAIT_V(8); PG8_WAIT_L(0); PG8_BAR; PG8_MMA(1, 0, At, B0); PG8_MMA(1, 1, At, B1); PG8_BAR; PG8_SCHED;
.LBB0_702:
	s_add_u32 s14, s26, s12
	s_addc_u32 s15, s27, s13
	s_add_u32 s14, s14, 0x5800100
	s_addc_u32 s15, s15, 0
	s_add_u32 s31, s28, s12
	s_addc_u32 s34, s29, s13
	s_add_i32 s35, 0, 0x10000
	s_cmpk_eq_i32 s12, 0xf00
	s_cselect_b32 s17, s9, s15
	s_cselect_b32 s16, s8, s14
	v_add_u32_e32 v89, s35, v87
	s_cselect_b32 s15, s7, s34
	s_cselect_b32 s14, s6, s31
	s_add_i32 s31, 0, 0x14000
	ds_read_b128 v[148:151], v89
	ds_read_b128 v[152:155], v89 offset:1024
	ds_read_b128 v[156:159], v89 offset:2048
	ds_read_b128 v[160:163], v89 offset:3072
	v_add_u32_e32 v89, s31, v87
	ds_read_b128 v[166:169], v89
	ds_read_b128 v[170:173], v89 offset:1024
	ds_read_b128 v[174:177], v89 offset:2048
	ds_read_b128 v[178:181], v89 offset:3072
	v_lshl_add_u64 v[90:91], v[74:75], 0, s[12:13]
	s_add_i32 m0, s20, 0xc000
	ds_read_b128 v[182:185], v88
	ds_read_b128 v[186:189], v88 offset:1024
	ds_read_b128 v[190:193], v88 offset:2048
	ds_read_b128 v[194:197], v88 offset:3072
	ds_read_b128 v[200:203], v88 offset:4096
	ds_read_b128 v[204:207], v88 offset:5120
	ds_read_b128 v[208:211], v88 offset:6144
	ds_read_b128 v[220:223], v88 offset:7168
	global_load_lds_dwordx4 v[90:91], off
	v_lshl_add_u64 v[90:91], v[84:85], 0, s[12:13]
	s_add_i32 m0, s20, 0xe000
	s_nop 0
	global_load_lds_dwordx4 v[90:91], off
	s_setprio 1
	s_waitcnt vmcnt(8)
	s_waitcnt lgkmcnt(0)
	s_barrier
	v_mfma_f32_16x16x32_bf16 v[144:147], v[148:151], v[182:185], v[144:147]
	v_mfma_f32_16x16x32_bf16 v[140:143], v[156:159], v[182:185], v[140:143]
	v_mfma_f32_16x16x32_bf16 v[128:131], v[148:151], v[190:193], v[128:131]
	v_mfma_f32_16x16x32_bf16 v[124:127], v[156:159], v[190:193], v[124:127]
	v_mfma_f32_16x16x32_bf16 v[112:115], v[148:151], v[200:203], v[112:115]
	v_mfma_f32_16x16x32_bf16 v[108:111], v[156:159], v[200:203], v[108:111]
	v_mfma_f32_16x16x32_bf16 v[96:99], v[148:151], v[208:211], v[96:99]
	v_mfma_f32_16x16x32_bf16 v[90:93], v[156:159], v[208:211], v[92:95]
	v_mfma_f32_16x16x32_bf16 v[144:147], v[152:155], v[186:189], v[144:147]
	v_mfma_f32_16x16x32_bf16 v[140:143], v[160:163], v[186:189], v[140:143]
	v_mfma_f32_16x16x32_bf16 v[128:131], v[152:155], v[194:197], v[128:131]
	v_mfma_f32_16x16x32_bf16 v[124:127], v[160:163], v[194:197], v[124:127]
	v_mfma_f32_16x16x32_bf16 v[112:115], v[152:155], v[204:207], v[112:115]
	v_mfma_f32_16x16x32_bf16 v[108:111], v[160:163], v[204:207], v[108:111]
	v_mfma_f32_16x16x32_bf16 v[96:99], v[152:155], v[220:223], v[96:99]
	v_mfma_f32_16x16x32_bf16 v[90:93], v[160:163], v[220:223], v[90:93]
	v_mfma_f32_16x16x32_bf16 v[136:139], v[166:169], v[182:185], v[136:139]
	v_mfma_f32_16x16x32_bf16 v[132:135], v[174:177], v[182:185], v[132:135]
	v_mfma_f32_16x16x32_bf16 v[120:123], v[166:169], v[190:193], v[120:123]
	v_mfma_f32_16x16x32_bf16 v[116:119], v[174:177], v[190:193], v[116:119]
	v_mfma_f32_16x16x32_bf16 v[104:107], v[166:169], v[200:203], v[104:107]
	v_mfma_f32_16x16x32_bf16 v[100:103], v[174:177], v[200:203], v[100:103]
	v_mfma_f32_16x16x32_bf16 v[80:83], v[166:169], v[208:211], v[80:83]
	v_mfma_f32_16x16x32_bf16 v[76:79], v[174:177], v[208:211], v[76:79]
	v_mfma_f32_16x16x32_bf16 v[136:139], v[170:173], v[186:189], v[136:139]
	v_mfma_f32_16x16x32_bf16 v[132:135], v[178:181], v[186:189], v[132:135]
	v_mfma_f32_16x16x32_bf16 v[120:123], v[170:173], v[194:197], v[120:123]
	v_mfma_f32_16x16x32_bf16 v[116:119], v[178:181], v[194:197], v[116:119]
	v_mfma_f32_16x16x32_bf16 v[104:107], v[170:173], v[204:207], v[104:107]
	v_mfma_f32_16x16x32_bf16 v[100:103], v[178:181], v[204:207], v[100:103]
	v_mfma_f32_16x16x32_bf16 v[80:83], v[170:173], v[220:223], v[80:83]
	v_mfma_f32_16x16x32_bf16 v[76:79], v[178:181], v[220:223], v[76:79]
	s_barrier
	s_add_i32 s34, s35, s18
	v_lshl_add_u64 v[224:225], s[14:15], 0, v[66:67]
	s_mov_b32 m0, s34
	ds_read_b128 v[182:185], v88 offset:16384
	ds_read_b128 v[186:189], v88 offset:17408
	ds_read_b128 v[190:193], v88 offset:18432
	ds_read_b128 v[194:197], v88 offset:19456
	ds_read_b128 v[200:203], v88 offset:20480
	ds_read_b128 v[204:207], v88 offset:21504
	ds_read_b128 v[208:211], v88 offset:22528
	ds_read_b128 v[220:223], v88 offset:23552
	global_load_lds_dwordx4 v[224:225], off
	s_add_i32 m0, s34, 0x2000
	s_add_u32 s34, s14, 0x80000
	v_lshl_add_u64 v[226:227], s[14:15], 0, v[72:73]
	s_addc_u32 s35, s15, 0
	s_add_i32 s31, s31, s18
	global_load_lds_dwordx4 v[226:227], off
	v_lshl_add_u64 v[94:95], s[34:35], 0, v[66:67]
	s_mov_b32 m0, s31
	v_lshl_add_u64 v[228:229], s[16:17], 0, v[68:69]
	global_load_lds_dwordx4 v[94:95], off
	v_lshl_add_u64 v[94:95], s[34:35], 0, v[72:73]
	s_add_i32 m0, s31, 0x2000
	v_lshl_add_u64 v[230:231], s[16:17], 0, v[70:71]
	global_load_lds_dwordx4 v[94:95], off
	s_mov_b32 m0, s20
	s_nop 0
	global_load_lds_dwordx4 v[228:229], off
	s_mov_b32 m0, s3
	s_nop 0
	global_load_lds_dwordx4 v[230:231], off
	s_setprio 0
	s_setprio 1
	s_setprio 0
	s_waitcnt lgkmcnt(0)
	s_setprio 1
	s_waitcnt vmcnt(8)
	s_waitcnt lgkmcnt(0)
	s_barrier
; #define PG8_STAGE(bufoff, gbase, voff) do { _Pragma("unroll") for (int _i = 0; _i < 2; ++_i) \
;         __builtin_amdgcn_global_load_lds((const unsigned*)((const char*)(gbase) + (voff)[_i]), (PG8_LAS unsigned*)(lds + (bufoff) + ldsw + _i * 8192), 16, 0, 0); } while (0)
; #define PG8_LDA(dst, b, h) do { _Pragma("unroll") for (int m = 0; m < 4; ++m) _Pragma("unroll") for (int k = 0; k < 2; ++k) dst[m][k] = *(const PG8_LAS bf16x8*)(lds + PG8_SA(b, h) + aoff + m * 2048 + k * 1024); } while (0)
; #define PG8_LDB(dst, b, h) do { _Pragma("unroll") for (int n = 0; n < 2; ++n) _Pragma("unroll") for (int k = 0; k < 2; ++k) dst[n][k] = *(const PG8_LAS bf16x8*)(lds + PG8_SB(b, h) + boff + n * 2048 + k * 1024); } while (0)
; #define PG8_MMA(ai, bj, At, Bt) do { __builtin_amdgcn_s_setprio(1); _Pragma("unroll") for (int m = 0; m < 4; ++m) _Pragma("unroll") for (int n = 0; n < 2; ++n) _Pragma("unroll") for (int k = 0; k < 2; ++k) \
;         acc[ai][bj][m][n] = __builtin_amdgcn_mfma_f32_16x16x32_bf16(Bt[n][k], At[m][k], acc[ai][bj][m][n], 0, 0, 0); __builtin_amdgcn_s_setprio(0); } while (0)
; #define PG8_WAIT_V(n) asm volatile("s_waitcnt vmcnt(" #n ")" ::: "memory")
; #define PG8_WAIT_L(n) asm volatile("s_waitcnt lgkmcnt(" #n ")" ::: "memory")
; #define PG8_BAR __builtin_amdgcn_s_barrier()
; #define PG8_SCHED __builtin_amdgcn_sched_barrier(0)
; template <class Epi, class Sched, bool ALIGN_EPI = false, bool SP2 = false>
; __device__ __forceinline__ void gemm_phase(PG8_LAS unsigned char* lds, const Gemm g, const Sched& S, const Epi& E) {
;     ...
;             PG8_WAIT_V(8); PG8_WAIT_L(0); PG8_BAR; PG8_MMA(1, 0, At, B0); PG8_MMA(1, 1, At, B1); PG8_BAR; PG8_SCHED;
;             PG8_LDB(B0, 1, 0); PG8_LDB(B1, 1, 1); PG8_SCHED; PG8_LDA(At, 1, 0); PG8_STAGE(PG8_SA(0, 1), a2 + hstep, voffA);
;             PG8_WAIT_V(8); PG8_WAIT_L(0); PG8_BAR; PG8_MMA(0, 0, At, B0); PG8_MMA(0, 1, At, B1); PG8_BAR; PG8_SCHED;
;             PG8_LDA(At, 1, 1); PG8_STAGE(PG8_SB(1, 0), b3, voffB); PG8_STAGE(PG8_SB(1, 1), b3 + hstep, voffB); PG8_STAGE(PG8_SA(1, 0), a3, voffA);
	v_mfma_f32_16x16x32_bf16 v[62:65], v[148:151], v[182:185], v[62:65]
	v_mfma_f32_16x16x32_bf16 v[58:61], v[156:159], v[182:185], v[58:61]
	v_mfma_f32_16x16x32_bf16 v[46:49], v[148:151], v[190:193], v[46:49]
	v_mfma_f32_16x16x32_bf16 v[42:45], v[156:159], v[190:193], v[42:45]
	v_mfma_f32_16x16x32_bf16 v[30:33], v[148:151], v[200:203], v[30:33]
	v_mfma_f32_16x16x32_bf16 v[26:29], v[156:159], v[200:203], v[26:29]
	v_mfma_f32_16x16x32_bf16 v[14:17], v[148:151], v[208:211], v[14:17]
	v_mfma_f32_16x16x32_bf16 v[10:13], v[156:159], v[208:211], v[10:13]
	v_mfma_f32_16x16x32_bf16 v[62:65], v[152:155], v[186:189], v[62:65]
	v_mfma_f32_16x16x32_bf16 v[58:61], v[160:163], v[186:189], v[58:61]
	v_mfma_f32_16x16x32_bf16 v[46:49], v[152:155], v[194:197], v[46:49]
	v_mfma_f32_16x16x32_bf16 v[42:45], v[160:163], v[194:197], v[42:45]
	v_mfma_f32_16x16x32_bf16 v[30:33], v[152:155], v[204:207], v[30:33]
	v_mfma_f32_16x16x32_bf16 v[26:29], v[160:163], v[204:207], v[26:29]
	v_mfma_f32_16x16x32_bf16 v[14:17], v[152:155], v[220:223], v[14:17]
	v_mfma_f32_16x16x32_bf16 v[10:13], v[160:163], v[220:223], v[10:13]
	v_mfma_f32_16x16x32_bf16 v[54:57], v[166:169], v[182:185], v[54:57]
	v_mfma_f32_16x16x32_bf16 v[50:53], v[174:177], v[182:185], v[50:53]
	v_mfma_f32_16x16x32_bf16 v[38:41], v[166:169], v[190:193], v[38:41]
	v_mfma_f32_16x16x32_bf16 v[34:37], v[174:177], v[190:193], v[34:37]
	v_mfma_f32_16x16x32_bf16 v[22:25], v[166:169], v[200:203], v[22:25]
	v_mfma_f32_16x16x32_bf16 v[18:21], v[174:177], v[200:203], v[18:21]
	v_mfma_f32_16x16x32_bf16 v[6:9], v[166:169], v[208:211], v[6:9]
	v_mfma_f32_16x16x32_bf16 v[2:5], v[174:177], v[208:211], v[2:5]
	v_mfma_f32_16x16x32_bf16 v[54:57], v[170:173], v[186:189], v[54:57]
	v_mfma_f32_16x16x32_bf16 v[50:53], v[178:181], v[186:189], v[50:53]
	v_mfma_f32_16x16x32_bf16 v[38:41], v[170:173], v[194:197], v[38:41]
	v_mfma_f32_16x16x32_bf16 v[34:37], v[178:181], v[194:197], v[34:37]
	v_mfma_f32_16x16x32_bf16 v[22:25], v[170:173], v[204:207], v[22:25]
	v_mfma_f32_16x16x32_bf16 v[18:21], v[178:181], v[204:207], v[18:21]
	v_mfma_f32_16x16x32_bf16 v[6:9], v[170:173], v[220:223], v[6:9]
	v_mfma_f32_16x16x32_bf16 v[2:5], v[178:181], v[220:223], v[2:5]
	s_barrier
	s_add_i32 s31, 0, 0x18000
	v_add_u32_e32 v89, s31, v87
	s_add_i32 s34, 0, 0x1c000
	ds_read_b128 v[148:151], v89
	ds_read_b128 v[152:155], v89 offset:1024
	ds_read_b128 v[156:159], v89 offset:2048
	ds_read_b128 v[160:163], v89 offset:3072
	v_add_u32_e32 v89, s34, v87
	ds_read_b128 v[166:169], v89
	ds_read_b128 v[170:173], v89 offset:1024
	ds_read_b128 v[174:177], v89 offset:2048
	ds_read_b128 v[178:181], v89 offset:3072
	s_add_u32 s16, s16, 0x80000
	s_addc_u32 s17, s17, 0
	s_mov_b32 m0, s21
	v_lshl_add_u64 v[94:95], s[16:17], 0, v[68:69]
	ds_read_b128 v[182:185], v88 offset:32768
	ds_read_b128 v[186:189], v88 offset:33792
	ds_read_b128 v[190:193], v88 offset:34816
	ds_read_b128 v[194:197], v88 offset:35840
	ds_read_b128 v[200:203], v88 offset:36864
	ds_read_b128 v[204:207], v88 offset:37888
	ds_read_b128 v[208:211], v88 offset:38912
	ds_read_b128 v[220:223], v88 offset:39936
	global_load_lds_dwordx4 v[94:95], off
	v_lshl_add_u64 v[94:95], s[16:17], 0, v[70:71]
	s_mov_b32 m0, s22
	s_nop 0
	global_load_lds_dwordx4 v[94:95], off
	s_setprio 0
	s_setprio 1
	s_setprio 0
	s_waitcnt lgkmcnt(0)
	s_setprio 1
	s_waitcnt vmcnt(8)
	s_waitcnt lgkmcnt(0)
	s_barrier
	v_mfma_f32_16x16x32_bf16 v[144:147], v[148:151], v[182:185], v[144:147]
	v_mfma_f32_16x16x32_bf16 v[140:143], v[156:159], v[182:185], v[140:143]
	v_mfma_f32_16x16x32_bf16 v[128:131], v[148:151], v[190:193], v[128:131]
	v_mfma_f32_16x16x32_bf16 v[124:127], v[156:159], v[190:193], v[124:127]
	v_mfma_f32_16x16x32_bf16 v[112:115], v[148:151], v[200:203], v[112:115]
	v_mfma_f32_16x16x32_bf16 v[108:111], v[156:159], v[200:203], v[108:111]
	v_mfma_f32_16x16x32_bf16 v[94:97], v[148:151], v[208:211], v[96:99]
	v_mfma_f32_16x16x32_bf16 v[90:93], v[156:159], v[208:211], v[90:93]
	v_mfma_f32_16x16x32_bf16 v[144:147], v[152:155], v[186:189], v[144:147]
	v_mfma_f32_16x16x32_bf16 v[140:143], v[160:163], v[186:189], v[140:143]
	v_mfma_f32_16x16x32_bf16 v[128:131], v[152:155], v[194:197], v[128:131]
	v_mfma_f32_16x16x32_bf16 v[124:127], v[160:163], v[194:197], v[124:127]
	v_mfma_f32_16x16x32_bf16 v[112:115], v[152:155], v[204:207], v[112:115]
	v_mfma_f32_16x16x32_bf16 v[108:111], v[160:163], v[204:207], v[108:111]
	v_mfma_f32_16x16x32_bf16 v[96:99], v[152:155], v[220:223], v[94:97]
	v_mfma_f32_16x16x32_bf16 v[92:95], v[160:163], v[220:223], v[90:93]
	v_mfma_f32_16x16x32_bf16 v[136:139], v[166:169], v[182:185], v[136:139]
	v_mfma_f32_16x16x32_bf16 v[132:135], v[174:177], v[182:185], v[132:135]
	v_mfma_f32_16x16x32_bf16 v[120:123], v[166:169], v[190:193], v[120:123]
	v_mfma_f32_16x16x32_bf16 v[116:119], v[174:177], v[190:193], v[116:119]
	v_mfma_f32_16x16x32_bf16 v[104:107], v[166:169], v[200:203], v[104:107]
	v_mfma_f32_16x16x32_bf16 v[100:103], v[174:177], v[200:203], v[100:103]
	v_mfma_f32_16x16x32_bf16 v[80:83], v[166:169], v[208:211], v[80:83]
	v_mfma_f32_16x16x32_bf16 v[76:79], v[174:177], v[208:211], v[76:79]
	v_mfma_f32_16x16x32_bf16 v[136:139], v[170:173], v[186:189], v[136:139]
	v_mfma_f32_16x16x32_bf16 v[132:135], v[178:181], v[186:189], v[132:135]
	v_mfma_f32_16x16x32_bf16 v[120:123], v[170:173], v[194:197], v[120:123]
	v_mfma_f32_16x16x32_bf16 v[116:119], v[178:181], v[194:197], v[116:119]
	v_mfma_f32_16x16x32_bf16 v[104:107], v[170:173], v[204:207], v[104:107]
	v_mfma_f32_16x16x32_bf16 v[100:103], v[178:181], v[204:207], v[100:103]
	v_mfma_f32_16x16x32_bf16 v[80:83], v[170:173], v[220:223], v[80:83]
	v_mfma_f32_16x16x32_bf16 v[76:79], v[178:181], v[220:223], v[76:79]
	s_barrier
; #define PG8_STAGE(bufoff, gbase, voff) do { _Pragma("unroll") for (int _i = 0; _i < 2; ++_i) \
;         __builtin_amdgcn_global_load_lds((const unsigned*)((const char*)(gbase) + (voff)[_i]), (PG8_LAS unsigned*)(lds + (bufoff) + ldsw + _i * 8192), 16, 0, 0); } while (0)
; #define PG8_LDA(dst, b, h) do { _Pragma("unroll") for (int m = 0; m < 4; ++m) _Pragma("unroll") for (int k = 0; k < 2; ++k) dst[m][k] = *(const PG8_LAS bf16x8*)(lds + PG8_SA(b, h) + aoff + m * 2048 + k * 1024); } while (0)
; #define PG8_LDB(dst, b, h) do { _Pragma("unroll") for (int n = 0; n < 2; ++n) _Pragma("unroll") for (int k = 0; k < 2; ++k) dst[n][k] = *(const PG8_LAS bf16x8*)(lds + PG8_SB(b, h) + boff + n * 2048 + k * 1024); } while (0)
; #define PG8_MMA(ai, bj, At, Bt) do { __builtin_amdgcn_s_setprio(1); _Pragma("unroll") for (int m = 0; m < 4; ++m) _Pragma("unroll") for (int n = 0; n < 2; ++n) _Pragma("unroll") for (int k = 0; k < 2; ++k) \
;         acc[ai][bj][m][n] = __builtin_amdgcn_mfma_f32_16x16x32_bf16(Bt[n][k], At[m][k], acc[ai][bj][m][n], 0, 0, 0); __builtin_amdgcn_s_setprio(0); } while (0)
; #define PG8_WAIT_V(n) asm volatile("s_waitcnt vmcnt(" #n ")" ::: "memory")
; template <class Epi, class Sched, bool ALIGN_EPI = false, bool SP2 = false>
; __device__ __forceinline__ void gemm_phase(PG8_LAS unsigned char* lds, const Gemm g, const Sched& S, const Epi& E) {
;     ...
;             PG8_LDB(B0, 0, 0); PG8_LDB(B1, 0, 1); PG8_SCHED; PG8_LDA(At, 0, 0); PG8_STAGE(PG8_SA(1, 1), a1 + hstep, voffA);
;             PG8_WAIT_V(8); PG8_WAIT_L(0); PG8_BAR; PG8_MMA(0, 0, At, B0); PG8_MMA(0, 1, At, B1); PG8_BAR; PG8_SCHED;
;             PG8_LDA(At, 0, 1); PG8_STAGE(PG8_SB(0, 0), b2, voffB); PG8_STAGE(PG8_SB(0, 1), b2 + hstep, voffB); PG8_STAGE(PG8_SA(0, 0), a2, voffA);
;             PG8_WAIT_V(8); PG8_WAIT_L(0); PG8_BAR; PG8_MMA(1, 0, At, B0); PG8_MMA(1, 1, At, B1); PG8_BAR; PG8_SCHED;
;             PG8_LDB(B0, 1, 0); PG8_LDB(B1, 1, 1); PG8_SCHED; PG8_LDA(At, 1, 0); PG8_STAGE(PG8_SA(0, 1), a2 + hstep, voffA);
;             PG8_WAIT_V(8); PG8_WAIT_L(0); PG8_BAR; PG8_MMA(0, 0, At, B0); PG8_MMA(0, 1, At, B1); PG8_BAR; PG8_SCHED;
;             PG8_LDA(At, 1, 1); PG8_STAGE(PG8_SB(1, 0), b3, voffB); PG8_STAGE(PG8_SB(1, 1), b3 + hstep, voffB); PG8_STAGE(PG8_SA(1, 0), a3, voffA);
;             PG8_WAIT_V(8); PG8_WAIT_L(0); PG8_BAR; PG8_MMA(1, 0, At, B0); PG8_MMA(1, 1, At, B1); PG8_BAR; PG8_SCHED;
	s_add_i32 s16, s31, s18
	v_lshl_add_u64 v[90:91], v[224:225], 0, s[88:89]
	s_mov_b32 m0, s16
	ds_read_b128 v[182:185], v88 offset:49152
	ds_read_b128 v[186:189], v88 offset:50176
	ds_read_b128 v[190:193], v88 offset:51200
	ds_read_b128 v[194:197], v88 offset:52224
	ds_read_b128 v[200:203], v88 offset:53248
	ds_read_b128 v[204:207], v88 offset:54272
	ds_read_b128 v[208:211], v88 offset:55296
	ds_read_b128 v[220:223], v88 offset:56320
	global_load_lds_dwordx4 v[90:91], off
	s_add_i32 m0, s16, 0x2000
	s_add_u32 s14, s14, 0x80080
	v_lshl_add_u64 v[90:91], v[226:227], 0, s[88:89]
	s_addc_u32 s15, s15, 0
	s_add_i32 s16, s34, s18
	global_load_lds_dwordx4 v[90:91], off
	v_lshl_add_u64 v[90:91], s[14:15], 0, v[66:67]
	s_mov_b32 m0, s16
	s_nop 0
	global_load_lds_dwordx4 v[90:91], off
	v_lshl_add_u64 v[90:91], s[14:15], 0, v[72:73]
	s_add_i32 m0, s16, 0x2000
	s_nop 0
	global_load_lds_dwordx4 v[90:91], off
	v_lshl_add_u64 v[90:91], v[228:229], 0, s[88:89]
	s_mov_b32 m0, s24
	s_nop 0
	global_load_lds_dwordx4 v[90:91], off
	v_lshl_add_u64 v[90:91], v[230:231], 0, s[88:89]
	s_mov_b32 m0, s25
	s_nop 0
	global_load_lds_dwordx4 v[90:91], off
	s_setprio 0
	s_setprio 1
	s_setprio 0
	s_waitcnt lgkmcnt(0)
	s_setprio 1
	s_waitcnt vmcnt(8)
	s_waitcnt lgkmcnt(0)
	s_barrier
	v_mfma_f32_16x16x32_bf16 v[62:65], v[148:151], v[182:185], v[62:65]
	v_mfma_f32_16x16x32_bf16 v[58:61], v[156:159], v[182:185], v[58:61]
	v_mfma_f32_16x16x32_bf16 v[46:49], v[148:151], v[190:193], v[46:49]
	v_mfma_f32_16x16x32_bf16 v[42:45], v[156:159], v[190:193], v[42:45]
	v_mfma_f32_16x16x32_bf16 v[30:33], v[148:151], v[200:203], v[30:33]
	v_mfma_f32_16x16x32_bf16 v[26:29], v[156:159], v[200:203], v[26:29]
	v_mfma_f32_16x16x32_bf16 v[14:17], v[148:151], v[208:211], v[14:17]
	v_mfma_f32_16x16x32_bf16 v[10:13], v[156:159], v[208:211], v[10:13]
	v_mfma_f32_16x16x32_bf16 v[62:65], v[152:155], v[186:189], v[62:65]
	v_mfma_f32_16x16x32_bf16 v[58:61], v[160:163], v[186:189], v[58:61]
	v_mfma_f32_16x16x32_bf16 v[46:49], v[152:155], v[194:197], v[46:49]
	v_mfma_f32_16x16x32_bf16 v[42:45], v[160:163], v[194:197], v[42:45]
	v_mfma_f32_16x16x32_bf16 v[30:33], v[152:155], v[204:207], v[30:33]
	v_mfma_f32_16x16x32_bf16 v[26:29], v[160:163], v[204:207], v[26:29]
	v_mfma_f32_16x16x32_bf16 v[14:17], v[152:155], v[220:223], v[14:17]
	v_mfma_f32_16x16x32_bf16 v[10:13], v[160:163], v[220:223], v[10:13]
	v_mfma_f32_16x16x32_bf16 v[54:57], v[166:169], v[182:185], v[54:57]
	v_mfma_f32_16x16x32_bf16 v[50:53], v[174:177], v[182:185], v[50:53]
	v_mfma_f32_16x16x32_bf16 v[38:41], v[166:169], v[190:193], v[38:41]
	v_mfma_f32_16x16x32_bf16 v[34:37], v[174:177], v[190:193], v[34:37]
	v_mfma_f32_16x16x32_bf16 v[22:25], v[166:169], v[200:203], v[22:25]
	v_mfma_f32_16x16x32_bf16 v[18:21], v[174:177], v[200:203], v[18:21]
	v_mfma_f32_16x16x32_bf16 v[6:9], v[166:169], v[208:211], v[6:9]
	v_mfma_f32_16x16x32_bf16 v[2:5], v[174:177], v[208:211], v[2:5]
	v_mfma_f32_16x16x32_bf16 v[54:57], v[170:173], v[186:189], v[54:57]
	v_mfma_f32_16x16x32_bf16 v[50:53], v[178:181], v[186:189], v[50:53]
	v_mfma_f32_16x16x32_bf16 v[38:41], v[170:173], v[194:197], v[38:41]
	v_mfma_f32_16x16x32_bf16 v[34:37], v[178:181], v[194:197], v[34:37]
	v_mfma_f32_16x16x32_bf16 v[22:25], v[170:173], v[204:207], v[22:25]
	v_mfma_f32_16x16x32_bf16 v[18:21], v[178:181], v[204:207], v[18:21]
	v_mfma_f32_16x16x32_bf16 v[6:9], v[170:173], v[220:223], v[6:9]
	v_mfma_f32_16x16x32_bf16 v[2:5], v[178:181], v[220:223], v[2:5]
	s_barrier
	s_setprio 0
	s_setprio 1
	s_setprio 0
	s_waitcnt lgkmcnt(0)
	s_add_i32 s30, s30, 2
	s_add_u32 s12, s12, 0x100
	s_addc_u32 s13, s13, 0
	s_cmp_gt_u32 s30, 29
	s_cbranch_scc0 .LBB0_702
	s_cmpk_lt_u32 s1, 0x100
	s_cbranch_scc0 .LBB0_705
	s_barrier

; #define PG8_STAGE(bufoff, gbase, voff) do { _Pragma("unroll") for (int _i = 0; _i < 2; ++_i) \
;         __builtin_amdgcn_global_load_lds((const unsigned*)((const char*)(gbase) + (voff)[_i]), (PG8_LAS unsigned*)(lds + (bufoff) + ldsw + _i * 8192), 16, 0, 0); } while (0)
; #define PG8_LDA(dst, b, h) do { _Pragma("unroll") for (int m = 0; m < 4; ++m) _Pragma("unroll") for (int k = 0; k < 2; ++k) dst[m][k] = *(const PG8_LAS bf16x8*)(lds + PG8_SA(b, h) + aoff + m * 2048 + k * 1024); } while (0)
; #define PG8_LDB(dst, b, h) do { _Pragma("unroll") for (int n = 0; n < 2; ++n) _Pragma("unroll") for (int k = 0; k < 2; ++k) dst[n][k] = *(const PG8_LAS bf16x8*)(lds + PG8_SB(b, h) + boff + n * 2048 + k * 1024); } while (0)
; template <class Epi, class Sched, bool ALIGN_EPI = false, bool SP2 = false>
; __device__ __forceinline__ void gemm_phase(PG8_LAS unsigned char* lds, const Gemm g, const Sched& S, const Epi& E) {
;     ...
;         for (int t = 0; t < nt; t += 2) {
;             const bool last = (t == nt - 2);
;             const char* a1 = cA + (size_t)(t + 1) * kstep;
;             const char* a2 = last ? nA : cA + (size_t)(t + 2) * kstep; const char* b2 = last ? nB : cB + (size_t)(t + 2) * kstep;
;             const char* a3 = a2 + kstep; const char* b3 = b2 + kstep;
;             if (last && has_next) S.a_ready(nxt);
;             if constexpr (SP2) {
;             PG8_LDB(B0, 0, 0); PG8_LDB(B1, 0, 1); PG8_SCHED; PG8_LDA(At, 0, 0); PG8_STAGE(PG8_SA(1, 1), a1 + hstep, voffA);
;             PG8_WAIT_V(8); PG8_WAIT_L(0); PG8_BAR; PG8_MMA(0, 0, At, B0); PG8_MMA(0, 1, At, B1); PG8_BAR; PG8_SCHED;
;             PG8_LDA(At, 0, 1); PG8_STAGE(PG8_SB(0, 0), b2, voffB); PG8_STAGE(PG8_SB(0, 1), b2 + hstep, voffB); PG8_STAGE(PG8_SA(0, 0), a2, voffA);
;             PG8_WAIT_V(8); PG8_WAIT_L(0); PG8_BAR; PG8_MMA(1, 0, At, B0); PG8_MMA(1, 1, At, B1); PG8_BAR; PG8_SCHED;
;             PG8_LDB(B0, 1, 0); PG8_LDB(B1, 1, 1); PG8_SCHED; PG8_LDA(At, 1, 0); PG8_STAGE(PG8_SA(0, 1), a2 + hstep, voffA);
;             PG8_WAIT_V(8); PG8_WAIT_L(0); PG8_BAR; PG8_MMA(0, 0, At, B0); PG8_MMA(0, 1, At, B1); PG8_BAR; PG8_SCHED;
;             PG8_LDA(At, 1, 1); PG8_STAGE(PG8_SB(1, 0), b3, voffB); PG8_STAGE(PG8_SB(1, 1), b3 + hstep, voffB); PG8_STAGE(PG8_SA(1, 0), a3, voffA);
;             PG8_WAIT_V(8); PG8_WAIT_L(0); PG8_BAR; PG8_MMA(1, 0, At, B0); PG8_MMA(1, 1, At, B1); PG8_BAR; PG8_SCHED;
.LBB0_782:
	s_add_u32 s1, s26, 0xfff80080
	s_addc_u32 s2, s27, -1
	s_add_i32 s3, 0, 0x10000
	s_cmpk_eq_i32 s28, 0x1e00
	s_cselect_b32 s35, s21, s2
	s_cselect_b32 s34, s50, s1
	v_add_u32_e32 v66, s3, v206
	s_cselect_b32 s31, s19, s53
	s_cselect_b32 s30, s51, s52
	s_add_i32 s1, 0, 0x14000
	ds_read_b128 v[152:155], v66
	ds_read_b128 v[156:159], v66 offset:1024
	ds_read_b128 v[160:163], v66 offset:2048
	ds_read_b128 v[164:167], v66 offset:3072
	v_add_u32_e32 v66, s1, v206
	ds_read_b128 v[168:171], v66
	ds_read_b128 v[172:175], v66 offset:1024
	ds_read_b128 v[176:179], v66 offset:2048
	ds_read_b128 v[180:183], v66 offset:3072
	v_lshl_add_u64 v[68:69], s[26:27], 0, v[142:143]
	s_add_i32 m0, s43, 0xc000
	ds_read_b128 v[184:187], v208
	ds_read_b128 v[188:191], v208 offset:1024
	ds_read_b128 v[192:195], v208 offset:2048
	ds_read_b128 v[196:199], v208 offset:3072
	ds_read_b128 v[200:203], v208 offset:4096
	ds_read_b128 v[220:223], v208 offset:5120
	ds_read_b128 v[224:227], v208 offset:6144
	ds_read_b128 v[228:231], v208 offset:7168
	global_load_lds_dwordx4 v[68:69], off
	v_lshl_add_u64 v[68:69], s[26:27], 0, v[144:145]
	s_add_i32 m0, s43, 0xe000
	s_nop 0
	global_load_lds_dwordx4 v[68:69], off
	s_setprio 1
	s_waitcnt vmcnt(8)
	s_waitcnt lgkmcnt(0)
	s_barrier
	v_mfma_f32_16x16x32_bf16 v[130:133], v[152:155], v[184:187], v[130:133]
	v_mfma_f32_16x16x32_bf16 v[126:129], v[160:163], v[184:187], v[126:129]
	v_mfma_f32_16x16x32_bf16 v[114:117], v[152:155], v[192:195], v[114:117]
	v_mfma_f32_16x16x32_bf16 v[110:113], v[160:163], v[192:195], v[110:113]
	v_mfma_f32_16x16x32_bf16 v[98:101], v[152:155], v[200:203], v[98:101]
	v_mfma_f32_16x16x32_bf16 v[94:97], v[160:163], v[200:203], v[94:97]
	v_mfma_f32_16x16x32_bf16 v[82:85], v[152:155], v[224:227], v[82:85]
	v_mfma_f32_16x16x32_bf16 v[78:81], v[160:163], v[224:227], v[78:81]
	v_mfma_f32_16x16x32_bf16 v[130:133], v[156:159], v[188:191], v[130:133]
	v_mfma_f32_16x16x32_bf16 v[126:129], v[164:167], v[188:191], v[126:129]
	v_mfma_f32_16x16x32_bf16 v[114:117], v[156:159], v[196:199], v[114:117]
	v_mfma_f32_16x16x32_bf16 v[110:113], v[164:167], v[196:199], v[110:113]
	v_mfma_f32_16x16x32_bf16 v[98:101], v[156:159], v[220:223], v[98:101]
	v_mfma_f32_16x16x32_bf16 v[94:97], v[164:167], v[220:223], v[94:97]
	v_mfma_f32_16x16x32_bf16 v[82:85], v[156:159], v[228:231], v[82:85]
	v_mfma_f32_16x16x32_bf16 v[78:81], v[164:167], v[228:231], v[78:81]
	v_mfma_f32_16x16x32_bf16 v[122:125], v[168:171], v[184:187], v[122:125]
	v_mfma_f32_16x16x32_bf16 v[118:121], v[176:179], v[184:187], v[118:121]
	v_mfma_f32_16x16x32_bf16 v[106:109], v[168:171], v[192:195], v[106:109]
	v_mfma_f32_16x16x32_bf16 v[102:105], v[176:179], v[192:195], v[102:105]
	v_mfma_f32_16x16x32_bf16 v[90:93], v[168:171], v[200:203], v[90:93]
	v_mfma_f32_16x16x32_bf16 v[86:89], v[176:179], v[200:203], v[86:89]
	v_mfma_f32_16x16x32_bf16 v[74:77], v[168:171], v[224:227], v[74:77]
	v_mfma_f32_16x16x32_bf16 v[68:71], v[176:179], v[224:227], v[70:73]
	v_mfma_f32_16x16x32_bf16 v[122:125], v[172:175], v[188:191], v[122:125]
	v_mfma_f32_16x16x32_bf16 v[118:121], v[180:183], v[188:191], v[118:121]
	v_mfma_f32_16x16x32_bf16 v[106:109], v[172:175], v[196:199], v[106:109]
	v_mfma_f32_16x16x32_bf16 v[102:105], v[180:183], v[196:199], v[102:105]
	v_mfma_f32_16x16x32_bf16 v[90:93], v[172:175], v[220:223], v[90:93]
	v_mfma_f32_16x16x32_bf16 v[86:89], v[180:183], v[220:223], v[86:89]
	v_mfma_f32_16x16x32_bf16 v[74:77], v[172:175], v[228:231], v[74:77]
	v_mfma_f32_16x16x32_bf16 v[68:71], v[180:183], v[228:231], v[68:71]
	s_barrier
	s_add_i32 s2, s3, s42
	v_lshl_add_u64 v[204:205], s[30:31], 0, v[138:139]
	s_mov_b32 m0, s2
	ds_read_b128 v[184:187], v208 offset:16384
	ds_read_b128 v[188:191], v208 offset:17408
	ds_read_b128 v[192:195], v208 offset:18432
	ds_read_b128 v[196:199], v208 offset:19456
	ds_read_b128 v[200:203], v208 offset:20480
	ds_read_b128 v[220:223], v208 offset:21504
	ds_read_b128 v[224:227], v208 offset:22528
	ds_read_b128 v[228:231], v208 offset:23552
	global_load_lds_dwordx4 v[204:205], off
	s_add_i32 m0, s2, 0x2000
	s_add_u32 s2, s30, 0x80000
	v_lshl_add_u64 v[210:211], s[30:31], 0, v[134:135]
	s_addc_u32 s3, s31, 0
	s_add_i32 s1, s1, s42
	global_load_lds_dwordx4 v[210:211], off
	v_lshl_add_u64 v[72:73], s[2:3], 0, v[138:139]
	s_mov_b32 m0, s1
	v_lshl_add_u64 v[232:233], s[34:35], 0, v[140:141]
	global_load_lds_dwordx4 v[72:73], off
	v_lshl_add_u64 v[72:73], s[2:3], 0, v[134:135]
	s_add_i32 m0, s1, 0x2000
	v_lshl_add_u64 v[234:235], s[34:35], 0, v[136:137]
	global_load_lds_dwordx4 v[72:73], off
	s_mov_b32 m0, s43
	s_nop 0
	global_load_lds_dwordx4 v[232:233], off
	s_mov_b32 m0, s44
	s_nop 0
	global_load_lds_dwordx4 v[234:235], off
	s_setprio 0
	s_setprio 1
	s_setprio 0
	s_waitcnt lgkmcnt(0)
	s_setprio 1
	s_waitcnt vmcnt(8)
	s_waitcnt lgkmcnt(0)
	s_barrier
; #define PG8_STAGE(bufoff, gbase, voff) do { _Pragma("unroll") for (int _i = 0; _i < 2; ++_i) \
;         __builtin_amdgcn_global_load_lds((const unsigned*)((const char*)(gbase) + (voff)[_i]), (PG8_LAS unsigned*)(lds + (bufoff) + ldsw + _i * 8192), 16, 0, 0); } while (0)
; #define PG8_LDA(dst, b, h) do { _Pragma("unroll") for (int m = 0; m < 4; ++m) _Pragma("unroll") for (int k = 0; k < 2; ++k) dst[m][k] = *(const PG8_LAS bf16x8*)(lds + PG8_SA(b, h) + aoff + m * 2048 + k * 1024); } while (0)
; #define PG8_LDB(dst, b, h) do { _Pragma("unroll") for (int n = 0; n < 2; ++n) _Pragma("unroll") for (int k = 0; k < 2; ++k) dst[n][k] = *(const PG8_LAS bf16x8*)(lds + PG8_SB(b, h) + boff + n * 2048 + k * 1024); } while (0)
; #define PG8_MMA(ai, bj, At, Bt) do { __builtin_amdgcn_s_setprio(1); _Pragma("unroll") for (int m = 0; m < 4; ++m) _Pragma("unroll") for (int n = 0; n < 2; ++n) _Pragma("unroll") for (int k = 0; k < 2; ++k) \
;         acc[ai][bj][m][n] = __builtin_amdgcn_mfma_f32_16x16x32_bf16(Bt[n][k], At[m][k], acc[ai][bj][m][n], 0, 0, 0); __builtin_amdgcn_s_setprio(0); } while (0)
; #define PG8_WAIT_V(n) asm volatile("s_waitcnt vmcnt(" #n ")" ::: "memory")
; #define PG8_WAIT_L(n) asm volatile("s_waitcnt lgkmcnt(" #n ")" ::: "memory")
; #define PG8_BAR __builtin_amdgcn_s_barrier()
; #define PG8_SCHED __builtin_amdgcn_sched_barrier(0)
; template <class Epi, class Sched, bool ALIGN_EPI = false, bool SP2 = false>
; __device__ __forceinline__ void gemm_phase(PG8_LAS unsigned char* lds, const Gemm g, const Sched& S, const Epi& E) {
;     ...
;             PG8_WAIT_V(8); PG8_WAIT_L(0); PG8_BAR; PG8_MMA(1, 0, At, B0); PG8_MMA(1, 1, At, B1); PG8_BAR; PG8_SCHED;
;             PG8_LDB(B0, 1, 0); PG8_LDB(B1, 1, 1); PG8_SCHED; PG8_LDA(At, 1, 0); PG8_STAGE(PG8_SA(0, 1), a2 + hstep, voffA);
;             PG8_WAIT_V(8); PG8_WAIT_L(0); PG8_BAR; PG8_MMA(0, 0, At, B0); PG8_MMA(0, 1, At, B1); PG8_BAR; PG8_SCHED;
;             PG8_LDA(At, 1, 1); PG8_STAGE(PG8_SB(1, 0), b3, voffB); PG8_STAGE(PG8_SB(1, 1), b3 + hstep, voffB); PG8_STAGE(PG8_SA(1, 0), a3, voffA);
	v_mfma_f32_16x16x32_bf16 v[62:65], v[152:155], v[184:187], v[62:65]
	v_mfma_f32_16x16x32_bf16 v[58:61], v[160:163], v[184:187], v[58:61]
	v_mfma_f32_16x16x32_bf16 v[46:49], v[152:155], v[192:195], v[46:49]
	v_mfma_f32_16x16x32_bf16 v[42:45], v[160:163], v[192:195], v[42:45]
	v_mfma_f32_16x16x32_bf16 v[30:33], v[152:155], v[200:203], v[30:33]
	v_mfma_f32_16x16x32_bf16 v[26:29], v[160:163], v[200:203], v[26:29]
	v_mfma_f32_16x16x32_bf16 v[14:17], v[152:155], v[224:227], v[14:17]
	v_mfma_f32_16x16x32_bf16 v[10:13], v[160:163], v[224:227], v[10:13]
	v_mfma_f32_16x16x32_bf16 v[62:65], v[156:159], v[188:191], v[62:65]
	v_mfma_f32_16x16x32_bf16 v[58:61], v[164:167], v[188:191], v[58:61]
	v_mfma_f32_16x16x32_bf16 v[46:49], v[156:159], v[196:199], v[46:49]
	v_mfma_f32_16x16x32_bf16 v[42:45], v[164:167], v[196:199], v[42:45]
	v_mfma_f32_16x16x32_bf16 v[30:33], v[156:159], v[220:223], v[30:33]
	v_mfma_f32_16x16x32_bf16 v[26:29], v[164:167], v[220:223], v[26:29]
	v_mfma_f32_16x16x32_bf16 v[14:17], v[156:159], v[228:231], v[14:17]
	v_mfma_f32_16x16x32_bf16 v[10:13], v[164:167], v[228:231], v[10:13]
	v_mfma_f32_16x16x32_bf16 v[54:57], v[168:171], v[184:187], v[54:57]
	v_mfma_f32_16x16x32_bf16 v[50:53], v[176:179], v[184:187], v[50:53]
	v_mfma_f32_16x16x32_bf16 v[38:41], v[168:171], v[192:195], v[38:41]
	v_mfma_f32_16x16x32_bf16 v[34:37], v[176:179], v[192:195], v[34:37]
	v_mfma_f32_16x16x32_bf16 v[22:25], v[168:171], v[200:203], v[22:25]
	v_mfma_f32_16x16x32_bf16 v[18:21], v[176:179], v[200:203], v[18:21]
	v_mfma_f32_16x16x32_bf16 v[6:9], v[168:171], v[224:227], v[6:9]
	v_mfma_f32_16x16x32_bf16 v[2:5], v[176:179], v[224:227], v[2:5]
	v_mfma_f32_16x16x32_bf16 v[54:57], v[172:175], v[188:191], v[54:57]
	v_mfma_f32_16x16x32_bf16 v[50:53], v[180:183], v[188:191], v[50:53]
	v_mfma_f32_16x16x32_bf16 v[38:41], v[172:175], v[196:199], v[38:41]
	v_mfma_f32_16x16x32_bf16 v[34:37], v[180:183], v[196:199], v[34:37]
	v_mfma_f32_16x16x32_bf16 v[22:25], v[172:175], v[220:223], v[22:25]
	v_mfma_f32_16x16x32_bf16 v[18:21], v[180:183], v[220:223], v[18:21]
	v_mfma_f32_16x16x32_bf16 v[6:9], v[172:175], v[228:231], v[6:9]
	v_mfma_f32_16x16x32_bf16 v[2:5], v[180:183], v[228:231], v[2:5]
	s_barrier
	s_add_i32 s1, 0, 0x18000
	v_add_u32_e32 v66, s1, v206
	s_add_i32 s55, 0, 0x1c000
	ds_read_b128 v[152:155], v66
	ds_read_b128 v[156:159], v66 offset:1024
	ds_read_b128 v[160:163], v66 offset:2048
	ds_read_b128 v[164:167], v66 offset:3072
	v_add_u32_e32 v66, s55, v206
	ds_read_b128 v[168:171], v66
	ds_read_b128 v[172:175], v66 offset:1024
	ds_read_b128 v[176:179], v66 offset:2048
	ds_read_b128 v[180:183], v66 offset:3072
	s_add_u32 s2, s34, 0x80000
	s_addc_u32 s3, s35, 0
	s_mov_b32 m0, s45
	v_lshl_add_u64 v[72:73], s[2:3], 0, v[140:141]
	ds_read_b128 v[184:187], v208 offset:32768
	ds_read_b128 v[188:191], v208 offset:33792
	ds_read_b128 v[192:195], v208 offset:34816
	ds_read_b128 v[196:199], v208 offset:35840
	ds_read_b128 v[200:203], v208 offset:36864
	ds_read_b128 v[220:223], v208 offset:37888
	ds_read_b128 v[224:227], v208 offset:38912
	ds_read_b128 v[228:231], v208 offset:39936
	global_load_lds_dwordx4 v[72:73], off
	v_lshl_add_u64 v[72:73], s[2:3], 0, v[136:137]
	s_mov_b32 m0, s46
	s_nop 0
	global_load_lds_dwordx4 v[72:73], off
	s_setprio 0
	s_setprio 1
	s_setprio 0
	s_waitcnt lgkmcnt(0)
	s_setprio 1
	s_waitcnt vmcnt(8)
	s_waitcnt lgkmcnt(0)
	s_barrier
	v_mfma_f32_16x16x32_bf16 v[130:133], v[152:155], v[184:187], v[130:133]
	v_mfma_f32_16x16x32_bf16 v[126:129], v[160:163], v[184:187], v[126:129]
	v_mfma_f32_16x16x32_bf16 v[114:117], v[152:155], v[192:195], v[114:117]
	v_mfma_f32_16x16x32_bf16 v[110:113], v[160:163], v[192:195], v[110:113]
	v_mfma_f32_16x16x32_bf16 v[98:101], v[152:155], v[200:203], v[98:101]
	v_mfma_f32_16x16x32_bf16 v[94:97], v[160:163], v[200:203], v[94:97]
	v_mfma_f32_16x16x32_bf16 v[82:85], v[152:155], v[224:227], v[82:85]
	v_mfma_f32_16x16x32_bf16 v[78:81], v[160:163], v[224:227], v[78:81]
	v_mfma_f32_16x16x32_bf16 v[130:133], v[156:159], v[188:191], v[130:133]
	v_mfma_f32_16x16x32_bf16 v[126:129], v[164:167], v[188:191], v[126:129]
	v_mfma_f32_16x16x32_bf16 v[114:117], v[156:159], v[196:199], v[114:117]
	v_mfma_f32_16x16x32_bf16 v[110:113], v[164:167], v[196:199], v[110:113]
	v_mfma_f32_16x16x32_bf16 v[98:101], v[156:159], v[220:223], v[98:101]
	v_mfma_f32_16x16x32_bf16 v[94:97], v[164:167], v[220:223], v[94:97]
	v_mfma_f32_16x16x32_bf16 v[82:85], v[156:159], v[228:231], v[82:85]
	v_mfma_f32_16x16x32_bf16 v[78:81], v[164:167], v[228:231], v[78:81]
	v_mfma_f32_16x16x32_bf16 v[122:125], v[168:171], v[184:187], v[122:125]
	v_mfma_f32_16x16x32_bf16 v[118:121], v[176:179], v[184:187], v[118:121]
	v_mfma_f32_16x16x32_bf16 v[106:109], v[168:171], v[192:195], v[106:109]
	v_mfma_f32_16x16x32_bf16 v[102:105], v[176:179], v[192:195], v[102:105]
	v_mfma_f32_16x16x32_bf16 v[90:93], v[168:171], v[200:203], v[90:93]
	v_mfma_f32_16x16x32_bf16 v[86:89], v[176:179], v[200:203], v[86:89]
	v_mfma_f32_16x16x32_bf16 v[72:75], v[168:171], v[224:227], v[74:77]
	v_mfma_f32_16x16x32_bf16 v[68:71], v[176:179], v[224:227], v[68:71]
	v_mfma_f32_16x16x32_bf16 v[122:125], v[172:175], v[188:191], v[122:125]
	v_mfma_f32_16x16x32_bf16 v[118:121], v[180:183], v[188:191], v[118:121]
	v_mfma_f32_16x16x32_bf16 v[106:109], v[172:175], v[196:199], v[106:109]
	v_mfma_f32_16x16x32_bf16 v[102:105], v[180:183], v[196:199], v[102:105]
	v_mfma_f32_16x16x32_bf16 v[90:93], v[172:175], v[220:223], v[90:93]
	v_mfma_f32_16x16x32_bf16 v[86:89], v[180:183], v[220:223], v[86:89]
	v_mfma_f32_16x16x32_bf16 v[74:77], v[172:175], v[228:231], v[72:75]
	v_mfma_f32_16x16x32_bf16 v[70:73], v[180:183], v[228:231], v[68:71]
	s_barrier
; #define PG8_STAGE(bufoff, gbase, voff) do { _Pragma("unroll") for (int _i = 0; _i < 2; ++_i) \
;         __builtin_amdgcn_global_load_lds((const unsigned*)((const char*)(gbase) + (voff)[_i]), (PG8_LAS unsigned*)(lds + (bufoff) + ldsw + _i * 8192), 16, 0, 0); } while (0)
; #define PG8_LDA(dst, b, h) do { _Pragma("unroll") for (int m = 0; m < 4; ++m) _Pragma("unroll") for (int k = 0; k < 2; ++k) dst[m][k] = *(const PG8_LAS bf16x8*)(lds + PG8_SA(b, h) + aoff + m * 2048 + k * 1024); } while (0)
; #define PG8_WAIT_V(n) asm volatile("s_waitcnt vmcnt(" #n ")" ::: "memory")
; #define PG8_WAIT_L(n) asm volatile("s_waitcnt lgkmcnt(" #n ")" ::: "memory")
; #define PG8_BAR __builtin_amdgcn_s_barrier()
;     __device__ __forceinline__ void mid(f32x4 (&acc)[2][2][4][2], const Unit& u, int seg, int wr, int wc, int fr, int fq) const {
;     ...
;             for (int m = 0; m < 4; ++m) { const unsigned char* rowp = G + (size_t)(row0 + ai * HALF + m * 16) * 8192 + col0 + seg * 2048;
; #pragma unroll
;                 for (int bj = 0; bj < 2; ++bj) { ga[ai][m][bj] = *(const u32x2v*)(rowp + bj * HALF); gb[ai][m][bj] = *(const u32x2v*)(rowp + 2048 + bj * HALF); } }
; template <class Epi, class Sched, bool ALIGN_EPI = false, bool SP2 = false>
; __device__ __forceinline__ void gemm_phase(PG8_LAS unsigned char* lds, const Gemm g, const Sched& S, const Epi& E) {
;     ...
;             PG8_LDB(B0, 0, 0); PG8_LDB(B1, 0, 1); PG8_SCHED; PG8_LDA(At, 0, 0); PG8_STAGE(PG8_SA(1, 1), a1 + hstep, voffA);
;             PG8_WAIT_V(8); PG8_WAIT_L(0); PG8_BAR; PG8_MMA(0, 0, At, B0); PG8_MMA(0, 1, At, B1); PG8_BAR; PG8_SCHED;
;             PG8_LDA(At, 0, 1); PG8_STAGE(PG8_SB(0, 0), b2, voffB); PG8_STAGE(PG8_SB(0, 1), b2 + hstep, voffB); PG8_STAGE(PG8_SA(0, 0), a2, voffA);
;             PG8_WAIT_V(8); PG8_WAIT_L(0); PG8_BAR; PG8_MMA(1, 0, At, B0); PG8_MMA(1, 1, At, B1); PG8_BAR; PG8_SCHED;
;             PG8_LDB(B0, 1, 0); PG8_LDB(B1, 1, 1); PG8_SCHED; PG8_LDA(At, 1, 0); PG8_STAGE(PG8_SA(0, 1), a2 + hstep, voffA);
;             PG8_WAIT_V(8); PG8_WAIT_L(0); PG8_BAR; PG8_MMA(0, 0, At, B0); PG8_MMA(0, 1, At, B1); PG8_BAR; PG8_SCHED;
;             PG8_LDA(At, 1, 1); PG8_STAGE(PG8_SB(1, 0), b3, voffB); PG8_STAGE(PG8_SB(1, 1), b3 + hstep, voffB); PG8_STAGE(PG8_SA(1, 0), a3, voffA);
;             PG8_WAIT_V(8); PG8_WAIT_L(0); PG8_BAR; PG8_MMA(1, 0, At, B0); PG8_MMA(1, 1, At, B1); PG8_BAR; PG8_SCHED;
	s_add_i32 s1, s1, s42
	v_lshl_add_u64 v[68:69], v[204:205], 0, s[88:89]
	s_mov_b32 m0, s1
	ds_read_b128 v[184:187], v208 offset:49152
	ds_read_b128 v[188:191], v208 offset:50176
	ds_read_b128 v[192:195], v208 offset:51200
	ds_read_b128 v[196:199], v208 offset:52224
	ds_read_b128 v[200:203], v208 offset:53248
	ds_read_b128 v[220:223], v208 offset:54272
	ds_read_b128 v[224:227], v208 offset:55296
	ds_read_b128 v[228:231], v208 offset:56320
	global_load_lds_dwordx4 v[68:69], off
	s_add_i32 m0, s1, 0x2000
	s_add_u32 s2, s30, 0x80080
	v_lshl_add_u64 v[68:69], v[210:211], 0, s[88:89]
	s_addc_u32 s3, s31, 0
	s_add_i32 s1, s55, s42
	global_load_lds_dwordx4 v[68:69], off
	v_lshl_add_u64 v[68:69], s[2:3], 0, v[138:139]
	s_mov_b32 m0, s1
	s_nop 0
	global_load_lds_dwordx4 v[68:69], off
	v_lshl_add_u64 v[68:69], s[2:3], 0, v[134:135]
	s_add_i32 m0, s1, 0x2000
	s_nop 0
	global_load_lds_dwordx4 v[68:69], off
	v_lshl_add_u64 v[68:69], v[232:233], 0, s[88:89]
	s_mov_b32 m0, s47
	s_nop 0
	global_load_lds_dwordx4 v[68:69], off
	v_lshl_add_u64 v[68:69], v[234:235], 0, s[88:89]
	s_mov_b32 m0, s48
	s_nop 0
	global_load_lds_dwordx4 v[68:69], off
	s_setprio 0
	s_setprio 1
	s_setprio 0
	s_waitcnt lgkmcnt(0)
	s_setprio 1
	s_waitcnt vmcnt(8)
	s_waitcnt lgkmcnt(0)
	s_barrier
	v_mfma_f32_16x16x32_bf16 v[62:65], v[152:155], v[184:187], v[62:65]
	v_mfma_f32_16x16x32_bf16 v[58:61], v[160:163], v[184:187], v[58:61]
	v_mfma_f32_16x16x32_bf16 v[46:49], v[152:155], v[192:195], v[46:49]
	v_mfma_f32_16x16x32_bf16 v[42:45], v[160:163], v[192:195], v[42:45]
	v_mfma_f32_16x16x32_bf16 v[30:33], v[152:155], v[200:203], v[30:33]
	v_mfma_f32_16x16x32_bf16 v[26:29], v[160:163], v[200:203], v[26:29]
	v_mfma_f32_16x16x32_bf16 v[14:17], v[152:155], v[224:227], v[14:17]
	v_mfma_f32_16x16x32_bf16 v[10:13], v[160:163], v[224:227], v[10:13]
	v_mfma_f32_16x16x32_bf16 v[62:65], v[156:159], v[188:191], v[62:65]
	v_mfma_f32_16x16x32_bf16 v[58:61], v[164:167], v[188:191], v[58:61]
	v_mfma_f32_16x16x32_bf16 v[46:49], v[156:159], v[196:199], v[46:49]
	v_mfma_f32_16x16x32_bf16 v[42:45], v[164:167], v[196:199], v[42:45]
	v_mfma_f32_16x16x32_bf16 v[30:33], v[156:159], v[220:223], v[30:33]
	v_mfma_f32_16x16x32_bf16 v[26:29], v[164:167], v[220:223], v[26:29]
	v_mfma_f32_16x16x32_bf16 v[14:17], v[156:159], v[228:231], v[14:17]
	v_mfma_f32_16x16x32_bf16 v[10:13], v[164:167], v[228:231], v[10:13]
	v_mfma_f32_16x16x32_bf16 v[54:57], v[168:171], v[184:187], v[54:57]
	v_mfma_f32_16x16x32_bf16 v[50:53], v[176:179], v[184:187], v[50:53]
	v_mfma_f32_16x16x32_bf16 v[38:41], v[168:171], v[192:195], v[38:41]
	v_mfma_f32_16x16x32_bf16 v[34:37], v[176:179], v[192:195], v[34:37]
	v_mfma_f32_16x16x32_bf16 v[22:25], v[168:171], v[200:203], v[22:25]
	v_mfma_f32_16x16x32_bf16 v[18:21], v[176:179], v[200:203], v[18:21]
	v_mfma_f32_16x16x32_bf16 v[6:9], v[168:171], v[224:227], v[6:9]
	v_mfma_f32_16x16x32_bf16 v[2:5], v[176:179], v[224:227], v[2:5]
	v_mfma_f32_16x16x32_bf16 v[54:57], v[172:175], v[188:191], v[54:57]
	v_mfma_f32_16x16x32_bf16 v[50:53], v[180:183], v[188:191], v[50:53]
	v_mfma_f32_16x16x32_bf16 v[38:41], v[172:175], v[196:199], v[38:41]
	v_mfma_f32_16x16x32_bf16 v[34:37], v[180:183], v[196:199], v[34:37]
	v_mfma_f32_16x16x32_bf16 v[22:25], v[172:175], v[220:223], v[22:25]
	v_mfma_f32_16x16x32_bf16 v[18:21], v[180:183], v[220:223], v[18:21]
	v_mfma_f32_16x16x32_bf16 v[6:9], v[172:175], v[228:231], v[6:9]
	v_mfma_f32_16x16x32_bf16 v[2:5], v[180:183], v[228:231], v[2:5]
	s_barrier
	s_setprio 0
	s_setprio 1
	s_setprio 0
	s_waitcnt lgkmcnt(0)
	s_mov_b32 s1, s54
	s_add_i32 s54, s54, 2
	s_and_b32 s2, s54, 6
	s_cmp_eq_u32 s2, 0
	s_cselect_b64 s[2:3], -1, 0
	s_cmp_gt_u32 s1, 29
	s_cselect_b64 s[30:31], -1, 0
	s_cmp_lt_u32 s1, 30
	s_cselect_b64 s[34:35], -1, 0
	s_and_b64 s[2:3], s[2:3], s[34:35]
	s_andn2_b64 vcc, exec, s[2:3]
	s_cbranch_vccnz .LBB0_781
	v_mov_b32_e32 v68, v148
	s_nop 0
	v_ashrrev_i32_e32 v69, 31, v68
	v_lshlrev_b64 v[68:69], 13, v[68:69]
	v_lshl_add_u64 v[68:69], s[28:29], 0, v[68:69]
	v_lshl_add_u64 v[68:69], v[150:151], 0, v[68:69]
	v_add_co_u32_e32 v152, vcc, 0xcbff000, v68
	s_nop 1
	v_addc_co_u32_e32 v153, vcc, 0, v69, vcc
	v_add_co_u32_e32 v154, vcc, 0xcc00000, v68
	s_nop 1
	v_addc_co_u32_e32 v155, vcc, 0, v69, vcc
	global_load_dwordx2 v[210:211], v[152:153], off offset:2560
	global_load_dwordx2 v[220:221], v[154:155], off offset:512
	global_load_dwordx2 v[222:223], v[154:155], off offset:640
	global_load_dwordx2 v[224:225], v[152:153], off offset:2688
	v_add_co_u32_e32 v152, vcc, 0xcc1f000, v68
	s_nop 1
	v_addc_co_u32_e32 v153, vcc, 0, v69, vcc
	v_add_co_u32_e32 v154, vcc, 0xcc20000, v68
	s_nop 0
	s_nop 0
	v_addc_co_u32_e32 v155, vcc, 0, v69, vcc
	global_load_dwordx2 v[202:203], v[152:153], off offset:2560
	global_load_dwordx2 v[204:205], v[154:155], off offset:512
	global_load_dwordx2 v[200:201], v[154:155], off offset:640
	global_load_dwordx2 v[198:199], v[152:153], off offset:2688
	v_add_co_u32_e32 v152, vcc, 0xcc3f000, v68
	s_nop 0
	s_nop 0
	v_addc_co_u32_e32 v153, vcc, 0, v69, vcc
	v_add_co_u32_e32 v154, vcc, 0xcc40000, v68
	s_nop 0
	s_nop 0
	v_addc_co_u32_e32 v155, vcc, 0, v69, vcc
	global_load_dwordx2 v[194:195], v[152:153], off offset:2560
	global_load_dwordx2 v[196:197], v[154:155], off offset:512
	global_load_dwordx2 v[192:193], v[154:155], off offset:640
	global_load_dwordx2 v[190:191], v[152:153], off offset:2688
	v_add_co_u32_e32 v152, vcc, 0xcc5f000, v68
	s_nop 0
	s_nop 0
	v_addc_co_u32_e32 v153, vcc, 0, v69, vcc
	v_add_co_u32_e32 v154, vcc, 0xcc60000, v68
	s_nop 1
	v_addc_co_u32_e32 v155, vcc, 0, v69, vcc
	global_load_dwordx2 v[186:187], v[152:153], off offset:2560
; __device__ __forceinline__ float gate_v(unsigned q) { return (float)q; }
;     __device__ __forceinline__ void mid(f32x4 (&acc)[2][2][4][2], const Unit& u, int seg, int wr, int wc, int fr, int fq) const {
;     ...
;                 for (int bj = 0; bj < 2; ++bj) { ga[ai][m][bj] = *(const u32x2v*)(rowp + bj * HALF); gb[ai][m][bj] = *(const u32x2v*)(rowp + 2048 + bj * HALF); } }
; #pragma unroll
;         for (int ai = 0; ai < 2; ++ai)
; #pragma unroll
;             for (int m = 0; m < 4; ++m)
; #pragma unroll
;                 for (int bj = 0; bj < 2; ++bj)
; #pragma unroll
;                     for (int e = 0; e < 8; ++e) { const unsigned a = (ga[ai][m][bj][e >> 2] >> (8 * (e & 3))) & 255u, b = (gb[ai][m][bj][e >> 2] >> (8 * (e & 3))) & 255u;
;                         acc[ai][bj][m][e >> 2][e & 3] *= gate_v(a) * __builtin_amdgcn_rcpf(gate_v(b)); }
	global_load_dwordx2 v[188:189], v[154:155], off offset:512
	global_load_dwordx2 v[184:185], v[154:155], off offset:640
	global_load_dwordx2 v[182:183], v[152:153], off offset:2688
	v_add_co_u32_e32 v152, vcc, 0xccff000, v68
	s_nop 1
	v_addc_co_u32_e32 v153, vcc, 0, v69, vcc
	v_add_co_u32_e32 v154, vcc, 0xcd00000, v68
	s_nop 1
	v_addc_co_u32_e32 v155, vcc, 0, v69, vcc
	global_load_dwordx2 v[178:179], v[152:153], off offset:2560
	global_load_dwordx2 v[180:181], v[154:155], off offset:512
	global_load_dwordx2 v[176:177], v[154:155], off offset:640
	global_load_dwordx2 v[174:175], v[152:153], off offset:2688
	v_add_co_u32_e32 v152, vcc, 0xcd1f000, v68
	s_nop 1
	v_addc_co_u32_e32 v153, vcc, 0, v69, vcc
	v_add_co_u32_e32 v154, vcc, 0xcd20000, v68
	s_nop 1
	v_addc_co_u32_e32 v155, vcc, 0, v69, vcc
	global_load_dwordx2 v[170:171], v[152:153], off offset:2560
	global_load_dwordx2 v[172:173], v[154:155], off offset:512
	global_load_dwordx2 v[168:169], v[154:155], off offset:640
	global_load_dwordx2 v[166:167], v[152:153], off offset:2688
	v_add_co_u32_e32 v152, vcc, 0xcd3f000, v68
	s_nop 1
	v_addc_co_u32_e32 v153, vcc, 0, v69, vcc
	v_add_co_u32_e32 v154, vcc, 0xcd40000, v68
	s_nop 1
	v_addc_co_u32_e32 v155, vcc, 0, v69, vcc
	v_add_co_u32_e32 v226, vcc, 0xcd5f000, v68
	global_load_dwordx2 v[162:163], v[152:153], off offset:2560
	global_load_dwordx2 v[164:165], v[154:155], off offset:512
	global_load_dwordx2 v[160:161], v[154:155], off offset:640
	global_load_dwordx2 v[158:159], v[152:153], off offset:2688
	v_addc_co_u32_e32 v227, vcc, 0, v69, vcc
	v_add_co_u32_e32 v68, vcc, 0xcd60000, v68
	s_nop 1
	v_addc_co_u32_e32 v69, vcc, 0, v69, vcc
	global_load_dwordx2 v[154:155], v[226:227], off offset:2560
	global_load_dwordx2 v[156:157], v[68:69], off offset:512
	global_load_dwordx2 v[152:153], v[68:69], off offset:640
	s_nop 0
	global_load_dwordx2 v[68:69], v[226:227], off offset:2688
	s_waitcnt vmcnt(28)
	v_cvt_f32_ubyte1_e32 v233, v210
	v_cvt_f32_ubyte0_e32 v66, v220
	v_cvt_f32_ubyte0_e32 v232, v210
	v_cvt_f32_ubyte3_e32 v231, v210
	v_cvt_f32_ubyte2_e32 v230, v210
	v_rcp_iflag_f32_e32 v226, v66
	v_cvt_f32_ubyte1_e32 v66, v220
	v_rcp_iflag_f32_e32 v227, v66
	v_cvt_f32_ubyte2_e32 v66, v220
	v_rcp_iflag_f32_e32 v228, v66
	v_cvt_f32_ubyte3_e32 v66, v220
	v_rcp_iflag_f32_e32 v229, v66
	v_pk_mul_f32 v[226:227], v[226:227], v[232:233]
	v_cvt_f32_ubyte0_e32 v66, v221
	v_pk_mul_f32 v[130:131], v[130:131], v[226:227]
	v_rcp_iflag_f32_e32 v226, v66
	v_cvt_f32_ubyte1_e32 v66, v221
	v_rcp_iflag_f32_e32 v227, v66
	v_cvt_f32_ubyte2_e32 v66, v221
	v_pk_mul_f32 v[228:229], v[228:229], v[230:231]
	v_rcp_iflag_f32_e32 v220, v66
	v_cvt_f32_ubyte3_e32 v66, v221
	v_cvt_f32_ubyte1_e32 v231, v211
	v_cvt_f32_ubyte0_e32 v230, v211
	v_pk_mul_f32 v[132:133], v[132:133], v[228:229]
	v_rcp_iflag_f32_e32 v221, v66
	v_cvt_f32_ubyte3_e32 v229, v211
	v_cvt_f32_ubyte2_e32 v228, v211
	v_pk_mul_f32 v[210:211], v[226:227], v[230:231]
	v_cvt_f32_ubyte0_e32 v66, v222
	v_pk_mul_f32 v[126:127], v[126:127], v[210:211]
	v_rcp_iflag_f32_e32 v210, v66
	v_cvt_f32_ubyte1_e32 v66, v222
	v_rcp_iflag_f32_e32 v211, v66
	v_pk_mul_f32 v[220:221], v[220:221], v[228:229]
	v_cvt_f32_ubyte2_e32 v66, v222
	v_pk_mul_f32 v[128:129], v[128:129], v[220:221]
	v_rcp_iflag_f32_e32 v220, v66
	v_cvt_f32_ubyte3_e32 v66, v222
	v_cvt_f32_ubyte1_e32 v229, v224
	v_cvt_f32_ubyte0_e32 v228, v224
	v_rcp_iflag_f32_e32 v221, v66
	v_pk_mul_f32 v[210:211], v[210:211], v[228:229]
	v_cvt_f32_ubyte0_e32 v66, v223
	v_pk_mul_f32 v[122:123], v[122:123], v[210:211]
	v_rcp_iflag_f32_e32 v210, v66
	v_cvt_f32_ubyte1_e32 v66, v223
	v_rcp_iflag_f32_e32 v211, v66
	v_cvt_f32_ubyte3_e32 v227, v224
	v_cvt_f32_ubyte2_e32 v226, v224
	v_pk_mul_f32 v[220:221], v[220:221], v[226:227]
	v_cvt_f32_ubyte2_e32 v66, v223
	v_pk_mul_f32 v[124:125], v[124:125], v[220:221]
	v_rcp_iflag_f32_e32 v220, v66
	v_cvt_f32_ubyte3_e32 v66, v223
	v_cvt_f32_ubyte1_e32 v227, v225
	v_cvt_f32_ubyte0_e32 v226, v225
	v_rcp_iflag_f32_e32 v221, v66
	v_pk_mul_f32 v[210:211], v[210:211], v[226:227]
	s_waitcnt vmcnt(26)
	v_cvt_f32_ubyte0_e32 v66, v204
	v_pk_mul_f32 v[118:119], v[118:119], v[210:211]
	v_rcp_iflag_f32_e32 v210, v66
	v_cvt_f32_ubyte1_e32 v66, v204
	v_rcp_iflag_f32_e32 v211, v66
	v_cvt_f32_ubyte3_e32 v223, v225
	v_cvt_f32_ubyte2_e32 v222, v225
	v_pk_mul_f32 v[220:221], v[220:221], v[222:223]
	v_cvt_f32_ubyte2_e32 v66, v204
	v_pk_mul_f32 v[120:121], v[120:121], v[220:221]
	v_rcp_iflag_f32_e32 v220, v66
	v_cvt_f32_ubyte3_e32 v66, v204
	v_cvt_f32_ubyte1_e32 v225, v202
	v_cvt_f32_ubyte0_e32 v224, v202
	v_rcp_iflag_f32_e32 v221, v66
	v_pk_mul_f32 v[210:211], v[210:211], v[224:225]
	v_cvt_f32_ubyte0_e32 v66, v205
	v_pk_mul_f32 v[114:115], v[114:115], v[210:211]
	v_rcp_iflag_f32_e32 v210, v66
	v_cvt_f32_ubyte1_e32 v66, v205
	v_rcp_iflag_f32_e32 v211, v66
	v_cvt_f32_ubyte3_e32 v223, v202
	v_cvt_f32_ubyte2_e32 v222, v202
	v_cvt_f32_ubyte2_e32 v66, v205
	v_pk_mul_f32 v[220:221], v[220:221], v[222:223]
	v_rcp_iflag_f32_e32 v204, v66
	v_cvt_f32_ubyte3_e32 v66, v205
	v_cvt_f32_ubyte1_e32 v223, v203
	v_cvt_f32_ubyte0_e32 v222, v203
	v_pk_mul_f32 v[116:117], v[116:117], v[220:221]
	v_rcp_iflag_f32_e32 v205, v66
	v_cvt_f32_ubyte3_e32 v221, v203
	v_cvt_f32_ubyte2_e32 v220, v203
	v_pk_mul_f32 v[202:203], v[210:211], v[222:223]
	s_waitcnt vmcnt(25)
	v_cvt_f32_ubyte0_e32 v66, v200
	v_pk_mul_f32 v[110:111], v[110:111], v[202:203]
	v_rcp_iflag_f32_e32 v202, v66
	v_cvt_f32_ubyte1_e32 v66, v200
	v_rcp_iflag_f32_e32 v203, v66
	v_pk_mul_f32 v[204:205], v[204:205], v[220:221]
	v_cvt_f32_ubyte2_e32 v66, v200
	v_pk_mul_f32 v[112:113], v[112:113], v[204:205]
	v_rcp_iflag_f32_e32 v204, v66
	v_cvt_f32_ubyte3_e32 v66, v200
	s_waitcnt vmcnt(24)
; __device__ __forceinline__ float gate_v(unsigned q) { return (float)q; }
;     __device__ __forceinline__ void mid(f32x4 (&acc)[2][2][4][2], const Unit& u, int seg, int wr, int wc, int fr, int fq) const {
;     ...
;         for (int ai = 0; ai < 2; ++ai)
; #pragma unroll
;             for (int m = 0; m < 4; ++m)
; #pragma unroll
;                 for (int bj = 0; bj < 2; ++bj)
; #pragma unroll
;                     for (int e = 0; e < 8; ++e) { const unsigned a = (ga[ai][m][bj][e >> 2] >> (8 * (e & 3))) & 255u, b = (gb[ai][m][bj][e >> 2] >> (8 * (e & 3))) & 255u;
;                         acc[ai][bj][m][e >> 2][e & 3] *= gate_v(a) * __builtin_amdgcn_rcpf(gate_v(b)); }
	v_cvt_f32_ubyte1_e32 v221, v198
	v_cvt_f32_ubyte0_e32 v220, v198
	v_rcp_iflag_f32_e32 v205, v66
	v_pk_mul_f32 v[202:203], v[202:203], v[220:221]
	v_cvt_f32_ubyte0_e32 v66, v201
	v_pk_mul_f32 v[106:107], v[106:107], v[202:203]
	v_rcp_iflag_f32_e32 v202, v66
	v_cvt_f32_ubyte1_e32 v66, v201
	v_rcp_iflag_f32_e32 v203, v66
	v_cvt_f32_ubyte3_e32 v211, v198
	v_cvt_f32_ubyte2_e32 v210, v198
	v_cvt_f32_ubyte2_e32 v66, v201
	v_pk_mul_f32 v[204:205], v[204:205], v[210:211]
	v_rcp_iflag_f32_e32 v200, v66
	v_cvt_f32_ubyte3_e32 v66, v201
	v_cvt_f32_ubyte1_e32 v211, v199
	v_cvt_f32_ubyte0_e32 v210, v199
	v_pk_mul_f32 v[108:109], v[108:109], v[204:205]
	v_rcp_iflag_f32_e32 v201, v66
	v_cvt_f32_ubyte3_e32 v205, v199
	v_cvt_f32_ubyte2_e32 v204, v199
	v_pk_mul_f32 v[198:199], v[202:203], v[210:211]
	s_waitcnt vmcnt(22)
	v_cvt_f32_ubyte0_e32 v66, v196
	v_pk_mul_f32 v[102:103], v[102:103], v[198:199]
	v_rcp_iflag_f32_e32 v198, v66
	v_cvt_f32_ubyte1_e32 v66, v196
	v_rcp_iflag_f32_e32 v199, v66
	v_pk_mul_f32 v[200:201], v[200:201], v[204:205]
	v_cvt_f32_ubyte2_e32 v66, v196
	v_pk_mul_f32 v[104:105], v[104:105], v[200:201]
	v_rcp_iflag_f32_e32 v200, v66
	v_cvt_f32_ubyte3_e32 v66, v196
	v_cvt_f32_ubyte1_e32 v205, v194
	v_cvt_f32_ubyte0_e32 v204, v194
	v_rcp_iflag_f32_e32 v201, v66
	v_pk_mul_f32 v[198:199], v[198:199], v[204:205]
	v_cvt_f32_ubyte0_e32 v66, v197
	v_pk_mul_f32 v[98:99], v[98:99], v[198:199]
	v_rcp_iflag_f32_e32 v198, v66
	v_cvt_f32_ubyte1_e32 v66, v197
	v_rcp_iflag_f32_e32 v199, v66
	v_cvt_f32_ubyte3_e32 v203, v194
	v_cvt_f32_ubyte2_e32 v202, v194
	v_cvt_f32_ubyte2_e32 v66, v197
	v_pk_mul_f32 v[200:201], v[200:201], v[202:203]
	v_rcp_iflag_f32_e32 v196, v66
	v_cvt_f32_ubyte3_e32 v66, v197
	v_cvt_f32_ubyte1_e32 v203, v195
	v_cvt_f32_ubyte0_e32 v202, v195
	v_pk_mul_f32 v[100:101], v[100:101], v[200:201]
	v_rcp_iflag_f32_e32 v197, v66
	v_cvt_f32_ubyte3_e32 v201, v195
	v_cvt_f32_ubyte2_e32 v200, v195
	v_pk_mul_f32 v[194:195], v[198:199], v[202:203]
	s_waitcnt vmcnt(21)
	v_cvt_f32_ubyte0_e32 v66, v192
	v_pk_mul_f32 v[94:95], v[94:95], v[194:195]
	v_rcp_iflag_f32_e32 v194, v66
	v_cvt_f32_ubyte1_e32 v66, v192
	v_rcp_iflag_f32_e32 v195, v66
	v_pk_mul_f32 v[196:197], v[196:197], v[200:201]
	v_cvt_f32_ubyte2_e32 v66, v192
	v_pk_mul_f32 v[96:97], v[96:97], v[196:197]
	v_rcp_iflag_f32_e32 v196, v66
	v_cvt_f32_ubyte3_e32 v66, v192
	s_waitcnt vmcnt(20)
	v_cvt_f32_ubyte1_e32 v201, v190
	v_cvt_f32_ubyte0_e32 v200, v190
	v_rcp_iflag_f32_e32 v197, v66
	v_pk_mul_f32 v[194:195], v[194:195], v[200:201]
	v_cvt_f32_ubyte0_e32 v66, v193
	v_pk_mul_f32 v[90:91], v[90:91], v[194:195]
	v_rcp_iflag_f32_e32 v194, v66
	v_cvt_f32_ubyte1_e32 v66, v193
	v_rcp_iflag_f32_e32 v195, v66
	v_cvt_f32_ubyte3_e32 v199, v190
	v_cvt_f32_ubyte2_e32 v198, v190
	v_cvt_f32_ubyte2_e32 v66, v193
	v_pk_mul_f32 v[196:197], v[196:197], v[198:199]
	v_rcp_iflag_f32_e32 v192, v66
	v_cvt_f32_ubyte3_e32 v66, v193
	v_cvt_f32_ubyte1_e32 v199, v191
	v_cvt_f32_ubyte0_e32 v198, v191
	v_pk_mul_f32 v[92:93], v[92:93], v[196:197]
	v_rcp_iflag_f32_e32 v193, v66
	v_cvt_f32_ubyte3_e32 v197, v191
	v_cvt_f32_ubyte2_e32 v196, v191
	v_pk_mul_f32 v[190:191], v[194:195], v[198:199]
	s_waitcnt vmcnt(18)
	v_cvt_f32_ubyte0_e32 v66, v188
	v_pk_mul_f32 v[86:87], v[86:87], v[190:191]
	v_rcp_iflag_f32_e32 v190, v66
	v_cvt_f32_ubyte1_e32 v66, v188
	v_rcp_iflag_f32_e32 v191, v66
	v_pk_mul_f32 v[192:193], v[192:193], v[196:197]
	v_cvt_f32_ubyte2_e32 v66, v188
	v_pk_mul_f32 v[88:89], v[88:89], v[192:193]
	v_rcp_iflag_f32_e32 v192, v66
	v_cvt_f32_ubyte3_e32 v66, v188
	v_cvt_f32_ubyte1_e32 v197, v186
	v_cvt_f32_ubyte0_e32 v196, v186
	v_rcp_iflag_f32_e32 v193, v66
	v_pk_mul_f32 v[190:191], v[190:191], v[196:197]
	v_cvt_f32_ubyte0_e32 v66, v189
	v_pk_mul_f32 v[82:83], v[82:83], v[190:191]
	v_rcp_iflag_f32_e32 v190, v66
	v_cvt_f32_ubyte1_e32 v66, v189
	v_rcp_iflag_f32_e32 v191, v66
	v_cvt_f32_ubyte3_e32 v195, v186
	v_cvt_f32_ubyte2_e32 v194, v186
	v_cvt_f32_ubyte2_e32 v66, v189
	v_pk_mul_f32 v[192:193], v[192:193], v[194:195]
	v_rcp_iflag_f32_e32 v188, v66
	v_cvt_f32_ubyte3_e32 v66, v189
	v_cvt_f32_ubyte1_e32 v195, v187
	v_cvt_f32_ubyte0_e32 v194, v187
	v_pk_mul_f32 v[84:85], v[84:85], v[192:193]
	v_rcp_iflag_f32_e32 v189, v66
	v_cvt_f32_ubyte3_e32 v193, v187
	v_cvt_f32_ubyte2_e32 v192, v187
	v_pk_mul_f32 v[186:187], v[190:191], v[194:195]
	s_waitcnt vmcnt(17)
	v_cvt_f32_ubyte0_e32 v66, v184
	v_pk_mul_f32 v[78:79], v[78:79], v[186:187]
	v_rcp_iflag_f32_e32 v186, v66
	v_cvt_f32_ubyte1_e32 v66, v184
	v_rcp_iflag_f32_e32 v187, v66
	v_pk_mul_f32 v[188:189], v[188:189], v[192:193]
	v_cvt_f32_ubyte2_e32 v66, v184
	v_pk_mul_f32 v[80:81], v[80:81], v[188:189]
	v_rcp_iflag_f32_e32 v188, v66
	v_cvt_f32_ubyte3_e32 v66, v184
	s_waitcnt vmcnt(16)
	v_cvt_f32_ubyte1_e32 v193, v182
	v_cvt_f32_ubyte0_e32 v192, v182
	v_rcp_iflag_f32_e32 v189, v66
	v_pk_mul_f32 v[186:187], v[186:187], v[192:193]
	v_cvt_f32_ubyte0_e32 v66, v185
	v_pk_mul_f32 v[74:75], v[74:75], v[186:187]
	v_rcp_iflag_f32_e32 v186, v66
	v_cvt_f32_ubyte1_e32 v66, v185
	v_rcp_iflag_f32_e32 v187, v66
	v_cvt_f32_ubyte3_e32 v191, v182
	v_cvt_f32_ubyte2_e32 v190, v182
	v_cvt_f32_ubyte2_e32 v66, v185
	v_pk_mul_f32 v[188:189], v[188:189], v[190:191]
	v_rcp_iflag_f32_e32 v184, v66
	v_cvt_f32_ubyte3_e32 v66, v185
	v_cvt_f32_ubyte1_e32 v191, v183
	v_cvt_f32_ubyte0_e32 v190, v183
	v_pk_mul_f32 v[76:77], v[76:77], v[188:189]
	v_rcp_iflag_f32_e32 v185, v66
	v_cvt_f32_ubyte3_e32 v189, v183
	v_cvt_f32_ubyte2_e32 v188, v183
	v_pk_mul_f32 v[182:183], v[186:187], v[190:191]
	s_waitcnt vmcnt(14)
; __device__ __forceinline__ float gate_v(unsigned q) { return (float)q; }
;     __device__ __forceinline__ void mid(f32x4 (&acc)[2][2][4][2], const Unit& u, int seg, int wr, int wc, int fr, int fq) const {
;     ...
;         for (int ai = 0; ai < 2; ++ai)
; #pragma unroll
;             for (int m = 0; m < 4; ++m)
; #pragma unroll
;                 for (int bj = 0; bj < 2; ++bj)
; #pragma unroll
;                     for (int e = 0; e < 8; ++e) { const unsigned a = (ga[ai][m][bj][e >> 2] >> (8 * (e & 3))) & 255u, b = (gb[ai][m][bj][e >> 2] >> (8 * (e & 3))) & 255u;
;                         acc[ai][bj][m][e >> 2][e & 3] *= gate_v(a) * __builtin_amdgcn_rcpf(gate_v(b)); }
	v_cvt_f32_ubyte0_e32 v66, v180
	v_pk_mul_f32 v[70:71], v[70:71], v[182:183]
	v_rcp_iflag_f32_e32 v182, v66
	v_cvt_f32_ubyte1_e32 v66, v180
	v_rcp_iflag_f32_e32 v183, v66
	v_pk_mul_f32 v[184:185], v[184:185], v[188:189]
	v_cvt_f32_ubyte2_e32 v66, v180
	v_pk_mul_f32 v[72:73], v[72:73], v[184:185]
	v_rcp_iflag_f32_e32 v184, v66
	v_cvt_f32_ubyte3_e32 v66, v180
	v_cvt_f32_ubyte1_e32 v189, v178
	v_cvt_f32_ubyte0_e32 v188, v178
	v_rcp_iflag_f32_e32 v185, v66
	v_pk_mul_f32 v[182:183], v[182:183], v[188:189]
	v_cvt_f32_ubyte0_e32 v66, v181
	v_pk_mul_f32 v[62:63], v[62:63], v[182:183]
	v_rcp_iflag_f32_e32 v182, v66
	v_cvt_f32_ubyte1_e32 v66, v181
	v_rcp_iflag_f32_e32 v183, v66
	v_cvt_f32_ubyte3_e32 v187, v178
	v_cvt_f32_ubyte2_e32 v186, v178
	v_cvt_f32_ubyte2_e32 v66, v181
	v_pk_mul_f32 v[184:185], v[184:185], v[186:187]
	v_rcp_iflag_f32_e32 v180, v66
	v_cvt_f32_ubyte3_e32 v66, v181
	v_cvt_f32_ubyte1_e32 v187, v179
	v_cvt_f32_ubyte0_e32 v186, v179
	v_pk_mul_f32 v[64:65], v[64:65], v[184:185]
	v_rcp_iflag_f32_e32 v181, v66
	v_cvt_f32_ubyte3_e32 v185, v179
	v_cvt_f32_ubyte2_e32 v184, v179
	v_pk_mul_f32 v[178:179], v[182:183], v[186:187]
	s_waitcnt vmcnt(13)
	v_cvt_f32_ubyte0_e32 v66, v176
	v_pk_mul_f32 v[58:59], v[58:59], v[178:179]
	v_rcp_iflag_f32_e32 v178, v66
	v_cvt_f32_ubyte1_e32 v66, v176
	v_rcp_iflag_f32_e32 v179, v66
	v_pk_mul_f32 v[180:181], v[180:181], v[184:185]
	v_cvt_f32_ubyte2_e32 v66, v176
	v_pk_mul_f32 v[60:61], v[60:61], v[180:181]
	v_rcp_iflag_f32_e32 v180, v66
	v_cvt_f32_ubyte3_e32 v66, v176
	s_waitcnt vmcnt(12)
	v_cvt_f32_ubyte1_e32 v185, v174
	v_cvt_f32_ubyte0_e32 v184, v174
	v_rcp_iflag_f32_e32 v181, v66
	v_pk_mul_f32 v[178:179], v[178:179], v[184:185]
	v_cvt_f32_ubyte0_e32 v66, v177
	v_pk_mul_f32 v[54:55], v[54:55], v[178:179]
	v_rcp_iflag_f32_e32 v178, v66
	v_cvt_f32_ubyte1_e32 v66, v177
	v_rcp_iflag_f32_e32 v179, v66
	v_cvt_f32_ubyte3_e32 v183, v174
	v_cvt_f32_ubyte2_e32 v182, v174
	v_cvt_f32_ubyte2_e32 v66, v177
	v_pk_mul_f32 v[180:181], v[180:181], v[182:183]
	v_rcp_iflag_f32_e32 v176, v66
	v_cvt_f32_ubyte3_e32 v66, v177
	v_cvt_f32_ubyte1_e32 v183, v175
	v_cvt_f32_ubyte0_e32 v182, v175
	v_pk_mul_f32 v[56:57], v[56:57], v[180:181]
	v_rcp_iflag_f32_e32 v177, v66
	v_cvt_f32_ubyte3_e32 v181, v175
	v_cvt_f32_ubyte2_e32 v180, v175
	v_pk_mul_f32 v[174:175], v[178:179], v[182:183]
	s_waitcnt vmcnt(10)
	v_cvt_f32_ubyte0_e32 v66, v172
	v_pk_mul_f32 v[50:51], v[50:51], v[174:175]
	v_rcp_iflag_f32_e32 v174, v66
	v_cvt_f32_ubyte1_e32 v66, v172
	v_rcp_iflag_f32_e32 v175, v66
	v_pk_mul_f32 v[176:177], v[176:177], v[180:181]
	v_cvt_f32_ubyte2_e32 v66, v172
	v_pk_mul_f32 v[52:53], v[52:53], v[176:177]
	v_rcp_iflag_f32_e32 v176, v66
	v_cvt_f32_ubyte3_e32 v66, v172
	v_cvt_f32_ubyte1_e32 v181, v170
	v_cvt_f32_ubyte0_e32 v180, v170
	v_rcp_iflag_f32_e32 v177, v66
	v_pk_mul_f32 v[174:175], v[174:175], v[180:181]
	v_cvt_f32_ubyte0_e32 v66, v173
	v_pk_mul_f32 v[46:47], v[46:47], v[174:175]
	v_rcp_iflag_f32_e32 v174, v66
	v_cvt_f32_ubyte1_e32 v66, v173
	v_rcp_iflag_f32_e32 v175, v66
	v_cvt_f32_ubyte3_e32 v179, v170
	v_cvt_f32_ubyte2_e32 v178, v170
	v_cvt_f32_ubyte2_e32 v66, v173
	v_pk_mul_f32 v[176:177], v[176:177], v[178:179]
	v_rcp_iflag_f32_e32 v172, v66
	v_cvt_f32_ubyte3_e32 v66, v173
	v_cvt_f32_ubyte1_e32 v179, v171
	v_cvt_f32_ubyte0_e32 v178, v171
	v_pk_mul_f32 v[48:49], v[48:49], v[176:177]
	v_rcp_iflag_f32_e32 v173, v66
	v_cvt_f32_ubyte3_e32 v177, v171
	v_cvt_f32_ubyte2_e32 v176, v171
	v_pk_mul_f32 v[170:171], v[174:175], v[178:179]
	s_waitcnt vmcnt(9)
	v_cvt_f32_ubyte0_e32 v66, v168
	v_pk_mul_f32 v[42:43], v[42:43], v[170:171]
	v_rcp_iflag_f32_e32 v170, v66
	v_cvt_f32_ubyte1_e32 v66, v168
	v_rcp_iflag_f32_e32 v171, v66
	v_pk_mul_f32 v[172:173], v[172:173], v[176:177]
	v_cvt_f32_ubyte2_e32 v66, v168
	v_pk_mul_f32 v[44:45], v[44:45], v[172:173]
	v_rcp_iflag_f32_e32 v172, v66
	v_cvt_f32_ubyte3_e32 v66, v168
	s_waitcnt vmcnt(8)
	v_cvt_f32_ubyte1_e32 v177, v166
	v_cvt_f32_ubyte0_e32 v176, v166
	v_rcp_iflag_f32_e32 v173, v66
	v_pk_mul_f32 v[170:171], v[170:171], v[176:177]
	v_cvt_f32_ubyte0_e32 v66, v169
	v_pk_mul_f32 v[38:39], v[38:39], v[170:171]
	v_rcp_iflag_f32_e32 v170, v66
	v_cvt_f32_ubyte1_e32 v66, v169
	v_rcp_iflag_f32_e32 v171, v66
	v_cvt_f32_ubyte3_e32 v175, v166
	v_cvt_f32_ubyte2_e32 v174, v166
	v_cvt_f32_ubyte2_e32 v66, v169
	v_pk_mul_f32 v[172:173], v[172:173], v[174:175]
	v_rcp_iflag_f32_e32 v168, v66
	v_cvt_f32_ubyte3_e32 v66, v169
	v_cvt_f32_ubyte1_e32 v175, v167
	v_cvt_f32_ubyte0_e32 v174, v167
	v_pk_mul_f32 v[40:41], v[40:41], v[172:173]
	v_rcp_iflag_f32_e32 v169, v66
	v_cvt_f32_ubyte3_e32 v173, v167
	v_cvt_f32_ubyte2_e32 v172, v167
	v_pk_mul_f32 v[166:167], v[170:171], v[174:175]
	s_waitcnt vmcnt(6)
; __device__ __forceinline__ float gate_v(unsigned q) { return (float)q; }
;     __device__ __forceinline__ void mid(f32x4 (&acc)[2][2][4][2], const Unit& u, int seg, int wr, int wc, int fr, int fq) const {
;     ...
;         for (int ai = 0; ai < 2; ++ai)
; #pragma unroll
;             for (int m = 0; m < 4; ++m)
; #pragma unroll
;                 for (int bj = 0; bj < 2; ++bj)
; #pragma unroll
;                     for (int e = 0; e < 8; ++e) { const unsigned a = (ga[ai][m][bj][e >> 2] >> (8 * (e & 3))) & 255u, b = (gb[ai][m][bj][e >> 2] >> (8 * (e & 3))) & 255u;
;                         acc[ai][bj][m][e >> 2][e & 3] *= gate_v(a) * __builtin_amdgcn_rcpf(gate_v(b)); }
;         asm volatile("" ::: "memory");
	v_cvt_f32_ubyte0_e32 v66, v164
	v_pk_mul_f32 v[34:35], v[34:35], v[166:167]
	v_rcp_iflag_f32_e32 v166, v66
	v_cvt_f32_ubyte1_e32 v66, v164
	v_rcp_iflag_f32_e32 v167, v66
	v_pk_mul_f32 v[168:169], v[168:169], v[172:173]
	v_cvt_f32_ubyte2_e32 v66, v164
	v_pk_mul_f32 v[36:37], v[36:37], v[168:169]
	v_rcp_iflag_f32_e32 v168, v66
	v_cvt_f32_ubyte3_e32 v66, v164
	v_cvt_f32_ubyte1_e32 v173, v162
	v_cvt_f32_ubyte0_e32 v172, v162
	v_rcp_iflag_f32_e32 v169, v66
	v_pk_mul_f32 v[166:167], v[166:167], v[172:173]
	v_cvt_f32_ubyte0_e32 v66, v165
	v_pk_mul_f32 v[30:31], v[30:31], v[166:167]
	v_rcp_iflag_f32_e32 v166, v66
	v_cvt_f32_ubyte1_e32 v66, v165
	v_rcp_iflag_f32_e32 v167, v66
	v_cvt_f32_ubyte3_e32 v171, v162
	v_cvt_f32_ubyte2_e32 v170, v162
	v_cvt_f32_ubyte2_e32 v66, v165
	v_pk_mul_f32 v[168:169], v[168:169], v[170:171]
	v_rcp_iflag_f32_e32 v164, v66
	v_cvt_f32_ubyte3_e32 v66, v165
	v_cvt_f32_ubyte1_e32 v171, v163
	v_cvt_f32_ubyte0_e32 v170, v163
	v_pk_mul_f32 v[32:33], v[32:33], v[168:169]
	v_rcp_iflag_f32_e32 v165, v66
	v_cvt_f32_ubyte3_e32 v169, v163
	v_cvt_f32_ubyte2_e32 v168, v163
	v_pk_mul_f32 v[162:163], v[166:167], v[170:171]
	s_waitcnt vmcnt(5)
	v_cvt_f32_ubyte0_e32 v66, v160
	v_pk_mul_f32 v[26:27], v[26:27], v[162:163]
	v_rcp_iflag_f32_e32 v162, v66
	v_cvt_f32_ubyte1_e32 v66, v160
	v_rcp_iflag_f32_e32 v163, v66
	v_pk_mul_f32 v[164:165], v[164:165], v[168:169]
	v_cvt_f32_ubyte2_e32 v66, v160
	v_pk_mul_f32 v[28:29], v[28:29], v[164:165]
	v_rcp_iflag_f32_e32 v164, v66
	v_cvt_f32_ubyte3_e32 v66, v160
	s_waitcnt vmcnt(4)
	v_cvt_f32_ubyte1_e32 v169, v158
	v_cvt_f32_ubyte0_e32 v168, v158
	v_rcp_iflag_f32_e32 v165, v66
	v_pk_mul_f32 v[162:163], v[162:163], v[168:169]
	v_cvt_f32_ubyte0_e32 v66, v161
	v_pk_mul_f32 v[22:23], v[22:23], v[162:163]
	v_rcp_iflag_f32_e32 v162, v66
	v_cvt_f32_ubyte1_e32 v66, v161
	v_rcp_iflag_f32_e32 v163, v66
	v_cvt_f32_ubyte3_e32 v167, v158
	v_cvt_f32_ubyte2_e32 v166, v158
	v_cvt_f32_ubyte2_e32 v66, v161
	v_pk_mul_f32 v[164:165], v[164:165], v[166:167]
	v_rcp_iflag_f32_e32 v160, v66
	v_cvt_f32_ubyte3_e32 v66, v161
	v_cvt_f32_ubyte1_e32 v167, v159
	v_cvt_f32_ubyte0_e32 v166, v159
	v_pk_mul_f32 v[24:25], v[24:25], v[164:165]
	v_rcp_iflag_f32_e32 v161, v66
	v_cvt_f32_ubyte3_e32 v165, v159
	v_cvt_f32_ubyte2_e32 v164, v159
	v_pk_mul_f32 v[158:159], v[162:163], v[166:167]
	s_waitcnt vmcnt(2)
	v_cvt_f32_ubyte0_e32 v66, v156
	v_pk_mul_f32 v[18:19], v[18:19], v[158:159]
	v_rcp_iflag_f32_e32 v158, v66
	v_cvt_f32_ubyte1_e32 v66, v156
	v_rcp_iflag_f32_e32 v159, v66
	v_pk_mul_f32 v[160:161], v[160:161], v[164:165]
	v_cvt_f32_ubyte2_e32 v66, v156
	v_pk_mul_f32 v[20:21], v[20:21], v[160:161]
	v_rcp_iflag_f32_e32 v160, v66
	v_cvt_f32_ubyte3_e32 v66, v156
	v_cvt_f32_ubyte1_e32 v165, v154
	v_cvt_f32_ubyte0_e32 v164, v154
	v_rcp_iflag_f32_e32 v161, v66
	v_pk_mul_f32 v[158:159], v[158:159], v[164:165]
	v_cvt_f32_ubyte0_e32 v66, v157
	v_pk_mul_f32 v[14:15], v[14:15], v[158:159]
	v_rcp_iflag_f32_e32 v158, v66
	v_cvt_f32_ubyte1_e32 v66, v157
	v_rcp_iflag_f32_e32 v159, v66
	v_cvt_f32_ubyte3_e32 v163, v154
	v_cvt_f32_ubyte2_e32 v162, v154
	v_cvt_f32_ubyte2_e32 v66, v157
	v_pk_mul_f32 v[160:161], v[160:161], v[162:163]
	v_rcp_iflag_f32_e32 v156, v66
	v_cvt_f32_ubyte3_e32 v66, v157
	v_cvt_f32_ubyte1_e32 v163, v155
	v_cvt_f32_ubyte0_e32 v162, v155
	v_pk_mul_f32 v[16:17], v[16:17], v[160:161]
	v_rcp_iflag_f32_e32 v157, v66
	v_cvt_f32_ubyte3_e32 v161, v155
	v_cvt_f32_ubyte2_e32 v160, v155
	v_pk_mul_f32 v[154:155], v[158:159], v[162:163]
	s_waitcnt vmcnt(1)
	v_cvt_f32_ubyte0_e32 v66, v152
	v_pk_mul_f32 v[10:11], v[10:11], v[154:155]
	v_rcp_iflag_f32_e32 v154, v66
	v_cvt_f32_ubyte1_e32 v66, v152
	v_rcp_iflag_f32_e32 v155, v66
	v_pk_mul_f32 v[156:157], v[156:157], v[160:161]
	v_cvt_f32_ubyte2_e32 v66, v152
	v_pk_mul_f32 v[12:13], v[12:13], v[156:157]
	v_rcp_iflag_f32_e32 v156, v66
	v_cvt_f32_ubyte3_e32 v66, v152
	s_waitcnt vmcnt(0)
	v_cvt_f32_ubyte1_e32 v161, v68
	v_cvt_f32_ubyte0_e32 v160, v68
	v_rcp_iflag_f32_e32 v157, v66
	v_pk_mul_f32 v[154:155], v[154:155], v[160:161]
	v_cvt_f32_ubyte0_e32 v66, v153
	v_pk_mul_f32 v[6:7], v[6:7], v[154:155]
	v_rcp_iflag_f32_e32 v154, v66
	v_cvt_f32_ubyte1_e32 v66, v153
	v_rcp_iflag_f32_e32 v155, v66
	v_cvt_f32_ubyte2_e32 v66, v153
	v_rcp_iflag_f32_e32 v152, v66
	v_cvt_f32_ubyte3_e32 v66, v153
	v_rcp_iflag_f32_e32 v153, v66
	v_cvt_f32_ubyte3_e32 v159, v68
	v_cvt_f32_ubyte2_e32 v158, v68
	v_pk_mul_f32 v[156:157], v[156:157], v[158:159]
	v_cvt_f32_ubyte1_e32 v159, v69
	v_pk_mul_f32 v[8:9], v[8:9], v[156:157]
	v_cvt_f32_ubyte3_e32 v157, v69
	v_cvt_f32_ubyte2_e32 v156, v69
	v_cvt_f32_ubyte0_e32 v158, v69
	v_pk_mul_f32 v[68:69], v[154:155], v[158:159]
	v_pk_mul_f32 v[152:153], v[152:153], v[156:157]
	v_pk_mul_f32 v[2:3], v[2:3], v[68:69]
	v_pk_mul_f32 v[4:5], v[4:5], v[152:153]
	s_branch .LBB0_781

; #define PG8_STAGE(bufoff, gbase, voff) do { _Pragma("unroll") for (int _i = 0; _i < 2; ++_i) \
;         __builtin_amdgcn_global_load_lds((const unsigned*)((const char*)(gbase) + (voff)[_i]), (PG8_LAS unsigned*)(lds + (bufoff) + ldsw + _i * 8192), 16, 0, 0); } while (0)
; #define PG8_LDA(dst, b, h) do { _Pragma("unroll") for (int m = 0; m < 4; ++m) _Pragma("unroll") for (int k = 0; k < 2; ++k) dst[m][k] = *(const PG8_LAS bf16x8*)(lds + PG8_SA(b, h) + aoff + m * 2048 + k * 1024); } while (0)
; #define PG8_LDB(dst, b, h) do { _Pragma("unroll") for (int n = 0; n < 2; ++n) _Pragma("unroll") for (int k = 0; k < 2; ++k) dst[n][k] = *(const PG8_LAS bf16x8*)(lds + PG8_SB(b, h) + boff + n * 2048 + k * 1024); } while (0)
; #define PG8_MMA(ai, bj, At, Bt) do { __builtin_amdgcn_s_setprio(1); _Pragma("unroll") for (int m = 0; m < 4; ++m) _Pragma("unroll") for (int n = 0; n < 2; ++n) _Pragma("unroll") for (int k = 0; k < 2; ++k) \
;         acc[ai][bj][m][n] = __builtin_amdgcn_mfma_f32_16x16x32_bf16(Bt[n][k], At[m][k], acc[ai][bj][m][n], 0, 0, 0); __builtin_amdgcn_s_setprio(0); } while (0)
; #define PG8_WAIT_V(n) asm volatile("s_waitcnt vmcnt(" #n ")" ::: "memory")
; #define PG8_WAIT_L(n) asm volatile("s_waitcnt lgkmcnt(" #n ")" ::: "memory")
; #define PG8_BAR __builtin_amdgcn_s_barrier()
; template <class Epi, class Sched, bool ALIGN_EPI = false, bool SP2 = false>
; __device__ __forceinline__ void gemm_phase(PG8_LAS unsigned char* lds, const Gemm g, const Sched& S, const Epi& E) {
;     ...
;             const char* a1 = cA + (size_t)(t + 1) * kstep;
;             const char* a2 = last ? nA : cA + (size_t)(t + 2) * kstep; const char* b2 = last ? nB : cB + (size_t)(t + 2) * kstep;
;             const char* a3 = a2 + kstep; const char* b3 = b2 + kstep;
;             if (last && has_next) S.a_ready(nxt);
;             if constexpr (SP2) {
;             PG8_LDB(B0, 0, 0); PG8_LDB(B1, 0, 1); PG8_SCHED; PG8_LDA(At, 0, 0); PG8_STAGE(PG8_SA(1, 1), a1 + hstep, voffA);
;             PG8_WAIT_V(8); PG8_WAIT_L(0); PG8_BAR; PG8_MMA(0, 0, At, B0); PG8_MMA(0, 1, At, B1); PG8_BAR; PG8_SCHED;
;             PG8_LDA(At, 0, 1); PG8_STAGE(PG8_SB(0, 0), b2, voffB); PG8_STAGE(PG8_SB(0, 1), b2 + hstep, voffB); PG8_STAGE(PG8_SA(0, 0), a2, voffA);
;             PG8_WAIT_V(8); PG8_WAIT_L(0); PG8_BAR; PG8_MMA(1, 0, At, B0); PG8_MMA(1, 1, At, B1); PG8_BAR; PG8_SCHED;
.LBB0_802:
	s_add_u32 s22, s20, 0x100
	s_addc_u32 s23, s21, 0
	s_cmp_eq_u32 s43, 4
	s_cselect_b32 s27, s19, s23
	s_cselect_b32 s26, s18, s22
	s_cselect_b32 s25, s17, s15
	s_cselect_b32 s24, s16, s13
	s_add_i32 s44, 0, 0x10000
	s_add_i32 s45, 0, 0x14000
	v_add_u32_e32 v168, s44, v0
	v_add_u32_e32 v184, s45, v0
	ds_read_b128 v[156:159], v168
	ds_read_b128 v[160:163], v168 offset:1024
	ds_read_b128 v[164:167], v168 offset:2048
	ds_read_b128 v[168:171], v168 offset:3072
	ds_read_b128 v[172:175], v184
	ds_read_b128 v[176:179], v184 offset:1024
	ds_read_b128 v[180:183], v184 offset:2048
	ds_read_b128 v[184:187], v184 offset:3072
	v_lshl_add_u64 v[228:229], s[20:21], 0, v[150:151]
	s_add_i32 m0, s30, 0xc000
	ds_read_b128 v[188:191], v155
	ds_read_b128 v[192:195], v155 offset:1024
	ds_read_b128 v[196:199], v155 offset:2048
	ds_read_b128 v[200:203], v155 offset:3072
	ds_read_b128 v[204:207], v155 offset:4096
	ds_read_b128 v[208:211], v155 offset:5120
	ds_read_b128 v[220:223], v155 offset:6144
	ds_read_b128 v[224:227], v155 offset:7168
	global_load_lds_dwordx4 v[228:229], off
	v_lshl_add_u64 v[228:229], s[20:21], 0, v[152:153]
	s_add_i32 m0, s30, 0xe000
	s_nop 0
	global_load_lds_dwordx4 v[228:229], off
	s_setprio 1
	s_waitcnt vmcnt(8)
	s_waitcnt lgkmcnt(0)
	s_barrier
	v_mfma_f32_16x16x32_bf16 v[128:131], v[156:159], v[188:191], v[128:131]
	v_mfma_f32_16x16x32_bf16 v[124:127], v[164:167], v[188:191], v[124:127]
	v_mfma_f32_16x16x32_bf16 v[120:123], v[156:159], v[196:199], v[120:123]
	v_mfma_f32_16x16x32_bf16 v[116:119], v[164:167], v[196:199], v[116:119]
	v_mfma_f32_16x16x32_bf16 v[112:115], v[156:159], v[204:207], v[112:115]
	v_mfma_f32_16x16x32_bf16 v[108:111], v[164:167], v[204:207], v[108:111]
	v_mfma_f32_16x16x32_bf16 v[100:103], v[156:159], v[220:223], v[100:103]
	v_mfma_f32_16x16x32_bf16 v[92:95], v[164:167], v[220:223], v[92:95]
	v_mfma_f32_16x16x32_bf16 v[128:131], v[160:163], v[192:195], v[128:131]
	v_mfma_f32_16x16x32_bf16 v[124:127], v[168:171], v[192:195], v[124:127]
	v_mfma_f32_16x16x32_bf16 v[120:123], v[160:163], v[200:203], v[120:123]
	v_mfma_f32_16x16x32_bf16 v[116:119], v[168:171], v[200:203], v[116:119]
	v_mfma_f32_16x16x32_bf16 v[112:115], v[160:163], v[208:211], v[112:115]
	v_mfma_f32_16x16x32_bf16 v[108:111], v[168:171], v[208:211], v[108:111]
	v_mfma_f32_16x16x32_bf16 v[100:103], v[160:163], v[224:227], v[100:103]
	v_mfma_f32_16x16x32_bf16 v[92:95], v[168:171], v[224:227], v[92:95]
	v_mfma_f32_16x16x32_bf16 v[104:107], v[172:175], v[188:191], v[104:107]
	v_mfma_f32_16x16x32_bf16 v[96:99], v[180:183], v[188:191], v[96:99]
	v_mfma_f32_16x16x32_bf16 v[88:91], v[172:175], v[196:199], v[88:91]
	v_mfma_f32_16x16x32_bf16 v[84:87], v[180:183], v[196:199], v[84:87]
	v_mfma_f32_16x16x32_bf16 v[80:83], v[172:175], v[204:207], v[80:83]
	v_mfma_f32_16x16x32_bf16 v[76:79], v[180:183], v[204:207], v[76:79]
	v_mfma_f32_16x16x32_bf16 v[72:75], v[172:175], v[220:223], v[72:75]
	v_mfma_f32_16x16x32_bf16 v[68:71], v[180:183], v[220:223], v[68:71]
	v_mfma_f32_16x16x32_bf16 v[104:107], v[176:179], v[192:195], v[104:107]
	v_mfma_f32_16x16x32_bf16 v[96:99], v[184:187], v[192:195], v[96:99]
	v_mfma_f32_16x16x32_bf16 v[88:91], v[176:179], v[200:203], v[88:91]
	v_mfma_f32_16x16x32_bf16 v[84:87], v[184:187], v[200:203], v[84:87]
	v_mfma_f32_16x16x32_bf16 v[80:83], v[176:179], v[208:211], v[80:83]
	v_mfma_f32_16x16x32_bf16 v[76:79], v[184:187], v[208:211], v[76:79]
	v_mfma_f32_16x16x32_bf16 v[72:75], v[176:179], v[224:227], v[72:75]
	v_mfma_f32_16x16x32_bf16 v[68:71], v[184:187], v[224:227], v[68:71]
	s_barrier
	s_add_i32 s20, s44, s1
	v_lshl_add_u64 v[228:229], s[24:25], 0, v[66:67]
	s_mov_b32 m0, s20
	ds_read_b128 v[188:191], v155 offset:16384
	ds_read_b128 v[192:195], v155 offset:17408
	ds_read_b128 v[196:199], v155 offset:18432
	ds_read_b128 v[200:203], v155 offset:19456
	ds_read_b128 v[204:207], v155 offset:20480
	ds_read_b128 v[208:211], v155 offset:21504
	ds_read_b128 v[220:223], v155 offset:22528
	ds_read_b128 v[224:227], v155 offset:23552
	global_load_lds_dwordx4 v[228:229], off
	s_add_i32 m0, s20, 0x2000
	s_add_u32 s20, s24, 0x80000
	v_lshl_add_u64 v[230:231], s[24:25], 0, v[132:133]
	s_addc_u32 s21, s25, 0
	s_add_i32 s44, s45, s1
	global_load_lds_dwordx4 v[230:231], off
	v_lshl_add_u64 v[232:233], s[20:21], 0, v[66:67]
	s_mov_b32 m0, s44
	v_lshl_add_u64 v[234:235], s[26:27], 0, v[132:133]
	global_load_lds_dwordx4 v[232:233], off
	v_lshl_add_u64 v[232:233], s[20:21], 0, v[132:133]
	s_add_i32 m0, s44, 0x2000
	s_nop 0
	global_load_lds_dwordx4 v[232:233], off
	v_lshl_add_u64 v[232:233], s[26:27], 0, v[66:67]
	s_mov_b32 m0, s30
	s_nop 0
	global_load_lds_dwordx4 v[232:233], off
	s_mov_b32 m0, s31
	s_nop 0
	global_load_lds_dwordx4 v[234:235], off
	s_setprio 0
	s_setprio 1
	s_setprio 0
	s_waitcnt lgkmcnt(0)
	s_setprio 1
	s_waitcnt vmcnt(8)
	s_waitcnt lgkmcnt(0)
	s_barrier
; #define PG8_STAGE(bufoff, gbase, voff) do { _Pragma("unroll") for (int _i = 0; _i < 2; ++_i) \
;         __builtin_amdgcn_global_load_lds((const unsigned*)((const char*)(gbase) + (voff)[_i]), (PG8_LAS unsigned*)(lds + (bufoff) + ldsw + _i * 8192), 16, 0, 0); } while (0)
; #define PG8_LDA(dst, b, h) do { _Pragma("unroll") for (int m = 0; m < 4; ++m) _Pragma("unroll") for (int k = 0; k < 2; ++k) dst[m][k] = *(const PG8_LAS bf16x8*)(lds + PG8_SA(b, h) + aoff + m * 2048 + k * 1024); } while (0)
; #define PG8_LDB(dst, b, h) do { _Pragma("unroll") for (int n = 0; n < 2; ++n) _Pragma("unroll") for (int k = 0; k < 2; ++k) dst[n][k] = *(const PG8_LAS bf16x8*)(lds + PG8_SB(b, h) + boff + n * 2048 + k * 1024); } while (0)
; #define PG8_MMA(ai, bj, At, Bt) do { __builtin_amdgcn_s_setprio(1); _Pragma("unroll") for (int m = 0; m < 4; ++m) _Pragma("unroll") for (int n = 0; n < 2; ++n) _Pragma("unroll") for (int k = 0; k < 2; ++k) \
;         acc[ai][bj][m][n] = __builtin_amdgcn_mfma_f32_16x16x32_bf16(Bt[n][k], At[m][k], acc[ai][bj][m][n], 0, 0, 0); __builtin_amdgcn_s_setprio(0); } while (0)
; #define PG8_WAIT_V(n) asm volatile("s_waitcnt vmcnt(" #n ")" ::: "memory")
; #define PG8_WAIT_L(n) asm volatile("s_waitcnt lgkmcnt(" #n ")" ::: "memory")
; #define PG8_BAR __builtin_amdgcn_s_barrier()
; #define PG8_SCHED __builtin_amdgcn_sched_barrier(0)
; template <class Epi, class Sched, bool ALIGN_EPI = false, bool SP2 = false>
; __device__ __forceinline__ void gemm_phase(PG8_LAS unsigned char* lds, const Gemm g, const Sched& S, const Epi& E) {
;     ...
;             PG8_WAIT_V(8); PG8_WAIT_L(0); PG8_BAR; PG8_MMA(1, 0, At, B0); PG8_MMA(1, 1, At, B1); PG8_BAR; PG8_SCHED;
;             PG8_LDB(B0, 1, 0); PG8_LDB(B1, 1, 1); PG8_SCHED; PG8_LDA(At, 1, 0); PG8_STAGE(PG8_SA(0, 1), a2 + hstep, voffA);
;             PG8_WAIT_V(8); PG8_WAIT_L(0); PG8_BAR; PG8_MMA(0, 0, At, B0); PG8_MMA(0, 1, At, B1); PG8_BAR; PG8_SCHED;
	v_mfma_f32_16x16x32_bf16 v[62:65], v[156:159], v[188:191], v[62:65]
	v_mfma_f32_16x16x32_bf16 v[58:61], v[164:167], v[188:191], v[58:61]
	v_mfma_f32_16x16x32_bf16 v[54:57], v[156:159], v[196:199], v[54:57]
	v_mfma_f32_16x16x32_bf16 v[50:53], v[164:167], v[196:199], v[50:53]
	v_mfma_f32_16x16x32_bf16 v[46:49], v[156:159], v[204:207], v[46:49]
	v_mfma_f32_16x16x32_bf16 v[42:45], v[164:167], v[204:207], v[42:45]
	v_mfma_f32_16x16x32_bf16 v[34:37], v[156:159], v[220:223], v[34:37]
	v_mfma_f32_16x16x32_bf16 v[26:29], v[164:167], v[220:223], v[26:29]
	v_mfma_f32_16x16x32_bf16 v[62:65], v[160:163], v[192:195], v[62:65]
	v_mfma_f32_16x16x32_bf16 v[58:61], v[168:171], v[192:195], v[58:61]
	v_mfma_f32_16x16x32_bf16 v[54:57], v[160:163], v[200:203], v[54:57]
	v_mfma_f32_16x16x32_bf16 v[50:53], v[168:171], v[200:203], v[50:53]
	v_mfma_f32_16x16x32_bf16 v[46:49], v[160:163], v[208:211], v[46:49]
	v_mfma_f32_16x16x32_bf16 v[42:45], v[168:171], v[208:211], v[42:45]
	v_mfma_f32_16x16x32_bf16 v[34:37], v[160:163], v[224:227], v[34:37]
	v_mfma_f32_16x16x32_bf16 v[26:29], v[168:171], v[224:227], v[26:29]
	v_mfma_f32_16x16x32_bf16 v[38:41], v[172:175], v[188:191], v[38:41]
	v_mfma_f32_16x16x32_bf16 v[30:33], v[180:183], v[188:191], v[30:33]
	v_mfma_f32_16x16x32_bf16 v[22:25], v[172:175], v[196:199], v[22:25]
	v_mfma_f32_16x16x32_bf16 v[18:21], v[180:183], v[196:199], v[18:21]
	v_mfma_f32_16x16x32_bf16 v[14:17], v[172:175], v[204:207], v[14:17]
	v_mfma_f32_16x16x32_bf16 v[10:13], v[180:183], v[204:207], v[10:13]
	v_mfma_f32_16x16x32_bf16 v[6:9], v[172:175], v[220:223], v[6:9]
	v_mfma_f32_16x16x32_bf16 v[2:5], v[180:183], v[220:223], v[2:5]
	v_mfma_f32_16x16x32_bf16 v[38:41], v[176:179], v[192:195], v[38:41]
	v_mfma_f32_16x16x32_bf16 v[30:33], v[184:187], v[192:195], v[30:33]
	v_mfma_f32_16x16x32_bf16 v[22:25], v[176:179], v[200:203], v[22:25]
	v_mfma_f32_16x16x32_bf16 v[18:21], v[184:187], v[200:203], v[18:21]
	v_mfma_f32_16x16x32_bf16 v[14:17], v[176:179], v[208:211], v[14:17]
	v_mfma_f32_16x16x32_bf16 v[10:13], v[184:187], v[208:211], v[10:13]
	v_mfma_f32_16x16x32_bf16 v[6:9], v[176:179], v[224:227], v[6:9]
	v_mfma_f32_16x16x32_bf16 v[2:5], v[184:187], v[224:227], v[2:5]
	s_barrier
	s_add_i32 s44, 0, 0x18000
	s_add_i32 s45, 0, 0x1c000
	v_add_u32_e32 v168, s44, v0
	v_add_u32_e32 v184, s45, v0
	ds_read_b128 v[156:159], v168
	ds_read_b128 v[160:163], v168 offset:1024
	ds_read_b128 v[164:167], v168 offset:2048
	ds_read_b128 v[168:171], v168 offset:3072
	ds_read_b128 v[172:175], v184
	ds_read_b128 v[176:179], v184 offset:1024
	ds_read_b128 v[180:183], v184 offset:2048
	ds_read_b128 v[184:187], v184 offset:3072
	s_add_u32 s20, s26, 0x80000
	s_addc_u32 s21, s27, 0
	s_mov_b32 m0, s34
	v_lshl_add_u64 v[246:247], s[20:21], 0, v[66:67]
	ds_read_b128 v[188:191], v155 offset:32768
	ds_read_b128 v[192:195], v155 offset:33792
	ds_read_b128 v[196:199], v155 offset:34816
	ds_read_b128 v[200:203], v155 offset:35840
	ds_read_b128 v[204:207], v155 offset:36864
	ds_read_b128 v[208:211], v155 offset:37888
	ds_read_b128 v[220:223], v155 offset:38912
	ds_read_b128 v[224:227], v155 offset:39936
	global_load_lds_dwordx4 v[246:247], off
	v_lshl_add_u64 v[246:247], s[20:21], 0, v[132:133]
	s_mov_b32 m0, s35
	s_nop 0
	global_load_lds_dwordx4 v[246:247], off
	s_setprio 0
	s_setprio 1
	s_setprio 0
	s_waitcnt lgkmcnt(0)
	s_setprio 1
	s_waitcnt vmcnt(8)
	s_waitcnt lgkmcnt(0)
	s_barrier
	v_mfma_f32_16x16x32_bf16 v[128:131], v[156:159], v[188:191], v[128:131]
	v_mfma_f32_16x16x32_bf16 v[124:127], v[164:167], v[188:191], v[124:127]
	v_mfma_f32_16x16x32_bf16 v[120:123], v[156:159], v[196:199], v[120:123]
	v_mfma_f32_16x16x32_bf16 v[116:119], v[164:167], v[196:199], v[116:119]
	v_mfma_f32_16x16x32_bf16 v[112:115], v[156:159], v[204:207], v[112:115]
	v_mfma_f32_16x16x32_bf16 v[108:111], v[164:167], v[204:207], v[108:111]
	v_mfma_f32_16x16x32_bf16 v[100:103], v[156:159], v[220:223], v[100:103]
	v_mfma_f32_16x16x32_bf16 v[92:95], v[164:167], v[220:223], v[92:95]
	v_mfma_f32_16x16x32_bf16 v[128:131], v[160:163], v[192:195], v[128:131]
	v_mfma_f32_16x16x32_bf16 v[124:127], v[168:171], v[192:195], v[124:127]
	v_mfma_f32_16x16x32_bf16 v[120:123], v[160:163], v[200:203], v[120:123]
	v_mfma_f32_16x16x32_bf16 v[116:119], v[168:171], v[200:203], v[116:119]
	v_mfma_f32_16x16x32_bf16 v[112:115], v[160:163], v[208:211], v[112:115]
	v_mfma_f32_16x16x32_bf16 v[108:111], v[168:171], v[208:211], v[108:111]
	v_mfma_f32_16x16x32_bf16 v[100:103], v[160:163], v[224:227], v[100:103]
	v_mfma_f32_16x16x32_bf16 v[92:95], v[168:171], v[224:227], v[92:95]
	v_mfma_f32_16x16x32_bf16 v[104:107], v[172:175], v[188:191], v[104:107]
	v_mfma_f32_16x16x32_bf16 v[96:99], v[180:183], v[188:191], v[96:99]
	v_mfma_f32_16x16x32_bf16 v[88:91], v[172:175], v[196:199], v[88:91]
	v_mfma_f32_16x16x32_bf16 v[84:87], v[180:183], v[196:199], v[84:87]
	v_mfma_f32_16x16x32_bf16 v[80:83], v[172:175], v[204:207], v[80:83]
	v_mfma_f32_16x16x32_bf16 v[76:79], v[180:183], v[204:207], v[76:79]
	v_mfma_f32_16x16x32_bf16 v[72:75], v[172:175], v[220:223], v[72:75]
	v_mfma_f32_16x16x32_bf16 v[68:71], v[180:183], v[220:223], v[68:71]
	v_mfma_f32_16x16x32_bf16 v[104:107], v[176:179], v[192:195], v[104:107]
	v_mfma_f32_16x16x32_bf16 v[96:99], v[184:187], v[192:195], v[96:99]
	v_mfma_f32_16x16x32_bf16 v[88:91], v[176:179], v[200:203], v[88:91]
	v_mfma_f32_16x16x32_bf16 v[84:87], v[184:187], v[200:203], v[84:87]
	v_mfma_f32_16x16x32_bf16 v[80:83], v[176:179], v[208:211], v[80:83]
	v_mfma_f32_16x16x32_bf16 v[76:79], v[184:187], v[208:211], v[76:79]
	v_mfma_f32_16x16x32_bf16 v[72:75], v[176:179], v[224:227], v[72:75]
	v_mfma_f32_16x16x32_bf16 v[68:71], v[184:187], v[224:227], v[68:71]
	s_barrier
; #define PG8_STAGE(bufoff, gbase, voff) do { _Pragma("unroll") for (int _i = 0; _i < 2; ++_i) \
;         __builtin_amdgcn_global_load_lds((const unsigned*)((const char*)(gbase) + (voff)[_i]), (PG8_LAS unsigned*)(lds + (bufoff) + ldsw + _i * 8192), 16, 0, 0); } while (0)
; #define PG8_LDA(dst, b, h) do { _Pragma("unroll") for (int m = 0; m < 4; ++m) _Pragma("unroll") for (int k = 0; k < 2; ++k) dst[m][k] = *(const PG8_LAS bf16x8*)(lds + PG8_SA(b, h) + aoff + m * 2048 + k * 1024); } while (0)
; #define PG8_MMA(ai, bj, At, Bt) do { __builtin_amdgcn_s_setprio(1); _Pragma("unroll") for (int m = 0; m < 4; ++m) _Pragma("unroll") for (int n = 0; n < 2; ++n) _Pragma("unroll") for (int k = 0; k < 2; ++k) \
;         acc[ai][bj][m][n] = __builtin_amdgcn_mfma_f32_16x16x32_bf16(Bt[n][k], At[m][k], acc[ai][bj][m][n], 0, 0, 0); __builtin_amdgcn_s_setprio(0); } while (0)
; #define PG8_WAIT_V(n) asm volatile("s_waitcnt vmcnt(" #n ")" ::: "memory")
; #define PG8_WAIT_L(n) asm volatile("s_waitcnt lgkmcnt(" #n ")" ::: "memory")
; #define PG8_BAR __builtin_amdgcn_s_barrier()
; #define PG8_SCHED __builtin_amdgcn_sched_barrier(0)
; template <class Epi, class Sched, bool ALIGN_EPI = false, bool SP2 = false>
; __device__ __forceinline__ void gemm_phase(PG8_LAS unsigned char* lds, const Gemm g, const Sched& S, const Epi& E) {
;     ...
;             PG8_LDA(At, 1, 1); PG8_STAGE(PG8_SB(1, 0), b3, voffB); PG8_STAGE(PG8_SB(1, 1), b3 + hstep, voffB); PG8_STAGE(PG8_SA(1, 0), a3, voffA);
;             PG8_WAIT_V(8); PG8_WAIT_L(0); PG8_BAR; PG8_MMA(1, 0, At, B0); PG8_MMA(1, 1, At, B1); PG8_BAR; PG8_SCHED;
	s_add_i32 s20, s44, s1
	v_lshl_add_u64 v[228:229], v[228:229], 0, s[88:89]
	s_mov_b32 m0, s20
	ds_read_b128 v[188:191], v155 offset:49152
	ds_read_b128 v[192:195], v155 offset:50176
	ds_read_b128 v[196:199], v155 offset:51200
	ds_read_b128 v[200:203], v155 offset:52224
	ds_read_b128 v[204:207], v155 offset:53248
	ds_read_b128 v[208:211], v155 offset:54272
	ds_read_b128 v[220:223], v155 offset:55296
	ds_read_b128 v[224:227], v155 offset:56320
	global_load_lds_dwordx4 v[228:229], off
	s_add_i32 m0, s20, 0x2000
	s_add_u32 s20, s24, 0x80080
	v_lshl_add_u64 v[228:229], v[230:231], 0, s[88:89]
	s_addc_u32 s21, s25, 0
	s_add_i32 s24, s45, s1
	global_load_lds_dwordx4 v[228:229], off
	v_lshl_add_u64 v[228:229], s[20:21], 0, v[66:67]
	s_mov_b32 m0, s24
	s_nop 0
	global_load_lds_dwordx4 v[228:229], off
	v_lshl_add_u64 v[228:229], s[20:21], 0, v[132:133]
	s_add_i32 m0, s24, 0x2000
	s_nop 0
	global_load_lds_dwordx4 v[228:229], off
	v_lshl_add_u64 v[228:229], v[232:233], 0, s[88:89]
	s_mov_b32 m0, s40
	s_nop 0
	global_load_lds_dwordx4 v[228:229], off
	v_lshl_add_u64 v[228:229], v[234:235], 0, s[88:89]
	s_mov_b32 m0, s41
	s_nop 0
	global_load_lds_dwordx4 v[228:229], off
	s_setprio 0
	s_setprio 1
	s_setprio 0
	s_waitcnt lgkmcnt(0)
	s_setprio 1
	s_waitcnt vmcnt(8)
	s_waitcnt lgkmcnt(0)
	s_barrier
	v_mfma_f32_16x16x32_bf16 v[62:65], v[156:159], v[188:191], v[62:65]
	v_mfma_f32_16x16x32_bf16 v[58:61], v[164:167], v[188:191], v[58:61]
	v_mfma_f32_16x16x32_bf16 v[54:57], v[156:159], v[196:199], v[54:57]
	v_mfma_f32_16x16x32_bf16 v[50:53], v[164:167], v[196:199], v[50:53]
	v_mfma_f32_16x16x32_bf16 v[46:49], v[156:159], v[204:207], v[46:49]
	v_mfma_f32_16x16x32_bf16 v[42:45], v[164:167], v[204:207], v[42:45]
	v_mfma_f32_16x16x32_bf16 v[34:37], v[156:159], v[220:223], v[34:37]
	v_mfma_f32_16x16x32_bf16 v[26:29], v[164:167], v[220:223], v[26:29]
	v_mfma_f32_16x16x32_bf16 v[62:65], v[160:163], v[192:195], v[62:65]
	v_mfma_f32_16x16x32_bf16 v[58:61], v[168:171], v[192:195], v[58:61]
	v_mfma_f32_16x16x32_bf16 v[54:57], v[160:163], v[200:203], v[54:57]
	v_mfma_f32_16x16x32_bf16 v[50:53], v[168:171], v[200:203], v[50:53]
	v_mfma_f32_16x16x32_bf16 v[46:49], v[160:163], v[208:211], v[46:49]
	v_mfma_f32_16x16x32_bf16 v[42:45], v[168:171], v[208:211], v[42:45]
	v_mfma_f32_16x16x32_bf16 v[34:37], v[160:163], v[224:227], v[34:37]
	v_mfma_f32_16x16x32_bf16 v[26:29], v[168:171], v[224:227], v[26:29]
	v_mfma_f32_16x16x32_bf16 v[38:41], v[172:175], v[188:191], v[38:41]
	v_mfma_f32_16x16x32_bf16 v[30:33], v[180:183], v[188:191], v[30:33]
	v_mfma_f32_16x16x32_bf16 v[22:25], v[172:175], v[196:199], v[22:25]
	v_mfma_f32_16x16x32_bf16 v[18:21], v[180:183], v[196:199], v[18:21]
	v_mfma_f32_16x16x32_bf16 v[14:17], v[172:175], v[204:207], v[14:17]
	v_mfma_f32_16x16x32_bf16 v[10:13], v[180:183], v[204:207], v[10:13]
	v_mfma_f32_16x16x32_bf16 v[6:9], v[172:175], v[220:223], v[6:9]
	v_mfma_f32_16x16x32_bf16 v[2:5], v[180:183], v[220:223], v[2:5]
	v_mfma_f32_16x16x32_bf16 v[38:41], v[176:179], v[192:195], v[38:41]
	v_mfma_f32_16x16x32_bf16 v[30:33], v[184:187], v[192:195], v[30:33]
	v_mfma_f32_16x16x32_bf16 v[22:25], v[176:179], v[200:203], v[22:25]
	v_mfma_f32_16x16x32_bf16 v[18:21], v[184:187], v[200:203], v[18:21]
	v_mfma_f32_16x16x32_bf16 v[14:17], v[176:179], v[208:211], v[14:17]
	v_mfma_f32_16x16x32_bf16 v[10:13], v[184:187], v[208:211], v[10:13]
	v_mfma_f32_16x16x32_bf16 v[6:9], v[176:179], v[224:227], v[6:9]
	v_mfma_f32_16x16x32_bf16 v[2:5], v[184:187], v[224:227], v[2:5]
	s_barrier
	s_setprio 0
	s_setprio 1
	s_setprio 0
	s_waitcnt lgkmcnt(0)
	s_add_i32 s43, s43, 2
	s_add_u32 s13, s13, 0x100
	s_addc_u32 s15, s15, 0
	s_cmp_gt_u32 s43, 5
	s_mov_b64 s[20:21], s[22:23]
	s_cbranch_scc0 .LBB0_802
	s_and_b64 vcc, exec, s[8:9]
	s_cbranch_vccz .LBB0_805
	s_barrier

; #define PG8_STAGE(bufoff, gbase, voff) do { _Pragma("unroll") for (int _i = 0; _i < 2; ++_i) \
;         __builtin_amdgcn_global_load_lds((const unsigned*)((const char*)(gbase) + (voff)[_i]), (PG8_LAS unsigned*)(lds + (bufoff) + ldsw + _i * 8192), 16, 0, 0); } while (0)
; #define PG8_LDA(dst, b, h) do { _Pragma("unroll") for (int m = 0; m < 4; ++m) _Pragma("unroll") for (int k = 0; k < 2; ++k) dst[m][k] = *(const PG8_LAS bf16x8*)(lds + PG8_SA(b, h) + aoff + m * 2048 + k * 1024); } while (0)
; #define PG8_LDB(dst, b, h) do { _Pragma("unroll") for (int n = 0; n < 2; ++n) _Pragma("unroll") for (int k = 0; k < 2; ++k) dst[n][k] = *(const PG8_LAS bf16x8*)(lds + PG8_SB(b, h) + boff + n * 2048 + k * 1024); } while (0)
; #define PG8_MMA(ai, bj, At, Bt) do { __builtin_amdgcn_s_setprio(1); _Pragma("unroll") for (int m = 0; m < 4; ++m) _Pragma("unroll") for (int n = 0; n < 2; ++n) _Pragma("unroll") for (int k = 0; k < 2; ++k) \
;         acc[ai][bj][m][n] = __builtin_amdgcn_mfma_f32_16x16x32_bf16(Bt[n][k], At[m][k], acc[ai][bj][m][n], 0, 0, 0); __builtin_amdgcn_s_setprio(0); } while (0)
; #define PG8_WAIT_V(n) asm volatile("s_waitcnt vmcnt(" #n ")" ::: "memory")
; #define PG8_WAIT_L(n) asm volatile("s_waitcnt lgkmcnt(" #n ")" ::: "memory")
; #define PG8_BAR __builtin_amdgcn_s_barrier()
; template <class Epi, class Sched, bool ALIGN_EPI = false, bool SP2 = false>
; __device__ __forceinline__ void gemm_phase(PG8_LAS unsigned char* lds, const Gemm g, const Sched& S, const Epi& E) {
;     ...
;             const char* a1 = cA + (size_t)(t + 1) * kstep;
;             const char* a2 = last ? nA : cA + (size_t)(t + 2) * kstep; const char* b2 = last ? nB : cB + (size_t)(t + 2) * kstep;
;             const char* a3 = a2 + kstep; const char* b3 = b2 + kstep;
;             if (last && has_next) S.a_ready(nxt);
;             if constexpr (SP2) {
;             PG8_LDB(B0, 0, 0); PG8_LDB(B1, 0, 1); PG8_SCHED; PG8_LDA(At, 0, 0); PG8_STAGE(PG8_SA(1, 1), a1 + hstep, voffA);
;             PG8_WAIT_V(8); PG8_WAIT_L(0); PG8_BAR; PG8_MMA(0, 0, At, B0); PG8_MMA(0, 1, At, B1); PG8_BAR; PG8_SCHED;
;             PG8_LDA(At, 0, 1); PG8_STAGE(PG8_SB(0, 0), b2, voffB); PG8_STAGE(PG8_SB(0, 1), b2 + hstep, voffB); PG8_STAGE(PG8_SA(0, 0), a2, voffA);
;             PG8_WAIT_V(8); PG8_WAIT_L(0); PG8_BAR; PG8_MMA(1, 0, At, B0); PG8_MMA(1, 1, At, B1); PG8_BAR; PG8_SCHED;
.LBB0_881:
	s_add_u32 s30, s28, 0x100
	s_addc_u32 s31, s29, 0
	s_add_i32 s59, 0, 0x10000
	s_cmp_eq_u32 s57, 28
	s_cselect_b32 s37, s2, s31
	s_cselect_b32 s36, s3, s30
	s_cselect_b32 s35, s21, s56
	s_cselect_b32 s34, s23, s55
	s_add_i32 s60, 0, 0x14000
	v_add_u32_e32 v144, s59, v156
	v_add_u32_e32 v154, s60, v156
	ds_read_b128 v[132:135], v144
	ds_read_b128 v[136:139], v144 offset:1024
	ds_read_b128 v[140:143], v144 offset:2048
	ds_read_b128 v[144:147], v144 offset:3072
	ds_read_b128 v[160:163], v154
	ds_read_b128 v[164:167], v154 offset:1024
	ds_read_b128 v[168:171], v154 offset:2048
	ds_read_b128 v[172:175], v154 offset:3072
	v_lshl_add_u64 v[154:155], s[28:29], 0, v[150:151]
	s_add_i32 m0, s39, 0xc000
	ds_read_b128 v[176:179], v158
	ds_read_b128 v[180:183], v158 offset:1024
	ds_read_b128 v[184:187], v158 offset:2048
	ds_read_b128 v[188:191], v158 offset:3072
	ds_read_b128 v[192:195], v158 offset:4096
	ds_read_b128 v[196:199], v158 offset:5120
	ds_read_b128 v[200:203], v158 offset:6144
	ds_read_b128 v[204:207], v158 offset:7168
	global_load_lds_dwordx4 v[154:155], off
	v_lshl_add_u64 v[154:155], s[28:29], 0, v[152:153]
	s_add_i32 m0, s39, 0xe000
	s_nop 0
	global_load_lds_dwordx4 v[154:155], off
	s_setprio 1
	s_waitcnt vmcnt(8)
	s_waitcnt lgkmcnt(0)
	s_barrier
	v_mfma_f32_16x16x32_bf16 v[128:131], v[132:135], v[176:179], v[128:131]
	v_mfma_f32_16x16x32_bf16 v[124:127], v[140:143], v[176:179], v[124:127]
	v_mfma_f32_16x16x32_bf16 v[120:123], v[132:135], v[184:187], v[120:123]
	v_mfma_f32_16x16x32_bf16 v[112:115], v[140:143], v[184:187], v[112:115]
	v_mfma_f32_16x16x32_bf16 v[104:107], v[132:135], v[192:195], v[104:107]
	v_mfma_f32_16x16x32_bf16 v[96:99], v[140:143], v[192:195], v[96:99]
	v_mfma_f32_16x16x32_bf16 v[88:91], v[132:135], v[200:203], v[88:91]
	v_mfma_f32_16x16x32_bf16 v[76:79], v[140:143], v[200:203], v[76:79]
	v_mfma_f32_16x16x32_bf16 v[128:131], v[136:139], v[180:183], v[128:131]
	v_mfma_f32_16x16x32_bf16 v[124:127], v[144:147], v[180:183], v[124:127]
	v_mfma_f32_16x16x32_bf16 v[120:123], v[136:139], v[188:191], v[120:123]
	v_mfma_f32_16x16x32_bf16 v[112:115], v[144:147], v[188:191], v[112:115]
	v_mfma_f32_16x16x32_bf16 v[104:107], v[136:139], v[196:199], v[104:107]
	v_mfma_f32_16x16x32_bf16 v[96:99], v[144:147], v[196:199], v[96:99]
	v_mfma_f32_16x16x32_bf16 v[88:91], v[136:139], v[204:207], v[88:91]
	v_mfma_f32_16x16x32_bf16 v[76:79], v[144:147], v[204:207], v[76:79]
	v_mfma_f32_16x16x32_bf16 v[116:119], v[160:163], v[176:179], v[116:119]
	v_mfma_f32_16x16x32_bf16 v[108:111], v[168:171], v[176:179], v[108:111]
	v_mfma_f32_16x16x32_bf16 v[100:103], v[160:163], v[184:187], v[100:103]
	v_mfma_f32_16x16x32_bf16 v[92:95], v[168:171], v[184:187], v[92:95]
	v_mfma_f32_16x16x32_bf16 v[84:87], v[160:163], v[192:195], v[84:87]
	v_mfma_f32_16x16x32_bf16 v[80:83], v[168:171], v[192:195], v[80:83]
	v_mfma_f32_16x16x32_bf16 v[72:75], v[160:163], v[200:203], v[72:75]
	v_mfma_f32_16x16x32_bf16 v[68:71], v[168:171], v[200:203], v[68:71]
	v_mfma_f32_16x16x32_bf16 v[116:119], v[164:167], v[180:183], v[116:119]
	v_mfma_f32_16x16x32_bf16 v[108:111], v[172:175], v[180:183], v[108:111]
	v_mfma_f32_16x16x32_bf16 v[100:103], v[164:167], v[188:191], v[100:103]
	v_mfma_f32_16x16x32_bf16 v[92:95], v[172:175], v[188:191], v[92:95]
	v_mfma_f32_16x16x32_bf16 v[84:87], v[164:167], v[196:199], v[84:87]
	v_mfma_f32_16x16x32_bf16 v[80:83], v[172:175], v[196:199], v[80:83]
	v_mfma_f32_16x16x32_bf16 v[72:75], v[164:167], v[204:207], v[72:75]
	v_mfma_f32_16x16x32_bf16 v[68:71], v[172:175], v[204:207], v[68:71]
	s_barrier
	s_add_i32 s28, s59, s38
	v_lshl_add_u64 v[154:155], s[34:35], 0, v[66:67]
	s_mov_b32 m0, s28
	ds_read_b128 v[176:179], v158 offset:16384
	ds_read_b128 v[180:183], v158 offset:17408
	ds_read_b128 v[184:187], v158 offset:18432
	ds_read_b128 v[188:191], v158 offset:19456
	ds_read_b128 v[192:195], v158 offset:20480
	ds_read_b128 v[196:199], v158 offset:21504
	ds_read_b128 v[200:203], v158 offset:22528
	ds_read_b128 v[204:207], v158 offset:23552
	global_load_lds_dwordx4 v[154:155], off
	s_add_i32 m0, s28, 0x2000
	s_add_u32 s28, s34, 0x80000
	v_lshl_add_u64 v[208:209], s[34:35], 0, v[148:149]
	s_addc_u32 s29, s35, 0
	s_add_i32 s59, s60, s38
	global_load_lds_dwordx4 v[208:209], off
	v_lshl_add_u64 v[210:211], s[28:29], 0, v[66:67]
	s_mov_b32 m0, s59
	v_lshl_add_u64 v[220:221], s[36:37], 0, v[148:149]
	global_load_lds_dwordx4 v[210:211], off
	v_lshl_add_u64 v[210:211], s[28:29], 0, v[148:149]
	s_add_i32 m0, s59, 0x2000
	s_nop 0
	global_load_lds_dwordx4 v[210:211], off
	v_lshl_add_u64 v[210:211], s[36:37], 0, v[66:67]
	s_mov_b32 m0, s39
	s_nop 0
	global_load_lds_dwordx4 v[210:211], off
	s_mov_b32 m0, s40
	s_nop 0
	global_load_lds_dwordx4 v[220:221], off
	s_setprio 0
	s_setprio 1
	s_setprio 0
	s_waitcnt lgkmcnt(0)
	s_setprio 1
	s_waitcnt vmcnt(8)
	s_waitcnt lgkmcnt(0)
	s_barrier
; #define PG8_STAGE(bufoff, gbase, voff) do { _Pragma("unroll") for (int _i = 0; _i < 2; ++_i) \
;         __builtin_amdgcn_global_load_lds((const unsigned*)((const char*)(gbase) + (voff)[_i]), (PG8_LAS unsigned*)(lds + (bufoff) + ldsw + _i * 8192), 16, 0, 0); } while (0)
; #define PG8_LDA(dst, b, h) do { _Pragma("unroll") for (int m = 0; m < 4; ++m) _Pragma("unroll") for (int k = 0; k < 2; ++k) dst[m][k] = *(const PG8_LAS bf16x8*)(lds + PG8_SA(b, h) + aoff + m * 2048 + k * 1024); } while (0)
; #define PG8_LDB(dst, b, h) do { _Pragma("unroll") for (int n = 0; n < 2; ++n) _Pragma("unroll") for (int k = 0; k < 2; ++k) dst[n][k] = *(const PG8_LAS bf16x8*)(lds + PG8_SB(b, h) + boff + n * 2048 + k * 1024); } while (0)
; #define PG8_MMA(ai, bj, At, Bt) do { __builtin_amdgcn_s_setprio(1); _Pragma("unroll") for (int m = 0; m < 4; ++m) _Pragma("unroll") for (int n = 0; n < 2; ++n) _Pragma("unroll") for (int k = 0; k < 2; ++k) \
;         acc[ai][bj][m][n] = __builtin_amdgcn_mfma_f32_16x16x32_bf16(Bt[n][k], At[m][k], acc[ai][bj][m][n], 0, 0, 0); __builtin_amdgcn_s_setprio(0); } while (0)
; #define PG8_WAIT_V(n) asm volatile("s_waitcnt vmcnt(" #n ")" ::: "memory")
; #define PG8_WAIT_L(n) asm volatile("s_waitcnt lgkmcnt(" #n ")" ::: "memory")
; #define PG8_BAR __builtin_amdgcn_s_barrier()
; #define PG8_SCHED __builtin_amdgcn_sched_barrier(0)
; template <class Epi, class Sched, bool ALIGN_EPI = false, bool SP2 = false>
; __device__ __forceinline__ void gemm_phase(PG8_LAS unsigned char* lds, const Gemm g, const Sched& S, const Epi& E) {
;     ...
;             PG8_WAIT_V(8); PG8_WAIT_L(0); PG8_BAR; PG8_MMA(1, 0, At, B0); PG8_MMA(1, 1, At, B1); PG8_BAR; PG8_SCHED;
;             PG8_LDB(B0, 1, 0); PG8_LDB(B1, 1, 1); PG8_SCHED; PG8_LDA(At, 1, 0); PG8_STAGE(PG8_SA(0, 1), a2 + hstep, voffA);
;             PG8_WAIT_V(8); PG8_WAIT_L(0); PG8_BAR; PG8_MMA(0, 0, At, B0); PG8_MMA(0, 1, At, B1); PG8_BAR; PG8_SCHED;
	v_mfma_f32_16x16x32_bf16 v[62:65], v[132:135], v[176:179], v[62:65]
	v_mfma_f32_16x16x32_bf16 v[58:61], v[140:143], v[176:179], v[58:61]
	v_mfma_f32_16x16x32_bf16 v[54:57], v[132:135], v[184:187], v[54:57]
	v_mfma_f32_16x16x32_bf16 v[46:49], v[140:143], v[184:187], v[46:49]
	v_mfma_f32_16x16x32_bf16 v[38:41], v[132:135], v[192:195], v[38:41]
	v_mfma_f32_16x16x32_bf16 v[30:33], v[140:143], v[192:195], v[30:33]
	v_mfma_f32_16x16x32_bf16 v[22:25], v[132:135], v[200:203], v[22:25]
	v_mfma_f32_16x16x32_bf16 v[10:13], v[140:143], v[200:203], v[10:13]
	v_mfma_f32_16x16x32_bf16 v[62:65], v[136:139], v[180:183], v[62:65]
	v_mfma_f32_16x16x32_bf16 v[58:61], v[144:147], v[180:183], v[58:61]
	v_mfma_f32_16x16x32_bf16 v[54:57], v[136:139], v[188:191], v[54:57]
	v_mfma_f32_16x16x32_bf16 v[46:49], v[144:147], v[188:191], v[46:49]
	v_mfma_f32_16x16x32_bf16 v[38:41], v[136:139], v[196:199], v[38:41]
	v_mfma_f32_16x16x32_bf16 v[30:33], v[144:147], v[196:199], v[30:33]
	v_mfma_f32_16x16x32_bf16 v[22:25], v[136:139], v[204:207], v[22:25]
	v_mfma_f32_16x16x32_bf16 v[10:13], v[144:147], v[204:207], v[10:13]
	v_mfma_f32_16x16x32_bf16 v[50:53], v[160:163], v[176:179], v[50:53]
	v_mfma_f32_16x16x32_bf16 v[42:45], v[168:171], v[176:179], v[42:45]
	v_mfma_f32_16x16x32_bf16 v[34:37], v[160:163], v[184:187], v[34:37]
	v_mfma_f32_16x16x32_bf16 v[26:29], v[168:171], v[184:187], v[26:29]
	v_mfma_f32_16x16x32_bf16 v[18:21], v[160:163], v[192:195], v[18:21]
	v_mfma_f32_16x16x32_bf16 v[14:17], v[168:171], v[192:195], v[14:17]
	v_mfma_f32_16x16x32_bf16 v[6:9], v[160:163], v[200:203], v[6:9]
	v_mfma_f32_16x16x32_bf16 v[2:5], v[168:171], v[200:203], v[2:5]
	v_mfma_f32_16x16x32_bf16 v[50:53], v[164:167], v[180:183], v[50:53]
	v_mfma_f32_16x16x32_bf16 v[42:45], v[172:175], v[180:183], v[42:45]
	v_mfma_f32_16x16x32_bf16 v[34:37], v[164:167], v[188:191], v[34:37]
	v_mfma_f32_16x16x32_bf16 v[26:29], v[172:175], v[188:191], v[26:29]
	v_mfma_f32_16x16x32_bf16 v[18:21], v[164:167], v[196:199], v[18:21]
	v_mfma_f32_16x16x32_bf16 v[14:17], v[172:175], v[196:199], v[14:17]
	v_mfma_f32_16x16x32_bf16 v[6:9], v[164:167], v[204:207], v[6:9]
	v_mfma_f32_16x16x32_bf16 v[2:5], v[172:175], v[204:207], v[2:5]
	s_barrier
	s_add_i32 s59, 0, 0x18000
	s_add_i32 s60, 0, 0x1c000
	v_add_u32_e32 v144, s59, v156
	v_add_u32_e32 v159, s60, v156
	ds_read_b128 v[132:135], v144
	ds_read_b128 v[136:139], v144 offset:1024
	ds_read_b128 v[140:143], v144 offset:2048
	ds_read_b128 v[144:147], v144 offset:3072
	ds_read_b128 v[160:163], v159
	ds_read_b128 v[164:167], v159 offset:1024
	ds_read_b128 v[168:171], v159 offset:2048
	ds_read_b128 v[172:175], v159 offset:3072
	s_add_u32 s28, s36, 0x80000
	s_addc_u32 s29, s37, 0
	s_mov_b32 m0, s41
	v_lshl_add_u64 v[222:223], s[28:29], 0, v[66:67]
	ds_read_b128 v[176:179], v158 offset:32768
	ds_read_b128 v[180:183], v158 offset:33792
	ds_read_b128 v[184:187], v158 offset:34816
	ds_read_b128 v[188:191], v158 offset:35840
	ds_read_b128 v[192:195], v158 offset:36864
	ds_read_b128 v[196:199], v158 offset:37888
	ds_read_b128 v[200:203], v158 offset:38912
	ds_read_b128 v[204:207], v158 offset:39936
	global_load_lds_dwordx4 v[222:223], off
	v_lshl_add_u64 v[222:223], s[28:29], 0, v[148:149]
	s_mov_b32 m0, s44
	s_nop 0
	global_load_lds_dwordx4 v[222:223], off
	s_setprio 0
	s_setprio 1
	s_setprio 0
	s_waitcnt lgkmcnt(0)
	s_setprio 1
	s_waitcnt vmcnt(8)
	s_waitcnt lgkmcnt(0)
	s_barrier
	v_mfma_f32_16x16x32_bf16 v[128:131], v[132:135], v[176:179], v[128:131]
	v_mfma_f32_16x16x32_bf16 v[124:127], v[140:143], v[176:179], v[124:127]
	v_mfma_f32_16x16x32_bf16 v[120:123], v[132:135], v[184:187], v[120:123]
	v_mfma_f32_16x16x32_bf16 v[112:115], v[140:143], v[184:187], v[112:115]
	v_mfma_f32_16x16x32_bf16 v[104:107], v[132:135], v[192:195], v[104:107]
	v_mfma_f32_16x16x32_bf16 v[96:99], v[140:143], v[192:195], v[96:99]
	v_mfma_f32_16x16x32_bf16 v[88:91], v[132:135], v[200:203], v[88:91]
	v_mfma_f32_16x16x32_bf16 v[76:79], v[140:143], v[200:203], v[76:79]
	v_mfma_f32_16x16x32_bf16 v[128:131], v[136:139], v[180:183], v[128:131]
	v_mfma_f32_16x16x32_bf16 v[124:127], v[144:147], v[180:183], v[124:127]
	v_mfma_f32_16x16x32_bf16 v[120:123], v[136:139], v[188:191], v[120:123]
	v_mfma_f32_16x16x32_bf16 v[112:115], v[144:147], v[188:191], v[112:115]
	v_mfma_f32_16x16x32_bf16 v[104:107], v[136:139], v[196:199], v[104:107]
	v_mfma_f32_16x16x32_bf16 v[96:99], v[144:147], v[196:199], v[96:99]
	v_mfma_f32_16x16x32_bf16 v[88:91], v[136:139], v[204:207], v[88:91]
	v_mfma_f32_16x16x32_bf16 v[76:79], v[144:147], v[204:207], v[76:79]
	v_mfma_f32_16x16x32_bf16 v[116:119], v[160:163], v[176:179], v[116:119]
	v_mfma_f32_16x16x32_bf16 v[108:111], v[168:171], v[176:179], v[108:111]
	v_mfma_f32_16x16x32_bf16 v[100:103], v[160:163], v[184:187], v[100:103]
	v_mfma_f32_16x16x32_bf16 v[92:95], v[168:171], v[184:187], v[92:95]
	v_mfma_f32_16x16x32_bf16 v[84:87], v[160:163], v[192:195], v[84:87]
	v_mfma_f32_16x16x32_bf16 v[80:83], v[168:171], v[192:195], v[80:83]
	v_mfma_f32_16x16x32_bf16 v[72:75], v[160:163], v[200:203], v[72:75]
	v_mfma_f32_16x16x32_bf16 v[68:71], v[168:171], v[200:203], v[68:71]
	v_mfma_f32_16x16x32_bf16 v[116:119], v[164:167], v[180:183], v[116:119]
	v_mfma_f32_16x16x32_bf16 v[108:111], v[172:175], v[180:183], v[108:111]
	v_mfma_f32_16x16x32_bf16 v[100:103], v[164:167], v[188:191], v[100:103]
	v_mfma_f32_16x16x32_bf16 v[92:95], v[172:175], v[188:191], v[92:95]
	v_mfma_f32_16x16x32_bf16 v[84:87], v[164:167], v[196:199], v[84:87]
	v_mfma_f32_16x16x32_bf16 v[80:83], v[172:175], v[196:199], v[80:83]
	v_mfma_f32_16x16x32_bf16 v[72:75], v[164:167], v[204:207], v[72:75]
	v_mfma_f32_16x16x32_bf16 v[68:71], v[172:175], v[204:207], v[68:71]
	s_barrier
; #define PG8_STAGE(bufoff, gbase, voff) do { _Pragma("unroll") for (int _i = 0; _i < 2; ++_i) \
;         __builtin_amdgcn_global_load_lds((const unsigned*)((const char*)(gbase) + (voff)[_i]), (PG8_LAS unsigned*)(lds + (bufoff) + ldsw + _i * 8192), 16, 0, 0); } while (0)
; #define PG8_LDA(dst, b, h) do { _Pragma("unroll") for (int m = 0; m < 4; ++m) _Pragma("unroll") for (int k = 0; k < 2; ++k) dst[m][k] = *(const PG8_LAS bf16x8*)(lds + PG8_SA(b, h) + aoff + m * 2048 + k * 1024); } while (0)
; #define PG8_MMA(ai, bj, At, Bt) do { __builtin_amdgcn_s_setprio(1); _Pragma("unroll") for (int m = 0; m < 4; ++m) _Pragma("unroll") for (int n = 0; n < 2; ++n) _Pragma("unroll") for (int k = 0; k < 2; ++k) \
;         acc[ai][bj][m][n] = __builtin_amdgcn_mfma_f32_16x16x32_bf16(Bt[n][k], At[m][k], acc[ai][bj][m][n], 0, 0, 0); __builtin_amdgcn_s_setprio(0); } while (0)
; #define PG8_WAIT_V(n) asm volatile("s_waitcnt vmcnt(" #n ")" ::: "memory")
; #define PG8_WAIT_L(n) asm volatile("s_waitcnt lgkmcnt(" #n ")" ::: "memory")
; #define PG8_BAR __builtin_amdgcn_s_barrier()
; #define PG8_SCHED __builtin_amdgcn_sched_barrier(0)
; template <class Epi, class Sched, bool ALIGN_EPI = false, bool SP2 = false>
; __device__ __forceinline__ void gemm_phase(PG8_LAS unsigned char* lds, const Gemm g, const Sched& S, const Epi& E) {
;     ...
;             PG8_LDA(At, 1, 1); PG8_STAGE(PG8_SB(1, 0), b3, voffB); PG8_STAGE(PG8_SB(1, 1), b3 + hstep, voffB); PG8_STAGE(PG8_SA(1, 0), a3, voffA);
;             PG8_WAIT_V(8); PG8_WAIT_L(0); PG8_BAR; PG8_MMA(1, 0, At, B0); PG8_MMA(1, 1, At, B1); PG8_BAR; PG8_SCHED;
	s_add_i32 s28, s59, s38
	v_lshl_add_u64 v[154:155], v[154:155], 0, s[88:89]
	s_mov_b32 m0, s28
	ds_read_b128 v[176:179], v158 offset:49152
	ds_read_b128 v[180:183], v158 offset:50176
	ds_read_b128 v[184:187], v158 offset:51200
	ds_read_b128 v[188:191], v158 offset:52224
	ds_read_b128 v[192:195], v158 offset:53248
	ds_read_b128 v[196:199], v158 offset:54272
	ds_read_b128 v[200:203], v158 offset:55296
	ds_read_b128 v[204:207], v158 offset:56320
	global_load_lds_dwordx4 v[154:155], off
	s_add_i32 m0, s28, 0x2000
	s_add_u32 s28, s34, 0x80080
	v_lshl_add_u64 v[154:155], v[208:209], 0, s[88:89]
	s_addc_u32 s29, s35, 0
	s_add_i32 s34, s60, s38
	global_load_lds_dwordx4 v[154:155], off
	v_lshl_add_u64 v[154:155], s[28:29], 0, v[66:67]
	s_mov_b32 m0, s34
	s_nop 0
	global_load_lds_dwordx4 v[154:155], off
	v_lshl_add_u64 v[154:155], s[28:29], 0, v[148:149]
	s_add_i32 m0, s34, 0x2000
	s_nop 0
	global_load_lds_dwordx4 v[154:155], off
	v_lshl_add_u64 v[154:155], v[210:211], 0, s[88:89]
	s_mov_b32 m0, s47
	s_nop 0
	global_load_lds_dwordx4 v[154:155], off
	v_lshl_add_u64 v[154:155], v[220:221], 0, s[88:89]
	s_mov_b32 m0, s50
	s_nop 0
	global_load_lds_dwordx4 v[154:155], off
	s_setprio 0
	s_setprio 1
	s_setprio 0
	s_waitcnt lgkmcnt(0)
	s_setprio 1
	s_waitcnt vmcnt(8)
	s_waitcnt lgkmcnt(0)
	s_barrier
	v_mfma_f32_16x16x32_bf16 v[62:65], v[132:135], v[176:179], v[62:65]
	v_mfma_f32_16x16x32_bf16 v[58:61], v[140:143], v[176:179], v[58:61]
	v_mfma_f32_16x16x32_bf16 v[54:57], v[132:135], v[184:187], v[54:57]
	v_mfma_f32_16x16x32_bf16 v[46:49], v[140:143], v[184:187], v[46:49]
	v_mfma_f32_16x16x32_bf16 v[38:41], v[132:135], v[192:195], v[38:41]
	v_mfma_f32_16x16x32_bf16 v[30:33], v[140:143], v[192:195], v[30:33]
	v_mfma_f32_16x16x32_bf16 v[22:25], v[132:135], v[200:203], v[22:25]
	v_mfma_f32_16x16x32_bf16 v[10:13], v[140:143], v[200:203], v[10:13]
	v_mfma_f32_16x16x32_bf16 v[62:65], v[136:139], v[180:183], v[62:65]
	v_mfma_f32_16x16x32_bf16 v[58:61], v[144:147], v[180:183], v[58:61]
	v_mfma_f32_16x16x32_bf16 v[54:57], v[136:139], v[188:191], v[54:57]
	v_mfma_f32_16x16x32_bf16 v[46:49], v[144:147], v[188:191], v[46:49]
	v_mfma_f32_16x16x32_bf16 v[38:41], v[136:139], v[196:199], v[38:41]
	v_mfma_f32_16x16x32_bf16 v[30:33], v[144:147], v[196:199], v[30:33]
	v_mfma_f32_16x16x32_bf16 v[22:25], v[136:139], v[204:207], v[22:25]
	v_mfma_f32_16x16x32_bf16 v[10:13], v[144:147], v[204:207], v[10:13]
	v_mfma_f32_16x16x32_bf16 v[50:53], v[160:163], v[176:179], v[50:53]
	v_mfma_f32_16x16x32_bf16 v[42:45], v[168:171], v[176:179], v[42:45]
	v_mfma_f32_16x16x32_bf16 v[34:37], v[160:163], v[184:187], v[34:37]
	v_mfma_f32_16x16x32_bf16 v[26:29], v[168:171], v[184:187], v[26:29]
	v_mfma_f32_16x16x32_bf16 v[18:21], v[160:163], v[192:195], v[18:21]
	v_mfma_f32_16x16x32_bf16 v[14:17], v[168:171], v[192:195], v[14:17]
	v_mfma_f32_16x16x32_bf16 v[6:9], v[160:163], v[200:203], v[6:9]
	v_mfma_f32_16x16x32_bf16 v[2:5], v[168:171], v[200:203], v[2:5]
	v_mfma_f32_16x16x32_bf16 v[50:53], v[164:167], v[180:183], v[50:53]
	v_mfma_f32_16x16x32_bf16 v[42:45], v[172:175], v[180:183], v[42:45]
	v_mfma_f32_16x16x32_bf16 v[34:37], v[164:167], v[188:191], v[34:37]
	v_mfma_f32_16x16x32_bf16 v[26:29], v[172:175], v[188:191], v[26:29]
	v_mfma_f32_16x16x32_bf16 v[18:21], v[164:167], v[196:199], v[18:21]
	v_mfma_f32_16x16x32_bf16 v[14:17], v[172:175], v[196:199], v[14:17]
	v_mfma_f32_16x16x32_bf16 v[6:9], v[164:167], v[204:207], v[6:9]
	v_mfma_f32_16x16x32_bf16 v[2:5], v[172:175], v[204:207], v[2:5]
	s_barrier
	s_setprio 0
	s_setprio 1
	s_setprio 0
	s_waitcnt lgkmcnt(0)
	s_add_i32 s57, s57, 2
	s_add_u32 s55, s55, 0x100
	s_addc_u32 s56, s56, 0
	s_cmp_gt_u32 s57, 29
	s_mov_b64 s[28:29], s[30:31]
	s_cbranch_scc0 .LBB0_881
	s_and_b64 vcc, exec, s[12:13]
	s_cbranch_vccz .LBB0_884
	s_barrier

; #define PG8_STAGE(bufoff, gbase, voff) do { _Pragma("unroll") for (int _i = 0; _i < 2; ++_i) \
;         __builtin_amdgcn_global_load_lds((const unsigned*)((const char*)(gbase) + (voff)[_i]), (PG8_LAS unsigned*)(lds + (bufoff) + ldsw + _i * 8192), 16, 0, 0); } while (0)
; #define PG8_LDA(dst, b, h) do { _Pragma("unroll") for (int m = 0; m < 4; ++m) _Pragma("unroll") for (int k = 0; k < 2; ++k) dst[m][k] = *(const PG8_LAS bf16x8*)(lds + PG8_SA(b, h) + aoff + m * 2048 + k * 1024); } while (0)
; #define PG8_LDB(dst, b, h) do { _Pragma("unroll") for (int n = 0; n < 2; ++n) _Pragma("unroll") for (int k = 0; k < 2; ++k) dst[n][k] = *(const PG8_LAS bf16x8*)(lds + PG8_SB(b, h) + boff + n * 2048 + k * 1024); } while (0)
; #define PG8_MMA(ai, bj, At, Bt) do { __builtin_amdgcn_s_setprio(1); _Pragma("unroll") for (int m = 0; m < 4; ++m) _Pragma("unroll") for (int n = 0; n < 2; ++n) _Pragma("unroll") for (int k = 0; k < 2; ++k) \
;         acc[ai][bj][m][n] = __builtin_amdgcn_mfma_f32_16x16x32_bf16(Bt[n][k], At[m][k], acc[ai][bj][m][n], 0, 0, 0); __builtin_amdgcn_s_setprio(0); } while (0)
; #define PG8_WAIT_V(n) asm volatile("s_waitcnt vmcnt(" #n ")" ::: "memory")
; #define PG8_WAIT_L(n) asm volatile("s_waitcnt lgkmcnt(" #n ")" ::: "memory")
; #define PG8_BAR __builtin_amdgcn_s_barrier()
; template <class Epi, class Sched, bool ALIGN_EPI = false, bool SP2 = false>
; __device__ __forceinline__ void gemm_phase(PG8_LAS unsigned char* lds, const Gemm g, const Sched& S, const Epi& E) {
;     ...
;             const char* a1 = cA + (size_t)(t + 1) * kstep;
;             const char* a2 = last ? nA : cA + (size_t)(t + 2) * kstep; const char* b2 = last ? nB : cB + (size_t)(t + 2) * kstep;
;             const char* a3 = a2 + kstep; const char* b3 = b2 + kstep;
;             if (last && has_next) S.a_ready(nxt);
;             if constexpr (SP2) {
;             PG8_LDB(B0, 0, 0); PG8_LDB(B1, 0, 1); PG8_SCHED; PG8_LDA(At, 0, 0); PG8_STAGE(PG8_SA(1, 1), a1 + hstep, voffA);
;             PG8_WAIT_V(8); PG8_WAIT_L(0); PG8_BAR; PG8_MMA(0, 0, At, B0); PG8_MMA(0, 1, At, B1); PG8_BAR; PG8_SCHED;
;             PG8_LDA(At, 0, 1); PG8_STAGE(PG8_SB(0, 0), b2, voffB); PG8_STAGE(PG8_SB(0, 1), b2 + hstep, voffB); PG8_STAGE(PG8_SA(0, 0), a2, voffA);
;             PG8_WAIT_V(8); PG8_WAIT_L(0); PG8_BAR; PG8_MMA(1, 0, At, B0); PG8_MMA(1, 1, At, B1); PG8_BAR; PG8_SCHED;
.LBB0_905:
	s_add_u32 s38, s22, s36
	s_addc_u32 s39, s23, s37
	s_add_u32 s38, s38, 0x100
	s_addc_u32 s39, s39, 0
	s_add_u32 s63, s3, s36
	s_addc_u32 s64, s59, s37
	s_add_i32 s65, 0, 0x10000
	s_cmpk_eq_i32 s36, 0xf00
	s_cselect_b32 s41, s29, s39
	s_cselect_b32 s40, s60, s38
	s_cselect_b32 s39, s27, s64
	s_cselect_b32 s38, s61, s63
	s_add_i32 s63, 0, 0x14000
	v_add_u32_e32 v156, s65, v142
	v_add_u32_e32 v172, s63, v142
	ds_read_b128 v[144:147], v156
	ds_read_b128 v[148:151], v156 offset:1024
	ds_read_b128 v[152:155], v156 offset:2048
	ds_read_b128 v[156:159], v156 offset:3072
	ds_read_b128 v[160:163], v172
	ds_read_b128 v[164:167], v172 offset:1024
	ds_read_b128 v[168:171], v172 offset:2048
	ds_read_b128 v[172:175], v172 offset:3072
	v_lshl_add_u64 v[188:189], v[134:135], 0, s[36:37]
	s_add_i32 m0, s51, 0xc000
	ds_read_b128 v[176:179], v143
	ds_read_b128 v[180:183], v143 offset:1024
	ds_read_b128 v[184:187], v143 offset:2048
	ds_read_b128 v[192:195], v143 offset:3072
	ds_read_b128 v[196:199], v143 offset:4096
	ds_read_b128 v[200:203], v143 offset:5120
	ds_read_b128 v[204:207], v143 offset:6144
	ds_read_b128 v[208:211], v143 offset:7168
	global_load_lds_dwordx4 v[188:189], off
	v_lshl_add_u64 v[188:189], v[140:141], 0, s[36:37]
	s_add_i32 m0, s51, 0xe000
	s_nop 0
	global_load_lds_dwordx4 v[188:189], off
	s_setprio 1
	s_waitcnt vmcnt(8)
	s_waitcnt lgkmcnt(0)
	s_barrier
	v_mfma_f32_16x16x32_bf16 v[68:71], v[144:147], v[176:179], v[68:71]
	v_mfma_f32_16x16x32_bf16 v[72:75], v[152:155], v[176:179], v[72:75]
	v_mfma_f32_16x16x32_bf16 v[92:95], v[144:147], v[184:187], v[92:95]
	v_mfma_f32_16x16x32_bf16 v[80:83], v[152:155], v[184:187], v[80:83]
	v_mfma_f32_16x16x32_bf16 v[128:131], v[144:147], v[196:199], v[128:131]
	v_mfma_f32_16x16x32_bf16 v[112:115], v[152:155], v[196:199], v[112:115]
	v_mfma_f32_16x16x32_bf16 v[136:139], v[144:147], v[204:207], v[136:139]
	v_mfma_f32_16x16x32_bf16 v[120:123], v[152:155], v[204:207], v[120:123]
	v_mfma_f32_16x16x32_bf16 v[68:71], v[148:151], v[180:183], v[68:71]
	v_mfma_f32_16x16x32_bf16 v[72:75], v[156:159], v[180:183], v[72:75]
	v_mfma_f32_16x16x32_bf16 v[92:95], v[148:151], v[192:195], v[92:95]
	v_mfma_f32_16x16x32_bf16 v[80:83], v[156:159], v[192:195], v[80:83]
	v_mfma_f32_16x16x32_bf16 v[128:131], v[148:151], v[200:203], v[128:131]
	v_mfma_f32_16x16x32_bf16 v[112:115], v[156:159], v[200:203], v[112:115]
	v_mfma_f32_16x16x32_bf16 v[136:139], v[148:151], v[208:211], v[136:139]
	v_mfma_f32_16x16x32_bf16 v[120:123], v[156:159], v[208:211], v[120:123]
	v_mfma_f32_16x16x32_bf16 v[58:61], v[160:163], v[176:179], v[58:61]
	v_mfma_f32_16x16x32_bf16 v[46:49], v[168:171], v[176:179], v[46:49]
	v_mfma_f32_16x16x32_bf16 v[76:79], v[160:163], v[184:187], v[76:79]
	v_mfma_f32_16x16x32_bf16 v[50:53], v[168:171], v[184:187], v[50:53]
	v_mfma_f32_16x16x32_bf16 v[124:127], v[160:163], v[196:199], v[124:127]
	v_mfma_f32_16x16x32_bf16 v[116:119], v[168:171], v[196:199], v[116:119]
	v_mfma_f32_16x16x32_bf16 v[108:111], v[160:163], v[204:207], v[108:111]
	v_mfma_f32_16x16x32_bf16 v[104:107], v[168:171], v[204:207], v[104:107]
	v_mfma_f32_16x16x32_bf16 v[58:61], v[164:167], v[180:183], v[58:61]
	v_mfma_f32_16x16x32_bf16 v[46:49], v[172:175], v[180:183], v[46:49]
	v_mfma_f32_16x16x32_bf16 v[76:79], v[164:167], v[192:195], v[76:79]
	v_mfma_f32_16x16x32_bf16 v[50:53], v[172:175], v[192:195], v[50:53]
	v_mfma_f32_16x16x32_bf16 v[124:127], v[164:167], v[200:203], v[124:127]
	v_mfma_f32_16x16x32_bf16 v[116:119], v[172:175], v[200:203], v[116:119]
	v_mfma_f32_16x16x32_bf16 v[108:111], v[164:167], v[208:211], v[108:111]
	v_mfma_f32_16x16x32_bf16 v[104:107], v[172:175], v[208:211], v[104:107]
	s_barrier
	s_add_i32 s64, s65, s50
	v_lshl_add_u64 v[188:189], s[38:39], 0, v[66:67]
	s_mov_b32 m0, s64
	ds_read_b128 v[176:179], v143 offset:16384
	ds_read_b128 v[180:183], v143 offset:17408
	ds_read_b128 v[184:187], v143 offset:18432
	ds_read_b128 v[192:195], v143 offset:19456
	ds_read_b128 v[196:199], v143 offset:20480
	ds_read_b128 v[200:203], v143 offset:21504
	ds_read_b128 v[204:207], v143 offset:22528
	ds_read_b128 v[208:211], v143 offset:23552
	global_load_lds_dwordx4 v[188:189], off
	s_add_i32 m0, s64, 0x2000
	s_add_u32 s64, s38, 0x80000
	v_lshl_add_u64 v[220:221], s[38:39], 0, v[84:85]
	s_addc_u32 s65, s39, 0
	s_add_i32 s63, s63, s50
	global_load_lds_dwordx4 v[220:221], off
	v_lshl_add_u64 v[222:223], s[64:65], 0, v[66:67]
	s_mov_b32 m0, s63
	v_lshl_add_u64 v[224:225], s[40:41], 0, v[84:85]
	global_load_lds_dwordx4 v[222:223], off
	v_lshl_add_u64 v[222:223], s[64:65], 0, v[84:85]
	s_add_i32 m0, s63, 0x2000
	s_nop 0
	global_load_lds_dwordx4 v[222:223], off
	v_lshl_add_u64 v[222:223], s[40:41], 0, v[66:67]
	s_mov_b32 m0, s51
	s_nop 0
	global_load_lds_dwordx4 v[222:223], off
	s_mov_b32 m0, s52
	s_nop 0
	global_load_lds_dwordx4 v[224:225], off
	s_setprio 0
	s_setprio 1
	s_setprio 0
	s_waitcnt lgkmcnt(0)
	s_setprio 1
	s_waitcnt vmcnt(8)
	s_waitcnt lgkmcnt(0)
	s_barrier
; #define PG8_STAGE(bufoff, gbase, voff) do { _Pragma("unroll") for (int _i = 0; _i < 2; ++_i) \
;         __builtin_amdgcn_global_load_lds((const unsigned*)((const char*)(gbase) + (voff)[_i]), (PG8_LAS unsigned*)(lds + (bufoff) + ldsw + _i * 8192), 16, 0, 0); } while (0)
; #define PG8_LDA(dst, b, h) do { _Pragma("unroll") for (int m = 0; m < 4; ++m) _Pragma("unroll") for (int k = 0; k < 2; ++k) dst[m][k] = *(const PG8_LAS bf16x8*)(lds + PG8_SA(b, h) + aoff + m * 2048 + k * 1024); } while (0)
; #define PG8_LDB(dst, b, h) do { _Pragma("unroll") for (int n = 0; n < 2; ++n) _Pragma("unroll") for (int k = 0; k < 2; ++k) dst[n][k] = *(const PG8_LAS bf16x8*)(lds + PG8_SB(b, h) + boff + n * 2048 + k * 1024); } while (0)
; #define PG8_MMA(ai, bj, At, Bt) do { __builtin_amdgcn_s_setprio(1); _Pragma("unroll") for (int m = 0; m < 4; ++m) _Pragma("unroll") for (int n = 0; n < 2; ++n) _Pragma("unroll") for (int k = 0; k < 2; ++k) \
;         acc[ai][bj][m][n] = __builtin_amdgcn_mfma_f32_16x16x32_bf16(Bt[n][k], At[m][k], acc[ai][bj][m][n], 0, 0, 0); __builtin_amdgcn_s_setprio(0); } while (0)
; #define PG8_WAIT_V(n) asm volatile("s_waitcnt vmcnt(" #n ")" ::: "memory")
; #define PG8_WAIT_L(n) asm volatile("s_waitcnt lgkmcnt(" #n ")" ::: "memory")
; #define PG8_BAR __builtin_amdgcn_s_barrier()
; #define PG8_SCHED __builtin_amdgcn_sched_barrier(0)
; template <class Epi, class Sched, bool ALIGN_EPI = false, bool SP2 = false>
; __device__ __forceinline__ void gemm_phase(PG8_LAS unsigned char* lds, const Gemm g, const Sched& S, const Epi& E) {
;     ...
;             PG8_WAIT_V(8); PG8_WAIT_L(0); PG8_BAR; PG8_MMA(1, 0, At, B0); PG8_MMA(1, 1, At, B1); PG8_BAR; PG8_SCHED;
;             PG8_LDB(B0, 1, 0); PG8_LDB(B1, 1, 1); PG8_SCHED; PG8_LDA(At, 1, 0); PG8_STAGE(PG8_SA(0, 1), a2 + hstep, voffA);
;             PG8_WAIT_V(8); PG8_WAIT_L(0); PG8_BAR; PG8_MMA(0, 0, At, B0); PG8_MMA(0, 1, At, B1); PG8_BAR; PG8_SCHED;
	v_mfma_f32_16x16x32_bf16 v[100:103], v[144:147], v[176:179], v[100:103]
	v_mfma_f32_16x16x32_bf16 v[96:99], v[152:155], v[176:179], v[96:99]
	v_mfma_f32_16x16x32_bf16 v[88:91], v[144:147], v[184:187], v[88:91]
	v_mfma_f32_16x16x32_bf16 v[42:45], v[152:155], v[184:187], v[42:45]
	v_mfma_f32_16x16x32_bf16 v[38:41], v[144:147], v[196:199], v[38:41]
	v_mfma_f32_16x16x32_bf16 v[26:29], v[152:155], v[196:199], v[26:29]
	v_mfma_f32_16x16x32_bf16 v[22:25], v[144:147], v[204:207], v[22:25]
	v_mfma_f32_16x16x32_bf16 v[14:17], v[152:155], v[204:207], v[14:17]
	v_mfma_f32_16x16x32_bf16 v[100:103], v[148:151], v[180:183], v[100:103]
	v_mfma_f32_16x16x32_bf16 v[96:99], v[156:159], v[180:183], v[96:99]
	v_mfma_f32_16x16x32_bf16 v[88:91], v[148:151], v[192:195], v[88:91]
	v_mfma_f32_16x16x32_bf16 v[42:45], v[156:159], v[192:195], v[42:45]
	v_mfma_f32_16x16x32_bf16 v[38:41], v[148:151], v[200:203], v[38:41]
	v_mfma_f32_16x16x32_bf16 v[26:29], v[156:159], v[200:203], v[26:29]
	v_mfma_f32_16x16x32_bf16 v[22:25], v[148:151], v[208:211], v[22:25]
	v_mfma_f32_16x16x32_bf16 v[14:17], v[156:159], v[208:211], v[14:17]
	v_mfma_f32_16x16x32_bf16 v[62:65], v[160:163], v[176:179], v[62:65]
	v_mfma_f32_16x16x32_bf16 v[54:57], v[168:171], v[176:179], v[54:57]
	v_mfma_f32_16x16x32_bf16 v[34:37], v[160:163], v[184:187], v[34:37]
	v_mfma_f32_16x16x32_bf16 v[30:33], v[168:171], v[184:187], v[30:33]
	v_mfma_f32_16x16x32_bf16 v[18:21], v[160:163], v[196:199], v[18:21]
	v_mfma_f32_16x16x32_bf16 v[10:13], v[168:171], v[196:199], v[10:13]
	v_mfma_f32_16x16x32_bf16 v[6:9], v[160:163], v[204:207], v[6:9]
	v_mfma_f32_16x16x32_bf16 v[2:5], v[168:171], v[204:207], v[2:5]
	v_mfma_f32_16x16x32_bf16 v[62:65], v[164:167], v[180:183], v[62:65]
	v_mfma_f32_16x16x32_bf16 v[54:57], v[172:175], v[180:183], v[54:57]
	v_mfma_f32_16x16x32_bf16 v[34:37], v[164:167], v[192:195], v[34:37]
	v_mfma_f32_16x16x32_bf16 v[30:33], v[172:175], v[192:195], v[30:33]
	v_mfma_f32_16x16x32_bf16 v[18:21], v[164:167], v[200:203], v[18:21]
	v_mfma_f32_16x16x32_bf16 v[10:13], v[172:175], v[200:203], v[10:13]
	v_mfma_f32_16x16x32_bf16 v[6:9], v[164:167], v[208:211], v[6:9]
	v_mfma_f32_16x16x32_bf16 v[2:5], v[172:175], v[208:211], v[2:5]
	s_barrier
	s_add_i32 s63, 0, 0x18000
	s_add_i32 s64, 0, 0x1c000
	v_add_u32_e32 v156, s63, v142
	v_add_u32_e32 v172, s64, v142
	ds_read_b128 v[144:147], v156
	ds_read_b128 v[148:151], v156 offset:1024
	ds_read_b128 v[152:155], v156 offset:2048
	ds_read_b128 v[156:159], v156 offset:3072
	ds_read_b128 v[160:163], v172
	ds_read_b128 v[164:167], v172 offset:1024
	ds_read_b128 v[168:171], v172 offset:2048
	ds_read_b128 v[172:175], v172 offset:3072
	s_add_u32 s40, s40, 0x80000
	s_addc_u32 s41, s41, 0
	s_mov_b32 m0, s1
	v_lshl_add_u64 v[226:227], s[40:41], 0, v[66:67]
	ds_read_b128 v[176:179], v143 offset:32768
	ds_read_b128 v[180:183], v143 offset:33792
	ds_read_b128 v[184:187], v143 offset:34816
	ds_read_b128 v[192:195], v143 offset:35840
	ds_read_b128 v[196:199], v143 offset:36864
	ds_read_b128 v[200:203], v143 offset:37888
	ds_read_b128 v[204:207], v143 offset:38912
	ds_read_b128 v[208:211], v143 offset:39936
	global_load_lds_dwordx4 v[226:227], off
	v_lshl_add_u64 v[226:227], s[40:41], 0, v[84:85]
	s_mov_b32 m0, s54
	s_nop 0
	global_load_lds_dwordx4 v[226:227], off
	s_setprio 0
	s_setprio 1
	s_setprio 0
	s_waitcnt lgkmcnt(0)
	s_setprio 1
	s_waitcnt vmcnt(8)
	s_waitcnt lgkmcnt(0)
	s_barrier
	v_mfma_f32_16x16x32_bf16 v[68:71], v[144:147], v[176:179], v[68:71]
	v_mfma_f32_16x16x32_bf16 v[72:75], v[152:155], v[176:179], v[72:75]
	v_mfma_f32_16x16x32_bf16 v[92:95], v[144:147], v[184:187], v[92:95]
	v_mfma_f32_16x16x32_bf16 v[80:83], v[152:155], v[184:187], v[80:83]
	v_mfma_f32_16x16x32_bf16 v[128:131], v[144:147], v[196:199], v[128:131]
	v_mfma_f32_16x16x32_bf16 v[112:115], v[152:155], v[196:199], v[112:115]
	v_mfma_f32_16x16x32_bf16 v[136:139], v[144:147], v[204:207], v[136:139]
	v_mfma_f32_16x16x32_bf16 v[120:123], v[152:155], v[204:207], v[120:123]
	v_mfma_f32_16x16x32_bf16 v[68:71], v[148:151], v[180:183], v[68:71]
	v_mfma_f32_16x16x32_bf16 v[72:75], v[156:159], v[180:183], v[72:75]
	v_mfma_f32_16x16x32_bf16 v[92:95], v[148:151], v[192:195], v[92:95]
	v_mfma_f32_16x16x32_bf16 v[80:83], v[156:159], v[192:195], v[80:83]
	v_mfma_f32_16x16x32_bf16 v[128:131], v[148:151], v[200:203], v[128:131]
	v_mfma_f32_16x16x32_bf16 v[112:115], v[156:159], v[200:203], v[112:115]
	v_mfma_f32_16x16x32_bf16 v[136:139], v[148:151], v[208:211], v[136:139]
	v_mfma_f32_16x16x32_bf16 v[120:123], v[156:159], v[208:211], v[120:123]
	v_mfma_f32_16x16x32_bf16 v[58:61], v[160:163], v[176:179], v[58:61]
	v_mfma_f32_16x16x32_bf16 v[46:49], v[168:171], v[176:179], v[46:49]
	v_mfma_f32_16x16x32_bf16 v[76:79], v[160:163], v[184:187], v[76:79]
	v_mfma_f32_16x16x32_bf16 v[50:53], v[168:171], v[184:187], v[50:53]
	v_mfma_f32_16x16x32_bf16 v[124:127], v[160:163], v[196:199], v[124:127]
	v_mfma_f32_16x16x32_bf16 v[116:119], v[168:171], v[196:199], v[116:119]
	v_mfma_f32_16x16x32_bf16 v[108:111], v[160:163], v[204:207], v[108:111]
	v_mfma_f32_16x16x32_bf16 v[104:107], v[168:171], v[204:207], v[104:107]
	v_mfma_f32_16x16x32_bf16 v[58:61], v[164:167], v[180:183], v[58:61]
	v_mfma_f32_16x16x32_bf16 v[46:49], v[172:175], v[180:183], v[46:49]
	v_mfma_f32_16x16x32_bf16 v[76:79], v[164:167], v[192:195], v[76:79]
	v_mfma_f32_16x16x32_bf16 v[50:53], v[172:175], v[192:195], v[50:53]
	v_mfma_f32_16x16x32_bf16 v[124:127], v[164:167], v[200:203], v[124:127]
	v_mfma_f32_16x16x32_bf16 v[116:119], v[172:175], v[200:203], v[116:119]
	v_mfma_f32_16x16x32_bf16 v[108:111], v[164:167], v[208:211], v[108:111]
	v_mfma_f32_16x16x32_bf16 v[104:107], v[172:175], v[208:211], v[104:107]
	s_barrier
; #define PG8_STAGE(bufoff, gbase, voff) do { _Pragma("unroll") for (int _i = 0; _i < 2; ++_i) \
;         __builtin_amdgcn_global_load_lds((const unsigned*)((const char*)(gbase) + (voff)[_i]), (PG8_LAS unsigned*)(lds + (bufoff) + ldsw + _i * 8192), 16, 0, 0); } while (0)
; #define PG8_LDA(dst, b, h) do { _Pragma("unroll") for (int m = 0; m < 4; ++m) _Pragma("unroll") for (int k = 0; k < 2; ++k) dst[m][k] = *(const PG8_LAS bf16x8*)(lds + PG8_SA(b, h) + aoff + m * 2048 + k * 1024); } while (0)
; #define PG8_MMA(ai, bj, At, Bt) do { __builtin_amdgcn_s_setprio(1); _Pragma("unroll") for (int m = 0; m < 4; ++m) _Pragma("unroll") for (int n = 0; n < 2; ++n) _Pragma("unroll") for (int k = 0; k < 2; ++k) \
;         acc[ai][bj][m][n] = __builtin_amdgcn_mfma_f32_16x16x32_bf16(Bt[n][k], At[m][k], acc[ai][bj][m][n], 0, 0, 0); __builtin_amdgcn_s_setprio(0); } while (0)
; #define PG8_WAIT_V(n) asm volatile("s_waitcnt vmcnt(" #n ")" ::: "memory")
; #define PG8_WAIT_L(n) asm volatile("s_waitcnt lgkmcnt(" #n ")" ::: "memory")
; #define PG8_BAR __builtin_amdgcn_s_barrier()
; #define PG8_SCHED __builtin_amdgcn_sched_barrier(0)
; template <class Epi, class Sched, bool ALIGN_EPI = false, bool SP2 = false>
; __device__ __forceinline__ void gemm_phase(PG8_LAS unsigned char* lds, const Gemm g, const Sched& S, const Epi& E) {
;     ...
;             PG8_LDA(At, 1, 1); PG8_STAGE(PG8_SB(1, 0), b3, voffB); PG8_STAGE(PG8_SB(1, 1), b3 + hstep, voffB); PG8_STAGE(PG8_SA(1, 0), a3, voffA);
;             PG8_WAIT_V(8); PG8_WAIT_L(0); PG8_BAR; PG8_MMA(1, 0, At, B0); PG8_MMA(1, 1, At, B1); PG8_BAR; PG8_SCHED;
;     ...
; #pragma unroll
;         for (int a = 0; a < 2; ++a)
; #pragma unroll
;             for (int b = 0; b < 2; ++b)
; #pragma unroll
;                 for (int m = 0; m < 4; ++m)
; #pragma unroll
;                     for (int n = 0; n < 2; ++n) acc[a][b][m][n] = (f32x4){0.f, 0.f, 0.f, 0.f};
;         cur = nxt; cA = nA; cB = nB; ++ui;
	s_add_i32 s40, s63, s50
	v_lshl_add_u64 v[188:189], v[188:189], 0, s[88:89]
	s_mov_b32 m0, s40
	ds_read_b128 v[176:179], v143 offset:49152
	ds_read_b128 v[180:183], v143 offset:50176
	ds_read_b128 v[184:187], v143 offset:51200
	ds_read_b128 v[192:195], v143 offset:52224
	ds_read_b128 v[196:199], v143 offset:53248
	ds_read_b128 v[200:203], v143 offset:54272
	ds_read_b128 v[204:207], v143 offset:55296
	ds_read_b128 v[208:211], v143 offset:56320
	global_load_lds_dwordx4 v[188:189], off
	s_add_i32 m0, s40, 0x2000
	s_add_u32 s38, s38, 0x80080
	v_lshl_add_u64 v[188:189], v[220:221], 0, s[88:89]
	s_addc_u32 s39, s39, 0
	s_add_i32 s40, s64, s50
	global_load_lds_dwordx4 v[188:189], off
	v_lshl_add_u64 v[188:189], s[38:39], 0, v[66:67]
	s_mov_b32 m0, s40
	s_nop 0
	global_load_lds_dwordx4 v[188:189], off
	v_lshl_add_u64 v[188:189], s[38:39], 0, v[84:85]
	s_add_i32 m0, s40, 0x2000
	s_nop 0
	global_load_lds_dwordx4 v[188:189], off
	v_lshl_add_u64 v[188:189], v[222:223], 0, s[88:89]
	s_mov_b32 m0, s55
	s_nop 0
	global_load_lds_dwordx4 v[188:189], off
	v_lshl_add_u64 v[188:189], v[224:225], 0, s[88:89]
	s_mov_b32 m0, s56
	s_nop 0
	global_load_lds_dwordx4 v[188:189], off
	s_setprio 0
	s_setprio 1
	s_setprio 0
	s_waitcnt lgkmcnt(0)
	s_setprio 1
	s_waitcnt vmcnt(8)
	s_waitcnt lgkmcnt(0)
	s_barrier
	v_mfma_f32_16x16x32_bf16 v[100:103], v[144:147], v[176:179], v[100:103]
	v_mfma_f32_16x16x32_bf16 v[96:99], v[152:155], v[176:179], v[96:99]
	v_mfma_f32_16x16x32_bf16 v[88:91], v[144:147], v[184:187], v[88:91]
	v_mfma_f32_16x16x32_bf16 v[42:45], v[152:155], v[184:187], v[42:45]
	v_mfma_f32_16x16x32_bf16 v[38:41], v[144:147], v[196:199], v[38:41]
	v_mfma_f32_16x16x32_bf16 v[26:29], v[152:155], v[196:199], v[26:29]
	v_mfma_f32_16x16x32_bf16 v[22:25], v[144:147], v[204:207], v[22:25]
	v_mfma_f32_16x16x32_bf16 v[14:17], v[152:155], v[204:207], v[14:17]
	v_mfma_f32_16x16x32_bf16 v[100:103], v[148:151], v[180:183], v[100:103]
	v_mfma_f32_16x16x32_bf16 v[96:99], v[156:159], v[180:183], v[96:99]
	v_mfma_f32_16x16x32_bf16 v[88:91], v[148:151], v[192:195], v[88:91]
	v_mfma_f32_16x16x32_bf16 v[42:45], v[156:159], v[192:195], v[42:45]
	v_mfma_f32_16x16x32_bf16 v[38:41], v[148:151], v[200:203], v[38:41]
	v_mfma_f32_16x16x32_bf16 v[26:29], v[156:159], v[200:203], v[26:29]
	v_mfma_f32_16x16x32_bf16 v[22:25], v[148:151], v[208:211], v[22:25]
	v_mfma_f32_16x16x32_bf16 v[14:17], v[156:159], v[208:211], v[14:17]
	v_mfma_f32_16x16x32_bf16 v[62:65], v[160:163], v[176:179], v[62:65]
	v_mfma_f32_16x16x32_bf16 v[54:57], v[168:171], v[176:179], v[54:57]
	v_mfma_f32_16x16x32_bf16 v[34:37], v[160:163], v[184:187], v[34:37]
	v_mfma_f32_16x16x32_bf16 v[30:33], v[168:171], v[184:187], v[30:33]
	v_mfma_f32_16x16x32_bf16 v[18:21], v[160:163], v[196:199], v[18:21]
	v_mfma_f32_16x16x32_bf16 v[10:13], v[168:171], v[196:199], v[10:13]
	v_mfma_f32_16x16x32_bf16 v[6:9], v[160:163], v[204:207], v[6:9]
	v_mfma_f32_16x16x32_bf16 v[2:5], v[168:171], v[204:207], v[2:5]
	v_mfma_f32_16x16x32_bf16 v[62:65], v[164:167], v[180:183], v[62:65]
	v_mfma_f32_16x16x32_bf16 v[54:57], v[172:175], v[180:183], v[54:57]
	v_mfma_f32_16x16x32_bf16 v[34:37], v[164:167], v[192:195], v[34:37]
	v_mfma_f32_16x16x32_bf16 v[30:33], v[172:175], v[192:195], v[30:33]
	v_mfma_f32_16x16x32_bf16 v[18:21], v[164:167], v[200:203], v[18:21]
	v_mfma_f32_16x16x32_bf16 v[10:13], v[172:175], v[200:203], v[10:13]
	v_mfma_f32_16x16x32_bf16 v[6:9], v[164:167], v[208:211], v[6:9]
	v_mfma_f32_16x16x32_bf16 v[2:5], v[172:175], v[208:211], v[2:5]
	s_barrier
	s_setprio 0
	s_setprio 1
	s_setprio 0
	s_waitcnt lgkmcnt(0)
	s_add_i32 s62, s62, 2
	s_add_u32 s36, s36, 0x100
	s_addc_u32 s37, s37, 0
	s_cmp_gt_u32 s62, 29
	s_cbranch_scc0 .LBB0_905
	s_add_u32 s36, s3, 0xffffff00
	s_addc_u32 s37, s59, -1
	s_andn2_b64 vcc, exec, s[10:11]
	s_cbranch_vccnz .LBB0_896
	v_mov_b32_e32 v2, 0
	s_mov_b32 s12, s26
	s_mov_b32 s46, s28
	s_mov_b64 s[22:23], s[34:35]
	s_mov_b32 s57, s2
	v_mov_b32_e32 v3, v2
	v_mov_b32_e32 v4, v2
	v_mov_b32_e32 v5, v2
	v_mov_b32_e32 v6, v2
	v_mov_b32_e32 v7, v2
	v_mov_b32_e32 v8, v2
	v_mov_b32_e32 v9, v2
	v_mov_b32_e32 v10, v2
	v_mov_b32_e32 v11, v2
	v_mov_b32_e32 v12, v2
	v_mov_b32_e32 v13, v2
	v_mov_b32_e32 v18, v2
	v_mov_b32_e32 v19, v2
	v_mov_b32_e32 v20, v2
	v_mov_b32_e32 v21, v2
	v_mov_b32_e32 v30, v2
	v_mov_b32_e32 v31, v2
	v_mov_b32_e32 v32, v2
	v_mov_b32_e32 v33, v2
	v_mov_b32_e32 v34, v2
	v_mov_b32_e32 v35, v2
	v_mov_b32_e32 v36, v2
	v_mov_b32_e32 v37, v2
	v_mov_b32_e32 v54, v2
	v_mov_b32_e32 v55, v2
	v_mov_b32_e32 v56, v2
	v_mov_b32_e32 v57, v2
	v_mov_b32_e32 v62, v2
	v_mov_b32_e32 v63, v2
	v_mov_b32_e32 v64, v2
	v_mov_b32_e32 v65, v2
	v_mov_b32_e32 v14, v2
	v_mov_b32_e32 v15, v2
	v_mov_b32_e32 v16, v2
	v_mov_b32_e32 v17, v2
	v_mov_b32_e32 v22, v2
	v_mov_b32_e32 v23, v2
	v_mov_b32_e32 v24, v2
	v_mov_b32_e32 v25, v2
	v_mov_b32_e32 v26, v2
	v_mov_b32_e32 v27, v2
	v_mov_b32_e32 v28, v2
	v_mov_b32_e32 v29, v2
	v_mov_b32_e32 v38, v2
	v_mov_b32_e32 v39, v2
	v_mov_b32_e32 v40, v2
	v_mov_b32_e32 v41, v2
	v_mov_b32_e32 v42, v2
	v_mov_b32_e32 v43, v2
	v_mov_b32_e32 v44, v2
	v_mov_b32_e32 v45, v2
	v_mov_b32_e32 v88, v2
	v_mov_b32_e32 v89, v2
	v_mov_b32_e32 v90, v2
	v_mov_b32_e32 v91, v2
	v_mov_b32_e32 v96, v2
	v_mov_b32_e32 v97, v2
	v_mov_b32_e32 v98, v2
	v_mov_b32_e32 v99, v2
	v_mov_b32_e32 v100, v2
	v_mov_b32_e32 v101, v2
	v_mov_b32_e32 v102, v2
	v_mov_b32_e32 v103, v2
	v_mov_b32_e32 v104, v2
	v_mov_b32_e32 v105, v2
	v_mov_b32_e32 v106, v2
	v_mov_b32_e32 v107, v2
	v_mov_b32_e32 v108, v2
	v_mov_b32_e32 v109, v2
	v_mov_b32_e32 v110, v2
	v_mov_b32_e32 v111, v2
	v_mov_b32_e32 v116, v2
	v_mov_b32_e32 v117, v2
	v_mov_b32_e32 v118, v2
	v_mov_b32_e32 v119, v2
	v_mov_b32_e32 v124, v2
	v_mov_b32_e32 v125, v2
	v_mov_b32_e32 v126, v2
	v_mov_b32_e32 v127, v2
	v_mov_b32_e32 v50, v2
	v_mov_b32_e32 v51, v2
	v_mov_b32_e32 v52, v2
	v_mov_b32_e32 v53, v2
	v_mov_b32_e32 v76, v2
	v_mov_b32_e32 v77, v2
	v_mov_b32_e32 v78, v2
	v_mov_b32_e32 v79, v2
	v_mov_b32_e32 v46, v2
	v_mov_b32_e32 v47, v2
	v_mov_b32_e32 v48, v2
	v_mov_b32_e32 v49, v2
	v_mov_b32_e32 v58, v2
	v_mov_b32_e32 v59, v2
	v_mov_b32_e32 v60, v2
	v_mov_b32_e32 v61, v2
	v_mov_b32_e32 v120, v2
	v_mov_b32_e32 v121, v2
	v_mov_b32_e32 v122, v2
	v_mov_b32_e32 v123, v2
	v_mov_b32_e32 v136, v2
	v_mov_b32_e32 v137, v2
	v_mov_b32_e32 v138, v2
	v_mov_b32_e32 v139, v2
	v_mov_b32_e32 v112, v2
	v_mov_b32_e32 v113, v2
	v_mov_b32_e32 v114, v2
	v_mov_b32_e32 v115, v2
	v_mov_b32_e32 v128, v2
	v_mov_b32_e32 v129, v2
	v_mov_b32_e32 v130, v2
	v_mov_b32_e32 v131, v2
	v_mov_b32_e32 v80, v2
	v_mov_b32_e32 v81, v2
	v_mov_b32_e32 v82, v2
	v_mov_b32_e32 v83, v2
	v_mov_b32_e32 v92, v2
	v_mov_b32_e32 v93, v2
	v_mov_b32_e32 v94, v2
	v_mov_b32_e32 v95, v2
	v_mov_b32_e32 v72, v2
	v_mov_b32_e32 v73, v2
	v_mov_b32_e32 v74, v2
	v_mov_b32_e32 v75, v2
	v_mov_b32_e32 v68, v2
	v_mov_b32_e32 v69, v2
	v_mov_b32_e32 v70, v2
	v_mov_b32_e32 v71, v2
	s_mov_b64 s[64:65], s[72:73]
	s_andn2_b64 vcc, exec, s[8:9]
	s_mov_b32 s72, s67
	s_cbranch_vccnz .LBB0_897

; #define PG8_STAGE(bufoff, gbase, voff) do { _Pragma("unroll") for (int _i = 0; _i < 2; ++_i) \
;         __builtin_amdgcn_global_load_lds((const unsigned*)((const char*)(gbase) + (voff)[_i]), (PG8_LAS unsigned*)(lds + (bufoff) + ldsw + _i * 8192), 16, 0, 0); } while (0)
; #define PG8_LDA(dst, b, h) do { _Pragma("unroll") for (int m = 0; m < 4; ++m) _Pragma("unroll") for (int k = 0; k < 2; ++k) dst[m][k] = *(const PG8_LAS bf16x8*)(lds + PG8_SA(b, h) + aoff + m * 2048 + k * 1024); } while (0)
; #define PG8_LDB(dst, b, h) do { _Pragma("unroll") for (int n = 0; n < 2; ++n) _Pragma("unroll") for (int k = 0; k < 2; ++k) dst[n][k] = *(const PG8_LAS bf16x8*)(lds + PG8_SB(b, h) + boff + n * 2048 + k * 1024); } while (0)
; #define PG8_MMA(ai, bj, At, Bt) do { __builtin_amdgcn_s_setprio(1); _Pragma("unroll") for (int m = 0; m < 4; ++m) _Pragma("unroll") for (int n = 0; n < 2; ++n) _Pragma("unroll") for (int k = 0; k < 2; ++k) \
;         acc[ai][bj][m][n] = __builtin_amdgcn_mfma_f32_16x16x32_bf16(Bt[n][k], At[m][k], acc[ai][bj][m][n], 0, 0, 0); __builtin_amdgcn_s_setprio(0); } while (0)
; #define PG8_WAIT_V(n) asm volatile("s_waitcnt vmcnt(" #n ")" ::: "memory")
; #define PG8_WAIT_L(n) asm volatile("s_waitcnt lgkmcnt(" #n ")" ::: "memory")
; #define PG8_BAR __builtin_amdgcn_s_barrier()
; template <class Epi, class Sched, bool ALIGN_EPI = false, bool SP2 = false>
; __device__ __forceinline__ void gemm_phase(PG8_LAS unsigned char* lds, const Gemm g, const Sched& S, const Epi& E) {
;     ...
;             const char* a1 = cA + (size_t)(t + 1) * kstep;
;             const char* a2 = last ? nA : cA + (size_t)(t + 2) * kstep; const char* b2 = last ? nB : cB + (size_t)(t + 2) * kstep;
;             const char* a3 = a2 + kstep; const char* b3 = b2 + kstep;
;             if (last && has_next) S.a_ready(nxt);
;             if constexpr (SP2) {
;             PG8_LDB(B0, 0, 0); PG8_LDB(B1, 0, 1); PG8_SCHED; PG8_LDA(At, 0, 0); PG8_STAGE(PG8_SA(1, 1), a1 + hstep, voffA);
;             PG8_WAIT_V(8); PG8_WAIT_L(0); PG8_BAR; PG8_MMA(0, 0, At, B0); PG8_MMA(0, 1, At, B1); PG8_BAR; PG8_SCHED;
;             PG8_LDA(At, 0, 1); PG8_STAGE(PG8_SB(0, 0), b2, voffB); PG8_STAGE(PG8_SB(0, 1), b2 + hstep, voffB); PG8_STAGE(PG8_SA(0, 0), a2, voffA);
;             PG8_WAIT_V(8); PG8_WAIT_L(0); PG8_BAR; PG8_MMA(1, 0, At, B0); PG8_MMA(1, 1, At, B1); PG8_BAR; PG8_SCHED;
.LBB0_979:
	s_xor_b64 s[40:41], s[38:39], -1
	s_add_u32 s27, s12, s2
	s_addc_u32 s29, s13, 0
	s_add_u32 s3, s27, 0x100
	s_addc_u32 s44, s29, 0
	s_and_b64 s[42:43], s[38:39], exec
	s_cselect_b32 s43, s44, s35
	s_cselect_b32 s42, s3, s34
	s_add_u32 s2, s20, s2
	s_addc_u32 s3, s21, 0
	s_add_u32 s44, s2, 0x100
	s_addc_u32 s45, s3, 0
	s_and_b64 s[2:3], s[38:39], exec
	s_cselect_b32 s39, s45, s31
	s_cselect_b32 s38, s44, s30
	s_add_i32 s44, 0, 0x10000
	s_add_i32 s45, 0, 0x14000
	v_add_u32_e32 v164, s44, v0
	v_add_u32_e32 v180, s45, v0
	ds_read_b128 v[152:155], v164
	ds_read_b128 v[156:159], v164 offset:1024
	ds_read_b128 v[160:163], v164 offset:2048
	ds_read_b128 v[164:167], v164 offset:3072
	ds_read_b128 v[168:171], v180
	ds_read_b128 v[172:175], v180 offset:1024
	ds_read_b128 v[176:179], v180 offset:2048
	ds_read_b128 v[180:183], v180 offset:3072
	s_add_u32 s2, s27, 0x80080
	s_addc_u32 s3, s29, 0
	v_lshl_add_u64 v[224:225], s[2:3], 0, v[66:67]
	s_add_i32 m0, s52, 0xc000
	ds_read_b128 v[184:187], v151
	ds_read_b128 v[188:191], v151 offset:1024
	ds_read_b128 v[192:195], v151 offset:2048
	ds_read_b128 v[196:199], v151 offset:3072
	ds_read_b128 v[200:203], v151 offset:4096
	ds_read_b128 v[204:207], v151 offset:5120
	ds_read_b128 v[208:211], v151 offset:6144
	ds_read_b128 v[220:223], v151 offset:7168
	global_load_lds_dwordx4 v[224:225], off
	v_lshl_add_u64 v[224:225], s[2:3], 0, v[132:133]
	s_add_i32 m0, s52, 0xe000
	s_nop 0
	global_load_lds_dwordx4 v[224:225], off
	s_setprio 1
	s_waitcnt vmcnt(8)
	s_waitcnt lgkmcnt(0)
	s_barrier
	v_mfma_f32_16x16x32_bf16 v[128:131], v[152:155], v[184:187], v[128:131]
	v_mfma_f32_16x16x32_bf16 v[124:127], v[160:163], v[184:187], v[124:127]
	v_mfma_f32_16x16x32_bf16 v[120:123], v[152:155], v[192:195], v[120:123]
	v_mfma_f32_16x16x32_bf16 v[116:119], v[160:163], v[192:195], v[116:119]
	v_mfma_f32_16x16x32_bf16 v[112:115], v[152:155], v[200:203], v[112:115]
	v_mfma_f32_16x16x32_bf16 v[108:111], v[160:163], v[200:203], v[108:111]
	v_mfma_f32_16x16x32_bf16 v[100:103], v[152:155], v[208:211], v[100:103]
	v_mfma_f32_16x16x32_bf16 v[92:95], v[160:163], v[208:211], v[92:95]
	v_mfma_f32_16x16x32_bf16 v[128:131], v[156:159], v[188:191], v[128:131]
	v_mfma_f32_16x16x32_bf16 v[124:127], v[164:167], v[188:191], v[124:127]
	v_mfma_f32_16x16x32_bf16 v[120:123], v[156:159], v[196:199], v[120:123]
	v_mfma_f32_16x16x32_bf16 v[116:119], v[164:167], v[196:199], v[116:119]
	v_mfma_f32_16x16x32_bf16 v[112:115], v[156:159], v[204:207], v[112:115]
	v_mfma_f32_16x16x32_bf16 v[108:111], v[164:167], v[204:207], v[108:111]
	v_mfma_f32_16x16x32_bf16 v[100:103], v[156:159], v[220:223], v[100:103]
	v_mfma_f32_16x16x32_bf16 v[92:95], v[164:167], v[220:223], v[92:95]
	v_mfma_f32_16x16x32_bf16 v[104:107], v[168:171], v[184:187], v[104:107]
	v_mfma_f32_16x16x32_bf16 v[96:99], v[176:179], v[184:187], v[96:99]
	v_mfma_f32_16x16x32_bf16 v[88:91], v[168:171], v[192:195], v[88:91]
	v_mfma_f32_16x16x32_bf16 v[84:87], v[176:179], v[192:195], v[84:87]
	v_mfma_f32_16x16x32_bf16 v[80:83], v[168:171], v[200:203], v[80:83]
	v_mfma_f32_16x16x32_bf16 v[76:79], v[176:179], v[200:203], v[76:79]
	v_mfma_f32_16x16x32_bf16 v[72:75], v[168:171], v[208:211], v[72:75]
	v_mfma_f32_16x16x32_bf16 v[68:71], v[176:179], v[208:211], v[68:71]
	v_mfma_f32_16x16x32_bf16 v[104:107], v[172:175], v[188:191], v[104:107]
	v_mfma_f32_16x16x32_bf16 v[96:99], v[180:183], v[188:191], v[96:99]
	v_mfma_f32_16x16x32_bf16 v[88:91], v[172:175], v[196:199], v[88:91]
	v_mfma_f32_16x16x32_bf16 v[84:87], v[180:183], v[196:199], v[84:87]
	v_mfma_f32_16x16x32_bf16 v[80:83], v[172:175], v[204:207], v[80:83]
	v_mfma_f32_16x16x32_bf16 v[76:79], v[180:183], v[204:207], v[76:79]
	v_mfma_f32_16x16x32_bf16 v[72:75], v[172:175], v[220:223], v[72:75]
	v_mfma_f32_16x16x32_bf16 v[68:71], v[180:183], v[220:223], v[68:71]
	s_barrier
	s_add_i32 s2, s44, s51
	v_lshl_add_u64 v[224:225], s[38:39], 0, v[66:67]
	s_mov_b32 m0, s2
	ds_read_b128 v[184:187], v151 offset:16384
	ds_read_b128 v[188:191], v151 offset:17408
	ds_read_b128 v[192:195], v151 offset:18432
	ds_read_b128 v[196:199], v151 offset:19456
	ds_read_b128 v[200:203], v151 offset:20480
	ds_read_b128 v[204:207], v151 offset:21504
	ds_read_b128 v[208:211], v151 offset:22528
	ds_read_b128 v[220:223], v151 offset:23552
	global_load_lds_dwordx4 v[224:225], off
	s_add_i32 m0, s2, 0x2000
	s_add_u32 s2, s38, 0x80000
	v_lshl_add_u64 v[226:227], s[38:39], 0, v[132:133]
	s_addc_u32 s3, s39, 0
	s_add_i32 s27, s45, s51
	global_load_lds_dwordx4 v[226:227], off
	v_lshl_add_u64 v[228:229], s[2:3], 0, v[66:67]
	s_mov_b32 m0, s27
	v_lshl_add_u64 v[230:231], s[42:43], 0, v[132:133]
	global_load_lds_dwordx4 v[228:229], off
	v_lshl_add_u64 v[228:229], s[2:3], 0, v[132:133]
	s_add_i32 m0, s27, 0x2000
	s_nop 0
	global_load_lds_dwordx4 v[228:229], off
	v_lshl_add_u64 v[228:229], s[42:43], 0, v[66:67]
	s_mov_b32 m0, s52
	s_nop 0
	global_load_lds_dwordx4 v[228:229], off
	s_mov_b32 m0, s53
	s_nop 0
	global_load_lds_dwordx4 v[230:231], off
	s_setprio 0
	s_setprio 1
	s_setprio 0
	s_waitcnt lgkmcnt(0)
	s_setprio 1
	s_waitcnt vmcnt(8)
	s_waitcnt lgkmcnt(0)
	s_barrier
; #define PG8_STAGE(bufoff, gbase, voff) do { _Pragma("unroll") for (int _i = 0; _i < 2; ++_i) \
;         __builtin_amdgcn_global_load_lds((const unsigned*)((const char*)(gbase) + (voff)[_i]), (PG8_LAS unsigned*)(lds + (bufoff) + ldsw + _i * 8192), 16, 0, 0); } while (0)
; #define PG8_LDA(dst, b, h) do { _Pragma("unroll") for (int m = 0; m < 4; ++m) _Pragma("unroll") for (int k = 0; k < 2; ++k) dst[m][k] = *(const PG8_LAS bf16x8*)(lds + PG8_SA(b, h) + aoff + m * 2048 + k * 1024); } while (0)
; #define PG8_LDB(dst, b, h) do { _Pragma("unroll") for (int n = 0; n < 2; ++n) _Pragma("unroll") for (int k = 0; k < 2; ++k) dst[n][k] = *(const PG8_LAS bf16x8*)(lds + PG8_SB(b, h) + boff + n * 2048 + k * 1024); } while (0)
; #define PG8_MMA(ai, bj, At, Bt) do { __builtin_amdgcn_s_setprio(1); _Pragma("unroll") for (int m = 0; m < 4; ++m) _Pragma("unroll") for (int n = 0; n < 2; ++n) _Pragma("unroll") for (int k = 0; k < 2; ++k) \
;         acc[ai][bj][m][n] = __builtin_amdgcn_mfma_f32_16x16x32_bf16(Bt[n][k], At[m][k], acc[ai][bj][m][n], 0, 0, 0); __builtin_amdgcn_s_setprio(0); } while (0)
; #define PG8_WAIT_V(n) asm volatile("s_waitcnt vmcnt(" #n ")" ::: "memory")
; #define PG8_WAIT_L(n) asm volatile("s_waitcnt lgkmcnt(" #n ")" ::: "memory")
; #define PG8_BAR __builtin_amdgcn_s_barrier()
; #define PG8_SCHED __builtin_amdgcn_sched_barrier(0)
; template <class Epi, class Sched, bool ALIGN_EPI = false, bool SP2 = false>
; __device__ __forceinline__ void gemm_phase(PG8_LAS unsigned char* lds, const Gemm g, const Sched& S, const Epi& E) {
;     ...
;             PG8_WAIT_V(8); PG8_WAIT_L(0); PG8_BAR; PG8_MMA(1, 0, At, B0); PG8_MMA(1, 1, At, B1); PG8_BAR; PG8_SCHED;
;             PG8_LDB(B0, 1, 0); PG8_LDB(B1, 1, 1); PG8_SCHED; PG8_LDA(At, 1, 0); PG8_STAGE(PG8_SA(0, 1), a2 + hstep, voffA);
;             PG8_WAIT_V(8); PG8_WAIT_L(0); PG8_BAR; PG8_MMA(0, 0, At, B0); PG8_MMA(0, 1, At, B1); PG8_BAR; PG8_SCHED;
	v_mfma_f32_16x16x32_bf16 v[62:65], v[152:155], v[184:187], v[62:65]
	v_mfma_f32_16x16x32_bf16 v[58:61], v[160:163], v[184:187], v[58:61]
	v_mfma_f32_16x16x32_bf16 v[54:57], v[152:155], v[192:195], v[54:57]
	v_mfma_f32_16x16x32_bf16 v[50:53], v[160:163], v[192:195], v[50:53]
	v_mfma_f32_16x16x32_bf16 v[46:49], v[152:155], v[200:203], v[46:49]
	v_mfma_f32_16x16x32_bf16 v[42:45], v[160:163], v[200:203], v[42:45]
	v_mfma_f32_16x16x32_bf16 v[34:37], v[152:155], v[208:211], v[34:37]
	v_mfma_f32_16x16x32_bf16 v[26:29], v[160:163], v[208:211], v[26:29]
	v_mfma_f32_16x16x32_bf16 v[62:65], v[156:159], v[188:191], v[62:65]
	v_mfma_f32_16x16x32_bf16 v[58:61], v[164:167], v[188:191], v[58:61]
	v_mfma_f32_16x16x32_bf16 v[54:57], v[156:159], v[196:199], v[54:57]
	v_mfma_f32_16x16x32_bf16 v[50:53], v[164:167], v[196:199], v[50:53]
	v_mfma_f32_16x16x32_bf16 v[46:49], v[156:159], v[204:207], v[46:49]
	v_mfma_f32_16x16x32_bf16 v[42:45], v[164:167], v[204:207], v[42:45]
	v_mfma_f32_16x16x32_bf16 v[34:37], v[156:159], v[220:223], v[34:37]
	v_mfma_f32_16x16x32_bf16 v[26:29], v[164:167], v[220:223], v[26:29]
	v_mfma_f32_16x16x32_bf16 v[38:41], v[168:171], v[184:187], v[38:41]
	v_mfma_f32_16x16x32_bf16 v[30:33], v[176:179], v[184:187], v[30:33]
	v_mfma_f32_16x16x32_bf16 v[22:25], v[168:171], v[192:195], v[22:25]
	v_mfma_f32_16x16x32_bf16 v[18:21], v[176:179], v[192:195], v[18:21]
	v_mfma_f32_16x16x32_bf16 v[14:17], v[168:171], v[200:203], v[14:17]
	v_mfma_f32_16x16x32_bf16 v[10:13], v[176:179], v[200:203], v[10:13]
	v_mfma_f32_16x16x32_bf16 v[6:9], v[168:171], v[208:211], v[6:9]
	v_mfma_f32_16x16x32_bf16 v[2:5], v[176:179], v[208:211], v[2:5]
	v_mfma_f32_16x16x32_bf16 v[38:41], v[172:175], v[188:191], v[38:41]
	v_mfma_f32_16x16x32_bf16 v[30:33], v[180:183], v[188:191], v[30:33]
	v_mfma_f32_16x16x32_bf16 v[22:25], v[172:175], v[196:199], v[22:25]
	v_mfma_f32_16x16x32_bf16 v[18:21], v[180:183], v[196:199], v[18:21]
	v_mfma_f32_16x16x32_bf16 v[14:17], v[172:175], v[204:207], v[14:17]
	v_mfma_f32_16x16x32_bf16 v[10:13], v[180:183], v[204:207], v[10:13]
	v_mfma_f32_16x16x32_bf16 v[6:9], v[172:175], v[220:223], v[6:9]
	v_mfma_f32_16x16x32_bf16 v[2:5], v[180:183], v[220:223], v[2:5]
	s_barrier
	s_add_i32 s27, 0, 0x18000
	s_add_i32 s29, 0, 0x1c000
	v_add_u32_e32 v164, s27, v0
	v_add_u32_e32 v180, s29, v0
	ds_read_b128 v[152:155], v164
	ds_read_b128 v[156:159], v164 offset:1024
	ds_read_b128 v[160:163], v164 offset:2048
	ds_read_b128 v[164:167], v164 offset:3072
	ds_read_b128 v[168:171], v180
	ds_read_b128 v[172:175], v180 offset:1024
	ds_read_b128 v[176:179], v180 offset:2048
	ds_read_b128 v[180:183], v180 offset:3072
	s_add_u32 s2, s42, 0x80000
	s_addc_u32 s3, s43, 0
	s_mov_b32 m0, s54
	v_lshl_add_u64 v[232:233], s[2:3], 0, v[66:67]
	ds_read_b128 v[184:187], v151 offset:32768
	ds_read_b128 v[188:191], v151 offset:33792
	ds_read_b128 v[192:195], v151 offset:34816
	ds_read_b128 v[196:199], v151 offset:35840
	ds_read_b128 v[200:203], v151 offset:36864
	ds_read_b128 v[204:207], v151 offset:37888
	ds_read_b128 v[208:211], v151 offset:38912
	ds_read_b128 v[220:223], v151 offset:39936
	global_load_lds_dwordx4 v[232:233], off
	v_lshl_add_u64 v[232:233], s[2:3], 0, v[132:133]
	s_mov_b32 m0, s55
	s_nop 0
	global_load_lds_dwordx4 v[232:233], off
	s_setprio 0
	s_setprio 1
	s_setprio 0
	s_waitcnt lgkmcnt(0)
	s_setprio 1
	s_waitcnt vmcnt(8)
	s_waitcnt lgkmcnt(0)
	s_barrier
	v_mfma_f32_16x16x32_bf16 v[128:131], v[152:155], v[184:187], v[128:131]
	v_mfma_f32_16x16x32_bf16 v[124:127], v[160:163], v[184:187], v[124:127]
	v_mfma_f32_16x16x32_bf16 v[120:123], v[152:155], v[192:195], v[120:123]
	v_mfma_f32_16x16x32_bf16 v[116:119], v[160:163], v[192:195], v[116:119]
	v_mfma_f32_16x16x32_bf16 v[112:115], v[152:155], v[200:203], v[112:115]
	v_mfma_f32_16x16x32_bf16 v[108:111], v[160:163], v[200:203], v[108:111]
	v_mfma_f32_16x16x32_bf16 v[100:103], v[152:155], v[208:211], v[100:103]
	v_mfma_f32_16x16x32_bf16 v[92:95], v[160:163], v[208:211], v[92:95]
	v_mfma_f32_16x16x32_bf16 v[128:131], v[156:159], v[188:191], v[128:131]
	v_mfma_f32_16x16x32_bf16 v[124:127], v[164:167], v[188:191], v[124:127]
	v_mfma_f32_16x16x32_bf16 v[120:123], v[156:159], v[196:199], v[120:123]
	v_mfma_f32_16x16x32_bf16 v[116:119], v[164:167], v[196:199], v[116:119]
	v_mfma_f32_16x16x32_bf16 v[112:115], v[156:159], v[204:207], v[112:115]
	v_mfma_f32_16x16x32_bf16 v[108:111], v[164:167], v[204:207], v[108:111]
	v_mfma_f32_16x16x32_bf16 v[100:103], v[156:159], v[220:223], v[100:103]
	v_mfma_f32_16x16x32_bf16 v[92:95], v[164:167], v[220:223], v[92:95]
	v_mfma_f32_16x16x32_bf16 v[104:107], v[168:171], v[184:187], v[104:107]
	v_mfma_f32_16x16x32_bf16 v[96:99], v[176:179], v[184:187], v[96:99]
	v_mfma_f32_16x16x32_bf16 v[88:91], v[168:171], v[192:195], v[88:91]
	v_mfma_f32_16x16x32_bf16 v[84:87], v[176:179], v[192:195], v[84:87]
	v_mfma_f32_16x16x32_bf16 v[80:83], v[168:171], v[200:203], v[80:83]
	v_mfma_f32_16x16x32_bf16 v[76:79], v[176:179], v[200:203], v[76:79]
	v_mfma_f32_16x16x32_bf16 v[72:75], v[168:171], v[208:211], v[72:75]
	v_mfma_f32_16x16x32_bf16 v[68:71], v[176:179], v[208:211], v[68:71]
	v_mfma_f32_16x16x32_bf16 v[104:107], v[172:175], v[188:191], v[104:107]
	v_mfma_f32_16x16x32_bf16 v[96:99], v[180:183], v[188:191], v[96:99]
	v_mfma_f32_16x16x32_bf16 v[88:91], v[172:175], v[196:199], v[88:91]
	v_mfma_f32_16x16x32_bf16 v[84:87], v[180:183], v[196:199], v[84:87]
	v_mfma_f32_16x16x32_bf16 v[80:83], v[172:175], v[204:207], v[80:83]
	v_mfma_f32_16x16x32_bf16 v[76:79], v[180:183], v[204:207], v[76:79]
	v_mfma_f32_16x16x32_bf16 v[72:75], v[172:175], v[220:223], v[72:75]
	v_mfma_f32_16x16x32_bf16 v[68:71], v[180:183], v[220:223], v[68:71]
	s_barrier
; #define PG8_STAGE(bufoff, gbase, voff) do { _Pragma("unroll") for (int _i = 0; _i < 2; ++_i) \
;         __builtin_amdgcn_global_load_lds((const unsigned*)((const char*)(gbase) + (voff)[_i]), (PG8_LAS unsigned*)(lds + (bufoff) + ldsw + _i * 8192), 16, 0, 0); } while (0)
; #define PG8_LDA(dst, b, h) do { _Pragma("unroll") for (int m = 0; m < 4; ++m) _Pragma("unroll") for (int k = 0; k < 2; ++k) dst[m][k] = *(const PG8_LAS bf16x8*)(lds + PG8_SA(b, h) + aoff + m * 2048 + k * 1024); } while (0)
; #define PG8_MMA(ai, bj, At, Bt) do { __builtin_amdgcn_s_setprio(1); _Pragma("unroll") for (int m = 0; m < 4; ++m) _Pragma("unroll") for (int n = 0; n < 2; ++n) _Pragma("unroll") for (int k = 0; k < 2; ++k) \
;         acc[ai][bj][m][n] = __builtin_amdgcn_mfma_f32_16x16x32_bf16(Bt[n][k], At[m][k], acc[ai][bj][m][n], 0, 0, 0); __builtin_amdgcn_s_setprio(0); } while (0)
; #define PG8_WAIT_V(n) asm volatile("s_waitcnt vmcnt(" #n ")" ::: "memory")
; #define PG8_WAIT_L(n) asm volatile("s_waitcnt lgkmcnt(" #n ")" ::: "memory")
; #define PG8_BAR __builtin_amdgcn_s_barrier()
; #define PG8_SCHED __builtin_amdgcn_sched_barrier(0)
; template <class Epi, class Sched, bool ALIGN_EPI = false, bool SP2 = false>
; __device__ __forceinline__ void gemm_phase(PG8_LAS unsigned char* lds, const Gemm g, const Sched& S, const Epi& E) {
;     ...
;             PG8_LDA(At, 1, 1); PG8_STAGE(PG8_SB(1, 0), b3, voffB); PG8_STAGE(PG8_SB(1, 1), b3 + hstep, voffB); PG8_STAGE(PG8_SA(1, 0), a3, voffA);
;             PG8_WAIT_V(8); PG8_WAIT_L(0); PG8_BAR; PG8_MMA(1, 0, At, B0); PG8_MMA(1, 1, At, B1); PG8_BAR; PG8_SCHED;
	s_add_i32 s2, s27, s51
	v_lshl_add_u64 v[224:225], v[224:225], 0, s[88:89]
	s_mov_b32 m0, s2
	ds_read_b128 v[184:187], v151 offset:49152
	ds_read_b128 v[188:191], v151 offset:50176
	ds_read_b128 v[192:195], v151 offset:51200
	ds_read_b128 v[196:199], v151 offset:52224
	ds_read_b128 v[200:203], v151 offset:53248
	ds_read_b128 v[204:207], v151 offset:54272
	ds_read_b128 v[208:211], v151 offset:55296
	ds_read_b128 v[220:223], v151 offset:56320
	global_load_lds_dwordx4 v[224:225], off
	s_add_i32 m0, s2, 0x2000
	s_add_u32 s2, s38, 0x80080
	v_lshl_add_u64 v[224:225], v[226:227], 0, s[88:89]
	s_addc_u32 s3, s39, 0
	s_add_i32 s27, s29, s51
	global_load_lds_dwordx4 v[224:225], off
	v_lshl_add_u64 v[224:225], s[2:3], 0, v[66:67]
	s_mov_b32 m0, s27
	s_nop 0
	global_load_lds_dwordx4 v[224:225], off
	v_lshl_add_u64 v[224:225], s[2:3], 0, v[132:133]
	s_add_i32 m0, s27, 0x2000
	s_nop 0
	global_load_lds_dwordx4 v[224:225], off
	v_lshl_add_u64 v[224:225], v[228:229], 0, s[88:89]
	s_mov_b32 m0, s59
	s_nop 0
	global_load_lds_dwordx4 v[224:225], off
	v_lshl_add_u64 v[224:225], v[230:231], 0, s[88:89]
	s_mov_b32 m0, s60
	s_nop 0
	global_load_lds_dwordx4 v[224:225], off
	s_setprio 0
	s_setprio 1
	s_setprio 0
	s_waitcnt lgkmcnt(0)
	s_setprio 1
	s_waitcnt vmcnt(8)
	s_waitcnt lgkmcnt(0)
	s_barrier
	v_mfma_f32_16x16x32_bf16 v[62:65], v[152:155], v[184:187], v[62:65]
	v_mfma_f32_16x16x32_bf16 v[58:61], v[160:163], v[184:187], v[58:61]
	v_mfma_f32_16x16x32_bf16 v[54:57], v[152:155], v[192:195], v[54:57]
	v_mfma_f32_16x16x32_bf16 v[50:53], v[160:163], v[192:195], v[50:53]
	v_mfma_f32_16x16x32_bf16 v[46:49], v[152:155], v[200:203], v[46:49]
	v_mfma_f32_16x16x32_bf16 v[42:45], v[160:163], v[200:203], v[42:45]
	v_mfma_f32_16x16x32_bf16 v[34:37], v[152:155], v[208:211], v[34:37]
	v_mfma_f32_16x16x32_bf16 v[26:29], v[160:163], v[208:211], v[26:29]
	v_mfma_f32_16x16x32_bf16 v[62:65], v[156:159], v[188:191], v[62:65]
	v_mfma_f32_16x16x32_bf16 v[58:61], v[164:167], v[188:191], v[58:61]
	v_mfma_f32_16x16x32_bf16 v[54:57], v[156:159], v[196:199], v[54:57]
	v_mfma_f32_16x16x32_bf16 v[50:53], v[164:167], v[196:199], v[50:53]
	v_mfma_f32_16x16x32_bf16 v[46:49], v[156:159], v[204:207], v[46:49]
	v_mfma_f32_16x16x32_bf16 v[42:45], v[164:167], v[204:207], v[42:45]
	v_mfma_f32_16x16x32_bf16 v[34:37], v[156:159], v[220:223], v[34:37]
	v_mfma_f32_16x16x32_bf16 v[26:29], v[164:167], v[220:223], v[26:29]
	v_mfma_f32_16x16x32_bf16 v[38:41], v[168:171], v[184:187], v[38:41]
	v_mfma_f32_16x16x32_bf16 v[30:33], v[176:179], v[184:187], v[30:33]
	v_mfma_f32_16x16x32_bf16 v[22:25], v[168:171], v[192:195], v[22:25]
	v_mfma_f32_16x16x32_bf16 v[18:21], v[176:179], v[192:195], v[18:21]
	v_mfma_f32_16x16x32_bf16 v[14:17], v[168:171], v[200:203], v[14:17]
	v_mfma_f32_16x16x32_bf16 v[10:13], v[176:179], v[200:203], v[10:13]
	v_mfma_f32_16x16x32_bf16 v[6:9], v[168:171], v[208:211], v[6:9]
	v_mfma_f32_16x16x32_bf16 v[2:5], v[176:179], v[208:211], v[2:5]
	v_mfma_f32_16x16x32_bf16 v[38:41], v[172:175], v[188:191], v[38:41]
	v_mfma_f32_16x16x32_bf16 v[30:33], v[180:183], v[188:191], v[30:33]
	v_mfma_f32_16x16x32_bf16 v[22:25], v[172:175], v[196:199], v[22:25]
	v_mfma_f32_16x16x32_bf16 v[18:21], v[180:183], v[196:199], v[18:21]
	v_mfma_f32_16x16x32_bf16 v[14:17], v[172:175], v[204:207], v[14:17]
	v_mfma_f32_16x16x32_bf16 v[10:13], v[180:183], v[204:207], v[10:13]
	v_mfma_f32_16x16x32_bf16 v[6:9], v[172:175], v[220:223], v[6:9]
	v_mfma_f32_16x16x32_bf16 v[2:5], v[180:183], v[220:223], v[2:5]
	s_barrier
	s_setprio 0
	s_setprio 1
	s_setprio 0
	s_waitcnt lgkmcnt(0)
	s_movk_i32 s2, 0x100
	s_mov_b64 s[38:39], 0
	s_and_b64 vcc, exec, s[40:41]
	s_cbranch_vccnz .LBB0_991

; #define PG8_STAGE(bufoff, gbase, voff) do { _Pragma("unroll") for (int _i = 0; _i < 2; ++_i) \
;         __builtin_amdgcn_global_load_lds((const unsigned*)((const char*)(gbase) + (voff)[_i]), (PG8_LAS unsigned*)(lds + (bufoff) + ldsw + _i * 8192), 16, 0, 0); } while (0)
; #define PG8_LDA(dst, b, h) do { _Pragma("unroll") for (int m = 0; m < 4; ++m) _Pragma("unroll") for (int k = 0; k < 2; ++k) dst[m][k] = *(const PG8_LAS bf16x8*)(lds + PG8_SA(b, h) + aoff + m * 2048 + k * 1024); } while (0)
; #define PG8_LDB(dst, b, h) do { _Pragma("unroll") for (int n = 0; n < 2; ++n) _Pragma("unroll") for (int k = 0; k < 2; ++k) dst[n][k] = *(const PG8_LAS bf16x8*)(lds + PG8_SB(b, h) + boff + n * 2048 + k * 1024); } while (0)
; #define PG8_MMA(ai, bj, At, Bt) do { __builtin_amdgcn_s_setprio(1); _Pragma("unroll") for (int m = 0; m < 4; ++m) _Pragma("unroll") for (int n = 0; n < 2; ++n) _Pragma("unroll") for (int k = 0; k < 2; ++k) \
;         acc[ai][bj][m][n] = __builtin_amdgcn_mfma_f32_16x16x32_bf16(Bt[n][k], At[m][k], acc[ai][bj][m][n], 0, 0, 0); __builtin_amdgcn_s_setprio(0); } while (0)
; #define PG8_WAIT_V(n) asm volatile("s_waitcnt vmcnt(" #n ")" ::: "memory")
; #define PG8_WAIT_L(n) asm volatile("s_waitcnt lgkmcnt(" #n ")" ::: "memory")
; #define PG8_BAR __builtin_amdgcn_s_barrier()
; template <class Epi, class Sched, bool ALIGN_EPI = false, bool SP2 = false>
; __device__ __forceinline__ void gemm_phase(PG8_LAS unsigned char* lds, const Gemm g, const Sched& S, const Epi& E) {
;     ...
;             const char* a1 = cA + (size_t)(t + 1) * kstep;
;             const char* a2 = last ? nA : cA + (size_t)(t + 2) * kstep; const char* b2 = last ? nB : cB + (size_t)(t + 2) * kstep;
;             const char* a3 = a2 + kstep; const char* b3 = b2 + kstep;
;             if (last && has_next) S.a_ready(nxt);
;             if constexpr (SP2) {
;             PG8_LDB(B0, 0, 0); PG8_LDB(B1, 0, 1); PG8_SCHED; PG8_LDA(At, 0, 0); PG8_STAGE(PG8_SA(1, 1), a1 + hstep, voffA);
;             PG8_WAIT_V(8); PG8_WAIT_L(0); PG8_BAR; PG8_MMA(0, 0, At, B0); PG8_MMA(0, 1, At, B1); PG8_BAR; PG8_SCHED;
;             PG8_LDA(At, 0, 1); PG8_STAGE(PG8_SB(0, 0), b2, voffB); PG8_STAGE(PG8_SB(0, 1), b2 + hstep, voffB); PG8_STAGE(PG8_SA(0, 0), a2, voffA);
;             PG8_WAIT_V(8); PG8_WAIT_L(0); PG8_BAR; PG8_MMA(1, 0, At, B0); PG8_MMA(1, 1, At, B1); PG8_BAR; PG8_SCHED;
.LBB0_1205:
	s_lshl_b32 s52, s31, 7
	s_add_u32 s53, s42, s52
	s_addc_u32 s54, s43, 0
	s_add_u32 s55, s53, 0x100
	s_addc_u32 s56, s54, 0
	s_and_b64 s[50:51], s[48:49], exec
	s_cselect_b32 s51, s56, s1
	s_cselect_b32 s50, s55, s2
	s_add_u32 s52, s44, s52
	s_addc_u32 s55, s45, 0
	s_add_u32 s52, s52, 0x100
	s_addc_u32 s55, s55, 0
	s_and_b64 s[48:49], s[48:49], exec
	s_cselect_b32 s49, s55, s3
	s_cselect_b32 s48, s52, s29
	s_add_i32 s55, 0, 0x10000
	v_add_u32_e32 v138, s55, v140
	s_add_i32 s56, 0, 0x14000
	ds_read_b128 v[144:147], v138
	ds_read_b128 v[148:151], v138 offset:1024
	ds_read_b128 v[152:155], v138 offset:2048
	ds_read_b128 v[156:159], v138 offset:3072
	v_add_u32_e32 v138, s56, v140
	ds_read_b128 v[160:163], v138
	ds_read_b128 v[164:167], v138 offset:1024
	ds_read_b128 v[168:171], v138 offset:2048
	ds_read_b128 v[172:175], v138 offset:3072
	s_add_u32 s52, s53, 0x80080
	s_addc_u32 s53, s54, 0
	v_lshl_add_u64 v[138:139], s[52:53], 0, v[132:133]
	s_add_i32 m0, s41, 0xc000
	ds_read_b128 v[176:179], v142
	ds_read_b128 v[180:183], v142 offset:1024
	ds_read_b128 v[184:187], v142 offset:2048
	ds_read_b128 v[188:191], v142 offset:3072
	ds_read_b128 v[192:195], v142 offset:4096
	ds_read_b128 v[196:199], v142 offset:5120
	ds_read_b128 v[200:203], v142 offset:6144
	ds_read_b128 v[204:207], v142 offset:7168
	global_load_lds_dwordx4 v[138:139], off
	v_lshl_add_u64 v[138:139], s[52:53], 0, v[134:135]
	s_add_i32 m0, s41, 0xe000
	s_nop 0
	global_load_lds_dwordx4 v[138:139], off
	s_setprio 1
	s_waitcnt vmcnt(8)
	s_waitcnt lgkmcnt(0)
	s_barrier
	v_mfma_f32_16x16x32_bf16 v[128:131], v[144:147], v[176:179], v[128:131]
	v_mfma_f32_16x16x32_bf16 v[124:127], v[152:155], v[176:179], v[124:127]
	v_mfma_f32_16x16x32_bf16 v[112:115], v[144:147], v[184:187], v[112:115]
	v_mfma_f32_16x16x32_bf16 v[108:111], v[152:155], v[184:187], v[108:111]
	v_mfma_f32_16x16x32_bf16 v[96:99], v[144:147], v[192:195], v[96:99]
	v_mfma_f32_16x16x32_bf16 v[92:95], v[152:155], v[192:195], v[92:95]
	v_mfma_f32_16x16x32_bf16 v[80:83], v[144:147], v[200:203], v[80:83]
	v_mfma_f32_16x16x32_bf16 v[76:79], v[152:155], v[200:203], v[76:79]
	v_mfma_f32_16x16x32_bf16 v[128:131], v[148:151], v[180:183], v[128:131]
	v_mfma_f32_16x16x32_bf16 v[124:127], v[156:159], v[180:183], v[124:127]
	v_mfma_f32_16x16x32_bf16 v[112:115], v[148:151], v[188:191], v[112:115]
	v_mfma_f32_16x16x32_bf16 v[108:111], v[156:159], v[188:191], v[108:111]
	v_mfma_f32_16x16x32_bf16 v[96:99], v[148:151], v[196:199], v[96:99]
	v_mfma_f32_16x16x32_bf16 v[92:95], v[156:159], v[196:199], v[92:95]
	v_mfma_f32_16x16x32_bf16 v[80:83], v[148:151], v[204:207], v[80:83]
	v_mfma_f32_16x16x32_bf16 v[76:79], v[156:159], v[204:207], v[76:79]
	v_mfma_f32_16x16x32_bf16 v[120:123], v[160:163], v[176:179], v[120:123]
	v_mfma_f32_16x16x32_bf16 v[116:119], v[168:171], v[176:179], v[116:119]
	v_mfma_f32_16x16x32_bf16 v[104:107], v[160:163], v[184:187], v[104:107]
	v_mfma_f32_16x16x32_bf16 v[100:103], v[168:171], v[184:187], v[100:103]
	v_mfma_f32_16x16x32_bf16 v[88:91], v[160:163], v[192:195], v[88:91]
	v_mfma_f32_16x16x32_bf16 v[84:87], v[168:171], v[192:195], v[84:87]
	v_mfma_f32_16x16x32_bf16 v[72:75], v[160:163], v[200:203], v[72:75]
	v_mfma_f32_16x16x32_bf16 v[68:71], v[168:171], v[200:203], v[68:71]
	v_mfma_f32_16x16x32_bf16 v[120:123], v[164:167], v[180:183], v[120:123]
	v_mfma_f32_16x16x32_bf16 v[116:119], v[172:175], v[180:183], v[116:119]
	v_mfma_f32_16x16x32_bf16 v[104:107], v[164:167], v[188:191], v[104:107]
	v_mfma_f32_16x16x32_bf16 v[100:103], v[172:175], v[188:191], v[100:103]
	v_mfma_f32_16x16x32_bf16 v[88:91], v[164:167], v[196:199], v[88:91]
	v_mfma_f32_16x16x32_bf16 v[84:87], v[172:175], v[196:199], v[84:87]
	v_mfma_f32_16x16x32_bf16 v[72:75], v[164:167], v[204:207], v[72:75]
	v_mfma_f32_16x16x32_bf16 v[68:71], v[172:175], v[204:207], v[68:71]
	s_barrier
	s_add_i32 s52, s55, s39
	v_lshl_add_u64 v[138:139], s[48:49], 0, v[66:67]
	s_mov_b32 m0, s52
	ds_read_b128 v[176:179], v142 offset:16384
	ds_read_b128 v[180:183], v142 offset:17408
	ds_read_b128 v[184:187], v142 offset:18432
	ds_read_b128 v[188:191], v142 offset:19456
	ds_read_b128 v[192:195], v142 offset:20480
	ds_read_b128 v[196:199], v142 offset:21504
	ds_read_b128 v[200:203], v142 offset:22528
	ds_read_b128 v[204:207], v142 offset:23552
	global_load_lds_dwordx4 v[138:139], off
	s_add_i32 m0, s52, 0x2000
	s_add_u32 s52, s48, 0x80000
	v_lshl_add_u64 v[208:209], s[48:49], 0, v[136:137]
	s_addc_u32 s53, s49, 0
	s_add_i32 s54, s56, s39
	global_load_lds_dwordx4 v[208:209], off
	v_lshl_add_u64 v[210:211], s[52:53], 0, v[66:67]
	s_mov_b32 m0, s54
	v_lshl_add_u64 v[220:221], s[50:51], 0, v[134:135]
	global_load_lds_dwordx4 v[210:211], off
	v_lshl_add_u64 v[210:211], s[52:53], 0, v[136:137]
	s_add_i32 m0, s54, 0x2000
	s_nop 0
	global_load_lds_dwordx4 v[210:211], off
	v_lshl_add_u64 v[210:211], s[50:51], 0, v[132:133]
	s_mov_b32 m0, s41
	s_nop 0
	global_load_lds_dwordx4 v[210:211], off
	s_mov_b32 m0, s68
	s_nop 0
	global_load_lds_dwordx4 v[220:221], off
	s_setprio 0
	s_setprio 1
	s_setprio 0
	s_waitcnt lgkmcnt(0)
	s_setprio 1
	s_waitcnt vmcnt(8)
	s_waitcnt lgkmcnt(0)
	s_barrier
; #define PG8_STAGE(bufoff, gbase, voff) do { _Pragma("unroll") for (int _i = 0; _i < 2; ++_i) \
;         __builtin_amdgcn_global_load_lds((const unsigned*)((const char*)(gbase) + (voff)[_i]), (PG8_LAS unsigned*)(lds + (bufoff) + ldsw + _i * 8192), 16, 0, 0); } while (0)
; #define PG8_LDA(dst, b, h) do { _Pragma("unroll") for (int m = 0; m < 4; ++m) _Pragma("unroll") for (int k = 0; k < 2; ++k) dst[m][k] = *(const PG8_LAS bf16x8*)(lds + PG8_SA(b, h) + aoff + m * 2048 + k * 1024); } while (0)
; #define PG8_LDB(dst, b, h) do { _Pragma("unroll") for (int n = 0; n < 2; ++n) _Pragma("unroll") for (int k = 0; k < 2; ++k) dst[n][k] = *(const PG8_LAS bf16x8*)(lds + PG8_SB(b, h) + boff + n * 2048 + k * 1024); } while (0)
; #define PG8_MMA(ai, bj, At, Bt) do { __builtin_amdgcn_s_setprio(1); _Pragma("unroll") for (int m = 0; m < 4; ++m) _Pragma("unroll") for (int n = 0; n < 2; ++n) _Pragma("unroll") for (int k = 0; k < 2; ++k) \
;         acc[ai][bj][m][n] = __builtin_amdgcn_mfma_f32_16x16x32_bf16(Bt[n][k], At[m][k], acc[ai][bj][m][n], 0, 0, 0); __builtin_amdgcn_s_setprio(0); } while (0)
; #define PG8_WAIT_V(n) asm volatile("s_waitcnt vmcnt(" #n ")" ::: "memory")
; #define PG8_WAIT_L(n) asm volatile("s_waitcnt lgkmcnt(" #n ")" ::: "memory")
; #define PG8_BAR __builtin_amdgcn_s_barrier()
; #define PG8_SCHED __builtin_amdgcn_sched_barrier(0)
; template <class Epi, class Sched, bool ALIGN_EPI = false, bool SP2 = false>
; __device__ __forceinline__ void gemm_phase(PG8_LAS unsigned char* lds, const Gemm g, const Sched& S, const Epi& E) {
;     ...
;             PG8_WAIT_V(8); PG8_WAIT_L(0); PG8_BAR; PG8_MMA(1, 0, At, B0); PG8_MMA(1, 1, At, B1); PG8_BAR; PG8_SCHED;
;             PG8_LDB(B0, 1, 0); PG8_LDB(B1, 1, 1); PG8_SCHED; PG8_LDA(At, 1, 0); PG8_STAGE(PG8_SA(0, 1), a2 + hstep, voffA);
;             PG8_WAIT_V(8); PG8_WAIT_L(0); PG8_BAR; PG8_MMA(0, 0, At, B0); PG8_MMA(0, 1, At, B1); PG8_BAR; PG8_SCHED;
	v_mfma_f32_16x16x32_bf16 v[62:65], v[144:147], v[176:179], v[62:65]
	v_mfma_f32_16x16x32_bf16 v[58:61], v[152:155], v[176:179], v[58:61]
	v_mfma_f32_16x16x32_bf16 v[46:49], v[144:147], v[184:187], v[46:49]
	v_mfma_f32_16x16x32_bf16 v[42:45], v[152:155], v[184:187], v[42:45]
	v_mfma_f32_16x16x32_bf16 v[30:33], v[144:147], v[192:195], v[30:33]
	v_mfma_f32_16x16x32_bf16 v[26:29], v[152:155], v[192:195], v[26:29]
	v_mfma_f32_16x16x32_bf16 v[14:17], v[144:147], v[200:203], v[14:17]
	v_mfma_f32_16x16x32_bf16 v[10:13], v[152:155], v[200:203], v[10:13]
	v_mfma_f32_16x16x32_bf16 v[62:65], v[148:151], v[180:183], v[62:65]
	v_mfma_f32_16x16x32_bf16 v[58:61], v[156:159], v[180:183], v[58:61]
	v_mfma_f32_16x16x32_bf16 v[46:49], v[148:151], v[188:191], v[46:49]
	v_mfma_f32_16x16x32_bf16 v[42:45], v[156:159], v[188:191], v[42:45]
	v_mfma_f32_16x16x32_bf16 v[30:33], v[148:151], v[196:199], v[30:33]
	v_mfma_f32_16x16x32_bf16 v[26:29], v[156:159], v[196:199], v[26:29]
	v_mfma_f32_16x16x32_bf16 v[14:17], v[148:151], v[204:207], v[14:17]
	v_mfma_f32_16x16x32_bf16 v[10:13], v[156:159], v[204:207], v[10:13]
	v_mfma_f32_16x16x32_bf16 v[54:57], v[160:163], v[176:179], v[54:57]
	v_mfma_f32_16x16x32_bf16 v[50:53], v[168:171], v[176:179], v[50:53]
	v_mfma_f32_16x16x32_bf16 v[38:41], v[160:163], v[184:187], v[38:41]
	v_mfma_f32_16x16x32_bf16 v[34:37], v[168:171], v[184:187], v[34:37]
	v_mfma_f32_16x16x32_bf16 v[22:25], v[160:163], v[192:195], v[22:25]
	v_mfma_f32_16x16x32_bf16 v[18:21], v[168:171], v[192:195], v[18:21]
	v_mfma_f32_16x16x32_bf16 v[6:9], v[160:163], v[200:203], v[6:9]
	v_mfma_f32_16x16x32_bf16 v[2:5], v[168:171], v[200:203], v[2:5]
	v_mfma_f32_16x16x32_bf16 v[54:57], v[164:167], v[180:183], v[54:57]
	v_mfma_f32_16x16x32_bf16 v[50:53], v[172:175], v[180:183], v[50:53]
	v_mfma_f32_16x16x32_bf16 v[38:41], v[164:167], v[188:191], v[38:41]
	v_mfma_f32_16x16x32_bf16 v[34:37], v[172:175], v[188:191], v[34:37]
	v_mfma_f32_16x16x32_bf16 v[22:25], v[164:167], v[196:199], v[22:25]
	v_mfma_f32_16x16x32_bf16 v[18:21], v[172:175], v[196:199], v[18:21]
	v_mfma_f32_16x16x32_bf16 v[6:9], v[164:167], v[204:207], v[6:9]
	v_mfma_f32_16x16x32_bf16 v[2:5], v[172:175], v[204:207], v[2:5]
	s_barrier
	s_add_i32 s52, 0, 0x18000
	v_add_u32_e32 v143, s52, v140
	s_add_i32 s53, 0, 0x1c000
	ds_read_b128 v[144:147], v143
	ds_read_b128 v[148:151], v143 offset:1024
	ds_read_b128 v[152:155], v143 offset:2048
	ds_read_b128 v[156:159], v143 offset:3072
	v_add_u32_e32 v143, s53, v140
	ds_read_b128 v[160:163], v143
	ds_read_b128 v[164:167], v143 offset:1024
	ds_read_b128 v[168:171], v143 offset:2048
	ds_read_b128 v[172:175], v143 offset:3072
	s_add_u32 s50, s50, 0x80000
	s_addc_u32 s51, s51, 0
	s_mov_b32 m0, s69
	v_lshl_add_u64 v[222:223], s[50:51], 0, v[132:133]
	ds_read_b128 v[176:179], v142 offset:32768
	ds_read_b128 v[180:183], v142 offset:33792
	ds_read_b128 v[184:187], v142 offset:34816
	ds_read_b128 v[188:191], v142 offset:35840
	ds_read_b128 v[192:195], v142 offset:36864
	ds_read_b128 v[196:199], v142 offset:37888
	ds_read_b128 v[200:203], v142 offset:38912
	ds_read_b128 v[204:207], v142 offset:39936
	global_load_lds_dwordx4 v[222:223], off
	v_lshl_add_u64 v[222:223], s[50:51], 0, v[134:135]
	s_mov_b32 m0, s70
	s_nop 0
	global_load_lds_dwordx4 v[222:223], off
	s_setprio 0
	s_setprio 1
	s_setprio 0
	s_waitcnt lgkmcnt(0)
	s_setprio 1
	s_waitcnt vmcnt(8)
	s_waitcnt lgkmcnt(0)
	s_barrier
	v_mfma_f32_16x16x32_bf16 v[128:131], v[144:147], v[176:179], v[128:131]
	v_mfma_f32_16x16x32_bf16 v[124:127], v[152:155], v[176:179], v[124:127]
	v_mfma_f32_16x16x32_bf16 v[112:115], v[144:147], v[184:187], v[112:115]
	v_mfma_f32_16x16x32_bf16 v[108:111], v[152:155], v[184:187], v[108:111]
	v_mfma_f32_16x16x32_bf16 v[96:99], v[144:147], v[192:195], v[96:99]
	v_mfma_f32_16x16x32_bf16 v[92:95], v[152:155], v[192:195], v[92:95]
	v_mfma_f32_16x16x32_bf16 v[80:83], v[144:147], v[200:203], v[80:83]
	v_mfma_f32_16x16x32_bf16 v[76:79], v[152:155], v[200:203], v[76:79]
	v_mfma_f32_16x16x32_bf16 v[128:131], v[148:151], v[180:183], v[128:131]
	v_mfma_f32_16x16x32_bf16 v[124:127], v[156:159], v[180:183], v[124:127]
	v_mfma_f32_16x16x32_bf16 v[112:115], v[148:151], v[188:191], v[112:115]
	v_mfma_f32_16x16x32_bf16 v[108:111], v[156:159], v[188:191], v[108:111]
	v_mfma_f32_16x16x32_bf16 v[96:99], v[148:151], v[196:199], v[96:99]
	v_mfma_f32_16x16x32_bf16 v[92:95], v[156:159], v[196:199], v[92:95]
	v_mfma_f32_16x16x32_bf16 v[80:83], v[148:151], v[204:207], v[80:83]
	v_mfma_f32_16x16x32_bf16 v[76:79], v[156:159], v[204:207], v[76:79]
	v_mfma_f32_16x16x32_bf16 v[120:123], v[160:163], v[176:179], v[120:123]
	v_mfma_f32_16x16x32_bf16 v[116:119], v[168:171], v[176:179], v[116:119]
	v_mfma_f32_16x16x32_bf16 v[104:107], v[160:163], v[184:187], v[104:107]
	v_mfma_f32_16x16x32_bf16 v[100:103], v[168:171], v[184:187], v[100:103]
	v_mfma_f32_16x16x32_bf16 v[88:91], v[160:163], v[192:195], v[88:91]
	v_mfma_f32_16x16x32_bf16 v[84:87], v[168:171], v[192:195], v[84:87]
	v_mfma_f32_16x16x32_bf16 v[72:75], v[160:163], v[200:203], v[72:75]
	v_mfma_f32_16x16x32_bf16 v[68:71], v[168:171], v[200:203], v[68:71]
	v_mfma_f32_16x16x32_bf16 v[120:123], v[164:167], v[180:183], v[120:123]
	v_mfma_f32_16x16x32_bf16 v[116:119], v[172:175], v[180:183], v[116:119]
	v_mfma_f32_16x16x32_bf16 v[104:107], v[164:167], v[188:191], v[104:107]
	v_mfma_f32_16x16x32_bf16 v[100:103], v[172:175], v[188:191], v[100:103]
	v_mfma_f32_16x16x32_bf16 v[88:91], v[164:167], v[196:199], v[88:91]
	v_mfma_f32_16x16x32_bf16 v[84:87], v[172:175], v[196:199], v[84:87]
	v_mfma_f32_16x16x32_bf16 v[72:75], v[164:167], v[204:207], v[72:75]
	v_mfma_f32_16x16x32_bf16 v[68:71], v[172:175], v[204:207], v[68:71]
	s_barrier
; #define PG8_STAGE(bufoff, gbase, voff) do { _Pragma("unroll") for (int _i = 0; _i < 2; ++_i) \
;         __builtin_amdgcn_global_load_lds((const unsigned*)((const char*)(gbase) + (voff)[_i]), (PG8_LAS unsigned*)(lds + (bufoff) + ldsw + _i * 8192), 16, 0, 0); } while (0)
; #define PG8_LDA(dst, b, h) do { _Pragma("unroll") for (int m = 0; m < 4; ++m) _Pragma("unroll") for (int k = 0; k < 2; ++k) dst[m][k] = *(const PG8_LAS bf16x8*)(lds + PG8_SA(b, h) + aoff + m * 2048 + k * 1024); } while (0)
; #define PG8_MMA(ai, bj, At, Bt) do { __builtin_amdgcn_s_setprio(1); _Pragma("unroll") for (int m = 0; m < 4; ++m) _Pragma("unroll") for (int n = 0; n < 2; ++n) _Pragma("unroll") for (int k = 0; k < 2; ++k) \
;         acc[ai][bj][m][n] = __builtin_amdgcn_mfma_f32_16x16x32_bf16(Bt[n][k], At[m][k], acc[ai][bj][m][n], 0, 0, 0); __builtin_amdgcn_s_setprio(0); } while (0)
; #define PG8_WAIT_V(n) asm volatile("s_waitcnt vmcnt(" #n ")" ::: "memory")
; #define PG8_WAIT_L(n) asm volatile("s_waitcnt lgkmcnt(" #n ")" ::: "memory")
; #define PG8_BAR __builtin_amdgcn_s_barrier()
; #define PG8_SCHED __builtin_amdgcn_sched_barrier(0)
; template <class Epi, class Sched, bool ALIGN_EPI = false, bool SP2 = false>
; __device__ __forceinline__ void gemm_phase(PG8_LAS unsigned char* lds, const Gemm g, const Sched& S, const Epi& E) {
;     ...
;             PG8_LDA(At, 1, 1); PG8_STAGE(PG8_SB(1, 0), b3, voffB); PG8_STAGE(PG8_SB(1, 1), b3 + hstep, voffB); PG8_STAGE(PG8_SA(1, 0), a3, voffA);
;             PG8_WAIT_V(8); PG8_WAIT_L(0); PG8_BAR; PG8_MMA(1, 0, At, B0); PG8_MMA(1, 1, At, B1); PG8_BAR; PG8_SCHED;
	s_add_i32 s50, s52, s39
	v_lshl_add_u64 v[138:139], v[138:139], 0, s[88:89]
	s_mov_b32 m0, s50
	ds_read_b128 v[176:179], v142 offset:49152
	ds_read_b128 v[180:183], v142 offset:50176
	ds_read_b128 v[184:187], v142 offset:51200
	ds_read_b128 v[188:191], v142 offset:52224
	ds_read_b128 v[192:195], v142 offset:53248
	ds_read_b128 v[196:199], v142 offset:54272
	ds_read_b128 v[200:203], v142 offset:55296
	ds_read_b128 v[204:207], v142 offset:56320
	global_load_lds_dwordx4 v[138:139], off
	s_add_i32 m0, s50, 0x2000
	s_add_u32 s48, s48, 0x80080
	v_lshl_add_u64 v[138:139], v[208:209], 0, s[88:89]
	s_addc_u32 s49, s49, 0
	s_add_i32 s50, s53, s39
	global_load_lds_dwordx4 v[138:139], off
	v_lshl_add_u64 v[138:139], s[48:49], 0, v[66:67]
	s_mov_b32 m0, s50
	s_nop 0
	global_load_lds_dwordx4 v[138:139], off
	v_lshl_add_u64 v[138:139], s[48:49], 0, v[136:137]
	s_add_i32 m0, s50, 0x2000
	s_nop 0
	global_load_lds_dwordx4 v[138:139], off
	v_lshl_add_u64 v[138:139], v[210:211], 0, s[88:89]
	s_mov_b32 m0, s71
	s_nop 0
	global_load_lds_dwordx4 v[138:139], off
	v_lshl_add_u64 v[138:139], v[220:221], 0, s[88:89]
	s_mov_b32 m0, s72
	s_nop 0
	global_load_lds_dwordx4 v[138:139], off
	s_setprio 0
	s_setprio 1
	s_setprio 0
	s_waitcnt lgkmcnt(0)
	s_setprio 1
	s_waitcnt vmcnt(8)
	s_waitcnt lgkmcnt(0)
	s_barrier
	v_mfma_f32_16x16x32_bf16 v[62:65], v[144:147], v[176:179], v[62:65]
	v_mfma_f32_16x16x32_bf16 v[58:61], v[152:155], v[176:179], v[58:61]
	v_mfma_f32_16x16x32_bf16 v[46:49], v[144:147], v[184:187], v[46:49]
	v_mfma_f32_16x16x32_bf16 v[42:45], v[152:155], v[184:187], v[42:45]
	v_mfma_f32_16x16x32_bf16 v[30:33], v[144:147], v[192:195], v[30:33]
	v_mfma_f32_16x16x32_bf16 v[26:29], v[152:155], v[192:195], v[26:29]
	v_mfma_f32_16x16x32_bf16 v[14:17], v[144:147], v[200:203], v[14:17]
	v_mfma_f32_16x16x32_bf16 v[10:13], v[152:155], v[200:203], v[10:13]
	v_mfma_f32_16x16x32_bf16 v[62:65], v[148:151], v[180:183], v[62:65]
	v_mfma_f32_16x16x32_bf16 v[58:61], v[156:159], v[180:183], v[58:61]
	v_mfma_f32_16x16x32_bf16 v[46:49], v[148:151], v[188:191], v[46:49]
	v_mfma_f32_16x16x32_bf16 v[42:45], v[156:159], v[188:191], v[42:45]
	v_mfma_f32_16x16x32_bf16 v[30:33], v[148:151], v[196:199], v[30:33]
	v_mfma_f32_16x16x32_bf16 v[26:29], v[156:159], v[196:199], v[26:29]
	v_mfma_f32_16x16x32_bf16 v[14:17], v[148:151], v[204:207], v[14:17]
	v_mfma_f32_16x16x32_bf16 v[10:13], v[156:159], v[204:207], v[10:13]
	v_mfma_f32_16x16x32_bf16 v[54:57], v[160:163], v[176:179], v[54:57]
	v_mfma_f32_16x16x32_bf16 v[50:53], v[168:171], v[176:179], v[50:53]
	v_mfma_f32_16x16x32_bf16 v[38:41], v[160:163], v[184:187], v[38:41]
	v_mfma_f32_16x16x32_bf16 v[34:37], v[168:171], v[184:187], v[34:37]
	v_mfma_f32_16x16x32_bf16 v[22:25], v[160:163], v[192:195], v[22:25]
	v_mfma_f32_16x16x32_bf16 v[18:21], v[168:171], v[192:195], v[18:21]
	v_mfma_f32_16x16x32_bf16 v[6:9], v[160:163], v[200:203], v[6:9]
	v_mfma_f32_16x16x32_bf16 v[2:5], v[168:171], v[200:203], v[2:5]
	v_mfma_f32_16x16x32_bf16 v[54:57], v[164:167], v[180:183], v[54:57]
	v_mfma_f32_16x16x32_bf16 v[50:53], v[172:175], v[180:183], v[50:53]
	v_mfma_f32_16x16x32_bf16 v[38:41], v[164:167], v[188:191], v[38:41]
	v_mfma_f32_16x16x32_bf16 v[34:37], v[172:175], v[188:191], v[34:37]
	v_mfma_f32_16x16x32_bf16 v[22:25], v[164:167], v[196:199], v[22:25]
	v_mfma_f32_16x16x32_bf16 v[18:21], v[172:175], v[196:199], v[18:21]
	v_mfma_f32_16x16x32_bf16 v[6:9], v[164:167], v[204:207], v[6:9]
	v_mfma_f32_16x16x32_bf16 v[2:5], v[172:175], v[204:207], v[2:5]
	s_barrier
	s_setprio 0
	s_setprio 1
	s_setprio 0
	s_waitcnt lgkmcnt(0)
	s_add_i32 s48, s31, 2
	s_cmp_gt_u32 s31, 29
	s_mov_b32 s31, s48
	s_cbranch_scc1 .LBB0_1217

; #define PG8_STAGE(bufoff, gbase, voff) do { _Pragma("unroll") for (int _i = 0; _i < 2; ++_i) \
;         __builtin_amdgcn_global_load_lds((const unsigned*)((const char*)(gbase) + (voff)[_i]), (PG8_LAS unsigned*)(lds + (bufoff) + ldsw + _i * 8192), 16, 0, 0); } while (0)
; #define PG8_LDA(dst, b, h) do { _Pragma("unroll") for (int m = 0; m < 4; ++m) _Pragma("unroll") for (int k = 0; k < 2; ++k) dst[m][k] = *(const PG8_LAS bf16x8*)(lds + PG8_SA(b, h) + aoff + m * 2048 + k * 1024); } while (0)
; #define PG8_LDB(dst, b, h) do { _Pragma("unroll") for (int n = 0; n < 2; ++n) _Pragma("unroll") for (int k = 0; k < 2; ++k) dst[n][k] = *(const PG8_LAS bf16x8*)(lds + PG8_SB(b, h) + boff + n * 2048 + k * 1024); } while (0)
; #define PG8_MMA(ai, bj, At, Bt) do { __builtin_amdgcn_s_setprio(1); _Pragma("unroll") for (int m = 0; m < 4; ++m) _Pragma("unroll") for (int n = 0; n < 2; ++n) _Pragma("unroll") for (int k = 0; k < 2; ++k) \
;         acc[ai][bj][m][n] = __builtin_amdgcn_mfma_f32_16x16x32_bf16(Bt[n][k], At[m][k], acc[ai][bj][m][n], 0, 0, 0); __builtin_amdgcn_s_setprio(0); } while (0)
; #define PG8_WAIT_V(n) asm volatile("s_waitcnt vmcnt(" #n ")" ::: "memory")
; #define PG8_WAIT_L(n) asm volatile("s_waitcnt lgkmcnt(" #n ")" ::: "memory")
; #define PG8_BAR __builtin_amdgcn_s_barrier()
; template <class Epi, class Sched, bool ALIGN_EPI = false, bool SP2 = false>
; __device__ __forceinline__ void gemm_phase(PG8_LAS unsigned char* lds, const Gemm g, const Sched& S, const Epi& E) {
;     ...
;             const char* a1 = cA + (size_t)(t + 1) * kstep;
;             const char* a2 = last ? nA : cA + (size_t)(t + 2) * kstep; const char* b2 = last ? nB : cB + (size_t)(t + 2) * kstep;
;             const char* a3 = a2 + kstep; const char* b3 = b2 + kstep;
;             if (last && has_next) S.a_ready(nxt);
;             if constexpr (SP2) {
;             PG8_LDB(B0, 0, 0); PG8_LDB(B1, 0, 1); PG8_SCHED; PG8_LDA(At, 0, 0); PG8_STAGE(PG8_SA(1, 1), a1 + hstep, voffA);
;             PG8_WAIT_V(8); PG8_WAIT_L(0); PG8_BAR; PG8_MMA(0, 0, At, B0); PG8_MMA(0, 1, At, B1); PG8_BAR; PG8_SCHED;
;             PG8_LDA(At, 0, 1); PG8_STAGE(PG8_SB(0, 0), b2, voffB); PG8_STAGE(PG8_SB(0, 1), b2 + hstep, voffB); PG8_STAGE(PG8_SA(0, 0), a2, voffA);
;             PG8_WAIT_V(8); PG8_WAIT_L(0); PG8_BAR; PG8_MMA(1, 0, At, B0); PG8_MMA(1, 1, At, B1); PG8_BAR; PG8_SCHED;
.LBB0_1294:
	s_add_u32 s26, s24, 0x100
	s_addc_u32 s27, s25, 0
	s_add_i32 s54, 0, 0x10000
	s_cmpk_eq_i32 s53, 0x54
	s_cselect_b32 s31, s13, s27
	s_cselect_b32 s30, s12, s26
	s_cselect_b32 s29, s23, s3
	s_cselect_b32 s28, s22, s2
	s_add_i32 s55, 0, 0x14000
	v_add_u32_e32 v144, s54, v156
	v_add_u32_e32 v154, s55, v156
	ds_read_b128 v[132:135], v144
	ds_read_b128 v[136:139], v144 offset:1024
	ds_read_b128 v[140:143], v144 offset:2048
	ds_read_b128 v[144:147], v144 offset:3072
	ds_read_b128 v[160:163], v154
	ds_read_b128 v[164:167], v154 offset:1024
	ds_read_b128 v[168:171], v154 offset:2048
	ds_read_b128 v[172:175], v154 offset:3072
	v_lshl_add_u64 v[154:155], s[24:25], 0, v[150:151]
	s_add_i32 m0, s39, 0xc000
	ds_read_b128 v[176:179], v158
	ds_read_b128 v[180:183], v158 offset:1024
	ds_read_b128 v[184:187], v158 offset:2048
	ds_read_b128 v[188:191], v158 offset:3072
	ds_read_b128 v[192:195], v158 offset:4096
	ds_read_b128 v[196:199], v158 offset:5120
	ds_read_b128 v[200:203], v158 offset:6144
	ds_read_b128 v[204:207], v158 offset:7168
	global_load_lds_dwordx4 v[154:155], off
	v_lshl_add_u64 v[154:155], s[24:25], 0, v[152:153]
	s_add_i32 m0, s39, 0xe000
	s_nop 0
	global_load_lds_dwordx4 v[154:155], off
	s_setprio 1
	s_waitcnt vmcnt(8)
	s_waitcnt lgkmcnt(0)
	s_barrier
	v_mfma_f32_16x16x32_bf16 v[128:131], v[132:135], v[176:179], v[128:131]
	v_mfma_f32_16x16x32_bf16 v[124:127], v[140:143], v[176:179], v[124:127]
	v_mfma_f32_16x16x32_bf16 v[120:123], v[132:135], v[184:187], v[120:123]
	v_mfma_f32_16x16x32_bf16 v[112:115], v[140:143], v[184:187], v[112:115]
	v_mfma_f32_16x16x32_bf16 v[104:107], v[132:135], v[192:195], v[104:107]
	v_mfma_f32_16x16x32_bf16 v[96:99], v[140:143], v[192:195], v[96:99]
	v_mfma_f32_16x16x32_bf16 v[88:91], v[132:135], v[200:203], v[88:91]
	v_mfma_f32_16x16x32_bf16 v[76:79], v[140:143], v[200:203], v[76:79]
	v_mfma_f32_16x16x32_bf16 v[128:131], v[136:139], v[180:183], v[128:131]
	v_mfma_f32_16x16x32_bf16 v[124:127], v[144:147], v[180:183], v[124:127]
	v_mfma_f32_16x16x32_bf16 v[120:123], v[136:139], v[188:191], v[120:123]
	v_mfma_f32_16x16x32_bf16 v[112:115], v[144:147], v[188:191], v[112:115]
	v_mfma_f32_16x16x32_bf16 v[104:107], v[136:139], v[196:199], v[104:107]
	v_mfma_f32_16x16x32_bf16 v[96:99], v[144:147], v[196:199], v[96:99]
	v_mfma_f32_16x16x32_bf16 v[88:91], v[136:139], v[204:207], v[88:91]
	v_mfma_f32_16x16x32_bf16 v[76:79], v[144:147], v[204:207], v[76:79]
	v_mfma_f32_16x16x32_bf16 v[116:119], v[160:163], v[176:179], v[116:119]
	v_mfma_f32_16x16x32_bf16 v[108:111], v[168:171], v[176:179], v[108:111]
	v_mfma_f32_16x16x32_bf16 v[100:103], v[160:163], v[184:187], v[100:103]
	v_mfma_f32_16x16x32_bf16 v[92:95], v[168:171], v[184:187], v[92:95]
	v_mfma_f32_16x16x32_bf16 v[84:87], v[160:163], v[192:195], v[84:87]
	v_mfma_f32_16x16x32_bf16 v[80:83], v[168:171], v[192:195], v[80:83]
	v_mfma_f32_16x16x32_bf16 v[72:75], v[160:163], v[200:203], v[72:75]
	v_mfma_f32_16x16x32_bf16 v[68:71], v[168:171], v[200:203], v[68:71]
	v_mfma_f32_16x16x32_bf16 v[116:119], v[164:167], v[180:183], v[116:119]
	v_mfma_f32_16x16x32_bf16 v[108:111], v[172:175], v[180:183], v[108:111]
	v_mfma_f32_16x16x32_bf16 v[100:103], v[164:167], v[188:191], v[100:103]
	v_mfma_f32_16x16x32_bf16 v[92:95], v[172:175], v[188:191], v[92:95]
	v_mfma_f32_16x16x32_bf16 v[84:87], v[164:167], v[196:199], v[84:87]
	v_mfma_f32_16x16x32_bf16 v[80:83], v[172:175], v[196:199], v[80:83]
	v_mfma_f32_16x16x32_bf16 v[72:75], v[164:167], v[204:207], v[72:75]
	v_mfma_f32_16x16x32_bf16 v[68:71], v[172:175], v[204:207], v[68:71]
	s_barrier
	s_add_i32 s24, s54, s38
	v_lshl_add_u64 v[154:155], s[28:29], 0, v[66:67]
	s_mov_b32 m0, s24
	ds_read_b128 v[176:179], v158 offset:16384
	ds_read_b128 v[180:183], v158 offset:17408
	ds_read_b128 v[184:187], v158 offset:18432
	ds_read_b128 v[188:191], v158 offset:19456
	ds_read_b128 v[192:195], v158 offset:20480
	ds_read_b128 v[196:199], v158 offset:21504
	ds_read_b128 v[200:203], v158 offset:22528
	ds_read_b128 v[204:207], v158 offset:23552
	global_load_lds_dwordx4 v[154:155], off
	s_add_i32 m0, s24, 0x2000
	s_add_u32 s24, s28, 0x160000
	v_lshl_add_u64 v[208:209], s[28:29], 0, v[148:149]
	s_addc_u32 s25, s29, 0
	s_add_i32 s54, s55, s38
	global_load_lds_dwordx4 v[208:209], off
	v_lshl_add_u64 v[210:211], s[24:25], 0, v[66:67]
	s_mov_b32 m0, s54
	v_lshl_add_u64 v[220:221], s[30:31], 0, v[148:149]
	global_load_lds_dwordx4 v[210:211], off
	v_lshl_add_u64 v[210:211], s[24:25], 0, v[148:149]
	s_add_i32 m0, s54, 0x2000
	s_nop 0
	global_load_lds_dwordx4 v[210:211], off
	v_lshl_add_u64 v[210:211], s[30:31], 0, v[66:67]
	s_mov_b32 m0, s39
	s_nop 0
	global_load_lds_dwordx4 v[210:211], off
	s_mov_b32 m0, s40
	s_nop 0
	global_load_lds_dwordx4 v[220:221], off
	s_setprio 0
	s_setprio 1
	s_setprio 0
	s_waitcnt lgkmcnt(0)
	s_setprio 1
	s_waitcnt vmcnt(8)
	s_waitcnt lgkmcnt(0)
	s_barrier
; #define PG8_STAGE(bufoff, gbase, voff) do { _Pragma("unroll") for (int _i = 0; _i < 2; ++_i) \
;         __builtin_amdgcn_global_load_lds((const unsigned*)((const char*)(gbase) + (voff)[_i]), (PG8_LAS unsigned*)(lds + (bufoff) + ldsw + _i * 8192), 16, 0, 0); } while (0)
; #define PG8_LDA(dst, b, h) do { _Pragma("unroll") for (int m = 0; m < 4; ++m) _Pragma("unroll") for (int k = 0; k < 2; ++k) dst[m][k] = *(const PG8_LAS bf16x8*)(lds + PG8_SA(b, h) + aoff + m * 2048 + k * 1024); } while (0)
; #define PG8_LDB(dst, b, h) do { _Pragma("unroll") for (int n = 0; n < 2; ++n) _Pragma("unroll") for (int k = 0; k < 2; ++k) dst[n][k] = *(const PG8_LAS bf16x8*)(lds + PG8_SB(b, h) + boff + n * 2048 + k * 1024); } while (0)
; #define PG8_MMA(ai, bj, At, Bt) do { __builtin_amdgcn_s_setprio(1); _Pragma("unroll") for (int m = 0; m < 4; ++m) _Pragma("unroll") for (int n = 0; n < 2; ++n) _Pragma("unroll") for (int k = 0; k < 2; ++k) \
;         acc[ai][bj][m][n] = __builtin_amdgcn_mfma_f32_16x16x32_bf16(Bt[n][k], At[m][k], acc[ai][bj][m][n], 0, 0, 0); __builtin_amdgcn_s_setprio(0); } while (0)
; #define PG8_WAIT_V(n) asm volatile("s_waitcnt vmcnt(" #n ")" ::: "memory")
; #define PG8_WAIT_L(n) asm volatile("s_waitcnt lgkmcnt(" #n ")" ::: "memory")
; #define PG8_BAR __builtin_amdgcn_s_barrier()
; #define PG8_SCHED __builtin_amdgcn_sched_barrier(0)
; template <class Epi, class Sched, bool ALIGN_EPI = false, bool SP2 = false>
; __device__ __forceinline__ void gemm_phase(PG8_LAS unsigned char* lds, const Gemm g, const Sched& S, const Epi& E) {
;     ...
;             PG8_WAIT_V(8); PG8_WAIT_L(0); PG8_BAR; PG8_MMA(1, 0, At, B0); PG8_MMA(1, 1, At, B1); PG8_BAR; PG8_SCHED;
;             PG8_LDB(B0, 1, 0); PG8_LDB(B1, 1, 1); PG8_SCHED; PG8_LDA(At, 1, 0); PG8_STAGE(PG8_SA(0, 1), a2 + hstep, voffA);
;             PG8_WAIT_V(8); PG8_WAIT_L(0); PG8_BAR; PG8_MMA(0, 0, At, B0); PG8_MMA(0, 1, At, B1); PG8_BAR; PG8_SCHED;
	v_mfma_f32_16x16x32_bf16 v[62:65], v[132:135], v[176:179], v[62:65]
	v_mfma_f32_16x16x32_bf16 v[58:61], v[140:143], v[176:179], v[58:61]
	v_mfma_f32_16x16x32_bf16 v[54:57], v[132:135], v[184:187], v[54:57]
	v_mfma_f32_16x16x32_bf16 v[46:49], v[140:143], v[184:187], v[46:49]
	v_mfma_f32_16x16x32_bf16 v[38:41], v[132:135], v[192:195], v[38:41]
	v_mfma_f32_16x16x32_bf16 v[30:33], v[140:143], v[192:195], v[30:33]
	v_mfma_f32_16x16x32_bf16 v[22:25], v[132:135], v[200:203], v[22:25]
	v_mfma_f32_16x16x32_bf16 v[10:13], v[140:143], v[200:203], v[10:13]
	v_mfma_f32_16x16x32_bf16 v[62:65], v[136:139], v[180:183], v[62:65]
	v_mfma_f32_16x16x32_bf16 v[58:61], v[144:147], v[180:183], v[58:61]
	v_mfma_f32_16x16x32_bf16 v[54:57], v[136:139], v[188:191], v[54:57]
	v_mfma_f32_16x16x32_bf16 v[46:49], v[144:147], v[188:191], v[46:49]
	v_mfma_f32_16x16x32_bf16 v[38:41], v[136:139], v[196:199], v[38:41]
	v_mfma_f32_16x16x32_bf16 v[30:33], v[144:147], v[196:199], v[30:33]
	v_mfma_f32_16x16x32_bf16 v[22:25], v[136:139], v[204:207], v[22:25]
	v_mfma_f32_16x16x32_bf16 v[10:13], v[144:147], v[204:207], v[10:13]
	v_mfma_f32_16x16x32_bf16 v[50:53], v[160:163], v[176:179], v[50:53]
	v_mfma_f32_16x16x32_bf16 v[42:45], v[168:171], v[176:179], v[42:45]
	v_mfma_f32_16x16x32_bf16 v[34:37], v[160:163], v[184:187], v[34:37]
	v_mfma_f32_16x16x32_bf16 v[26:29], v[168:171], v[184:187], v[26:29]
	v_mfma_f32_16x16x32_bf16 v[18:21], v[160:163], v[192:195], v[18:21]
	v_mfma_f32_16x16x32_bf16 v[14:17], v[168:171], v[192:195], v[14:17]
	v_mfma_f32_16x16x32_bf16 v[6:9], v[160:163], v[200:203], v[6:9]
	v_mfma_f32_16x16x32_bf16 v[2:5], v[168:171], v[200:203], v[2:5]
	v_mfma_f32_16x16x32_bf16 v[50:53], v[164:167], v[180:183], v[50:53]
	v_mfma_f32_16x16x32_bf16 v[42:45], v[172:175], v[180:183], v[42:45]
	v_mfma_f32_16x16x32_bf16 v[34:37], v[164:167], v[188:191], v[34:37]
	v_mfma_f32_16x16x32_bf16 v[26:29], v[172:175], v[188:191], v[26:29]
	v_mfma_f32_16x16x32_bf16 v[18:21], v[164:167], v[196:199], v[18:21]
	v_mfma_f32_16x16x32_bf16 v[14:17], v[172:175], v[196:199], v[14:17]
	v_mfma_f32_16x16x32_bf16 v[6:9], v[164:167], v[204:207], v[6:9]
	v_mfma_f32_16x16x32_bf16 v[2:5], v[172:175], v[204:207], v[2:5]
	s_barrier
	s_add_i32 s54, 0, 0x18000
	s_add_i32 s55, 0, 0x1c000
	v_add_u32_e32 v144, s54, v156
	v_add_u32_e32 v159, s55, v156
	ds_read_b128 v[132:135], v144
	ds_read_b128 v[136:139], v144 offset:1024
	ds_read_b128 v[140:143], v144 offset:2048
	ds_read_b128 v[144:147], v144 offset:3072
	ds_read_b128 v[160:163], v159
	ds_read_b128 v[164:167], v159 offset:1024
	ds_read_b128 v[168:171], v159 offset:2048
	ds_read_b128 v[172:175], v159 offset:3072
	s_add_u32 s24, s30, 0x160000
	s_addc_u32 s25, s31, 0
	s_mov_b32 m0, s41
	v_lshl_add_u64 v[222:223], s[24:25], 0, v[66:67]
	ds_read_b128 v[176:179], v158 offset:32768
	ds_read_b128 v[180:183], v158 offset:33792
	ds_read_b128 v[184:187], v158 offset:34816
	ds_read_b128 v[188:191], v158 offset:35840
	ds_read_b128 v[192:195], v158 offset:36864
	ds_read_b128 v[196:199], v158 offset:37888
	ds_read_b128 v[200:203], v158 offset:38912
	ds_read_b128 v[204:207], v158 offset:39936
	global_load_lds_dwordx4 v[222:223], off
	v_lshl_add_u64 v[222:223], s[24:25], 0, v[148:149]
	s_mov_b32 m0, s42
	s_nop 0
	global_load_lds_dwordx4 v[222:223], off
	s_setprio 0
	s_setprio 1
	s_setprio 0
	s_waitcnt lgkmcnt(0)
	s_setprio 1
	s_waitcnt vmcnt(8)
	s_waitcnt lgkmcnt(0)
	s_barrier
	v_mfma_f32_16x16x32_bf16 v[128:131], v[132:135], v[176:179], v[128:131]
	v_mfma_f32_16x16x32_bf16 v[124:127], v[140:143], v[176:179], v[124:127]
	v_mfma_f32_16x16x32_bf16 v[120:123], v[132:135], v[184:187], v[120:123]
	v_mfma_f32_16x16x32_bf16 v[112:115], v[140:143], v[184:187], v[112:115]
	v_mfma_f32_16x16x32_bf16 v[104:107], v[132:135], v[192:195], v[104:107]
	v_mfma_f32_16x16x32_bf16 v[96:99], v[140:143], v[192:195], v[96:99]
	v_mfma_f32_16x16x32_bf16 v[88:91], v[132:135], v[200:203], v[88:91]
	v_mfma_f32_16x16x32_bf16 v[76:79], v[140:143], v[200:203], v[76:79]
	v_mfma_f32_16x16x32_bf16 v[128:131], v[136:139], v[180:183], v[128:131]
	v_mfma_f32_16x16x32_bf16 v[124:127], v[144:147], v[180:183], v[124:127]
	v_mfma_f32_16x16x32_bf16 v[120:123], v[136:139], v[188:191], v[120:123]
	v_mfma_f32_16x16x32_bf16 v[112:115], v[144:147], v[188:191], v[112:115]
	v_mfma_f32_16x16x32_bf16 v[104:107], v[136:139], v[196:199], v[104:107]
	v_mfma_f32_16x16x32_bf16 v[96:99], v[144:147], v[196:199], v[96:99]
	v_mfma_f32_16x16x32_bf16 v[88:91], v[136:139], v[204:207], v[88:91]
	v_mfma_f32_16x16x32_bf16 v[76:79], v[144:147], v[204:207], v[76:79]
	v_mfma_f32_16x16x32_bf16 v[116:119], v[160:163], v[176:179], v[116:119]
	v_mfma_f32_16x16x32_bf16 v[108:111], v[168:171], v[176:179], v[108:111]
	v_mfma_f32_16x16x32_bf16 v[100:103], v[160:163], v[184:187], v[100:103]
	v_mfma_f32_16x16x32_bf16 v[92:95], v[168:171], v[184:187], v[92:95]
	v_mfma_f32_16x16x32_bf16 v[84:87], v[160:163], v[192:195], v[84:87]
	v_mfma_f32_16x16x32_bf16 v[80:83], v[168:171], v[192:195], v[80:83]
	v_mfma_f32_16x16x32_bf16 v[72:75], v[160:163], v[200:203], v[72:75]
	v_mfma_f32_16x16x32_bf16 v[68:71], v[168:171], v[200:203], v[68:71]
	v_mfma_f32_16x16x32_bf16 v[116:119], v[164:167], v[180:183], v[116:119]
	v_mfma_f32_16x16x32_bf16 v[108:111], v[172:175], v[180:183], v[108:111]
	v_mfma_f32_16x16x32_bf16 v[100:103], v[164:167], v[188:191], v[100:103]
	v_mfma_f32_16x16x32_bf16 v[92:95], v[172:175], v[188:191], v[92:95]
	v_mfma_f32_16x16x32_bf16 v[84:87], v[164:167], v[196:199], v[84:87]
	v_mfma_f32_16x16x32_bf16 v[80:83], v[172:175], v[196:199], v[80:83]
	v_mfma_f32_16x16x32_bf16 v[72:75], v[164:167], v[204:207], v[72:75]
	v_mfma_f32_16x16x32_bf16 v[68:71], v[172:175], v[204:207], v[68:71]
	s_barrier
; #define PG8_STAGE(bufoff, gbase, voff) do { _Pragma("unroll") for (int _i = 0; _i < 2; ++_i) \
;         __builtin_amdgcn_global_load_lds((const unsigned*)((const char*)(gbase) + (voff)[_i]), (PG8_LAS unsigned*)(lds + (bufoff) + ldsw + _i * 8192), 16, 0, 0); } while (0)
; #define PG8_LDA(dst, b, h) do { _Pragma("unroll") for (int m = 0; m < 4; ++m) _Pragma("unroll") for (int k = 0; k < 2; ++k) dst[m][k] = *(const PG8_LAS bf16x8*)(lds + PG8_SA(b, h) + aoff + m * 2048 + k * 1024); } while (0)
; #define PG8_MMA(ai, bj, At, Bt) do { __builtin_amdgcn_s_setprio(1); _Pragma("unroll") for (int m = 0; m < 4; ++m) _Pragma("unroll") for (int n = 0; n < 2; ++n) _Pragma("unroll") for (int k = 0; k < 2; ++k) \
;         acc[ai][bj][m][n] = __builtin_amdgcn_mfma_f32_16x16x32_bf16(Bt[n][k], At[m][k], acc[ai][bj][m][n], 0, 0, 0); __builtin_amdgcn_s_setprio(0); } while (0)
; #define PG8_WAIT_V(n) asm volatile("s_waitcnt vmcnt(" #n ")" ::: "memory")
; #define PG8_WAIT_L(n) asm volatile("s_waitcnt lgkmcnt(" #n ")" ::: "memory")
; #define PG8_BAR __builtin_amdgcn_s_barrier()
; #define PG8_SCHED __builtin_amdgcn_sched_barrier(0)
; template <class Epi, class Sched, bool ALIGN_EPI = false, bool SP2 = false>
; __device__ __forceinline__ void gemm_phase(PG8_LAS unsigned char* lds, const Gemm g, const Sched& S, const Epi& E) {
;     ...
;             PG8_LDA(At, 1, 1); PG8_STAGE(PG8_SB(1, 0), b3, voffB); PG8_STAGE(PG8_SB(1, 1), b3 + hstep, voffB); PG8_STAGE(PG8_SA(1, 0), a3, voffA);
;             PG8_WAIT_V(8); PG8_WAIT_L(0); PG8_BAR; PG8_MMA(1, 0, At, B0); PG8_MMA(1, 1, At, B1); PG8_BAR; PG8_SCHED;
	s_add_i32 s24, s54, s38
	v_lshl_add_u64 v[154:155], v[154:155], 0, s[88:89]
	s_mov_b32 m0, s24
	ds_read_b128 v[176:179], v158 offset:49152
	ds_read_b128 v[180:183], v158 offset:50176
	ds_read_b128 v[184:187], v158 offset:51200
	ds_read_b128 v[188:191], v158 offset:52224
	ds_read_b128 v[192:195], v158 offset:53248
	ds_read_b128 v[196:199], v158 offset:54272
	ds_read_b128 v[200:203], v158 offset:55296
	ds_read_b128 v[204:207], v158 offset:56320
	global_load_lds_dwordx4 v[154:155], off
	s_add_i32 m0, s24, 0x2000
	s_add_u32 s24, s28, 0x160080
	v_lshl_add_u64 v[154:155], v[208:209], 0, s[88:89]
	s_addc_u32 s25, s29, 0
	s_add_i32 s28, s55, s38
	global_load_lds_dwordx4 v[154:155], off
	v_lshl_add_u64 v[154:155], s[24:25], 0, v[66:67]
	s_mov_b32 m0, s28
	s_nop 0
	global_load_lds_dwordx4 v[154:155], off
	v_lshl_add_u64 v[154:155], s[24:25], 0, v[148:149]
	s_add_i32 m0, s28, 0x2000
	s_nop 0
	global_load_lds_dwordx4 v[154:155], off
	v_lshl_add_u64 v[154:155], v[210:211], 0, s[88:89]
	s_mov_b32 m0, s45
	s_nop 0
	global_load_lds_dwordx4 v[154:155], off
	v_lshl_add_u64 v[154:155], v[220:221], 0, s[88:89]
	s_mov_b32 m0, s46
	s_nop 0
	global_load_lds_dwordx4 v[154:155], off
	s_setprio 0
	s_setprio 1
	s_setprio 0
	s_waitcnt lgkmcnt(0)
	s_setprio 1
	s_waitcnt vmcnt(8)
	s_waitcnt lgkmcnt(0)
	s_barrier
	v_mfma_f32_16x16x32_bf16 v[62:65], v[132:135], v[176:179], v[62:65]
	v_mfma_f32_16x16x32_bf16 v[58:61], v[140:143], v[176:179], v[58:61]
	v_mfma_f32_16x16x32_bf16 v[54:57], v[132:135], v[184:187], v[54:57]
	v_mfma_f32_16x16x32_bf16 v[46:49], v[140:143], v[184:187], v[46:49]
	v_mfma_f32_16x16x32_bf16 v[38:41], v[132:135], v[192:195], v[38:41]
	v_mfma_f32_16x16x32_bf16 v[30:33], v[140:143], v[192:195], v[30:33]
	v_mfma_f32_16x16x32_bf16 v[22:25], v[132:135], v[200:203], v[22:25]
	v_mfma_f32_16x16x32_bf16 v[10:13], v[140:143], v[200:203], v[10:13]
	v_mfma_f32_16x16x32_bf16 v[62:65], v[136:139], v[180:183], v[62:65]
	v_mfma_f32_16x16x32_bf16 v[58:61], v[144:147], v[180:183], v[58:61]
	v_mfma_f32_16x16x32_bf16 v[54:57], v[136:139], v[188:191], v[54:57]
	v_mfma_f32_16x16x32_bf16 v[46:49], v[144:147], v[188:191], v[46:49]
	v_mfma_f32_16x16x32_bf16 v[38:41], v[136:139], v[196:199], v[38:41]
	v_mfma_f32_16x16x32_bf16 v[30:33], v[144:147], v[196:199], v[30:33]
	v_mfma_f32_16x16x32_bf16 v[22:25], v[136:139], v[204:207], v[22:25]
	v_mfma_f32_16x16x32_bf16 v[10:13], v[144:147], v[204:207], v[10:13]
	v_mfma_f32_16x16x32_bf16 v[50:53], v[160:163], v[176:179], v[50:53]
	v_mfma_f32_16x16x32_bf16 v[42:45], v[168:171], v[176:179], v[42:45]
	v_mfma_f32_16x16x32_bf16 v[34:37], v[160:163], v[184:187], v[34:37]
	v_mfma_f32_16x16x32_bf16 v[26:29], v[168:171], v[184:187], v[26:29]
	v_mfma_f32_16x16x32_bf16 v[18:21], v[160:163], v[192:195], v[18:21]
	v_mfma_f32_16x16x32_bf16 v[14:17], v[168:171], v[192:195], v[14:17]
	v_mfma_f32_16x16x32_bf16 v[6:9], v[160:163], v[200:203], v[6:9]
	v_mfma_f32_16x16x32_bf16 v[2:5], v[168:171], v[200:203], v[2:5]
	v_mfma_f32_16x16x32_bf16 v[50:53], v[164:167], v[180:183], v[50:53]
	v_mfma_f32_16x16x32_bf16 v[42:45], v[172:175], v[180:183], v[42:45]
	v_mfma_f32_16x16x32_bf16 v[34:37], v[164:167], v[188:191], v[34:37]
	v_mfma_f32_16x16x32_bf16 v[26:29], v[172:175], v[188:191], v[26:29]
	v_mfma_f32_16x16x32_bf16 v[18:21], v[164:167], v[196:199], v[18:21]
	v_mfma_f32_16x16x32_bf16 v[14:17], v[172:175], v[196:199], v[14:17]
	v_mfma_f32_16x16x32_bf16 v[6:9], v[164:167], v[204:207], v[6:9]
	v_mfma_f32_16x16x32_bf16 v[2:5], v[172:175], v[204:207], v[2:5]
	s_barrier
	s_setprio 0
	s_setprio 1
	s_setprio 0
	s_waitcnt lgkmcnt(0)
	s_add_i32 s53, s53, 2
	s_add_u32 s2, s2, 0x100
	s_addc_u32 s3, s3, 0
	s_cmpk_gt_u32 s53, 0x55
	s_mov_b64 s[24:25], s[26:27]
	s_cbranch_scc0 .LBB0_1294
	s_and_b64 vcc, exec, s[20:21]
	s_cbranch_vccz .LBB0_1297
	s_barrier

; #define PG8_STAGE(bufoff, gbase, voff) do { _Pragma("unroll") for (int _i = 0; _i < 2; ++_i) \
;         __builtin_amdgcn_global_load_lds((const unsigned*)((const char*)(gbase) + (voff)[_i]), (PG8_LAS unsigned*)(lds + (bufoff) + ldsw + _i * 8192), 16, 0, 0); } while (0)
; #define PG8_LDA(dst, b, h) do { _Pragma("unroll") for (int m = 0; m < 4; ++m) _Pragma("unroll") for (int k = 0; k < 2; ++k) dst[m][k] = *(const PG8_LAS bf16x8*)(lds + PG8_SA(b, h) + aoff + m * 2048 + k * 1024); } while (0)
; #define PG8_LDB(dst, b, h) do { _Pragma("unroll") for (int n = 0; n < 2; ++n) _Pragma("unroll") for (int k = 0; k < 2; ++k) dst[n][k] = *(const PG8_LAS bf16x8*)(lds + PG8_SB(b, h) + boff + n * 2048 + k * 1024); } while (0)
; #define PG8_MMA(ai, bj, At, Bt) do { __builtin_amdgcn_s_setprio(1); _Pragma("unroll") for (int m = 0; m < 4; ++m) _Pragma("unroll") for (int n = 0; n < 2; ++n) _Pragma("unroll") for (int k = 0; k < 2; ++k) \
;         acc[ai][bj][m][n] = __builtin_amdgcn_mfma_f32_16x16x32_bf16(Bt[n][k], At[m][k], acc[ai][bj][m][n], 0, 0, 0); __builtin_amdgcn_s_setprio(0); } while (0)
; #define PG8_WAIT_V(n) asm volatile("s_waitcnt vmcnt(" #n ")" ::: "memory")
; #define PG8_WAIT_L(n) asm volatile("s_waitcnt lgkmcnt(" #n ")" ::: "memory")
; #define PG8_BAR __builtin_amdgcn_s_barrier()
; template <class Epi, class Sched, bool ALIGN_EPI = false, bool SP2 = false>
; __device__ __forceinline__ void gemm_phase(PG8_LAS unsigned char* lds, const Gemm g, const Sched& S, const Epi& E) {
;     ...
;             const char* a1 = cA + (size_t)(t + 1) * kstep;
;             const char* a2 = last ? nA : cA + (size_t)(t + 2) * kstep; const char* b2 = last ? nB : cB + (size_t)(t + 2) * kstep;
;             const char* a3 = a2 + kstep; const char* b3 = b2 + kstep;
;             if (last && has_next) S.a_ready(nxt);
;             if constexpr (SP2) {
;             PG8_LDB(B0, 0, 0); PG8_LDB(B1, 0, 1); PG8_SCHED; PG8_LDA(At, 0, 0); PG8_STAGE(PG8_SA(1, 1), a1 + hstep, voffA);
;             PG8_WAIT_V(8); PG8_WAIT_L(0); PG8_BAR; PG8_MMA(0, 0, At, B0); PG8_MMA(0, 1, At, B1); PG8_BAR; PG8_SCHED;
;             PG8_LDA(At, 0, 1); PG8_STAGE(PG8_SB(0, 0), b2, voffB); PG8_STAGE(PG8_SB(0, 1), b2 + hstep, voffB); PG8_STAGE(PG8_SA(0, 0), a2, voffA);
;             PG8_WAIT_V(8); PG8_WAIT_L(0); PG8_BAR; PG8_MMA(1, 0, At, B0); PG8_MMA(1, 1, At, B1); PG8_BAR; PG8_SCHED;
.LBB0_1324:
	s_add_u32 s28, s22, s26
	s_addc_u32 s29, s23, s27
	s_add_u32 s28, s28, 0x100
	s_addc_u32 s29, s29, 0
	s_add_u32 s54, s3, s26
	s_addc_u32 s55, s52, s27
	s_add_i32 s56, 0, 0x10000
	s_cmpk_eq_i32 s26, 0x2b00
	s_cselect_b32 s31, s25, s29
	s_cselect_b32 s30, s24, s28
	s_cselect_b32 s29, s13, s55
	s_cselect_b32 s28, s12, s54
	s_add_i32 s57, 0, 0x14000
	v_add_u32_e32 v156, s56, v142
	v_add_u32_e32 v172, s57, v142
	ds_read_b128 v[144:147], v156
	ds_read_b128 v[148:151], v156 offset:1024
	ds_read_b128 v[152:155], v156 offset:2048
	ds_read_b128 v[156:159], v156 offset:3072
	ds_read_b128 v[160:163], v172
	ds_read_b128 v[164:167], v172 offset:1024
	ds_read_b128 v[168:171], v172 offset:2048
	ds_read_b128 v[172:175], v172 offset:3072
	v_lshl_add_u64 v[208:209], v[138:139], 0, s[26:27]
	s_add_i32 m0, s43, 0xc000
	ds_read_b128 v[176:179], v143
	ds_read_b128 v[180:183], v143 offset:1024
	ds_read_b128 v[184:187], v143 offset:2048
	ds_read_b128 v[188:191], v143 offset:3072
	ds_read_b128 v[192:195], v143 offset:4096
	ds_read_b128 v[196:199], v143 offset:5120
	ds_read_b128 v[200:203], v143 offset:6144
	ds_read_b128 v[204:207], v143 offset:7168
	global_load_lds_dwordx4 v[208:209], off
	v_lshl_add_u64 v[208:209], v[140:141], 0, s[26:27]
	s_add_i32 m0, s43, 0xe000
	s_nop 0
	global_load_lds_dwordx4 v[208:209], off
	s_setprio 1
	s_waitcnt vmcnt(8)
	s_waitcnt lgkmcnt(0)
	s_barrier
	v_mfma_f32_16x16x32_bf16 v[128:131], v[144:147], v[176:179], v[128:131]
	v_mfma_f32_16x16x32_bf16 v[124:127], v[152:155], v[176:179], v[124:127]
	v_mfma_f32_16x16x32_bf16 v[112:115], v[144:147], v[184:187], v[112:115]
	v_mfma_f32_16x16x32_bf16 v[104:107], v[152:155], v[184:187], v[104:107]
	v_mfma_f32_16x16x32_bf16 v[96:99], v[144:147], v[192:195], v[96:99]
	v_mfma_f32_16x16x32_bf16 v[88:91], v[152:155], v[192:195], v[88:91]
	v_mfma_f32_16x16x32_bf16 v[80:83], v[144:147], v[200:203], v[80:83]
	v_mfma_f32_16x16x32_bf16 v[72:75], v[152:155], v[200:203], v[72:75]
	v_mfma_f32_16x16x32_bf16 v[128:131], v[148:151], v[180:183], v[128:131]
	v_mfma_f32_16x16x32_bf16 v[124:127], v[156:159], v[180:183], v[124:127]
	v_mfma_f32_16x16x32_bf16 v[112:115], v[148:151], v[188:191], v[112:115]
	v_mfma_f32_16x16x32_bf16 v[104:107], v[156:159], v[188:191], v[104:107]
	v_mfma_f32_16x16x32_bf16 v[96:99], v[148:151], v[196:199], v[96:99]
	v_mfma_f32_16x16x32_bf16 v[88:91], v[156:159], v[196:199], v[88:91]
	v_mfma_f32_16x16x32_bf16 v[80:83], v[148:151], v[204:207], v[80:83]
	v_mfma_f32_16x16x32_bf16 v[72:75], v[156:159], v[204:207], v[72:75]
	v_mfma_f32_16x16x32_bf16 v[116:119], v[160:163], v[176:179], v[116:119]
	v_mfma_f32_16x16x32_bf16 v[108:111], v[168:171], v[176:179], v[108:111]
	v_mfma_f32_16x16x32_bf16 v[100:103], v[160:163], v[184:187], v[100:103]
	v_mfma_f32_16x16x32_bf16 v[92:95], v[168:171], v[184:187], v[92:95]
	v_mfma_f32_16x16x32_bf16 v[84:87], v[160:163], v[192:195], v[84:87]
	v_mfma_f32_16x16x32_bf16 v[76:79], v[168:171], v[192:195], v[76:79]
	v_mfma_f32_16x16x32_bf16 v[68:71], v[160:163], v[200:203], v[68:71]
	v_mfma_f32_16x16x32_bf16 v[62:65], v[168:171], v[200:203], v[62:65]
	v_mfma_f32_16x16x32_bf16 v[116:119], v[164:167], v[180:183], v[116:119]
	v_mfma_f32_16x16x32_bf16 v[108:111], v[172:175], v[180:183], v[108:111]
	v_mfma_f32_16x16x32_bf16 v[100:103], v[164:167], v[188:191], v[100:103]
	v_mfma_f32_16x16x32_bf16 v[92:95], v[172:175], v[188:191], v[92:95]
	v_mfma_f32_16x16x32_bf16 v[84:87], v[164:167], v[196:199], v[84:87]
	v_mfma_f32_16x16x32_bf16 v[76:79], v[172:175], v[196:199], v[76:79]
	v_mfma_f32_16x16x32_bf16 v[68:71], v[164:167], v[204:207], v[68:71]
	v_mfma_f32_16x16x32_bf16 v[62:65], v[172:175], v[204:207], v[62:65]
	s_barrier
	s_add_i32 s54, s56, s42
	v_lshl_add_u64 v[208:209], s[28:29], 0, v[66:67]
	s_mov_b32 m0, s54
	ds_read_b128 v[176:179], v143 offset:16384
	ds_read_b128 v[180:183], v143 offset:17408
	ds_read_b128 v[184:187], v143 offset:18432
	ds_read_b128 v[188:191], v143 offset:19456
	ds_read_b128 v[192:195], v143 offset:20480
	ds_read_b128 v[196:199], v143 offset:21504
	ds_read_b128 v[200:203], v143 offset:22528
	ds_read_b128 v[204:207], v143 offset:23552
	global_load_lds_dwordx4 v[208:209], off
	s_add_i32 m0, s54, 0x2000
	s_add_u32 s54, s28, 0x160000
	v_lshl_add_u64 v[210:211], s[28:29], 0, v[132:133]
	s_addc_u32 s55, s29, 0
	s_add_i32 s56, s57, s42
	global_load_lds_dwordx4 v[210:211], off
	v_lshl_add_u64 v[220:221], s[54:55], 0, v[66:67]
	s_mov_b32 m0, s56
	v_lshl_add_u64 v[222:223], s[30:31], 0, v[132:133]
	global_load_lds_dwordx4 v[220:221], off
	v_lshl_add_u64 v[220:221], s[54:55], 0, v[132:133]
	s_add_i32 m0, s56, 0x2000
	s_nop 0
	global_load_lds_dwordx4 v[220:221], off
	v_lshl_add_u64 v[220:221], s[30:31], 0, v[66:67]
	s_mov_b32 m0, s43
	s_nop 0
	global_load_lds_dwordx4 v[220:221], off
	s_mov_b32 m0, s44
	s_nop 0
	global_load_lds_dwordx4 v[222:223], off
	s_setprio 0
	s_setprio 1
	s_setprio 0
	s_waitcnt lgkmcnt(0)
	s_setprio 1
	s_waitcnt vmcnt(8)
	s_waitcnt lgkmcnt(0)
	s_barrier
; #define PG8_STAGE(bufoff, gbase, voff) do { _Pragma("unroll") for (int _i = 0; _i < 2; ++_i) \
;         __builtin_amdgcn_global_load_lds((const unsigned*)((const char*)(gbase) + (voff)[_i]), (PG8_LAS unsigned*)(lds + (bufoff) + ldsw + _i * 8192), 16, 0, 0); } while (0)
; #define PG8_LDA(dst, b, h) do { _Pragma("unroll") for (int m = 0; m < 4; ++m) _Pragma("unroll") for (int k = 0; k < 2; ++k) dst[m][k] = *(const PG8_LAS bf16x8*)(lds + PG8_SA(b, h) + aoff + m * 2048 + k * 1024); } while (0)
; #define PG8_LDB(dst, b, h) do { _Pragma("unroll") for (int n = 0; n < 2; ++n) _Pragma("unroll") for (int k = 0; k < 2; ++k) dst[n][k] = *(const PG8_LAS bf16x8*)(lds + PG8_SB(b, h) + boff + n * 2048 + k * 1024); } while (0)
; #define PG8_MMA(ai, bj, At, Bt) do { __builtin_amdgcn_s_setprio(1); _Pragma("unroll") for (int m = 0; m < 4; ++m) _Pragma("unroll") for (int n = 0; n < 2; ++n) _Pragma("unroll") for (int k = 0; k < 2; ++k) \
;         acc[ai][bj][m][n] = __builtin_amdgcn_mfma_f32_16x16x32_bf16(Bt[n][k], At[m][k], acc[ai][bj][m][n], 0, 0, 0); __builtin_amdgcn_s_setprio(0); } while (0)
; #define PG8_WAIT_V(n) asm volatile("s_waitcnt vmcnt(" #n ")" ::: "memory")
; #define PG8_WAIT_L(n) asm volatile("s_waitcnt lgkmcnt(" #n ")" ::: "memory")
; #define PG8_BAR __builtin_amdgcn_s_barrier()
; #define PG8_SCHED __builtin_amdgcn_sched_barrier(0)
; template <class Epi, class Sched, bool ALIGN_EPI = false, bool SP2 = false>
; __device__ __forceinline__ void gemm_phase(PG8_LAS unsigned char* lds, const Gemm g, const Sched& S, const Epi& E) {
;     ...
;             PG8_WAIT_V(8); PG8_WAIT_L(0); PG8_BAR; PG8_MMA(1, 0, At, B0); PG8_MMA(1, 1, At, B1); PG8_BAR; PG8_SCHED;
;             PG8_LDB(B0, 1, 0); PG8_LDB(B1, 1, 1); PG8_SCHED; PG8_LDA(At, 1, 0); PG8_STAGE(PG8_SA(0, 1), a2 + hstep, voffA);
;             PG8_WAIT_V(8); PG8_WAIT_L(0); PG8_BAR; PG8_MMA(0, 0, At, B0); PG8_MMA(0, 1, At, B1); PG8_BAR; PG8_SCHED;
	v_mfma_f32_16x16x32_bf16 v[58:61], v[144:147], v[176:179], v[58:61]
	v_mfma_f32_16x16x32_bf16 v[54:57], v[152:155], v[176:179], v[54:57]
	v_mfma_f32_16x16x32_bf16 v[46:49], v[144:147], v[184:187], v[46:49]
	v_mfma_f32_16x16x32_bf16 v[38:41], v[152:155], v[184:187], v[38:41]
	v_mfma_f32_16x16x32_bf16 v[30:33], v[144:147], v[192:195], v[30:33]
	v_mfma_f32_16x16x32_bf16 v[22:25], v[152:155], v[192:195], v[22:25]
	v_mfma_f32_16x16x32_bf16 v[120:123], v[144:147], v[200:203], v[120:123]
	v_mfma_f32_16x16x32_bf16 v[10:13], v[152:155], v[200:203], v[10:13]
	v_mfma_f32_16x16x32_bf16 v[58:61], v[148:151], v[180:183], v[58:61]
	v_mfma_f32_16x16x32_bf16 v[54:57], v[156:159], v[180:183], v[54:57]
	v_mfma_f32_16x16x32_bf16 v[46:49], v[148:151], v[188:191], v[46:49]
	v_mfma_f32_16x16x32_bf16 v[38:41], v[156:159], v[188:191], v[38:41]
	v_mfma_f32_16x16x32_bf16 v[30:33], v[148:151], v[196:199], v[30:33]
	v_mfma_f32_16x16x32_bf16 v[22:25], v[156:159], v[196:199], v[22:25]
	v_mfma_f32_16x16x32_bf16 v[120:123], v[148:151], v[204:207], v[120:123]
	v_mfma_f32_16x16x32_bf16 v[10:13], v[156:159], v[204:207], v[10:13]
	v_mfma_f32_16x16x32_bf16 v[50:53], v[160:163], v[176:179], v[50:53]
	v_mfma_f32_16x16x32_bf16 v[42:45], v[168:171], v[176:179], v[42:45]
	v_mfma_f32_16x16x32_bf16 v[34:37], v[160:163], v[184:187], v[34:37]
	v_mfma_f32_16x16x32_bf16 v[26:29], v[168:171], v[184:187], v[26:29]
	v_mfma_f32_16x16x32_bf16 v[18:21], v[160:163], v[192:195], v[18:21]
	v_mfma_f32_16x16x32_bf16 v[14:17], v[168:171], v[192:195], v[14:17]
	v_mfma_f32_16x16x32_bf16 v[6:9], v[160:163], v[200:203], v[6:9]
	v_mfma_f32_16x16x32_bf16 v[2:5], v[168:171], v[200:203], v[2:5]
	v_mfma_f32_16x16x32_bf16 v[50:53], v[164:167], v[180:183], v[50:53]
	v_mfma_f32_16x16x32_bf16 v[42:45], v[172:175], v[180:183], v[42:45]
	v_mfma_f32_16x16x32_bf16 v[34:37], v[164:167], v[188:191], v[34:37]
	v_mfma_f32_16x16x32_bf16 v[26:29], v[172:175], v[188:191], v[26:29]
	v_mfma_f32_16x16x32_bf16 v[18:21], v[164:167], v[196:199], v[18:21]
	v_mfma_f32_16x16x32_bf16 v[14:17], v[172:175], v[196:199], v[14:17]
	v_mfma_f32_16x16x32_bf16 v[6:9], v[164:167], v[204:207], v[6:9]
	v_mfma_f32_16x16x32_bf16 v[2:5], v[172:175], v[204:207], v[2:5]
	s_barrier
	s_add_i32 s54, 0, 0x18000
	s_add_i32 s55, 0, 0x1c000
	v_add_u32_e32 v156, s54, v142
	v_add_u32_e32 v172, s55, v142
	ds_read_b128 v[144:147], v156
	ds_read_b128 v[148:151], v156 offset:1024
	ds_read_b128 v[152:155], v156 offset:2048
	ds_read_b128 v[156:159], v156 offset:3072
	ds_read_b128 v[160:163], v172
	ds_read_b128 v[164:167], v172 offset:1024
	ds_read_b128 v[168:171], v172 offset:2048
	ds_read_b128 v[172:175], v172 offset:3072
	s_add_u32 s30, s30, 0x160000
	s_addc_u32 s31, s31, 0
	s_mov_b32 m0, s45
	v_lshl_add_u64 v[224:225], s[30:31], 0, v[66:67]
	ds_read_b128 v[176:179], v143 offset:32768
	ds_read_b128 v[180:183], v143 offset:33792
	ds_read_b128 v[184:187], v143 offset:34816
	ds_read_b128 v[188:191], v143 offset:35840
	ds_read_b128 v[192:195], v143 offset:36864
	ds_read_b128 v[196:199], v143 offset:37888
	ds_read_b128 v[200:203], v143 offset:38912
	ds_read_b128 v[204:207], v143 offset:39936
	global_load_lds_dwordx4 v[224:225], off
	v_lshl_add_u64 v[224:225], s[30:31], 0, v[132:133]
	s_mov_b32 m0, s1
	s_nop 0
	global_load_lds_dwordx4 v[224:225], off
	s_setprio 0
	s_setprio 1
	s_setprio 0
	s_waitcnt lgkmcnt(0)
	s_setprio 1
	s_waitcnt vmcnt(8)
	s_waitcnt lgkmcnt(0)
	s_barrier
	v_mfma_f32_16x16x32_bf16 v[128:131], v[144:147], v[176:179], v[128:131]
	v_mfma_f32_16x16x32_bf16 v[124:127], v[152:155], v[176:179], v[124:127]
	v_mfma_f32_16x16x32_bf16 v[112:115], v[144:147], v[184:187], v[112:115]
	v_mfma_f32_16x16x32_bf16 v[104:107], v[152:155], v[184:187], v[104:107]
	v_mfma_f32_16x16x32_bf16 v[96:99], v[144:147], v[192:195], v[96:99]
	v_mfma_f32_16x16x32_bf16 v[88:91], v[152:155], v[192:195], v[88:91]
	v_mfma_f32_16x16x32_bf16 v[80:83], v[144:147], v[200:203], v[80:83]
	v_mfma_f32_16x16x32_bf16 v[72:75], v[152:155], v[200:203], v[72:75]
	v_mfma_f32_16x16x32_bf16 v[128:131], v[148:151], v[180:183], v[128:131]
	v_mfma_f32_16x16x32_bf16 v[124:127], v[156:159], v[180:183], v[124:127]
	v_mfma_f32_16x16x32_bf16 v[112:115], v[148:151], v[188:191], v[112:115]
	v_mfma_f32_16x16x32_bf16 v[104:107], v[156:159], v[188:191], v[104:107]
	v_mfma_f32_16x16x32_bf16 v[96:99], v[148:151], v[196:199], v[96:99]
	v_mfma_f32_16x16x32_bf16 v[88:91], v[156:159], v[196:199], v[88:91]
	v_mfma_f32_16x16x32_bf16 v[80:83], v[148:151], v[204:207], v[80:83]
	v_mfma_f32_16x16x32_bf16 v[72:75], v[156:159], v[204:207], v[72:75]
	v_mfma_f32_16x16x32_bf16 v[116:119], v[160:163], v[176:179], v[116:119]
	v_mfma_f32_16x16x32_bf16 v[108:111], v[168:171], v[176:179], v[108:111]
	v_mfma_f32_16x16x32_bf16 v[100:103], v[160:163], v[184:187], v[100:103]
	v_mfma_f32_16x16x32_bf16 v[92:95], v[168:171], v[184:187], v[92:95]
	v_mfma_f32_16x16x32_bf16 v[84:87], v[160:163], v[192:195], v[84:87]
	v_mfma_f32_16x16x32_bf16 v[76:79], v[168:171], v[192:195], v[76:79]
	v_mfma_f32_16x16x32_bf16 v[68:71], v[160:163], v[200:203], v[68:71]
	v_mfma_f32_16x16x32_bf16 v[62:65], v[168:171], v[200:203], v[62:65]
	v_mfma_f32_16x16x32_bf16 v[116:119], v[164:167], v[180:183], v[116:119]
	v_mfma_f32_16x16x32_bf16 v[108:111], v[172:175], v[180:183], v[108:111]
	v_mfma_f32_16x16x32_bf16 v[100:103], v[164:167], v[188:191], v[100:103]
	v_mfma_f32_16x16x32_bf16 v[92:95], v[172:175], v[188:191], v[92:95]
	v_mfma_f32_16x16x32_bf16 v[84:87], v[164:167], v[196:199], v[84:87]
	v_mfma_f32_16x16x32_bf16 v[76:79], v[172:175], v[196:199], v[76:79]
	v_mfma_f32_16x16x32_bf16 v[68:71], v[164:167], v[204:207], v[68:71]
	v_mfma_f32_16x16x32_bf16 v[62:65], v[172:175], v[204:207], v[62:65]
	s_barrier
; #define PG8_STAGE(bufoff, gbase, voff) do { _Pragma("unroll") for (int _i = 0; _i < 2; ++_i) \
;         __builtin_amdgcn_global_load_lds((const unsigned*)((const char*)(gbase) + (voff)[_i]), (PG8_LAS unsigned*)(lds + (bufoff) + ldsw + _i * 8192), 16, 0, 0); } while (0)
; #define PG8_LDA(dst, b, h) do { _Pragma("unroll") for (int m = 0; m < 4; ++m) _Pragma("unroll") for (int k = 0; k < 2; ++k) dst[m][k] = *(const PG8_LAS bf16x8*)(lds + PG8_SA(b, h) + aoff + m * 2048 + k * 1024); } while (0)
; #define PG8_MMA(ai, bj, At, Bt) do { __builtin_amdgcn_s_setprio(1); _Pragma("unroll") for (int m = 0; m < 4; ++m) _Pragma("unroll") for (int n = 0; n < 2; ++n) _Pragma("unroll") for (int k = 0; k < 2; ++k) \
;         acc[ai][bj][m][n] = __builtin_amdgcn_mfma_f32_16x16x32_bf16(Bt[n][k], At[m][k], acc[ai][bj][m][n], 0, 0, 0); __builtin_amdgcn_s_setprio(0); } while (0)
; #define PG8_WAIT_V(n) asm volatile("s_waitcnt vmcnt(" #n ")" ::: "memory")
; #define PG8_WAIT_L(n) asm volatile("s_waitcnt lgkmcnt(" #n ")" ::: "memory")
; #define PG8_BAR __builtin_amdgcn_s_barrier()
; #define PG8_SCHED __builtin_amdgcn_sched_barrier(0)
; template <class Epi, class Sched, bool ALIGN_EPI = false, bool SP2 = false>
; __device__ __forceinline__ void gemm_phase(PG8_LAS unsigned char* lds, const Gemm g, const Sched& S, const Epi& E) {
;     ...
;             PG8_LDA(At, 1, 1); PG8_STAGE(PG8_SB(1, 0), b3, voffB); PG8_STAGE(PG8_SB(1, 1), b3 + hstep, voffB); PG8_STAGE(PG8_SA(1, 0), a3, voffA);
;             PG8_WAIT_V(8); PG8_WAIT_L(0); PG8_BAR; PG8_MMA(1, 0, At, B0); PG8_MMA(1, 1, At, B1); PG8_BAR; PG8_SCHED;
;     ...
; #pragma unroll
;         for (int a = 0; a < 2; ++a)
; #pragma unroll
;             for (int b = 0; b < 2; ++b)
; #pragma unroll
;                 for (int m = 0; m < 4; ++m)
; #pragma unroll
;                     for (int n = 0; n < 2; ++n) acc[a][b][m][n] = (f32x4){0.f, 0.f, 0.f, 0.f};
;         cur = nxt; cA = nA; cB = nB; ++ui;
	s_add_i32 s30, s54, s42
	v_lshl_add_u64 v[208:209], v[208:209], 0, s[88:89]
	s_mov_b32 m0, s30
	ds_read_b128 v[176:179], v143 offset:49152
	ds_read_b128 v[180:183], v143 offset:50176
	ds_read_b128 v[184:187], v143 offset:51200
	ds_read_b128 v[188:191], v143 offset:52224
	ds_read_b128 v[192:195], v143 offset:53248
	ds_read_b128 v[196:199], v143 offset:54272
	ds_read_b128 v[200:203], v143 offset:55296
	ds_read_b128 v[204:207], v143 offset:56320
	global_load_lds_dwordx4 v[208:209], off
	s_add_i32 m0, s30, 0x2000
	s_add_u32 s28, s28, 0x160080
	v_lshl_add_u64 v[208:209], v[210:211], 0, s[88:89]
	s_addc_u32 s29, s29, 0
	s_add_i32 s30, s55, s42
	global_load_lds_dwordx4 v[208:209], off
	v_lshl_add_u64 v[208:209], s[28:29], 0, v[66:67]
	s_mov_b32 m0, s30
	s_nop 0
	global_load_lds_dwordx4 v[208:209], off
	v_lshl_add_u64 v[208:209], s[28:29], 0, v[132:133]
	s_add_i32 m0, s30, 0x2000
	s_nop 0
	global_load_lds_dwordx4 v[208:209], off
	v_lshl_add_u64 v[208:209], v[220:221], 0, s[88:89]
	s_mov_b32 m0, s47
	s_nop 0
	global_load_lds_dwordx4 v[208:209], off
	v_lshl_add_u64 v[208:209], v[222:223], 0, s[88:89]
	s_mov_b32 m0, s48
	s_nop 0
	global_load_lds_dwordx4 v[208:209], off
	s_setprio 0
	s_setprio 1
	s_setprio 0
	s_waitcnt lgkmcnt(0)
	s_setprio 1
	s_waitcnt vmcnt(8)
	s_waitcnt lgkmcnt(0)
	s_barrier
	v_mfma_f32_16x16x32_bf16 v[58:61], v[144:147], v[176:179], v[58:61]
	v_mfma_f32_16x16x32_bf16 v[54:57], v[152:155], v[176:179], v[54:57]
	v_mfma_f32_16x16x32_bf16 v[46:49], v[144:147], v[184:187], v[46:49]
	v_mfma_f32_16x16x32_bf16 v[38:41], v[152:155], v[184:187], v[38:41]
	v_mfma_f32_16x16x32_bf16 v[30:33], v[144:147], v[192:195], v[30:33]
	v_mfma_f32_16x16x32_bf16 v[22:25], v[152:155], v[192:195], v[22:25]
	v_mfma_f32_16x16x32_bf16 v[120:123], v[144:147], v[200:203], v[120:123]
	v_mfma_f32_16x16x32_bf16 v[10:13], v[152:155], v[200:203], v[10:13]
	v_mfma_f32_16x16x32_bf16 v[58:61], v[148:151], v[180:183], v[58:61]
	v_mfma_f32_16x16x32_bf16 v[54:57], v[156:159], v[180:183], v[54:57]
	v_mfma_f32_16x16x32_bf16 v[46:49], v[148:151], v[188:191], v[46:49]
	v_mfma_f32_16x16x32_bf16 v[38:41], v[156:159], v[188:191], v[38:41]
	v_mfma_f32_16x16x32_bf16 v[30:33], v[148:151], v[196:199], v[30:33]
	v_mfma_f32_16x16x32_bf16 v[22:25], v[156:159], v[196:199], v[22:25]
	v_mfma_f32_16x16x32_bf16 v[120:123], v[148:151], v[204:207], v[120:123]
	v_mfma_f32_16x16x32_bf16 v[10:13], v[156:159], v[204:207], v[10:13]
	v_mfma_f32_16x16x32_bf16 v[50:53], v[160:163], v[176:179], v[50:53]
	v_mfma_f32_16x16x32_bf16 v[42:45], v[168:171], v[176:179], v[42:45]
	v_mfma_f32_16x16x32_bf16 v[34:37], v[160:163], v[184:187], v[34:37]
	v_mfma_f32_16x16x32_bf16 v[26:29], v[168:171], v[184:187], v[26:29]
	v_mfma_f32_16x16x32_bf16 v[18:21], v[160:163], v[192:195], v[18:21]
	v_mfma_f32_16x16x32_bf16 v[14:17], v[168:171], v[192:195], v[14:17]
	v_mfma_f32_16x16x32_bf16 v[6:9], v[160:163], v[200:203], v[6:9]
	v_mfma_f32_16x16x32_bf16 v[2:5], v[168:171], v[200:203], v[2:5]
	v_mfma_f32_16x16x32_bf16 v[50:53], v[164:167], v[180:183], v[50:53]
	v_mfma_f32_16x16x32_bf16 v[42:45], v[172:175], v[180:183], v[42:45]
	v_mfma_f32_16x16x32_bf16 v[34:37], v[164:167], v[188:191], v[34:37]
	v_mfma_f32_16x16x32_bf16 v[26:29], v[172:175], v[188:191], v[26:29]
	v_mfma_f32_16x16x32_bf16 v[18:21], v[164:167], v[196:199], v[18:21]
	v_mfma_f32_16x16x32_bf16 v[14:17], v[172:175], v[196:199], v[14:17]
	v_mfma_f32_16x16x32_bf16 v[6:9], v[164:167], v[204:207], v[6:9]
	v_mfma_f32_16x16x32_bf16 v[2:5], v[172:175], v[204:207], v[2:5]
	s_barrier
	s_setprio 0
	s_setprio 1
	s_setprio 0
	s_waitcnt lgkmcnt(0)
	s_add_i32 s53, s53, 2
	s_add_u32 s26, s26, 0x100
	s_addc_u32 s27, s27, 0
	s_cmpk_gt_u32 s53, 0x55
	s_cbranch_scc0 .LBB0_1324
	s_add_u32 s26, s3, 0xffffff00
	s_addc_u32 s27, s52, -1
	s_and_b64 vcc, exec, s[10:11]
	s_cbranch_vccnz .LBB0_1311
	v_mov_b32_e32 v2, 0
	s_mov_b32 s20, s50
	s_mov_b32 s40, s51
	s_mov_b64 s[22:23], s[24:25]
	s_mov_b32 s49, s2
	v_mov_b32_e32 v3, v2
	v_mov_b32_e32 v4, v2
	v_mov_b32_e32 v5, v2
	v_mov_b32_e32 v6, v2
	v_mov_b32_e32 v7, v2
	v_mov_b32_e32 v8, v2
	v_mov_b32_e32 v9, v2
	v_mov_b32_e32 v14, v2
	v_mov_b32_e32 v15, v2
	v_mov_b32_e32 v16, v2
	v_mov_b32_e32 v17, v2
	v_mov_b32_e32 v18, v2
	v_mov_b32_e32 v19, v2
	v_mov_b32_e32 v20, v2
	v_mov_b32_e32 v21, v2
	v_mov_b32_e32 v26, v2
	v_mov_b32_e32 v27, v2
	v_mov_b32_e32 v28, v2
	v_mov_b32_e32 v29, v2
	v_mov_b32_e32 v34, v2
	v_mov_b32_e32 v35, v2
	v_mov_b32_e32 v36, v2
	v_mov_b32_e32 v37, v2
	v_mov_b32_e32 v42, v2
	v_mov_b32_e32 v43, v2
	v_mov_b32_e32 v44, v2
	v_mov_b32_e32 v45, v2
	v_mov_b32_e32 v50, v2
	v_mov_b32_e32 v51, v2
	v_mov_b32_e32 v52, v2
	v_mov_b32_e32 v53, v2
	v_mov_b32_e32 v10, v2
	v_mov_b32_e32 v11, v2
	v_mov_b32_e32 v12, v2
	v_mov_b32_e32 v13, v2
	v_mov_b32_e32 v120, v2
	v_mov_b32_e32 v121, v2
	v_mov_b32_e32 v122, v2
	v_mov_b32_e32 v123, v2
	v_mov_b32_e32 v22, v2
	v_mov_b32_e32 v23, v2
	v_mov_b32_e32 v24, v2
	v_mov_b32_e32 v25, v2
	v_mov_b32_e32 v30, v2
	v_mov_b32_e32 v31, v2
	v_mov_b32_e32 v32, v2
	v_mov_b32_e32 v33, v2
	v_mov_b32_e32 v38, v2
	v_mov_b32_e32 v39, v2
	v_mov_b32_e32 v40, v2
	v_mov_b32_e32 v41, v2
	v_mov_b32_e32 v46, v2
	v_mov_b32_e32 v47, v2
	v_mov_b32_e32 v48, v2
	v_mov_b32_e32 v49, v2
	v_mov_b32_e32 v54, v2
	v_mov_b32_e32 v55, v2
	v_mov_b32_e32 v56, v2
	v_mov_b32_e32 v57, v2
	v_mov_b32_e32 v58, v2
	v_mov_b32_e32 v59, v2
	v_mov_b32_e32 v60, v2
	v_mov_b32_e32 v61, v2
	v_mov_b32_e32 v62, v2
	v_mov_b32_e32 v63, v2
	v_mov_b32_e32 v64, v2
	v_mov_b32_e32 v65, v2
	v_mov_b32_e32 v68, v2
	v_mov_b32_e32 v69, v2
	v_mov_b32_e32 v70, v2
	v_mov_b32_e32 v71, v2
	v_mov_b32_e32 v76, v2
	v_mov_b32_e32 v77, v2
	v_mov_b32_e32 v78, v2
	v_mov_b32_e32 v79, v2
	v_mov_b32_e32 v84, v2
	v_mov_b32_e32 v85, v2
	v_mov_b32_e32 v86, v2
	v_mov_b32_e32 v87, v2
	v_mov_b32_e32 v92, v2
	v_mov_b32_e32 v93, v2
	v_mov_b32_e32 v94, v2
	v_mov_b32_e32 v95, v2
	v_mov_b32_e32 v100, v2
	v_mov_b32_e32 v101, v2
	v_mov_b32_e32 v102, v2
	v_mov_b32_e32 v103, v2
	v_mov_b32_e32 v108, v2
	v_mov_b32_e32 v109, v2
	v_mov_b32_e32 v110, v2
	v_mov_b32_e32 v111, v2
	v_mov_b32_e32 v116, v2
	v_mov_b32_e32 v117, v2
	v_mov_b32_e32 v118, v2
	v_mov_b32_e32 v119, v2
	v_mov_b32_e32 v72, v2
	v_mov_b32_e32 v73, v2
	v_mov_b32_e32 v74, v2
	v_mov_b32_e32 v75, v2
	v_mov_b32_e32 v80, v2
	v_mov_b32_e32 v81, v2
	v_mov_b32_e32 v82, v2
	v_mov_b32_e32 v83, v2
	v_mov_b32_e32 v88, v2
	v_mov_b32_e32 v89, v2
	v_mov_b32_e32 v90, v2
	v_mov_b32_e32 v91, v2
	v_mov_b32_e32 v96, v2
	v_mov_b32_e32 v97, v2
	v_mov_b32_e32 v98, v2
	v_mov_b32_e32 v99, v2
	v_mov_b32_e32 v104, v2
	v_mov_b32_e32 v105, v2
	v_mov_b32_e32 v106, v2
	v_mov_b32_e32 v107, v2
	v_mov_b32_e32 v112, v2
	v_mov_b32_e32 v113, v2
	v_mov_b32_e32 v114, v2
	v_mov_b32_e32 v115, v2
	v_mov_b32_e32 v124, v2
	v_mov_b32_e32 v125, v2
	v_mov_b32_e32 v126, v2
	v_mov_b32_e32 v127, v2
	v_mov_b32_e32 v128, v2
	v_mov_b32_e32 v129, v2
	v_mov_b32_e32 v130, v2
	v_mov_b32_e32 v131, v2
	s_andn2_b64 vcc, exec, s[6:7]
	s_cbranch_vccnz .LBB0_1312

; #define PG8_STAGE(bufoff, gbase, voff) do { _Pragma("unroll") for (int _i = 0; _i < 2; ++_i) \
;         __builtin_amdgcn_global_load_lds((const unsigned*)((const char*)(gbase) + (voff)[_i]), (PG8_LAS unsigned*)(lds + (bufoff) + ldsw + _i * 8192), 16, 0, 0); } while (0)
; #define PG8_LDA(dst, b, h) do { _Pragma("unroll") for (int m = 0; m < 4; ++m) _Pragma("unroll") for (int k = 0; k < 2; ++k) dst[m][k] = *(const PG8_LAS bf16x8*)(lds + PG8_SA(b, h) + aoff + m * 2048 + k * 1024); } while (0)
; #define PG8_LDB(dst, b, h) do { _Pragma("unroll") for (int n = 0; n < 2; ++n) _Pragma("unroll") for (int k = 0; k < 2; ++k) dst[n][k] = *(const PG8_LAS bf16x8*)(lds + PG8_SB(b, h) + boff + n * 2048 + k * 1024); } while (0)
; #define PG8_MMA(ai, bj, At, Bt) do { __builtin_amdgcn_s_setprio(1); _Pragma("unroll") for (int m = 0; m < 4; ++m) _Pragma("unroll") for (int n = 0; n < 2; ++n) _Pragma("unroll") for (int k = 0; k < 2; ++k) \
;         acc[ai][bj][m][n] = __builtin_amdgcn_mfma_f32_16x16x32_bf16(Bt[n][k], At[m][k], acc[ai][bj][m][n], 0, 0, 0); __builtin_amdgcn_s_setprio(0); } while (0)
; #define PG8_WAIT_V(n) asm volatile("s_waitcnt vmcnt(" #n ")" ::: "memory")
; #define PG8_WAIT_L(n) asm volatile("s_waitcnt lgkmcnt(" #n ")" ::: "memory")
; #define PG8_BAR __builtin_amdgcn_s_barrier()
; template <class Epi, class Sched, bool ALIGN_EPI = false, bool SP2 = false>
; __device__ __forceinline__ void gemm_phase(PG8_LAS unsigned char* lds, const Gemm g, const Sched& S, const Epi& E) {
;     ...
;             const char* a1 = cA + (size_t)(t + 1) * kstep;
;             const char* a2 = last ? nA : cA + (size_t)(t + 2) * kstep; const char* b2 = last ? nB : cB + (size_t)(t + 2) * kstep;
;             const char* a3 = a2 + kstep; const char* b3 = b2 + kstep;
;             if (last && has_next) S.a_ready(nxt);
;             if constexpr (SP2) {
;             PG8_LDB(B0, 0, 0); PG8_LDB(B1, 0, 1); PG8_SCHED; PG8_LDA(At, 0, 0); PG8_STAGE(PG8_SA(1, 1), a1 + hstep, voffA);
;             PG8_WAIT_V(8); PG8_WAIT_L(0); PG8_BAR; PG8_MMA(0, 0, At, B0); PG8_MMA(0, 1, At, B1); PG8_BAR; PG8_SCHED;
;             PG8_LDA(At, 0, 1); PG8_STAGE(PG8_SB(0, 0), b2, voffB); PG8_STAGE(PG8_SB(0, 1), b2 + hstep, voffB); PG8_STAGE(PG8_SA(0, 0), a2, voffA);
;             PG8_WAIT_V(8); PG8_WAIT_L(0); PG8_BAR; PG8_MMA(1, 0, At, B0); PG8_MMA(1, 1, At, B1); PG8_BAR; PG8_SCHED;
.LBB0_1583:
	s_add_u32 s20, s18, 0x100
	s_addc_u32 s21, s19, 0
	s_cmp_eq_u32 s43, 4
	s_cselect_b32 s25, s17, s21
	s_cselect_b32 s24, s16, s20
	s_cselect_b32 s23, s15, s42
	s_cselect_b32 s22, s14, s13
	s_add_i32 s44, 0, 0x10000
	s_add_i32 s45, 0, 0x14000
	v_add_u32_e32 v168, s44, v0
	v_add_u32_e32 v184, s45, v0
	ds_read_b128 v[156:159], v168
	ds_read_b128 v[160:163], v168 offset:1024
	ds_read_b128 v[164:167], v168 offset:2048
	ds_read_b128 v[168:171], v168 offset:3072
	ds_read_b128 v[172:175], v184
	ds_read_b128 v[176:179], v184 offset:1024
	ds_read_b128 v[180:183], v184 offset:2048
	ds_read_b128 v[184:187], v184 offset:3072
	v_lshl_add_u64 v[228:229], s[18:19], 0, v[150:151]
	s_add_i32 m0, s28, 0xc000
	ds_read_b128 v[188:191], v155
	ds_read_b128 v[192:195], v155 offset:1024
	ds_read_b128 v[196:199], v155 offset:2048
	ds_read_b128 v[200:203], v155 offset:3072
	ds_read_b128 v[204:207], v155 offset:4096
	ds_read_b128 v[208:211], v155 offset:5120
	ds_read_b128 v[220:223], v155 offset:6144
	ds_read_b128 v[224:227], v155 offset:7168
	global_load_lds_dwordx4 v[228:229], off
	v_lshl_add_u64 v[228:229], s[18:19], 0, v[152:153]
	s_add_i32 m0, s28, 0xe000
	s_nop 0
	global_load_lds_dwordx4 v[228:229], off
	s_setprio 1
	s_waitcnt vmcnt(8)
	s_waitcnt lgkmcnt(0)
	s_barrier
	v_mfma_f32_16x16x32_bf16 v[128:131], v[156:159], v[188:191], v[128:131]
	v_mfma_f32_16x16x32_bf16 v[124:127], v[164:167], v[188:191], v[124:127]
	v_mfma_f32_16x16x32_bf16 v[120:123], v[156:159], v[196:199], v[120:123]
	v_mfma_f32_16x16x32_bf16 v[116:119], v[164:167], v[196:199], v[116:119]
	v_mfma_f32_16x16x32_bf16 v[112:115], v[156:159], v[204:207], v[112:115]
	v_mfma_f32_16x16x32_bf16 v[108:111], v[164:167], v[204:207], v[108:111]
	v_mfma_f32_16x16x32_bf16 v[100:103], v[156:159], v[220:223], v[100:103]
	v_mfma_f32_16x16x32_bf16 v[92:95], v[164:167], v[220:223], v[92:95]
	v_mfma_f32_16x16x32_bf16 v[128:131], v[160:163], v[192:195], v[128:131]
	v_mfma_f32_16x16x32_bf16 v[124:127], v[168:171], v[192:195], v[124:127]
	v_mfma_f32_16x16x32_bf16 v[120:123], v[160:163], v[200:203], v[120:123]
	v_mfma_f32_16x16x32_bf16 v[116:119], v[168:171], v[200:203], v[116:119]
	v_mfma_f32_16x16x32_bf16 v[112:115], v[160:163], v[208:211], v[112:115]
	v_mfma_f32_16x16x32_bf16 v[108:111], v[168:171], v[208:211], v[108:111]
	v_mfma_f32_16x16x32_bf16 v[100:103], v[160:163], v[224:227], v[100:103]
	v_mfma_f32_16x16x32_bf16 v[92:95], v[168:171], v[224:227], v[92:95]
	v_mfma_f32_16x16x32_bf16 v[104:107], v[172:175], v[188:191], v[104:107]
	v_mfma_f32_16x16x32_bf16 v[96:99], v[180:183], v[188:191], v[96:99]
	v_mfma_f32_16x16x32_bf16 v[88:91], v[172:175], v[196:199], v[88:91]
	v_mfma_f32_16x16x32_bf16 v[84:87], v[180:183], v[196:199], v[84:87]
	v_mfma_f32_16x16x32_bf16 v[80:83], v[172:175], v[204:207], v[80:83]
	v_mfma_f32_16x16x32_bf16 v[76:79], v[180:183], v[204:207], v[76:79]
	v_mfma_f32_16x16x32_bf16 v[72:75], v[172:175], v[220:223], v[72:75]
	v_mfma_f32_16x16x32_bf16 v[68:71], v[180:183], v[220:223], v[68:71]
	v_mfma_f32_16x16x32_bf16 v[104:107], v[176:179], v[192:195], v[104:107]
	v_mfma_f32_16x16x32_bf16 v[96:99], v[184:187], v[192:195], v[96:99]
	v_mfma_f32_16x16x32_bf16 v[88:91], v[176:179], v[200:203], v[88:91]
	v_mfma_f32_16x16x32_bf16 v[84:87], v[184:187], v[200:203], v[84:87]
	v_mfma_f32_16x16x32_bf16 v[80:83], v[176:179], v[208:211], v[80:83]
	v_mfma_f32_16x16x32_bf16 v[76:79], v[184:187], v[208:211], v[76:79]
	v_mfma_f32_16x16x32_bf16 v[72:75], v[176:179], v[224:227], v[72:75]
	v_mfma_f32_16x16x32_bf16 v[68:71], v[184:187], v[224:227], v[68:71]
	s_barrier
	s_add_i32 s18, s44, s1
	v_lshl_add_u64 v[228:229], s[22:23], 0, v[66:67]
	s_mov_b32 m0, s18
	ds_read_b128 v[188:191], v155 offset:16384
	ds_read_b128 v[192:195], v155 offset:17408
	ds_read_b128 v[196:199], v155 offset:18432
	ds_read_b128 v[200:203], v155 offset:19456
	ds_read_b128 v[204:207], v155 offset:20480
	ds_read_b128 v[208:211], v155 offset:21504
	ds_read_b128 v[220:223], v155 offset:22528
	ds_read_b128 v[224:227], v155 offset:23552
	global_load_lds_dwordx4 v[228:229], off
	s_add_i32 m0, s18, 0x2000
	s_add_u32 s18, s22, 0x160000
	v_lshl_add_u64 v[230:231], s[22:23], 0, v[132:133]
	s_addc_u32 s19, s23, 0
	s_add_i32 s44, s45, s1
	global_load_lds_dwordx4 v[230:231], off
	v_lshl_add_u64 v[232:233], s[18:19], 0, v[66:67]
	s_mov_b32 m0, s44
	v_lshl_add_u64 v[234:235], s[24:25], 0, v[132:133]
	global_load_lds_dwordx4 v[232:233], off
	v_lshl_add_u64 v[232:233], s[18:19], 0, v[132:133]
	s_add_i32 m0, s44, 0x2000
	s_nop 0
	global_load_lds_dwordx4 v[232:233], off
	v_lshl_add_u64 v[232:233], s[24:25], 0, v[66:67]
	s_mov_b32 m0, s28
	s_nop 0
	global_load_lds_dwordx4 v[232:233], off
	s_mov_b32 m0, s29
	s_nop 0
	global_load_lds_dwordx4 v[234:235], off
	s_setprio 0
	s_setprio 1
	s_setprio 0
	s_waitcnt lgkmcnt(0)
	s_setprio 1
	s_waitcnt vmcnt(8)
	s_waitcnt lgkmcnt(0)
	s_barrier
; #define PG8_STAGE(bufoff, gbase, voff) do { _Pragma("unroll") for (int _i = 0; _i < 2; ++_i) \
;         __builtin_amdgcn_global_load_lds((const unsigned*)((const char*)(gbase) + (voff)[_i]), (PG8_LAS unsigned*)(lds + (bufoff) + ldsw + _i * 8192), 16, 0, 0); } while (0)
; #define PG8_LDA(dst, b, h) do { _Pragma("unroll") for (int m = 0; m < 4; ++m) _Pragma("unroll") for (int k = 0; k < 2; ++k) dst[m][k] = *(const PG8_LAS bf16x8*)(lds + PG8_SA(b, h) + aoff + m * 2048 + k * 1024); } while (0)
; #define PG8_LDB(dst, b, h) do { _Pragma("unroll") for (int n = 0; n < 2; ++n) _Pragma("unroll") for (int k = 0; k < 2; ++k) dst[n][k] = *(const PG8_LAS bf16x8*)(lds + PG8_SB(b, h) + boff + n * 2048 + k * 1024); } while (0)
; #define PG8_MMA(ai, bj, At, Bt) do { __builtin_amdgcn_s_setprio(1); _Pragma("unroll") for (int m = 0; m < 4; ++m) _Pragma("unroll") for (int n = 0; n < 2; ++n) _Pragma("unroll") for (int k = 0; k < 2; ++k) \
;         acc[ai][bj][m][n] = __builtin_amdgcn_mfma_f32_16x16x32_bf16(Bt[n][k], At[m][k], acc[ai][bj][m][n], 0, 0, 0); __builtin_amdgcn_s_setprio(0); } while (0)
; #define PG8_WAIT_V(n) asm volatile("s_waitcnt vmcnt(" #n ")" ::: "memory")
; #define PG8_WAIT_L(n) asm volatile("s_waitcnt lgkmcnt(" #n ")" ::: "memory")
; #define PG8_BAR __builtin_amdgcn_s_barrier()
; #define PG8_SCHED __builtin_amdgcn_sched_barrier(0)
; template <class Epi, class Sched, bool ALIGN_EPI = false, bool SP2 = false>
; __device__ __forceinline__ void gemm_phase(PG8_LAS unsigned char* lds, const Gemm g, const Sched& S, const Epi& E) {
;     ...
;             PG8_WAIT_V(8); PG8_WAIT_L(0); PG8_BAR; PG8_MMA(1, 0, At, B0); PG8_MMA(1, 1, At, B1); PG8_BAR; PG8_SCHED;
;             PG8_LDB(B0, 1, 0); PG8_LDB(B1, 1, 1); PG8_SCHED; PG8_LDA(At, 1, 0); PG8_STAGE(PG8_SA(0, 1), a2 + hstep, voffA);
;             PG8_WAIT_V(8); PG8_WAIT_L(0); PG8_BAR; PG8_MMA(0, 0, At, B0); PG8_MMA(0, 1, At, B1); PG8_BAR; PG8_SCHED;
	v_mfma_f32_16x16x32_bf16 v[62:65], v[156:159], v[188:191], v[62:65]
	v_mfma_f32_16x16x32_bf16 v[58:61], v[164:167], v[188:191], v[58:61]
	v_mfma_f32_16x16x32_bf16 v[54:57], v[156:159], v[196:199], v[54:57]
	v_mfma_f32_16x16x32_bf16 v[50:53], v[164:167], v[196:199], v[50:53]
	v_mfma_f32_16x16x32_bf16 v[46:49], v[156:159], v[204:207], v[46:49]
	v_mfma_f32_16x16x32_bf16 v[42:45], v[164:167], v[204:207], v[42:45]
	v_mfma_f32_16x16x32_bf16 v[34:37], v[156:159], v[220:223], v[34:37]
	v_mfma_f32_16x16x32_bf16 v[26:29], v[164:167], v[220:223], v[26:29]
	v_mfma_f32_16x16x32_bf16 v[62:65], v[160:163], v[192:195], v[62:65]
	v_mfma_f32_16x16x32_bf16 v[58:61], v[168:171], v[192:195], v[58:61]
	v_mfma_f32_16x16x32_bf16 v[54:57], v[160:163], v[200:203], v[54:57]
	v_mfma_f32_16x16x32_bf16 v[50:53], v[168:171], v[200:203], v[50:53]
	v_mfma_f32_16x16x32_bf16 v[46:49], v[160:163], v[208:211], v[46:49]
	v_mfma_f32_16x16x32_bf16 v[42:45], v[168:171], v[208:211], v[42:45]
	v_mfma_f32_16x16x32_bf16 v[34:37], v[160:163], v[224:227], v[34:37]
	v_mfma_f32_16x16x32_bf16 v[26:29], v[168:171], v[224:227], v[26:29]
	v_mfma_f32_16x16x32_bf16 v[38:41], v[172:175], v[188:191], v[38:41]
	v_mfma_f32_16x16x32_bf16 v[30:33], v[180:183], v[188:191], v[30:33]
	v_mfma_f32_16x16x32_bf16 v[22:25], v[172:175], v[196:199], v[22:25]
	v_mfma_f32_16x16x32_bf16 v[18:21], v[180:183], v[196:199], v[18:21]
	v_mfma_f32_16x16x32_bf16 v[14:17], v[172:175], v[204:207], v[14:17]
	v_mfma_f32_16x16x32_bf16 v[10:13], v[180:183], v[204:207], v[10:13]
	v_mfma_f32_16x16x32_bf16 v[6:9], v[172:175], v[220:223], v[6:9]
	v_mfma_f32_16x16x32_bf16 v[2:5], v[180:183], v[220:223], v[2:5]
	v_mfma_f32_16x16x32_bf16 v[38:41], v[176:179], v[192:195], v[38:41]
	v_mfma_f32_16x16x32_bf16 v[30:33], v[184:187], v[192:195], v[30:33]
	v_mfma_f32_16x16x32_bf16 v[22:25], v[176:179], v[200:203], v[22:25]
	v_mfma_f32_16x16x32_bf16 v[18:21], v[184:187], v[200:203], v[18:21]
	v_mfma_f32_16x16x32_bf16 v[14:17], v[176:179], v[208:211], v[14:17]
	v_mfma_f32_16x16x32_bf16 v[10:13], v[184:187], v[208:211], v[10:13]
	v_mfma_f32_16x16x32_bf16 v[6:9], v[176:179], v[224:227], v[6:9]
	v_mfma_f32_16x16x32_bf16 v[2:5], v[184:187], v[224:227], v[2:5]
	s_barrier
	s_add_i32 s44, 0, 0x18000
	s_add_i32 s45, 0, 0x1c000
	v_add_u32_e32 v168, s44, v0
	v_add_u32_e32 v184, s45, v0
	ds_read_b128 v[156:159], v168
	ds_read_b128 v[160:163], v168 offset:1024
	ds_read_b128 v[164:167], v168 offset:2048
	ds_read_b128 v[168:171], v168 offset:3072
	ds_read_b128 v[172:175], v184
	ds_read_b128 v[176:179], v184 offset:1024
	ds_read_b128 v[180:183], v184 offset:2048
	ds_read_b128 v[184:187], v184 offset:3072
	s_add_u32 s18, s24, 0x160000
	s_addc_u32 s19, s25, 0
	s_mov_b32 m0, s30
	v_lshl_add_u64 v[246:247], s[18:19], 0, v[66:67]
	ds_read_b128 v[188:191], v155 offset:32768
	ds_read_b128 v[192:195], v155 offset:33792
	ds_read_b128 v[196:199], v155 offset:34816
	ds_read_b128 v[200:203], v155 offset:35840
	ds_read_b128 v[204:207], v155 offset:36864
	ds_read_b128 v[208:211], v155 offset:37888
	ds_read_b128 v[220:223], v155 offset:38912
	ds_read_b128 v[224:227], v155 offset:39936
	global_load_lds_dwordx4 v[246:247], off
	v_lshl_add_u64 v[246:247], s[18:19], 0, v[132:133]
	s_mov_b32 m0, s31
	s_nop 0
	global_load_lds_dwordx4 v[246:247], off
	s_setprio 0
	s_setprio 1
	s_setprio 0
	s_waitcnt lgkmcnt(0)
	s_setprio 1
	s_waitcnt vmcnt(8)
	s_waitcnt lgkmcnt(0)
	s_barrier
	v_mfma_f32_16x16x32_bf16 v[128:131], v[156:159], v[188:191], v[128:131]
	v_mfma_f32_16x16x32_bf16 v[124:127], v[164:167], v[188:191], v[124:127]
	v_mfma_f32_16x16x32_bf16 v[120:123], v[156:159], v[196:199], v[120:123]
	v_mfma_f32_16x16x32_bf16 v[116:119], v[164:167], v[196:199], v[116:119]
	v_mfma_f32_16x16x32_bf16 v[112:115], v[156:159], v[204:207], v[112:115]
	v_mfma_f32_16x16x32_bf16 v[108:111], v[164:167], v[204:207], v[108:111]
	v_mfma_f32_16x16x32_bf16 v[100:103], v[156:159], v[220:223], v[100:103]
	v_mfma_f32_16x16x32_bf16 v[92:95], v[164:167], v[220:223], v[92:95]
	v_mfma_f32_16x16x32_bf16 v[128:131], v[160:163], v[192:195], v[128:131]
	v_mfma_f32_16x16x32_bf16 v[124:127], v[168:171], v[192:195], v[124:127]
	v_mfma_f32_16x16x32_bf16 v[120:123], v[160:163], v[200:203], v[120:123]
	v_mfma_f32_16x16x32_bf16 v[116:119], v[168:171], v[200:203], v[116:119]
	v_mfma_f32_16x16x32_bf16 v[112:115], v[160:163], v[208:211], v[112:115]
	v_mfma_f32_16x16x32_bf16 v[108:111], v[168:171], v[208:211], v[108:111]
	v_mfma_f32_16x16x32_bf16 v[100:103], v[160:163], v[224:227], v[100:103]
	v_mfma_f32_16x16x32_bf16 v[92:95], v[168:171], v[224:227], v[92:95]
	v_mfma_f32_16x16x32_bf16 v[104:107], v[172:175], v[188:191], v[104:107]
	v_mfma_f32_16x16x32_bf16 v[96:99], v[180:183], v[188:191], v[96:99]
	v_mfma_f32_16x16x32_bf16 v[88:91], v[172:175], v[196:199], v[88:91]
	v_mfma_f32_16x16x32_bf16 v[84:87], v[180:183], v[196:199], v[84:87]
	v_mfma_f32_16x16x32_bf16 v[80:83], v[172:175], v[204:207], v[80:83]
	v_mfma_f32_16x16x32_bf16 v[76:79], v[180:183], v[204:207], v[76:79]
	v_mfma_f32_16x16x32_bf16 v[72:75], v[172:175], v[220:223], v[72:75]
	v_mfma_f32_16x16x32_bf16 v[68:71], v[180:183], v[220:223], v[68:71]
	v_mfma_f32_16x16x32_bf16 v[104:107], v[176:179], v[192:195], v[104:107]
	v_mfma_f32_16x16x32_bf16 v[96:99], v[184:187], v[192:195], v[96:99]
	v_mfma_f32_16x16x32_bf16 v[88:91], v[176:179], v[200:203], v[88:91]
	v_mfma_f32_16x16x32_bf16 v[84:87], v[184:187], v[200:203], v[84:87]
	v_mfma_f32_16x16x32_bf16 v[80:83], v[176:179], v[208:211], v[80:83]
	v_mfma_f32_16x16x32_bf16 v[76:79], v[184:187], v[208:211], v[76:79]
	v_mfma_f32_16x16x32_bf16 v[72:75], v[176:179], v[224:227], v[72:75]
	v_mfma_f32_16x16x32_bf16 v[68:71], v[184:187], v[224:227], v[68:71]
	s_barrier
; #define PG8_STAGE(bufoff, gbase, voff) do { _Pragma("unroll") for (int _i = 0; _i < 2; ++_i) \
;         __builtin_amdgcn_global_load_lds((const unsigned*)((const char*)(gbase) + (voff)[_i]), (PG8_LAS unsigned*)(lds + (bufoff) + ldsw + _i * 8192), 16, 0, 0); } while (0)
; #define PG8_LDA(dst, b, h) do { _Pragma("unroll") for (int m = 0; m < 4; ++m) _Pragma("unroll") for (int k = 0; k < 2; ++k) dst[m][k] = *(const PG8_LAS bf16x8*)(lds + PG8_SA(b, h) + aoff + m * 2048 + k * 1024); } while (0)
; #define PG8_MMA(ai, bj, At, Bt) do { __builtin_amdgcn_s_setprio(1); _Pragma("unroll") for (int m = 0; m < 4; ++m) _Pragma("unroll") for (int n = 0; n < 2; ++n) _Pragma("unroll") for (int k = 0; k < 2; ++k) \
;         acc[ai][bj][m][n] = __builtin_amdgcn_mfma_f32_16x16x32_bf16(Bt[n][k], At[m][k], acc[ai][bj][m][n], 0, 0, 0); __builtin_amdgcn_s_setprio(0); } while (0)
; #define PG8_WAIT_V(n) asm volatile("s_waitcnt vmcnt(" #n ")" ::: "memory")
; #define PG8_WAIT_L(n) asm volatile("s_waitcnt lgkmcnt(" #n ")" ::: "memory")
; #define PG8_BAR __builtin_amdgcn_s_barrier()
; #define PG8_SCHED __builtin_amdgcn_sched_barrier(0)
; template <class Epi, class Sched, bool ALIGN_EPI = false, bool SP2 = false>
; __device__ __forceinline__ void gemm_phase(PG8_LAS unsigned char* lds, const Gemm g, const Sched& S, const Epi& E) {
;     ...
;             PG8_LDA(At, 1, 1); PG8_STAGE(PG8_SB(1, 0), b3, voffB); PG8_STAGE(PG8_SB(1, 1), b3 + hstep, voffB); PG8_STAGE(PG8_SA(1, 0), a3, voffA);
;             PG8_WAIT_V(8); PG8_WAIT_L(0); PG8_BAR; PG8_MMA(1, 0, At, B0); PG8_MMA(1, 1, At, B1); PG8_BAR; PG8_SCHED;
	s_add_i32 s18, s44, s1
	v_lshl_add_u64 v[228:229], v[228:229], 0, s[88:89]
	s_mov_b32 m0, s18
	ds_read_b128 v[188:191], v155 offset:49152
	ds_read_b128 v[192:195], v155 offset:50176
	ds_read_b128 v[196:199], v155 offset:51200
	ds_read_b128 v[200:203], v155 offset:52224
	ds_read_b128 v[204:207], v155 offset:53248
	ds_read_b128 v[208:211], v155 offset:54272
	ds_read_b128 v[220:223], v155 offset:55296
	ds_read_b128 v[224:227], v155 offset:56320
	global_load_lds_dwordx4 v[228:229], off
	s_add_i32 m0, s18, 0x2000
	s_add_u32 s18, s22, 0x160080
	v_lshl_add_u64 v[228:229], v[230:231], 0, s[88:89]
	s_addc_u32 s19, s23, 0
	s_add_i32 s22, s45, s1
	global_load_lds_dwordx4 v[228:229], off
	v_lshl_add_u64 v[228:229], s[18:19], 0, v[66:67]
	s_mov_b32 m0, s22
	s_nop 0
	global_load_lds_dwordx4 v[228:229], off
	v_lshl_add_u64 v[228:229], s[18:19], 0, v[132:133]
	s_add_i32 m0, s22, 0x2000
	s_nop 0
	global_load_lds_dwordx4 v[228:229], off
	v_lshl_add_u64 v[228:229], v[232:233], 0, s[88:89]
	s_mov_b32 m0, s38
	s_nop 0
	global_load_lds_dwordx4 v[228:229], off
	v_lshl_add_u64 v[228:229], v[234:235], 0, s[88:89]
	s_mov_b32 m0, s39
	s_nop 0
	global_load_lds_dwordx4 v[228:229], off
	s_setprio 0
	s_setprio 1
	s_setprio 0
	s_waitcnt lgkmcnt(0)
	s_setprio 1
	s_waitcnt vmcnt(8)
	s_waitcnt lgkmcnt(0)
	s_barrier
	v_mfma_f32_16x16x32_bf16 v[62:65], v[156:159], v[188:191], v[62:65]
	v_mfma_f32_16x16x32_bf16 v[58:61], v[164:167], v[188:191], v[58:61]
	v_mfma_f32_16x16x32_bf16 v[54:57], v[156:159], v[196:199], v[54:57]
	v_mfma_f32_16x16x32_bf16 v[50:53], v[164:167], v[196:199], v[50:53]
	v_mfma_f32_16x16x32_bf16 v[46:49], v[156:159], v[204:207], v[46:49]
	v_mfma_f32_16x16x32_bf16 v[42:45], v[164:167], v[204:207], v[42:45]
	v_mfma_f32_16x16x32_bf16 v[34:37], v[156:159], v[220:223], v[34:37]
	v_mfma_f32_16x16x32_bf16 v[26:29], v[164:167], v[220:223], v[26:29]
	v_mfma_f32_16x16x32_bf16 v[62:65], v[160:163], v[192:195], v[62:65]
	v_mfma_f32_16x16x32_bf16 v[58:61], v[168:171], v[192:195], v[58:61]
	v_mfma_f32_16x16x32_bf16 v[54:57], v[160:163], v[200:203], v[54:57]
	v_mfma_f32_16x16x32_bf16 v[50:53], v[168:171], v[200:203], v[50:53]
	v_mfma_f32_16x16x32_bf16 v[46:49], v[160:163], v[208:211], v[46:49]
	v_mfma_f32_16x16x32_bf16 v[42:45], v[168:171], v[208:211], v[42:45]
	v_mfma_f32_16x16x32_bf16 v[34:37], v[160:163], v[224:227], v[34:37]
	v_mfma_f32_16x16x32_bf16 v[26:29], v[168:171], v[224:227], v[26:29]
	v_mfma_f32_16x16x32_bf16 v[38:41], v[172:175], v[188:191], v[38:41]
	v_mfma_f32_16x16x32_bf16 v[30:33], v[180:183], v[188:191], v[30:33]
	v_mfma_f32_16x16x32_bf16 v[22:25], v[172:175], v[196:199], v[22:25]
	v_mfma_f32_16x16x32_bf16 v[18:21], v[180:183], v[196:199], v[18:21]
	v_mfma_f32_16x16x32_bf16 v[14:17], v[172:175], v[204:207], v[14:17]
	v_mfma_f32_16x16x32_bf16 v[10:13], v[180:183], v[204:207], v[10:13]
	v_mfma_f32_16x16x32_bf16 v[6:9], v[172:175], v[220:223], v[6:9]
	v_mfma_f32_16x16x32_bf16 v[2:5], v[180:183], v[220:223], v[2:5]
	v_mfma_f32_16x16x32_bf16 v[38:41], v[176:179], v[192:195], v[38:41]
	v_mfma_f32_16x16x32_bf16 v[30:33], v[184:187], v[192:195], v[30:33]
	v_mfma_f32_16x16x32_bf16 v[22:25], v[176:179], v[200:203], v[22:25]
	v_mfma_f32_16x16x32_bf16 v[18:21], v[184:187], v[200:203], v[18:21]
	v_mfma_f32_16x16x32_bf16 v[14:17], v[176:179], v[208:211], v[14:17]
	v_mfma_f32_16x16x32_bf16 v[10:13], v[184:187], v[208:211], v[10:13]
	v_mfma_f32_16x16x32_bf16 v[6:9], v[176:179], v[224:227], v[6:9]
	v_mfma_f32_16x16x32_bf16 v[2:5], v[184:187], v[224:227], v[2:5]
	s_barrier
	s_setprio 0
	s_setprio 1
	s_setprio 0
	s_waitcnt lgkmcnt(0)
	s_add_i32 s43, s43, 2
	s_add_u32 s13, s13, 0x100
	s_addc_u32 s42, s42, 0
	s_cmp_gt_u32 s43, 5
	s_mov_b64 s[18:19], s[20:21]
	s_cbranch_scc0 .LBB0_1583
	s_and_b64 vcc, exec, s[10:11]
	s_cbranch_vccz .LBB0_1586
	s_barrier
